# GEMM epilogue half-exchange (st_pair): cndmask+ds_bpermute+2 cndmask per dword replaced by v_mov x2 + v_permlane16_swap (480 of 512 sites); removed slots kept as s_nop so hazard distances are unchange
# baseline (speedup 1.0000x reference)
.LBB0_147:
	s_waitcnt lgkmcnt(0)
	s_barrier
	ds_read_b128 v[224:227], v184
	ds_read_b128 v[228:231], v184 offset:1024
	ds_read_b128 v[232:235], v184 offset:2048
	ds_read_b128 v[236:239], v184 offset:3072
	ds_read_b128 v[190:193], v185
	ds_read_b128 v[194:197], v185 offset:1024
	ds_read_b128 v[198:201], v185 offset:2048
	ds_read_b128 v[204:207], v185 offset:3072
	ds_read_b128 v[208:211], v185 offset:4096
	ds_read_b128 v[212:215], v185 offset:5120
	ds_read_b128 v[216:219], v185 offset:6144
	ds_read_b128 v[220:223], v185 offset:7168
	s_movk_i32 vcc_lo, 0x6000
	s_cmp_eq_u32 m0, 2
	s_cselect_b32 vcc_lo, 0xffff4000, vcc_lo
	s_add_u32 m0, m0, 1
	s_cmp_eq_u32 m0, 3
	s_cselect_b32 m0, 0, m0
	v_add_u32_e32 v185, vcc_lo, v185
	v_add_u32_e32 v184, vcc_lo, v184
	v_xor_b32_e32 v185, 64, v185
	v_xor_b32_e32 v184, 64, v184
	s_waitcnt lgkmcnt(7)
	v_mfma_f32_16x16x32_bf16 v[172:175], v[224:227], v[190:193], v[172:175]
	v_mfma_f32_16x16x32_bf16 v[168:171], v[228:231], v[190:193], v[168:171]
	v_mfma_f32_16x16x32_bf16 v[164:167], v[232:235], v[190:193], v[164:167]
	v_mfma_f32_16x16x32_bf16 v[160:163], v[236:239], v[190:193], v[160:163]
	ds_read_b128 v[190:193], v185
	s_waitcnt lgkmcnt(7)
	v_mfma_f32_16x16x32_bf16 v[156:159], v[224:227], v[194:197], v[156:159]
	v_mfma_f32_16x16x32_bf16 v[152:155], v[228:231], v[194:197], v[152:155]
	v_mfma_f32_16x16x32_bf16 v[148:151], v[232:235], v[194:197], v[148:151]
	v_mfma_f32_16x16x32_bf16 v[144:147], v[236:239], v[194:197], v[144:147]
	ds_read_b128 v[194:197], v185 offset:1024
	s_waitcnt lgkmcnt(7)
	v_mfma_f32_16x16x32_bf16 v[136:139], v[224:227], v[198:201], v[136:139]
	v_mfma_f32_16x16x32_bf16 v[132:135], v[228:231], v[198:201], v[132:135]
	v_mfma_f32_16x16x32_bf16 v[128:131], v[232:235], v[198:201], v[128:131]
	v_mfma_f32_16x16x32_bf16 v[124:127], v[236:239], v[198:201], v[124:127]
	ds_read_b128 v[198:201], v185 offset:2048
	s_waitcnt lgkmcnt(7)
	v_mfma_f32_16x16x32_bf16 v[120:123], v[224:227], v[204:207], v[120:123]
	v_mfma_f32_16x16x32_bf16 v[108:111], v[228:231], v[204:207], v[108:111]
	v_mfma_f32_16x16x32_bf16 v[100:103], v[232:235], v[204:207], v[100:103]
	v_mfma_f32_16x16x32_bf16 v[96:99], v[236:239], v[204:207], v[96:99]
	ds_read_b128 v[204:207], v185 offset:3072
	s_waitcnt lgkmcnt(7)
	v_mfma_f32_16x16x32_bf16 v[92:95], v[224:227], v[208:211], v[92:95]
	v_mfma_f32_16x16x32_bf16 v[84:87], v[228:231], v[208:211], v[84:87]
	v_mfma_f32_16x16x32_bf16 v[76:79], v[232:235], v[208:211], v[76:79]
	v_mfma_f32_16x16x32_bf16 v[72:75], v[236:239], v[208:211], v[72:75]
	ds_read_b128 v[208:211], v185 offset:4096
	s_waitcnt lgkmcnt(7)
	v_mfma_f32_16x16x32_bf16 v[64:67], v[224:227], v[212:215], v[64:67]
	v_mfma_f32_16x16x32_bf16 v[52:55], v[228:231], v[212:215], v[52:55]
	v_mfma_f32_16x16x32_bf16 v[48:51], v[232:235], v[212:215], v[48:51]
	v_mfma_f32_16x16x32_bf16 v[44:47], v[236:239], v[212:215], v[44:47]
	ds_read_b128 v[212:215], v185 offset:5120
	s_waitcnt lgkmcnt(7)
	v_mfma_f32_16x16x32_bf16 v[36:39], v[224:227], v[216:219], v[36:39]
	v_mfma_f32_16x16x32_bf16 v[28:31], v[228:231], v[216:219], v[28:31]
	v_mfma_f32_16x16x32_bf16 v[24:27], v[232:235], v[216:219], v[24:27]
	v_mfma_f32_16x16x32_bf16 v[20:23], v[236:239], v[216:219], v[20:23]
	ds_read_b128 v[216:219], v185 offset:6144
	s_waitcnt lgkmcnt(7)
	v_mfma_f32_16x16x32_bf16 v[12:15], v[224:227], v[220:223], v[12:15]
	v_mfma_f32_16x16x32_bf16 v[4:7], v[228:231], v[220:223], v[4:7]
	v_mfma_f32_16x16x32_bf16 v[0:3], v[232:235], v[220:223], v[0:3]
	v_mfma_f32_16x16x32_bf16 v[140:143], v[236:239], v[220:223], v[140:143]
	ds_read_b128 v[220:223], v185 offset:7168
	ds_read_b128 v[224:227], v184
	ds_read_b128 v[228:231], v184 offset:1024
	ds_read_b128 v[232:235], v184 offset:2048
	ds_read_b128 v[236:239], v184 offset:3072
	s_movk_i32 vcc_lo, 0x6000
	s_cmp_eq_u32 m0, 2
	s_cselect_b32 vcc_lo, 0xffff4000, vcc_lo
	s_add_u32 m0, m0, 1
	s_cmp_eq_u32 m0, 3
	s_cselect_b32 m0, 0, m0
	v_add_u32_e32 v185, vcc_lo, v185
	v_add_u32_e32 v184, vcc_lo, v184
	v_xor_b32_e32 v185, 64, v185
	v_xor_b32_e32 v184, 64, v184
	s_sub_u32 vcc_lo, s8, s98
	v_add_u32_e32 v186, vcc_lo, v178
	v_add_u32_e32 v187, vcc_lo, v180
	s_barrier
	s_waitcnt lgkmcnt(0)
	v_mfma_f32_16x16x32_bf16 v[172:175], v[224:227], v[190:193], v[172:175]
	s_waitcnt vmcnt(11)
	v_mfma_f32_16x16x32_bf16 v[168:171], v[228:231], v[190:193], v[168:171]
	ds_write_b128 v183, v[116:119]
	v_add_u32_e32 v116, s26, v187
	v_mfma_f32_16x16x32_bf16 v[164:167], v[232:235], v[190:193], v[164:167]
	global_load_dwordx4 v[116:119], v116, s[98:99] offset:128
	v_mfma_f32_16x16x32_bf16 v[160:163], v[236:239], v[190:193], v[160:163]
	s_waitcnt vmcnt(11)
	ds_write_b128 v183, v[112:115] offset:2048
	v_mfma_f32_16x16x32_bf16 v[156:159], v[224:227], v[194:197], v[156:159]
	v_add_u32_e32 v112, s27, v187
	v_mfma_f32_16x16x32_bf16 v[152:155], v[228:231], v[194:197], v[152:155]
	global_load_dwordx4 v[112:115], v112, s[98:99] offset:128
	s_waitcnt vmcnt(11)
	v_mfma_f32_16x16x32_bf16 v[148:151], v[232:235], v[194:197], v[148:151]
	ds_write_b128 v183, v[104:107] offset:4096
	v_mfma_f32_16x16x32_bf16 v[144:147], v[236:239], v[194:197], v[144:147]
	v_add_u32_e32 v104, s20, v187
	global_load_dwordx4 v[104:107], v104, s[98:99] offset:128
	v_mfma_f32_16x16x32_bf16 v[136:139], v[224:227], v[198:201], v[136:139]
	s_waitcnt vmcnt(11)
	v_mfma_f32_16x16x32_bf16 v[132:135], v[228:231], v[198:201], v[132:135]
	ds_write_b128 v183, v[88:91] offset:6144
	v_add_u32_e32 v88, s21, v187
	v_mfma_f32_16x16x32_bf16 v[128:131], v[232:235], v[198:201], v[128:131]
	global_load_dwordx4 v[88:91], v88, s[98:99] offset:128
	v_mfma_f32_16x16x32_bf16 v[124:127], v[236:239], v[198:201], v[124:127]
	s_waitcnt vmcnt(11)
	ds_write_b128 v183, v[80:83] offset:8192
	v_mfma_f32_16x16x32_bf16 v[120:123], v[224:227], v[204:207], v[120:123]
	v_add_u32_e32 v80, s56, v187
	v_mfma_f32_16x16x32_bf16 v[108:111], v[228:231], v[204:207], v[108:111]
	global_load_dwordx4 v[80:83], v80, s[98:99] offset:128
	s_waitcnt vmcnt(11)
	v_mfma_f32_16x16x32_bf16 v[100:103], v[232:235], v[204:207], v[100:103]
	ds_write_b128 v183, v[68:71] offset:10240
	v_mfma_f32_16x16x32_bf16 v[96:99], v[236:239], v[204:207], v[96:99]
	v_add_u32_e32 v68, s57, v187
	global_load_dwordx4 v[68:71], v68, s[98:99] offset:128
	v_mfma_f32_16x16x32_bf16 v[92:95], v[224:227], v[208:211], v[92:95]
	s_waitcnt vmcnt(11)
	v_mfma_f32_16x16x32_bf16 v[84:87], v[228:231], v[208:211], v[84:87]
	ds_write_b128 v183, v[60:63] offset:12288
	v_add_u32_e32 v60, s24, v187
	v_mfma_f32_16x16x32_bf16 v[76:79], v[232:235], v[208:211], v[76:79]
	global_load_dwordx4 v[60:63], v60, s[98:99] offset:128
	v_mfma_f32_16x16x32_bf16 v[72:75], v[236:239], v[208:211], v[72:75]
	s_waitcnt vmcnt(11)
	ds_write_b128 v183, v[40:43] offset:14336
	v_mfma_f32_16x16x32_bf16 v[64:67], v[224:227], v[212:215], v[64:67]
	v_add_u32_e32 v40, s96, v187
	v_mfma_f32_16x16x32_bf16 v[52:55], v[228:231], v[212:215], v[52:55]
	global_load_dwordx4 v[40:43], v40, s[98:99] offset:128
	s_waitcnt vmcnt(11)
	v_mfma_f32_16x16x32_bf16 v[48:51], v[232:235], v[212:215], v[48:51]
	ds_write_b128 v183, v[56:59] offset:16384
	v_mfma_f32_16x16x32_bf16 v[44:47], v[236:239], v[212:215], v[44:47]
	v_mov_b32_e32 v56, v186
	global_load_dwordx4 v[56:59], v56, s[98:99] offset:128
	v_mfma_f32_16x16x32_bf16 v[36:39], v[224:227], v[216:219], v[36:39]
	s_waitcnt vmcnt(11)
	v_mfma_f32_16x16x32_bf16 v[28:31], v[228:231], v[216:219], v[28:31]
	ds_write_b128 v183, v[32:35] offset:18432
	v_add_u32_e32 v32, s31, v186
	v_mfma_f32_16x16x32_bf16 v[24:27], v[232:235], v[216:219], v[24:27]
	global_load_dwordx4 v[32:35], v32, s[98:99] offset:128
	v_mfma_f32_16x16x32_bf16 v[20:23], v[236:239], v[216:219], v[20:23]
	s_waitcnt vmcnt(11)
	ds_write_b128 v183, v[16:19] offset:20480
	v_mfma_f32_16x16x32_bf16 v[12:15], v[224:227], v[220:223], v[12:15]
	v_add_u32_e32 v16, s14, v186
	v_mfma_f32_16x16x32_bf16 v[4:7], v[228:231], v[220:223], v[4:7]
	global_load_dwordx4 v[16:19], v16, s[98:99] offset:128
	s_waitcnt vmcnt(11)
	v_mfma_f32_16x16x32_bf16 v[0:3], v[232:235], v[220:223], v[0:3]
	ds_write_b128 v183, v[8:11] offset:22528
	v_mfma_f32_16x16x32_bf16 v[140:143], v[236:239], v[220:223], v[140:143]
	v_add_u32_e32 v8, s13, v186
	global_load_dwordx4 v[8:11], v8, s[98:99] offset:128
	v_cmp_gt_u32_e32 vcc, 0x6000, v183
	v_add_u32_e32 v182, 0xc000, v183
	v_add_u32_e32 v183, 0xffffa000, v183
	s_nop 0
	v_cndmask_b32_e32 v183, v183, v182, vcc
	s_add_u32 s8, s8, 0x80
	s_addc_u32 s9, s9, 0
	s_cmpk_lg_i32 s8, 0x780
	s_cbranch_scc1 .LBB0_147
	s_waitcnt lgkmcnt(0)
	s_barrier
	ds_read_b128 v[224:227], v184
	ds_read_b128 v[228:231], v184 offset:1024
	ds_read_b128 v[232:235], v184 offset:2048
	ds_read_b128 v[236:239], v184 offset:3072
	ds_read_b128 v[190:193], v185
	ds_read_b128 v[194:197], v185 offset:1024
	ds_read_b128 v[198:201], v185 offset:2048
	ds_read_b128 v[204:207], v185 offset:3072
	ds_read_b128 v[208:211], v185 offset:4096
	ds_read_b128 v[212:215], v185 offset:5120
	ds_read_b128 v[216:219], v185 offset:6144
	ds_read_b128 v[220:223], v185 offset:7168
	s_movk_i32 vcc_lo, 0x6000
	s_cmp_eq_u32 m0, 2
	s_cselect_b32 vcc_lo, 0xffff4000, vcc_lo
	s_add_u32 m0, m0, 1
	s_cmp_eq_u32 m0, 3
	s_cselect_b32 m0, 0, m0
	v_add_u32_e32 v185, vcc_lo, v185
	v_add_u32_e32 v184, vcc_lo, v184
	v_xor_b32_e32 v185, 64, v185
	v_xor_b32_e32 v184, 64, v184
	s_waitcnt lgkmcnt(7)
	v_mfma_f32_16x16x32_bf16 v[172:175], v[224:227], v[190:193], v[172:175]
	v_mfma_f32_16x16x32_bf16 v[168:171], v[228:231], v[190:193], v[168:171]
	v_mfma_f32_16x16x32_bf16 v[164:167], v[232:235], v[190:193], v[164:167]
	v_mfma_f32_16x16x32_bf16 v[160:163], v[236:239], v[190:193], v[160:163]
	ds_read_b128 v[190:193], v185
	s_waitcnt lgkmcnt(7)
	v_mfma_f32_16x16x32_bf16 v[156:159], v[224:227], v[194:197], v[156:159]
	v_mfma_f32_16x16x32_bf16 v[152:155], v[228:231], v[194:197], v[152:155]
	v_mfma_f32_16x16x32_bf16 v[148:151], v[232:235], v[194:197], v[148:151]
	v_mfma_f32_16x16x32_bf16 v[144:147], v[236:239], v[194:197], v[144:147]
	ds_read_b128 v[194:197], v185 offset:1024
	s_waitcnt lgkmcnt(7)
	v_mfma_f32_16x16x32_bf16 v[136:139], v[224:227], v[198:201], v[136:139]
	v_mfma_f32_16x16x32_bf16 v[132:135], v[228:231], v[198:201], v[132:135]
	v_mfma_f32_16x16x32_bf16 v[128:131], v[232:235], v[198:201], v[128:131]
	v_mfma_f32_16x16x32_bf16 v[124:127], v[236:239], v[198:201], v[124:127]
	ds_read_b128 v[198:201], v185 offset:2048
	s_waitcnt lgkmcnt(7)
	v_mfma_f32_16x16x32_bf16 v[120:123], v[224:227], v[204:207], v[120:123]
	v_mfma_f32_16x16x32_bf16 v[108:111], v[228:231], v[204:207], v[108:111]
	v_mfma_f32_16x16x32_bf16 v[100:103], v[232:235], v[204:207], v[100:103]
	v_mfma_f32_16x16x32_bf16 v[96:99], v[236:239], v[204:207], v[96:99]
	ds_read_b128 v[204:207], v185 offset:3072
	s_waitcnt lgkmcnt(7)
	v_mfma_f32_16x16x32_bf16 v[92:95], v[224:227], v[208:211], v[92:95]
	v_mfma_f32_16x16x32_bf16 v[84:87], v[228:231], v[208:211], v[84:87]
	v_mfma_f32_16x16x32_bf16 v[76:79], v[232:235], v[208:211], v[76:79]
	v_mfma_f32_16x16x32_bf16 v[72:75], v[236:239], v[208:211], v[72:75]
	ds_read_b128 v[208:211], v185 offset:4096
	s_waitcnt lgkmcnt(7)
	v_mfma_f32_16x16x32_bf16 v[64:67], v[224:227], v[212:215], v[64:67]
	v_mfma_f32_16x16x32_bf16 v[52:55], v[228:231], v[212:215], v[52:55]
	v_mfma_f32_16x16x32_bf16 v[48:51], v[232:235], v[212:215], v[48:51]
	v_mfma_f32_16x16x32_bf16 v[44:47], v[236:239], v[212:215], v[44:47]
	ds_read_b128 v[212:215], v185 offset:5120
	s_waitcnt lgkmcnt(7)
	v_mfma_f32_16x16x32_bf16 v[36:39], v[224:227], v[216:219], v[36:39]
	v_mfma_f32_16x16x32_bf16 v[28:31], v[228:231], v[216:219], v[28:31]
	v_mfma_f32_16x16x32_bf16 v[24:27], v[232:235], v[216:219], v[24:27]
	v_mfma_f32_16x16x32_bf16 v[20:23], v[236:239], v[216:219], v[20:23]
	ds_read_b128 v[216:219], v185 offset:6144
	s_waitcnt lgkmcnt(7)
	v_mfma_f32_16x16x32_bf16 v[12:15], v[224:227], v[220:223], v[12:15]
	v_mfma_f32_16x16x32_bf16 v[4:7], v[228:231], v[220:223], v[4:7]
	v_mfma_f32_16x16x32_bf16 v[0:3], v[232:235], v[220:223], v[0:3]
	v_mfma_f32_16x16x32_bf16 v[140:143], v[236:239], v[220:223], v[140:143]
	ds_read_b128 v[220:223], v185 offset:7168
	ds_read_b128 v[224:227], v184
	ds_read_b128 v[228:231], v184 offset:1024
	ds_read_b128 v[232:235], v184 offset:2048
	ds_read_b128 v[236:239], v184 offset:3072
	s_movk_i32 vcc_lo, 0x6000
	s_cmp_eq_u32 m0, 2
	s_cselect_b32 vcc_lo, 0xffff4000, vcc_lo
	s_add_u32 m0, m0, 1
	s_cmp_eq_u32 m0, 3
	s_cselect_b32 m0, 0, m0
	v_add_u32_e32 v185, vcc_lo, v185
	v_add_u32_e32 v184, vcc_lo, v184
	v_xor_b32_e32 v185, 64, v185
	v_xor_b32_e32 v184, 64, v184
	s_waitcnt lgkmcnt(0)
	v_mfma_f32_16x16x32_bf16 v[172:175], v[224:227], v[190:193], v[172:175]
	v_mfma_f32_16x16x32_bf16 v[168:171], v[228:231], v[190:193], v[168:171]
	v_mfma_f32_16x16x32_bf16 v[164:167], v[232:235], v[190:193], v[164:167]
	v_mfma_f32_16x16x32_bf16 v[160:163], v[236:239], v[190:193], v[160:163]
	v_mfma_f32_16x16x32_bf16 v[156:159], v[224:227], v[194:197], v[156:159]
	v_mfma_f32_16x16x32_bf16 v[152:155], v[228:231], v[194:197], v[152:155]
	v_mfma_f32_16x16x32_bf16 v[148:151], v[232:235], v[194:197], v[148:151]
	v_mfma_f32_16x16x32_bf16 v[144:147], v[236:239], v[194:197], v[144:147]
	v_mfma_f32_16x16x32_bf16 v[136:139], v[224:227], v[198:201], v[136:139]
	v_mfma_f32_16x16x32_bf16 v[132:135], v[228:231], v[198:201], v[132:135]
	v_mfma_f32_16x16x32_bf16 v[128:131], v[232:235], v[198:201], v[128:131]
	v_mfma_f32_16x16x32_bf16 v[124:127], v[236:239], v[198:201], v[124:127]
	v_mfma_f32_16x16x32_bf16 v[120:123], v[224:227], v[204:207], v[120:123]
	v_mfma_f32_16x16x32_bf16 v[108:111], v[228:231], v[204:207], v[108:111]
	v_mfma_f32_16x16x32_bf16 v[100:103], v[232:235], v[204:207], v[100:103]
	v_mfma_f32_16x16x32_bf16 v[96:99], v[236:239], v[204:207], v[96:99]
	v_mfma_f32_16x16x32_bf16 v[92:95], v[224:227], v[208:211], v[92:95]
	v_mfma_f32_16x16x32_bf16 v[84:87], v[228:231], v[208:211], v[84:87]
	v_mfma_f32_16x16x32_bf16 v[76:79], v[232:235], v[208:211], v[76:79]
	v_mfma_f32_16x16x32_bf16 v[72:75], v[236:239], v[208:211], v[72:75]
	v_mfma_f32_16x16x32_bf16 v[64:67], v[224:227], v[212:215], v[64:67]
	v_mfma_f32_16x16x32_bf16 v[52:55], v[228:231], v[212:215], v[52:55]
	v_mfma_f32_16x16x32_bf16 v[48:51], v[232:235], v[212:215], v[48:51]
	v_mfma_f32_16x16x32_bf16 v[44:47], v[236:239], v[212:215], v[44:47]
	v_mfma_f32_16x16x32_bf16 v[36:39], v[224:227], v[216:219], v[36:39]
	v_mfma_f32_16x16x32_bf16 v[28:31], v[228:231], v[216:219], v[28:31]
	v_mfma_f32_16x16x32_bf16 v[24:27], v[232:235], v[216:219], v[24:27]
	v_mfma_f32_16x16x32_bf16 v[20:23], v[236:239], v[216:219], v[20:23]
	v_mfma_f32_16x16x32_bf16 v[12:15], v[224:227], v[220:223], v[12:15]
	v_mfma_f32_16x16x32_bf16 v[4:7], v[228:231], v[220:223], v[4:7]
	v_mfma_f32_16x16x32_bf16 v[0:3], v[232:235], v[220:223], v[0:3]
	v_mfma_f32_16x16x32_bf16 v[140:143], v[236:239], v[220:223], v[140:143]
	v_lshrrev_b32_e32 v224, 4, v188
	v_and_b32_e32 v225, 7, v188
	v_bitop3_b32 v226, v224, v225, 3 bitop3:0x6c
	v_lshlrev_b32_e32 v227, 7, v188
	v_bfe_u32 v228, v188, 4, 2
	v_and_b32_e32 v229, 0xffffc780, v227
	v_and_b32_e32 v227, 0x2780, v227
	v_bitop3_b32 v228, v228, v225, 4 bitop3:0x36
	v_lshlrev_b32_e32 v226, 4, v226
	v_lshlrev_b32_e32 v228, 4, v228
	v_or_b32_e32 v185, v229, v226
	v_or_b32_e32 v184, v227, v226
	v_or_b32_e32 v183, v229, v228
	v_or_b32_e32 v182, v227, v228
	s_waitcnt vmcnt(0)
	s_barrier
	s_waitcnt vmcnt(10)
	ds_write_b128 v176, v[116:119]
	s_waitcnt vmcnt(9)
	ds_write_b128 v176, v[112:115] offset:4096
	s_waitcnt vmcnt(8)
	ds_write_b128 v176, v[104:107] offset:8192
	s_waitcnt vmcnt(7)
	ds_write_b128 v176, v[88:91] offset:12288
	s_waitcnt vmcnt(6)
	ds_write_b128 v176, v[80:83] offset:16384
	s_waitcnt vmcnt(5)
	ds_write_b128 v176, v[68:71] offset:20480
	s_waitcnt vmcnt(4)
	ds_write_b128 v176, v[60:63] offset:24576
	s_waitcnt vmcnt(3)
	ds_write_b128 v176, v[40:43] offset:28672
	ds_write_b128 v176, v[56:59] offset:32768
	s_waitcnt vmcnt(2)
	ds_write_b128 v176, v[32:35] offset:36864
	s_waitcnt vmcnt(1)
	ds_write_b128 v176, v[16:19] offset:40960
	s_waitcnt vmcnt(0)
	ds_write_b128 v176, v[8:11] offset:45056
	s_waitcnt lgkmcnt(0)
	s_barrier
	ds_read_b128 v[8:11], v185
	ds_read_b128 v[16:19], v185 offset:2048
	ds_read_b128 v[32:35], v185 offset:4096
	ds_read_b128 v[40:43], v185 offset:6144
	ds_read_b128 v[56:59], v185 offset:8192
	ds_read_b128 v[60:63], v185 offset:10240
	ds_read_b128 v[68:71], v185 offset:12288
	ds_read_b128 v[80:83], v185 offset:14336
	ds_read_b128 v[88:91], v184 offset:32768
	ds_read_b128 v[104:107], v184 offset:34816
	ds_read_b128 v[112:115], v184 offset:36864
	ds_read_b128 v[116:119], v184 offset:38912
	s_waitcnt lgkmcnt(3)
	v_mfma_f32_16x16x32_bf16 v[172:175], v[88:91], v[8:11], v[172:175]
	s_waitcnt lgkmcnt(2)
	v_mfma_f32_16x16x32_bf16 v[168:171], v[104:107], v[8:11], v[168:171]
	s_waitcnt lgkmcnt(1)
	v_mfma_f32_16x16x32_bf16 v[164:167], v[112:115], v[8:11], v[164:167]
	s_waitcnt lgkmcnt(0)
	v_mfma_f32_16x16x32_bf16 v[8:11], v[116:119], v[8:11], v[160:163]
	v_mfma_f32_16x16x32_bf16 v[156:159], v[88:91], v[16:19], v[156:159]
	v_mfma_f32_16x16x32_bf16 v[152:155], v[104:107], v[16:19], v[152:155]
	v_mfma_f32_16x16x32_bf16 v[148:151], v[112:115], v[16:19], v[148:151]
	v_mfma_f32_16x16x32_bf16 v[16:19], v[116:119], v[16:19], v[144:147]
	v_mfma_f32_16x16x32_bf16 v[136:139], v[88:91], v[32:35], v[136:139]
	v_mfma_f32_16x16x32_bf16 v[132:135], v[104:107], v[32:35], v[132:135]
	v_mfma_f32_16x16x32_bf16 v[128:131], v[112:115], v[32:35], v[128:131]
	v_mfma_f32_16x16x32_bf16 v[32:35], v[116:119], v[32:35], v[124:127]
	v_mfma_f32_16x16x32_bf16 v[120:123], v[88:91], v[40:43], v[120:123]
	v_mfma_f32_16x16x32_bf16 v[108:111], v[104:107], v[40:43], v[108:111]
	v_mfma_f32_16x16x32_bf16 v[100:103], v[112:115], v[40:43], v[100:103]
	v_mfma_f32_16x16x32_bf16 v[40:43], v[116:119], v[40:43], v[96:99]
	v_mfma_f32_16x16x32_bf16 v[92:95], v[88:91], v[56:59], v[92:95]
	v_mfma_f32_16x16x32_bf16 v[84:87], v[104:107], v[56:59], v[84:87]
	v_mfma_f32_16x16x32_bf16 v[76:79], v[112:115], v[56:59], v[76:79]
	v_mfma_f32_16x16x32_bf16 v[56:59], v[116:119], v[56:59], v[72:75]
	v_mfma_f32_16x16x32_bf16 v[64:67], v[88:91], v[60:63], v[64:67]
	v_mfma_f32_16x16x32_bf16 v[52:55], v[104:107], v[60:63], v[52:55]
	v_mfma_f32_16x16x32_bf16 v[72:75], v[112:115], v[60:63], v[48:51]
	v_mfma_f32_16x16x32_bf16 v[60:63], v[116:119], v[60:63], v[44:47]
	v_mfma_f32_16x16x32_bf16 v[96:99], v[88:91], v[68:71], v[36:39]
	v_mfma_f32_16x16x32_bf16 v[28:31], v[104:107], v[68:71], v[28:31]
	v_mfma_f32_16x16x32_bf16 v[124:127], v[112:115], v[68:71], v[24:27]
	v_mfma_f32_16x16x32_bf16 v[20:23], v[116:119], v[68:71], v[20:23]
	v_mfma_f32_16x16x32_bf16 v[12:15], v[88:91], v[80:83], v[12:15]
	v_mfma_f32_16x16x32_bf16 v[4:7], v[104:107], v[80:83], v[4:7]
	v_mfma_f32_16x16x32_bf16 v[0:3], v[112:115], v[80:83], v[0:3]
	v_mfma_f32_16x16x32_bf16 v[68:71], v[116:119], v[80:83], v[140:143]
	ds_read_b128 v[24:27], v183
	ds_read_b128 v[36:39], v183 offset:2048
	ds_read_b128 v[44:47], v183 offset:4096
	ds_read_b128 v[80:83], v183 offset:6144
	ds_read_b128 v[88:91], v183 offset:8192
	ds_read_b128 v[104:107], v183 offset:10240
	ds_read_b128 v[112:115], v183 offset:12288
	ds_read_b128 v[116:119], v183 offset:14336
	ds_read_b128 v[140:143], v182 offset:32768
	ds_read_b128 v[144:147], v182 offset:34816
	ds_read_b128 v[160:163], v182 offset:36864
	ds_read_b128 v[178:181], v182 offset:38912
	s_waitcnt lgkmcnt(3)
	v_mfma_f32_16x16x32_bf16 v[172:175], v[140:143], v[24:27], v[172:175]
	v_mov_b32_e32 v49, v188
	v_cmp_lt_i32_e32 vcc, v189, v202
	s_waitcnt lgkmcnt(2)
	v_mfma_f32_16x16x32_bf16 v[168:171], v[144:147], v[24:27], v[168:171]
	v_mov_b32_e32 v48, v188
	v_readlane_b32 s8, v253, 24
	s_waitcnt lgkmcnt(1)
	v_mfma_f32_16x16x32_bf16 v[164:167], v[160:163], v[24:27], v[164:167]
	v_and_b32_e32 v50, 0xffffff80, v48
	v_add_u32_e32 v51, s11, v50
	v_and_or_b32 v50, v48, 64, s12
	s_waitcnt lgkmcnt(0)
	v_mfma_f32_16x16x32_bf16 v[8:11], v[178:181], v[24:27], v[8:11]
	v_bfe_u32 v26, v49, 4, 1
	v_cndmask_b32_e32 v24, v203, v189, vcc
	v_cmp_eq_u32_e32 vcc, 0, v26
	v_lshlrev_b32_e32 v186, 2, v24
	v_mfma_f32_16x16x32_bf16 v[182:185], v[178:181], v[36:39], v[16:19]
	v_and_or_b32 v48, v49, 15, v51
	v_ashrrev_i32_e32 v51, 31, v50
	v_lshl_add_u64 v[50:51], v[50:51], 1, s[6:7]
	s_nop 0
	s_nop 0
	s_nop 0
	s_nop 0
	s_nop 0
	s_nop 0
	s_nop 0
	s_nop 0
	v_lshlrev_b32_e32 v176, 5, v26
	v_lshrrev_b32_e32 v27, 1, v49
	v_lshl_add_u64 v[24:25], v[50:51], 0, v[176:177]
	v_and_b32_e32 v176, 16, v27
	v_ashrrev_i32_e32 v49, 31, v48
	v_mfma_f32_16x16x32_bf16 v[156:159], v[140:143], v[36:39], v[156:159]
	v_lshl_add_u64 v[50:51], v[24:25], 0, v[176:177]
	v_lshlrev_b64 v[24:25], 11, v[48:49]
	s_waitcnt lgkmcnt(0)
	s_nop 0
	v_mfma_f32_16x16x32_bf16 v[152:155], v[144:147], v[36:39], v[152:155]
	v_mov_b32_e32 v26, v172
	v_mov_b32_e32 v27, v168
	s_nop 1
	v_permlane16_swap_b32_e32 v26, v27
	s_waitcnt lgkmcnt(0)
	s_nop 0
	v_lshl_add_u64 v[24:25], v[50:51], 0, v[24:25]
	v_mfma_f32_16x16x32_bf16 v[148:151], v[160:163], v[36:39], v[148:151]
	v_mov_b32_e32 v16, v173
	v_mov_b32_e32 v36, v169
	s_nop 1
	v_permlane16_swap_b32_e32 v16, v36
	s_waitcnt lgkmcnt(0)
	s_nop 0
	v_cvt_pk_bf16_f32 v16, v26, v16
	v_mfma_f32_16x16x32_bf16 v[190:193], v[178:181], v[44:47], v[32:35]
	v_readlane_b32 s9, v253, 25
	s_nop 1
	v_mov_b32_e32 v17, v174
	v_mov_b32_e32 v32, v170
	s_nop 1
	v_permlane16_swap_b32_e32 v17, v32
	s_waitcnt lgkmcnt(0)
	s_nop 0
	v_mov_b32_e32 v18, v175
	v_mov_b32_e32 v19, v171
	s_nop 1
	v_permlane16_swap_b32_e32 v18, v19
	v_cvt_pk_bf16_f32 v17, v17, v18
	v_cvt_pk_bf16_f32 v18, v27, v36
	v_cvt_pk_bf16_f32 v19, v32, v19
	global_store_dwordx4 v[24:25], v[16:19], off
	v_mfma_f32_16x16x32_bf16 v[120:123], v[140:143], v[80:83], v[120:123]
	s_nop 0
	s_nop 0
	s_nop 0
	s_nop 0
	s_nop 0
	s_nop 0
	s_nop 0
	s_nop 0
	s_nop 0
	v_mfma_f32_16x16x32_bf16 v[108:111], v[144:147], v[80:83], v[108:111]
	s_waitcnt lgkmcnt(0)
	s_nop 0
	v_mov_b32_e32 v26, v164
	v_mov_b32_e32 v16, v8
	s_nop 1
	v_permlane16_swap_b32_e32 v26, v16
	s_waitcnt lgkmcnt(0)
	s_nop 0
	v_mov_b32_e32 v8, v165
	v_mov_b32_e32 v17, v9
	s_nop 1
	v_permlane16_swap_b32_e32 v8, v17
	s_waitcnt lgkmcnt(0)
	s_nop 0
	v_mov_b32_e32 v9, v166
	v_mov_b32_e32 v18, v10
	s_nop 1
	v_permlane16_swap_b32_e32 v9, v18
	s_waitcnt lgkmcnt(0)
	s_nop 0
	v_mov_b32_e32 v10, v167
	s_nop 1
	v_permlane16_swap_b32_e32 v10, v11
	v_cvt_pk_bf16_f32 v8, v26, v8
	v_cvt_pk_bf16_f32 v9, v9, v10
	v_cvt_pk_bf16_f32 v10, v16, v17
	v_cvt_pk_bf16_f32 v11, v18, v11
	global_store_dwordx4 v[24:25], v[8:11], off offset:64
	v_mfma_f32_16x16x32_bf16 v[100:103], v[160:163], v[80:83], v[100:103]
	s_nop 0
	v_or_b32_e32 v8, 16, v48
	v_ashrrev_i32_e32 v9, 31, v8
	v_lshlrev_b64 v[8:9], 11, v[8:9]
	v_mfma_f32_16x16x32_bf16 v[80:83], v[178:181], v[80:83], v[40:43]
	s_nop 0
	s_nop 0
	s_nop 0
	v_mfma_f32_16x16x32_bf16 v[40:43], v[140:143], v[104:107], v[64:67]
	s_nop 0
	s_nop 1
	v_lshl_add_u64 v[64:65], v[50:51], 0, v[8:9]
	s_nop 0
	s_nop 0
	s_nop 0
	s_nop 0
	v_mfma_f32_16x16x32_bf16 v[136:139], v[140:143], v[44:47], v[136:139]
	s_waitcnt lgkmcnt(0)
	s_nop 0
	v_mfma_f32_16x16x32_bf16 v[132:135], v[144:147], v[44:47], v[132:135]
	v_mfma_f32_16x16x32_bf16 v[128:131], v[160:163], v[44:47], v[128:131]
	v_mfma_f32_16x16x32_bf16 v[44:47], v[144:147], v[104:107], v[52:55]
	v_mfma_f32_16x16x32_bf16 v[36:39], v[178:181], v[104:107], v[60:63]
	s_nop 1
	v_mov_b32_e32 v49, v156
	v_mov_b32_e32 v54, v152
	s_nop 1
	v_permlane16_swap_b32_e32 v49, v54
	s_waitcnt lgkmcnt(0)
	s_nop 0
	v_mov_b32_e32 v8, v157
	v_mov_b32_e32 v55, v153
	s_nop 1
	v_permlane16_swap_b32_e32 v8, v55
	s_nop 0
	v_mov_b32_e32 v53, v158
	v_mov_b32_e32 v60, v154
	s_nop 1
	v_permlane16_swap_b32_e32 v53, v60
	s_nop 0
	v_mov_b32_e32 v61, v159
	v_mov_b32_e32 v62, v155
	s_nop 1
	v_permlane16_swap_b32_e32 v61, v62
	v_cvt_pk_bf16_f32 v52, v49, v8
	v_cvt_pk_bf16_f32 v53, v53, v61
	v_cvt_pk_bf16_f32 v54, v54, v55
	v_cvt_pk_bf16_f32 v55, v60, v62
	v_mfma_f32_16x16x32_bf16 v[8:11], v[140:143], v[116:119], v[12:15]
	global_store_dwordx4 v[64:65], v[52:55], off
	s_nop 0
	s_nop 0
	v_mfma_f32_16x16x32_bf16 v[12:15], v[144:147], v[116:119], v[4:7]
	s_nop 0
	s_nop 0
	s_nop 0
	v_cndmask_b32_e32 v4, v148, v182, vcc
	ds_bpermute_b32 v54, v186, v4
	s_nop 0
	s_waitcnt lgkmcnt(1)
	s_nop 0
	v_mov_b32_e32 v60, v149
	v_mov_b32_e32 v49, v183
	s_nop 1
	v_permlane16_swap_b32_e32 v60, v49
	s_waitcnt lgkmcnt(1)
	s_nop 0
	s_waitcnt lgkmcnt(0)
	v_cndmask_b32_e32 v55, v54, v148, vcc
	v_cndmask_b32_e32 v54, v182, v54, vcc
	v_mov_b32_e32 v61, v150
	v_mov_b32_e32 v62, v184
	s_nop 1
	v_permlane16_swap_b32_e32 v61, v62
	s_waitcnt lgkmcnt(0)
	s_nop 0
	v_mov_b32_e32 v63, v151
	v_mov_b32_e32 v66, v185
	s_nop 1
	v_permlane16_swap_b32_e32 v63, v66
	v_cvt_pk_bf16_f32 v52, v55, v60
	v_cvt_pk_bf16_f32 v53, v61, v63
	v_cvt_pk_bf16_f32 v54, v54, v49
	v_cvt_pk_bf16_f32 v55, v62, v66
	global_store_dwordx4 v[64:65], v[52:55], off offset:64
	s_nop 0
	s_nop 0
	v_or_b32_e32 v52, 32, v48
	v_ashrrev_i32_e32 v53, 31, v52
	v_lshlrev_b64 v[52:53], 11, v[52:53]
	v_lshl_add_u64 v[60:61], v[50:51], 0, v[52:53]
	s_nop 0
	s_nop 0
	s_nop 0
	s_nop 0
	s_nop 0
	s_nop 0
	s_waitcnt lgkmcnt(0)
	s_nop 0
	v_mov_b32_e32 v55, v136
	v_mov_b32_e32 v49, v132
	s_nop 1
	v_permlane16_swap_b32_e32 v55, v49
	s_waitcnt lgkmcnt(0)
	s_nop 0
	v_mov_b32_e32 v62, v137
	v_mov_b32_e32 v63, v133
	s_nop 1
	v_permlane16_swap_b32_e32 v62, v63
	s_waitcnt lgkmcnt(0)
	s_nop 0
	v_mov_b32_e32 v64, v138
	v_mov_b32_e32 v65, v134
	s_nop 1
	v_permlane16_swap_b32_e32 v64, v65
	s_waitcnt lgkmcnt(0)
	s_nop 0
	v_mov_b32_e32 v53, v139
	v_mov_b32_e32 v66, v135
	s_nop 1
	v_permlane16_swap_b32_e32 v53, v66
	v_cvt_pk_bf16_f32 v52, v55, v62
	v_cvt_pk_bf16_f32 v53, v64, v53
	v_cvt_pk_bf16_f32 v54, v49, v63
	v_cvt_pk_bf16_f32 v55, v65, v66
	global_store_dwordx4 v[60:61], v[52:55], off
	s_nop 0
	s_nop 0
	s_nop 0
	s_nop 0
	s_nop 0
	s_nop 0
	s_nop 0
	s_nop 0
	s_waitcnt lgkmcnt(0)
	s_nop 0
	v_mov_b32_e32 v55, v128
	v_mov_b32_e32 v49, v190
	s_nop 1
	v_permlane16_swap_b32_e32 v55, v49
	s_waitcnt lgkmcnt(0)
	s_nop 0
	v_mov_b32_e32 v62, v129
	v_mov_b32_e32 v63, v191
	s_nop 1
	v_permlane16_swap_b32_e32 v62, v63
	s_waitcnt lgkmcnt(0)
	s_nop 0
	v_mov_b32_e32 v64, v130
	v_mov_b32_e32 v65, v192
	s_nop 1
	v_permlane16_swap_b32_e32 v64, v65
	s_waitcnt lgkmcnt(0)
	s_nop 0
	v_mov_b32_e32 v53, v131
	v_mov_b32_e32 v66, v193
	s_nop 1
	v_permlane16_swap_b32_e32 v53, v66
	v_cvt_pk_bf16_f32 v52, v55, v62
	v_cvt_pk_bf16_f32 v53, v64, v53
	v_cvt_pk_bf16_f32 v54, v49, v63
	v_cvt_pk_bf16_f32 v55, v65, v66
	global_store_dwordx4 v[60:61], v[52:55], off offset:64
	s_nop 0
	s_nop 0
	v_or_b32_e32 v52, 48, v48
	v_ashrrev_i32_e32 v53, 31, v52
	v_lshlrev_b64 v[52:53], 11, v[52:53]
	v_lshl_add_u64 v[60:61], v[50:51], 0, v[52:53]
	s_nop 0
	s_nop 0
	s_nop 0
	s_nop 0
	s_nop 0
	s_nop 0
	s_waitcnt lgkmcnt(0)
	s_nop 0
	v_mov_b32_e32 v55, v120
	v_mov_b32_e32 v49, v108
	s_nop 1
	v_permlane16_swap_b32_e32 v55, v49
	s_waitcnt lgkmcnt(0)
	s_nop 0
	v_mov_b32_e32 v62, v121
	v_mov_b32_e32 v63, v109
	s_nop 1
	v_permlane16_swap_b32_e32 v62, v63
	s_waitcnt lgkmcnt(0)
	s_nop 0
	v_mov_b32_e32 v64, v122
	v_mov_b32_e32 v65, v110
	s_nop 1
	v_permlane16_swap_b32_e32 v64, v65
	s_waitcnt lgkmcnt(0)
	s_nop 0
	v_mov_b32_e32 v53, v123
	v_mov_b32_e32 v66, v111
	s_nop 1
	v_permlane16_swap_b32_e32 v53, v66
	v_cvt_pk_bf16_f32 v52, v55, v62
	v_cvt_pk_bf16_f32 v53, v64, v53
	v_cvt_pk_bf16_f32 v54, v49, v63
	v_cvt_pk_bf16_f32 v55, v65, v66
	global_store_dwordx4 v[60:61], v[52:55], off
	s_nop 0
	s_nop 0
	s_nop 0
	s_nop 0
	s_nop 0
	s_nop 0
	s_nop 0
	s_nop 0
	s_waitcnt lgkmcnt(0)
	s_nop 0
	v_mov_b32_e32 v55, v100
	v_mov_b32_e32 v49, v80
	s_nop 1
	v_permlane16_swap_b32_e32 v55, v49
	s_waitcnt lgkmcnt(0)
	s_nop 0
	v_mov_b32_e32 v62, v101
	v_mov_b32_e32 v63, v81
	s_nop 1
	v_permlane16_swap_b32_e32 v62, v63
	s_waitcnt lgkmcnt(0)
	s_nop 0
	v_mov_b32_e32 v64, v102
	v_mov_b32_e32 v65, v82
	s_nop 1
	v_permlane16_swap_b32_e32 v64, v65
	s_waitcnt lgkmcnt(0)
	s_nop 0
	v_mov_b32_e32 v53, v103
	v_mov_b32_e32 v66, v83
	s_nop 1
	v_permlane16_swap_b32_e32 v53, v66
	v_mfma_f32_16x16x32_bf16 v[92:95], v[140:143], v[88:91], v[92:95]
	v_cvt_pk_bf16_f32 v52, v55, v62
	v_cvt_pk_bf16_f32 v53, v64, v53
	v_cvt_pk_bf16_f32 v54, v49, v63
	v_mfma_f32_16x16x32_bf16 v[84:87], v[144:147], v[88:91], v[84:87]
	v_cvt_pk_bf16_f32 v55, v65, v66
	global_store_dwordx4 v[60:61], v[52:55], off offset:64
	v_mfma_f32_16x16x32_bf16 v[76:79], v[160:163], v[88:91], v[76:79]
	s_nop 0
	v_or_b32_e32 v52, 64, v48
	v_ashrrev_i32_e32 v53, 31, v52
	v_lshlrev_b64 v[52:53], 11, v[52:53]
	v_lshl_add_u64 v[60:61], v[50:51], 0, v[52:53]
	s_nop 0
	s_nop 0
	s_nop 0
	s_nop 0
	s_nop 0
	s_nop 0
	s_nop 0
	s_nop 0
	v_mfma_f32_16x16x32_bf16 v[56:59], v[178:181], v[88:91], v[56:59]
	s_waitcnt lgkmcnt(0)
	s_nop 0
	v_mov_b32_e32 v55, v92
	v_mov_b32_e32 v49, v84
	s_nop 1
	v_permlane16_swap_b32_e32 v55, v49
	s_waitcnt lgkmcnt(0)
	s_nop 0
	v_mov_b32_e32 v62, v93
	v_mov_b32_e32 v63, v85
	s_nop 1
	v_permlane16_swap_b32_e32 v62, v63
	s_waitcnt lgkmcnt(0)
	s_nop 0
	v_mov_b32_e32 v64, v94
	v_mov_b32_e32 v65, v86
	s_nop 1
	v_permlane16_swap_b32_e32 v64, v65
	s_waitcnt lgkmcnt(0)
	s_nop 0
	v_mov_b32_e32 v53, v95
	v_mov_b32_e32 v66, v87
	s_nop 1
	v_permlane16_swap_b32_e32 v53, v66
	v_cvt_pk_bf16_f32 v52, v55, v62
	v_cvt_pk_bf16_f32 v53, v64, v53
	v_cvt_pk_bf16_f32 v54, v49, v63
	v_cvt_pk_bf16_f32 v55, v65, v66
	global_store_dwordx4 v[60:61], v[52:55], off
	s_nop 0
	s_nop 0
	s_nop 0
	s_nop 0
	s_nop 0
	s_nop 0
	s_nop 0
	s_nop 0
	s_waitcnt lgkmcnt(0)
	s_nop 0
	v_mov_b32_e32 v55, v76
	v_mov_b32_e32 v49, v56
	s_nop 1
	v_permlane16_swap_b32_e32 v55, v49
	s_waitcnt lgkmcnt(0)
	s_nop 0
	v_mov_b32_e32 v56, v77
	s_nop 1
	v_permlane16_swap_b32_e32 v56, v57
	s_waitcnt lgkmcnt(0)
	s_nop 0
	v_mov_b32_e32 v62, v78
	s_nop 1
	v_permlane16_swap_b32_e32 v62, v58
	s_waitcnt lgkmcnt(0)
	s_nop 0
	v_mov_b32_e32 v53, v79
	s_nop 1
	v_permlane16_swap_b32_e32 v53, v59
	v_cvt_pk_bf16_f32 v52, v55, v56
	v_cvt_pk_bf16_f32 v53, v62, v53
	v_cvt_pk_bf16_f32 v54, v49, v57
	v_cvt_pk_bf16_f32 v55, v58, v59
	global_store_dwordx4 v[60:61], v[52:55], off offset:64
	s_nop 0
	s_nop 0
	s_nop 0
	s_nop 0
	s_nop 0
	s_nop 0
	s_nop 0
	s_nop 0
	v_mfma_f32_16x16x32_bf16 v[32:35], v[160:163], v[104:107], v[72:75]
	v_or_b32_e32 v52, 0x50, v48
	v_ashrrev_i32_e32 v53, 31, v52
	v_lshlrev_b64 v[52:53], 11, v[52:53]
	s_waitcnt lgkmcnt(0)
	s_nop 0
	s_nop 1
	v_permlane16_swap_b32_e32 v40, v44
	s_waitcnt lgkmcnt(0)
	s_nop 0
	s_nop 1
	v_permlane16_swap_b32_e32 v41, v45
	s_waitcnt lgkmcnt(0)
	s_nop 0
	s_nop 1
	v_permlane16_swap_b32_e32 v42, v46
	s_waitcnt lgkmcnt(0)
	s_nop 0
	s_nop 1
	v_permlane16_swap_b32_e32 v43, v47
	v_lshl_add_u64 v[52:53], v[50:51], 0, v[52:53]
	v_cvt_pk_bf16_f32 v40, v40, v41
	v_cvt_pk_bf16_f32 v41, v42, v43
	v_cvt_pk_bf16_f32 v42, v44, v45
	v_cvt_pk_bf16_f32 v43, v46, v47
	global_store_dwordx4 v[52:53], v[40:43], off
	v_mfma_f32_16x16x32_bf16 v[24:27], v[140:143], v[112:115], v[96:99]
	s_nop 0
	s_nop 0
	s_nop 0
	s_nop 0
	s_nop 0
	s_nop 0
	s_nop 0
	s_nop 0
	s_nop 0
	v_mfma_f32_16x16x32_bf16 v[28:31], v[144:147], v[112:115], v[28:31]
	s_waitcnt lgkmcnt(0)
	s_nop 0
	s_nop 1
	v_permlane16_swap_b32_e32 v32, v36
	s_waitcnt lgkmcnt(0)
	s_nop 0
	s_nop 1
	v_permlane16_swap_b32_e32 v33, v37
	s_waitcnt lgkmcnt(0)
	s_nop 0
	s_nop 1
	v_permlane16_swap_b32_e32 v34, v38
	s_waitcnt lgkmcnt(0)
	s_nop 0
	s_nop 1
	v_permlane16_swap_b32_e32 v35, v39
	v_cvt_pk_bf16_f32 v32, v32, v33
	v_cvt_pk_bf16_f32 v33, v34, v35
	v_cvt_pk_bf16_f32 v34, v36, v37
	v_cvt_pk_bf16_f32 v35, v38, v39
	global_store_dwordx4 v[52:53], v[32:35], off offset:64
	s_nop 0
	s_nop 0
	s_nop 0
	s_nop 0
	s_nop 0
	s_nop 0
	s_nop 0
	s_nop 0
	v_mfma_f32_16x16x32_bf16 v[16:19], v[160:163], v[112:115], v[124:127]
	v_or_b32_e32 v32, 0x60, v48
	v_ashrrev_i32_e32 v33, 31, v32
	v_lshlrev_b64 v[32:33], 11, v[32:33]
	v_mfma_f32_16x16x32_bf16 v[20:23], v[178:181], v[112:115], v[20:23]
	s_waitcnt lgkmcnt(0)
	s_nop 0
	s_nop 1
	v_permlane16_swap_b32_e32 v24, v28
	s_waitcnt lgkmcnt(0)
	s_nop 0
	s_nop 1
	v_permlane16_swap_b32_e32 v25, v29
	s_waitcnt lgkmcnt(0)
	s_nop 0
	s_nop 1
	v_permlane16_swap_b32_e32 v26, v30
	s_waitcnt lgkmcnt(0)
	s_nop 0
	s_nop 1
	v_permlane16_swap_b32_e32 v27, v31
	v_lshl_add_u64 v[32:33], v[50:51], 0, v[32:33]
	v_cvt_pk_bf16_f32 v24, v24, v25
	v_cvt_pk_bf16_f32 v25, v26, v27
	v_cvt_pk_bf16_f32 v26, v28, v29
	v_cvt_pk_bf16_f32 v27, v30, v31
	global_store_dwordx4 v[32:33], v[24:27], off
	v_mfma_f32_16x16x32_bf16 v[0:3], v[160:163], v[116:119], v[0:3]
	s_nop 0
	s_nop 0
	s_nop 0
	s_nop 0
	s_nop 0
	s_nop 0
	s_nop 0
	s_nop 0
	s_nop 0
	v_mfma_f32_16x16x32_bf16 v[4:7], v[178:181], v[116:119], v[68:71]
	s_waitcnt lgkmcnt(0)
	s_nop 0
	s_nop 1
	v_permlane16_swap_b32_e32 v16, v20
	s_waitcnt lgkmcnt(0)
	s_nop 0
	s_nop 1
	v_permlane16_swap_b32_e32 v17, v21
	s_waitcnt lgkmcnt(0)
	s_nop 0
	s_nop 1
	v_permlane16_swap_b32_e32 v18, v22
	s_waitcnt lgkmcnt(0)
	s_nop 0
	s_nop 1
	v_permlane16_swap_b32_e32 v19, v23
	v_cvt_pk_bf16_f32 v16, v16, v17
	v_cvt_pk_bf16_f32 v17, v18, v19
	v_cvt_pk_bf16_f32 v18, v20, v21
	v_cvt_pk_bf16_f32 v19, v22, v23
	global_store_dwordx4 v[32:33], v[16:19], off offset:64
	s_nop 0
	s_nop 0
	s_nop 0
	s_nop 0
	s_nop 0
	s_nop 0
	s_nop 0
	s_nop 0
	v_or_b32_e32 v16, 0x70, v48
	v_ashrrev_i32_e32 v17, 31, v16
	v_lshlrev_b64 v[16:17], 11, v[16:17]
	s_waitcnt lgkmcnt(0)
	s_nop 0
	s_nop 1
	v_permlane16_swap_b32_e32 v8, v12
	s_waitcnt lgkmcnt(0)
	s_nop 0
	s_nop 1
	v_permlane16_swap_b32_e32 v9, v13
	s_waitcnt lgkmcnt(0)
	s_nop 0
	s_nop 1
	v_permlane16_swap_b32_e32 v10, v14
	s_waitcnt lgkmcnt(0)
	s_nop 0
	s_nop 1
	v_permlane16_swap_b32_e32 v11, v15
	v_lshl_add_u64 v[16:17], v[50:51], 0, v[16:17]
	v_cvt_pk_bf16_f32 v8, v8, v9
	v_cvt_pk_bf16_f32 v9, v10, v11
	v_cvt_pk_bf16_f32 v10, v12, v13
	v_cvt_pk_bf16_f32 v11, v14, v15
	global_store_dwordx4 v[16:17], v[8:11], off
	s_nop 1
	s_nop 0
	s_nop 0
	s_nop 0
	s_nop 0
	s_nop 0
	s_nop 0
	s_nop 0
	s_nop 0
	s_waitcnt lgkmcnt(0)
	s_nop 0
	s_nop 1
	v_permlane16_swap_b32_e32 v0, v4
	s_waitcnt lgkmcnt(0)
	s_nop 0
	s_nop 1
	v_permlane16_swap_b32_e32 v1, v5
	s_waitcnt lgkmcnt(0)
	s_nop 0
	s_nop 1
	v_permlane16_swap_b32_e32 v2, v6
	s_waitcnt lgkmcnt(0)
	s_nop 0
	s_nop 1
	v_permlane16_swap_b32_e32 v3, v7
	v_cvt_pk_bf16_f32 v0, v0, v1
	v_cvt_pk_bf16_f32 v1, v2, v3
	v_cvt_pk_bf16_f32 v2, v4, v5
	v_cvt_pk_bf16_f32 v3, v6, v7
	global_store_dwordx4 v[16:17], v[0:3], off offset:64
	s_load_dword s8, s[8:9], 0x0
	s_waitcnt lgkmcnt(0)
	s_add_i32 s10, s8, s10
	s_cmpk_gt_i32 s10, 0xff
	s_cbranch_scc0 .LBB0_146

.LBB0_403:
	s_or_b64 exec, exec, s[0:1]
	s_waitcnt vmcnt(0)
	v_add_f32_e32 v128, 0, v128
	v_add_f32_e32 v128, v128, v129
	v_add_f32_e32 v128, v128, v130
	v_add_f32_e32 v128, v128, v131
	v_add_f32_e32 v128, v128, v138
	v_add_f32_e32 v128, v128, v139
	v_fmamk_f32 v128, v128, 0x3b2aaaab, v252
	v_mul_f32_e32 v129, 0x4b800000, v128
	v_cmp_gt_f32_e32 vcc, s25, v128
	v_cmp_lt_i32_e64 s[0:1], v189, v202
	v_lshrrev_b32_e32 v140, 4, v137
	v_cndmask_b32_e32 v128, v128, v129, vcc
	v_rsq_f32_e32 v128, v128
	v_cndmask_b32_e64 v129, v203, v189, s[0:1]
	v_lshlrev_b32_e32 v130, 2, v129
	v_lshlrev_b32_e32 v141, 2, v140
	v_mul_f32_e32 v129, 0x45800000, v128
	v_cndmask_b32_e32 v128, v128, v129, vcc
	v_ashrrev_i32_e32 v137, 31, v136
	v_and_b32_e32 v140, 1, v140
	v_mul_f32_e32 v138, 0x3dd53b94, v128
	v_mov_b64_e32 v[128:129], s[22:23]
	s_movk_i32 s8, 0xc00
	v_mad_i64_i32 v[146:147], s[0:1], v145, s8, v[128:129]
	v_lshlrev_b64 v[128:129], 1, v[136:137]
	v_pk_mul_f32 v[126:127], v[138:139], v[126:127] op_sel_hi:[0,1]
	v_pk_mul_f32 v[124:125], v[138:139], v[124:125] op_sel_hi:[0,1]
	v_pk_mul_f32 v[122:123], v[138:139], v[122:123] op_sel_hi:[0,1]
	v_pk_mul_f32 v[120:121], v[138:139], v[120:121] op_sel_hi:[0,1]
	v_cmp_eq_u32_e32 vcc, 0, v140
	v_and_b32_e32 v131, 8, v141
	v_lshl_add_u64 v[136:137], v[146:147], 0, v[128:129]
	s_nop 0
	s_nop 0
	s_nop 0
	s_nop 0
	s_nop 0
	s_nop 0
	s_nop 0
	s_nop 0
	v_lshlrev_b32_e32 v176, 1, v131
	s_waitcnt lgkmcnt(0)
	s_nop 0
	v_mov_b32_e32 v139, v120
	s_nop 1
	v_permlane16_swap_b32_e32 v124, v139
	s_waitcnt lgkmcnt(0)
	s_nop 0
	v_mov_b32_e32 v120, v125
	v_mov_b32_e32 v125, v121
	s_nop 1
	v_permlane16_swap_b32_e32 v120, v125
	s_waitcnt lgkmcnt(0)
	s_nop 0
	v_mov_b32_e32 v121, v126
	v_mov_b32_e32 v126, v122
	s_nop 1
	v_permlane16_swap_b32_e32 v121, v126
	s_waitcnt lgkmcnt(0)
	s_nop 0
	v_mov_b32_e32 v122, v127
	s_nop 1
	v_permlane16_swap_b32_e32 v122, v123
	v_cvt_pk_bf16_f32 v120, v124, v120
	v_cvt_pk_bf16_f32 v121, v121, v122
	v_cvt_pk_bf16_f32 v122, v139, v125
	v_lshlrev_b32_e32 v124, 5, v140
	v_mov_b32_e32 v125, v177
	v_cvt_pk_bf16_f32 v123, v126, v123
	v_lshl_add_u64 v[126:127], v[136:137], 0, v[124:125]
	v_lshl_add_u64 v[126:127], v[126:127], 0, v[176:177]
	v_pk_mul_f32 v[118:119], v[138:139], v[118:119] op_sel_hi:[0,1]
	v_pk_mul_f32 v[116:117], v[138:139], v[116:117] op_sel_hi:[0,1]
	v_pk_mul_f32 v[114:115], v[138:139], v[114:115] op_sel_hi:[0,1]
	v_pk_mul_f32 v[112:113], v[138:139], v[112:113] op_sel_hi:[0,1]
	global_store_dwordx4 v[126:127], v[120:123], off
	s_nop 0
	v_cndmask_b32_e32 v127, v119, v115, vcc
	s_nop 0
	s_nop 0
	s_nop 0
	s_nop 0
	s_nop 0
	ds_bpermute_b32 v127, v130, v127
	v_mov_b64_e32 v[120:121], s[34:35]
	v_mad_i64_i32 v[120:121], s[0:1], v145, s8, v[120:121]
	v_lshl_add_u64 v[120:121], v[120:121], 0, v[128:129]
	s_waitcnt lgkmcnt(1)
	s_nop 0
	v_mov_b32_e32 v122, v112
	s_nop 1
	v_permlane16_swap_b32_e32 v116, v122
	s_waitcnt lgkmcnt(1)
	s_nop 0
	v_mov_b32_e32 v112, v117
	v_mov_b32_e32 v117, v113
	s_nop 1
	v_permlane16_swap_b32_e32 v112, v117
	s_waitcnt lgkmcnt(1)
	s_nop 0
	v_mov_b32_e32 v113, v118
	v_mov_b32_e32 v118, v114
	s_nop 1
	v_permlane16_swap_b32_e32 v113, v118
	s_waitcnt lgkmcnt(0)
	v_cndmask_b32_e32 v114, v127, v119, vcc
	v_cvt_pk_bf16_f32 v112, v116, v112
	v_cvt_pk_bf16_f32 v113, v113, v114
	v_cvt_pk_bf16_f32 v114, v122, v117
	v_lshl_add_u64 v[116:117], v[120:121], 0, v[124:125]
	v_cndmask_b32_e32 v115, v115, v127, vcc
	v_lshl_add_u64 v[116:117], v[116:117], 0, v[176:177]
	s_mov_b32 s0, 0x3900000
	v_cvt_pk_bf16_f32 v115, v118, v115
	v_add_co_u32_e64 v116, s[0:1], s0, v116
	v_or_b32_e32 v118, 16, v143
	s_nop 0
	v_addc_co_u32_e64 v117, s[0:1], 0, v117, s[0:1]
	v_or_b32_e32 v120, v144, v118
	global_store_dwordx4 v[116:117], v[112:115], off offset:64
	s_nop 1
	v_lshlrev_b32_e32 v112, 3, v120
	v_ashrrev_i32_e32 v113, 31, v112
	v_lshl_add_u64 v[112:113], v[112:113], 2, s[4:5]
	global_load_dwordx2 v[116:117], v[112:113], off offset:16
	s_nop 0
	global_load_dwordx4 v[112:115], v[112:113], off
	s_and_saveexec_b64 s[0:1], s[40:41]
	s_cbranch_execz .LBB0_405
	v_or_b32_e32 v118, v142, v118
	v_lshlrev_b32_e32 v118, 7, v118
	v_mov_b32_e32 v119, v177
	v_lshl_add_u64 v[126:127], v[134:135], 0, v[118:119]
	v_lshl_add_u64 v[146:147], v[132:133], 0, v[118:119]
	global_load_dwordx4 v[122:125], v[126:127], off
	global_load_dwordx4 v[136:139], v[146:147], off
	s_waitcnt vmcnt(0)
	v_pk_mul_f32 v[148:149], v[108:109], v[136:137]
	v_pk_mul_f32 v[118:119], v[100:101], v[136:137]
	v_mul_f32_e32 v136, v110, v124
	v_mul_f32_e32 v150, v102, v138
	v_mul_f32_e32 v152, v110, v138
	v_mul_f32_e32 v124, v102, v124
	v_mov_b32_e32 v102, v111
	v_mov_b32_e32 v138, v125
	v_mov_b32_e32 v110, v103
	v_pk_mul_f32 v[154:155], v[102:103], v[138:139]
	v_pk_mul_f32 v[102:103], v[110:111], v[138:139]
	v_mov_b32_e32 v137, v154
	v_mov_b32_e32 v151, v155
	v_mov_b32_e32 v125, v102
	v_mov_b32_e32 v153, v103
	v_pk_fma_f32 v[108:109], v[108:109], v[122:123], v[118:119] neg_lo:[0,0,1] neg_hi:[0,0,1]
	v_pk_add_f32 v[118:119], v[136:137], v[150:151] neg_lo:[0,1] neg_hi:[0,1]
	v_pk_fma_f32 v[100:101], v[100:101], v[122:123], v[148:149]
	v_pk_add_f32 v[102:103], v[124:125], v[152:153]
	global_load_dwordx4 v[122:125], v[126:127], off offset:64
	global_load_dwordx4 v[136:139], v[146:147], off offset:64
	s_waitcnt vmcnt(0)
	v_pk_mul_f32 v[110:111], v[104:105], v[136:137]
	v_pk_mul_f32 v[126:127], v[96:97], v[136:137]
	v_mul_f32_e32 v136, v106, v124
	v_mul_f32_e32 v146, v98, v138
	v_mul_f32_e32 v148, v106, v138
	v_mul_f32_e32 v124, v98, v124
	v_mov_b32_e32 v98, v107
	v_mov_b32_e32 v138, v125
	v_pk_mul_f32 v[150:151], v[98:99], v[138:139]
	v_mov_b32_e32 v106, v99
	v_mov_b32_e32 v137, v150
	v_mov_b32_e32 v147, v151
	v_pk_mul_f32 v[98:99], v[106:107], v[138:139]
	v_pk_fma_f32 v[104:105], v[104:105], v[122:123], v[126:127] neg_lo:[0,0,1] neg_hi:[0,0,1]
	v_pk_add_f32 v[126:127], v[136:137], v[146:147] neg_lo:[0,1] neg_hi:[0,1]
	v_mov_b32_e32 v125, v98
	v_mov_b32_e32 v149, v99
	v_pk_fma_f32 v[96:97], v[96:97], v[122:123], v[110:111]
	v_pk_add_f32 v[98:99], v[124:125], v[148:149]
	v_mov_b32_e32 v106, v126
	v_mov_b32_e32 v107, v127
	v_mov_b32_e32 v110, v118
	v_mov_b32_e32 v111, v119
.LBB0_405:
	s_or_b64 exec, exec, s[0:1]
	s_waitcnt vmcnt(0)
	v_add_f32_e32 v112, 0, v112
	v_add_f32_e32 v112, v112, v113
	v_add_f32_e32 v112, v112, v114
	v_add_f32_e32 v112, v112, v115
	v_add_f32_e32 v112, v112, v116
	v_add_f32_e32 v112, v112, v117
	v_fmamk_f32 v112, v112, 0x3b2aaaab, v252
	v_mul_f32_e32 v113, 0x4b800000, v112
	v_cmp_gt_f32_e64 s[0:1], s25, v112
	v_lshlrev_b32_e32 v115, 4, v140
	s_nop 0
	v_cndmask_b32_e64 v112, v112, v113, s[0:1]
	v_rsq_f32_e32 v114, v112
	v_mov_b64_e32 v[112:113], s[22:23]
	v_mul_f32_e32 v116, 0x45800000, v114
	v_cndmask_b32_e64 v114, v114, v116, s[0:1]
	v_mul_f32_e32 v114, 0x3dd53b94, v114
	v_pk_mul_f32 v[108:109], v[114:115], v[108:109] op_sel_hi:[0,1]
	v_pk_mul_f32 v[104:105], v[114:115], v[104:105] op_sel_hi:[0,1]
	v_pk_mul_f32 v[110:111], v[114:115], v[110:111] op_sel_hi:[0,1]
	v_pk_mul_f32 v[106:107], v[114:115], v[106:107] op_sel_hi:[0,1]
	s_nop 0
	s_nop 0
	s_nop 0
	s_nop 0
	s_nop 0
	s_nop 0
	s_nop 0
	s_nop 0
	v_mad_i64_i32 v[112:113], s[0:1], v120, s8, v[112:113]
	s_waitcnt lgkmcnt(0)
	s_nop 0
	s_nop 1
	v_permlane16_swap_b32_e32 v108, v104
	s_waitcnt lgkmcnt(0)
	s_nop 0
	s_nop 1
	v_permlane16_swap_b32_e32 v109, v105
	v_lshl_add_u64 v[112:113], v[112:113], 0, v[128:129]
	s_waitcnt lgkmcnt(0)
	s_nop 0
	v_mov_b32_e32 v116, v106
	s_nop 1
	v_permlane16_swap_b32_e32 v110, v116
	s_waitcnt lgkmcnt(0)
	s_nop 0
	v_cvt_pk_bf16_f32 v106, v108, v109
	v_cvt_pk_bf16_f32 v108, v104, v105
	v_lshlrev_b32_e32 v104, 1, v115
	v_mov_b32_e32 v105, v177
	v_mov_b32_e32 v117, v107
	s_nop 1
	v_permlane16_swap_b32_e32 v111, v117
	v_cvt_pk_bf16_f32 v107, v110, v111
	v_lshl_add_u64 v[110:111], v[112:113], 0, v[104:105]
	v_cvt_pk_bf16_f32 v109, v116, v117
	v_lshl_add_u64 v[110:111], v[110:111], 0, v[176:177]
	v_pk_mul_f32 v[102:103], v[114:115], v[102:103] op_sel_hi:[0,1]
	v_pk_mul_f32 v[100:101], v[114:115], v[100:101] op_sel_hi:[0,1]
	v_pk_mul_f32 v[98:99], v[114:115], v[98:99] op_sel_hi:[0,1]
	v_pk_mul_f32 v[96:97], v[114:115], v[96:97] op_sel_hi:[0,1]
	global_store_dwordx4 v[110:111], v[106:109], off
	s_nop 0
	v_cndmask_b32_e32 v111, v103, v99, vcc
	s_nop 0
	s_nop 0
	s_nop 0
	s_nop 0
	s_nop 0
	ds_bpermute_b32 v111, v130, v111
	v_mov_b64_e32 v[106:107], s[34:35]
	v_mad_i64_i32 v[106:107], s[0:1], v120, s8, v[106:107]
	v_lshl_add_u64 v[106:107], v[106:107], 0, v[128:129]
	s_waitcnt lgkmcnt(1)
	s_nop 0
	v_mov_b32_e32 v108, v96
	s_nop 1
	v_permlane16_swap_b32_e32 v100, v108
	s_waitcnt lgkmcnt(1)
	s_nop 0
	v_mov_b32_e32 v96, v101
	v_mov_b32_e32 v101, v97
	s_nop 1
	v_permlane16_swap_b32_e32 v96, v101
	s_waitcnt lgkmcnt(1)
	s_nop 0
	v_mov_b32_e32 v97, v102
	v_mov_b32_e32 v102, v98
	s_nop 1
	v_permlane16_swap_b32_e32 v97, v102
	s_waitcnt lgkmcnt(0)
	v_cndmask_b32_e32 v98, v111, v103, vcc
	v_cvt_pk_bf16_f32 v96, v100, v96
	v_cvt_pk_bf16_f32 v97, v97, v98
	v_cvt_pk_bf16_f32 v98, v108, v101
	v_lshl_add_u64 v[100:101], v[106:107], 0, v[104:105]
	v_cndmask_b32_e32 v99, v99, v111, vcc
	v_lshl_add_u64 v[100:101], v[100:101], 0, v[176:177]
	s_mov_b32 s0, 0x3900000
	v_cvt_pk_bf16_f32 v99, v102, v99
	v_add_co_u32_e64 v100, s[0:1], s0, v100
	v_or_b32_e32 v102, 32, v143
	s_nop 0
	v_addc_co_u32_e64 v101, s[0:1], 0, v101, s[0:1]
	v_or_b32_e32 v106, v144, v102
	global_store_dwordx4 v[100:101], v[96:99], off offset:64
	s_nop 1
	v_lshlrev_b32_e32 v96, 3, v106
	v_ashrrev_i32_e32 v97, 31, v96
	v_lshl_add_u64 v[96:97], v[96:97], 2, s[4:5]
	global_load_dwordx2 v[100:101], v[96:97], off offset:16
	s_nop 0
	global_load_dwordx4 v[96:99], v[96:97], off
	s_and_saveexec_b64 s[0:1], s[40:41]
	s_cbranch_execz .LBB0_407
	v_or_b32_e32 v102, v142, v102
	v_lshlrev_b32_e32 v102, 7, v102
	v_mov_b32_e32 v103, v177
	v_lshl_add_u64 v[116:117], v[134:135], 0, v[102:103]
	v_lshl_add_u64 v[118:119], v[132:133], 0, v[102:103]
	global_load_dwordx4 v[108:111], v[116:117], off
	global_load_dwordx4 v[112:115], v[118:119], off
	s_waitcnt vmcnt(0)
	v_pk_mul_f32 v[120:121], v[92:93], v[112:113]
	v_pk_mul_f32 v[102:103], v[84:85], v[112:113]
	v_mul_f32_e32 v112, v94, v110
	v_mul_f32_e32 v122, v86, v114
	v_mul_f32_e32 v124, v94, v114
	v_mul_f32_e32 v110, v86, v110
	v_mov_b32_e32 v86, v95
	v_mov_b32_e32 v114, v111
	v_mov_b32_e32 v94, v87
	v_pk_mul_f32 v[126:127], v[86:87], v[114:115]
	v_pk_mul_f32 v[86:87], v[94:95], v[114:115]
	v_mov_b32_e32 v113, v126
	v_mov_b32_e32 v123, v127
	v_mov_b32_e32 v111, v86
	v_mov_b32_e32 v125, v87
	v_pk_fma_f32 v[92:93], v[92:93], v[108:109], v[102:103] neg_lo:[0,0,1] neg_hi:[0,0,1]
	v_pk_add_f32 v[102:103], v[112:113], v[122:123] neg_lo:[0,1] neg_hi:[0,1]
	v_pk_fma_f32 v[84:85], v[84:85], v[108:109], v[120:121]
	v_pk_add_f32 v[86:87], v[110:111], v[124:125]
	global_load_dwordx4 v[108:111], v[116:117], off offset:64
	global_load_dwordx4 v[112:115], v[118:119], off offset:64
	s_waitcnt vmcnt(1)
	v_mul_f32_e32 v116, v90, v110
	s_waitcnt vmcnt(0)
	v_mul_f32_e32 v118, v82, v114
	v_mul_f32_e32 v120, v90, v114
	v_mul_f32_e32 v110, v82, v110
	v_mov_b32_e32 v82, v91
	v_mov_b32_e32 v114, v111
	v_pk_mul_f32 v[122:123], v[82:83], v[114:115]
	v_mov_b32_e32 v90, v83
	v_pk_mul_f32 v[94:95], v[88:89], v[112:113]
	v_pk_mul_f32 v[112:113], v[80:81], v[112:113]
	v_mov_b32_e32 v117, v122
	v_mov_b32_e32 v119, v123
	v_pk_mul_f32 v[82:83], v[90:91], v[114:115]
	v_pk_fma_f32 v[88:89], v[88:89], v[108:109], v[112:113] neg_lo:[0,0,1] neg_hi:[0,0,1]
	v_pk_add_f32 v[112:113], v[116:117], v[118:119] neg_lo:[0,1] neg_hi:[0,1]
	v_mov_b32_e32 v111, v82
	v_mov_b32_e32 v121, v83
	v_pk_fma_f32 v[80:81], v[80:81], v[108:109], v[94:95]
	v_pk_add_f32 v[82:83], v[110:111], v[120:121]
	v_mov_b32_e32 v90, v112
	v_mov_b32_e32 v91, v113
	v_mov_b32_e32 v94, v102
	v_mov_b32_e32 v95, v103
.LBB0_407:
	s_or_b64 exec, exec, s[0:1]
	s_waitcnt vmcnt(0)
	v_add_f32_e32 v96, 0, v96
	v_add_f32_e32 v96, v96, v97
	v_add_f32_e32 v96, v96, v98
	v_add_f32_e32 v96, v96, v99
	v_add_f32_e32 v96, v96, v100
	v_add_f32_e32 v96, v96, v101
	v_fmamk_f32 v96, v96, 0x3b2aaaab, v252
	v_mul_f32_e32 v97, 0x4b800000, v96
	v_cmp_gt_f32_e64 s[0:1], s25, v96
	s_nop 1
	v_cndmask_b32_e64 v96, v96, v97, s[0:1]
	v_rsq_f32_e32 v98, v96
	v_mov_b64_e32 v[96:97], s[22:23]
	v_mul_f32_e32 v99, 0x45800000, v98
	v_cndmask_b32_e64 v98, v98, v99, s[0:1]
	v_mul_f32_e32 v98, 0x3dd53b94, v98
	v_pk_mul_f32 v[94:95], v[98:99], v[94:95] op_sel_hi:[0,1]
	v_pk_mul_f32 v[92:93], v[98:99], v[92:93] op_sel_hi:[0,1]
	v_pk_mul_f32 v[90:91], v[98:99], v[90:91] op_sel_hi:[0,1]
	v_pk_mul_f32 v[88:89], v[98:99], v[88:89] op_sel_hi:[0,1]
	s_nop 0
	s_nop 0
	s_nop 0
	s_nop 0
	s_nop 0
	s_nop 0
	s_nop 0
	s_nop 0
	v_mad_i64_i32 v[96:97], s[0:1], v106, s8, v[96:97]
	v_lshl_add_u64 v[96:97], v[96:97], 0, v[128:129]
	s_waitcnt lgkmcnt(0)
	s_nop 0
	v_mov_b32_e32 v99, v88
	s_nop 1
	v_permlane16_swap_b32_e32 v92, v99
	s_waitcnt lgkmcnt(0)
	s_nop 0
	v_mov_b32_e32 v88, v93
	v_mov_b32_e32 v93, v89
	s_nop 1
	v_permlane16_swap_b32_e32 v88, v93
	s_waitcnt lgkmcnt(0)
	s_nop 0
	v_mov_b32_e32 v89, v94
	v_mov_b32_e32 v94, v90
	s_nop 1
	v_permlane16_swap_b32_e32 v89, v94
	s_waitcnt lgkmcnt(0)
	s_nop 0
	v_mov_b32_e32 v90, v95
	s_nop 1
	v_permlane16_swap_b32_e32 v90, v91
	v_cvt_pk_bf16_f32 v88, v92, v88
	v_cvt_pk_bf16_f32 v89, v89, v90
	v_cvt_pk_bf16_f32 v90, v99, v93
	v_lshl_add_u64 v[92:93], v[96:97], 0, v[104:105]
	v_cvt_pk_bf16_f32 v91, v94, v91
	v_lshl_add_u64 v[92:93], v[92:93], 0, v[176:177]
	v_pk_mul_f32 v[86:87], v[98:99], v[86:87] op_sel_hi:[0,1]
	v_pk_mul_f32 v[84:85], v[98:99], v[84:85] op_sel_hi:[0,1]
	v_pk_mul_f32 v[82:83], v[98:99], v[82:83] op_sel_hi:[0,1]
	v_pk_mul_f32 v[80:81], v[98:99], v[80:81] op_sel_hi:[0,1]
	global_store_dwordx4 v[92:93], v[88:91], off
	s_nop 0
	v_cndmask_b32_e32 v93, v87, v83, vcc
	s_nop 0
	s_nop 0
	s_nop 0
	s_nop 0
	s_nop 0
	ds_bpermute_b32 v93, v130, v93
	v_mov_b64_e32 v[88:89], s[34:35]
	v_mad_i64_i32 v[88:89], s[0:1], v106, s8, v[88:89]
	v_lshl_add_u64 v[88:89], v[88:89], 0, v[128:129]
	s_waitcnt lgkmcnt(1)
	s_nop 0
	v_mov_b32_e32 v90, v80
	s_nop 1
	v_permlane16_swap_b32_e32 v84, v90
	s_waitcnt lgkmcnt(1)
	s_nop 0
	v_mov_b32_e32 v80, v85
	v_mov_b32_e32 v85, v81
	s_nop 1
	v_permlane16_swap_b32_e32 v80, v85
	s_waitcnt lgkmcnt(1)
	s_nop 0
	v_mov_b32_e32 v81, v86
	v_mov_b32_e32 v86, v82
	s_nop 1
	v_permlane16_swap_b32_e32 v81, v86
	s_waitcnt lgkmcnt(0)
	v_cndmask_b32_e32 v82, v93, v87, vcc
	v_cvt_pk_bf16_f32 v80, v84, v80
	v_cvt_pk_bf16_f32 v81, v81, v82
	v_cvt_pk_bf16_f32 v82, v90, v85
	v_lshl_add_u64 v[84:85], v[88:89], 0, v[104:105]
	v_cndmask_b32_e32 v83, v83, v93, vcc
	v_lshl_add_u64 v[84:85], v[84:85], 0, v[176:177]
	s_mov_b32 s0, 0x3900000
	v_cvt_pk_bf16_f32 v83, v86, v83
	v_add_co_u32_e64 v84, s[0:1], s0, v84
	v_or_b32_e32 v86, 48, v143
	s_nop 0
	v_addc_co_u32_e64 v85, s[0:1], 0, v85, s[0:1]
	v_or_b32_e32 v88, v144, v86
	global_store_dwordx4 v[84:85], v[80:83], off offset:64
	s_nop 1
	v_lshlrev_b32_e32 v80, 3, v88
	v_ashrrev_i32_e32 v81, 31, v80
	v_lshl_add_u64 v[80:81], v[80:81], 2, s[4:5]
	global_load_dwordx2 v[84:85], v[80:81], off offset:16
	s_nop 0
	global_load_dwordx4 v[80:83], v[80:81], off
	s_and_saveexec_b64 s[0:1], s[40:41]
	s_cbranch_execz .LBB0_409
	v_or_b32_e32 v86, v142, v86
	v_lshlrev_b32_e32 v86, 7, v86
	v_mov_b32_e32 v87, v177
	v_lshl_add_u64 v[98:99], v[134:135], 0, v[86:87]
	v_lshl_add_u64 v[100:101], v[132:133], 0, v[86:87]
	global_load_dwordx4 v[90:93], v[98:99], off
	global_load_dwordx4 v[94:97], v[100:101], off
	s_waitcnt vmcnt(0)
	v_pk_mul_f32 v[102:103], v[76:77], v[94:95]
	v_pk_mul_f32 v[86:87], v[68:69], v[94:95]
	v_mul_f32_e32 v94, v78, v92
	v_mul_f32_e32 v106, v70, v96
	v_mul_f32_e32 v108, v78, v96
	v_mul_f32_e32 v92, v70, v92
	v_mov_b32_e32 v70, v79
	v_mov_b32_e32 v96, v93
	v_mov_b32_e32 v78, v71
	v_pk_mul_f32 v[110:111], v[70:71], v[96:97]
	v_pk_mul_f32 v[70:71], v[78:79], v[96:97]
	v_mov_b32_e32 v95, v110
	v_mov_b32_e32 v107, v111
	v_mov_b32_e32 v93, v70
	v_mov_b32_e32 v109, v71
	v_pk_fma_f32 v[76:77], v[76:77], v[90:91], v[86:87] neg_lo:[0,0,1] neg_hi:[0,0,1]
	v_pk_add_f32 v[86:87], v[94:95], v[106:107] neg_lo:[0,1] neg_hi:[0,1]
	v_pk_fma_f32 v[68:69], v[68:69], v[90:91], v[102:103]
	v_pk_add_f32 v[70:71], v[92:93], v[108:109]
	global_load_dwordx4 v[90:93], v[98:99], off offset:64
	global_load_dwordx4 v[94:97], v[100:101], off offset:64
	s_waitcnt vmcnt(1)
	v_mul_f32_e32 v98, v74, v92
	s_waitcnt vmcnt(0)
	v_mul_f32_e32 v100, v66, v96
	v_mul_f32_e32 v102, v74, v96
	v_mul_f32_e32 v92, v66, v92
	v_mov_b32_e32 v66, v75
	v_mov_b32_e32 v96, v93
	v_pk_mul_f32 v[106:107], v[66:67], v[96:97]
	v_mov_b32_e32 v74, v67
	v_pk_mul_f32 v[78:79], v[72:73], v[94:95]
	v_pk_mul_f32 v[94:95], v[64:65], v[94:95]
	v_mov_b32_e32 v99, v106
	v_mov_b32_e32 v101, v107
	v_pk_mul_f32 v[66:67], v[74:75], v[96:97]
	v_pk_fma_f32 v[72:73], v[72:73], v[90:91], v[94:95] neg_lo:[0,0,1] neg_hi:[0,0,1]
	v_pk_add_f32 v[94:95], v[98:99], v[100:101] neg_lo:[0,1] neg_hi:[0,1]
	v_mov_b32_e32 v93, v66
	v_mov_b32_e32 v103, v67
	v_pk_fma_f32 v[64:65], v[64:65], v[90:91], v[78:79]
	v_pk_add_f32 v[66:67], v[92:93], v[102:103]
	v_mov_b32_e32 v74, v94
	v_mov_b32_e32 v75, v95
	v_mov_b32_e32 v78, v86
	v_mov_b32_e32 v79, v87
.LBB0_409:
	s_or_b64 exec, exec, s[0:1]
	s_waitcnt vmcnt(0)
	v_add_f32_e32 v80, 0, v80
	v_add_f32_e32 v80, v80, v81
	v_add_f32_e32 v80, v80, v82
	v_add_f32_e32 v80, v80, v83
	v_add_f32_e32 v80, v80, v84
	v_add_f32_e32 v80, v80, v85
	v_fmamk_f32 v80, v80, 0x3b2aaaab, v252
	v_mul_f32_e32 v81, 0x4b800000, v80
	v_cmp_gt_f32_e64 s[0:1], s25, v80
	v_mov_b32_e32 v105, v177
	s_nop 0
	v_cndmask_b32_e64 v80, v80, v81, s[0:1]
	v_rsq_f32_e32 v82, v80
	v_mov_b64_e32 v[80:81], s[22:23]
	v_mul_f32_e32 v83, 0x45800000, v82
	v_cndmask_b32_e64 v82, v82, v83, s[0:1]
	v_mul_f32_e32 v82, 0x3dd53b94, v82
	v_pk_mul_f32 v[78:79], v[82:83], v[78:79] op_sel_hi:[0,1]
	v_pk_mul_f32 v[76:77], v[82:83], v[76:77] op_sel_hi:[0,1]
	v_pk_mul_f32 v[74:75], v[82:83], v[74:75] op_sel_hi:[0,1]
	v_pk_mul_f32 v[72:73], v[82:83], v[72:73] op_sel_hi:[0,1]
	s_nop 0
	s_nop 0
	s_nop 0
	s_nop 0
	s_nop 0
	s_nop 0
	s_nop 0
	s_nop 0
	v_mad_i64_i32 v[80:81], s[0:1], v88, s8, v[80:81]
	v_lshl_add_u64 v[80:81], v[80:81], 0, v[128:129]
	s_waitcnt lgkmcnt(0)
	s_nop 0
	v_mov_b32_e32 v83, v72
	s_nop 1
	v_permlane16_swap_b32_e32 v76, v83
	s_waitcnt lgkmcnt(0)
	s_nop 0
	v_mov_b32_e32 v72, v77
	v_mov_b32_e32 v77, v73
	s_nop 1
	v_permlane16_swap_b32_e32 v72, v77
	s_waitcnt lgkmcnt(0)
	s_nop 0
	v_mov_b32_e32 v73, v78
	v_mov_b32_e32 v78, v74
	s_nop 1
	v_permlane16_swap_b32_e32 v73, v78
	s_waitcnt lgkmcnt(0)
	s_nop 0
	v_mov_b32_e32 v74, v79
	s_nop 1
	v_permlane16_swap_b32_e32 v74, v75
	v_cvt_pk_bf16_f32 v72, v76, v72
	v_cvt_pk_bf16_f32 v73, v73, v74
	v_cvt_pk_bf16_f32 v74, v83, v77
	v_lshl_add_u64 v[76:77], v[80:81], 0, v[104:105]
	v_cvt_pk_bf16_f32 v75, v78, v75
	v_lshl_add_u64 v[76:77], v[76:77], 0, v[176:177]
	v_pk_mul_f32 v[70:71], v[82:83], v[70:71] op_sel_hi:[0,1]
	v_pk_mul_f32 v[68:69], v[82:83], v[68:69] op_sel_hi:[0,1]
	v_pk_mul_f32 v[66:67], v[82:83], v[66:67] op_sel_hi:[0,1]
	v_pk_mul_f32 v[64:65], v[82:83], v[64:65] op_sel_hi:[0,1]
	global_store_dwordx4 v[76:77], v[72:75], off
	s_nop 0
	v_cndmask_b32_e32 v77, v71, v67, vcc
	s_nop 0
	s_nop 0
	s_nop 0
	s_nop 0
	s_nop 0
	ds_bpermute_b32 v77, v130, v77
	v_mov_b64_e32 v[72:73], s[34:35]
	v_mad_i64_i32 v[72:73], s[0:1], v88, s8, v[72:73]
	v_lshl_add_u64 v[72:73], v[72:73], 0, v[128:129]
	s_waitcnt lgkmcnt(1)
	s_nop 0
	v_mov_b32_e32 v74, v64
	s_nop 1
	v_permlane16_swap_b32_e32 v68, v74
	s_waitcnt lgkmcnt(1)
	s_nop 0
	v_mov_b32_e32 v64, v69
	v_mov_b32_e32 v69, v65
	s_nop 1
	v_permlane16_swap_b32_e32 v64, v69
	s_waitcnt lgkmcnt(1)
	s_nop 0
	v_mov_b32_e32 v65, v70
	v_mov_b32_e32 v70, v66
	s_nop 1
	v_permlane16_swap_b32_e32 v65, v70
	s_waitcnt lgkmcnt(0)
	v_cndmask_b32_e32 v66, v77, v71, vcc
	v_cvt_pk_bf16_f32 v64, v68, v64
	v_cvt_pk_bf16_f32 v65, v65, v66
	v_cvt_pk_bf16_f32 v66, v74, v69
	v_lshl_add_u64 v[68:69], v[72:73], 0, v[104:105]
	v_cndmask_b32_e32 v67, v67, v77, vcc
	v_lshl_add_u64 v[68:69], v[68:69], 0, v[176:177]
	s_mov_b32 s0, 0x3900000
	v_cvt_pk_bf16_f32 v67, v70, v67
	v_add_co_u32_e64 v68, s[0:1], s0, v68
	v_or_b32_e32 v70, 64, v143
	s_nop 0
	v_addc_co_u32_e64 v69, s[0:1], 0, v69, s[0:1]
	v_or_b32_e32 v72, v144, v70
	global_store_dwordx4 v[68:69], v[64:67], off offset:64
	s_nop 1
	v_lshlrev_b32_e32 v64, 3, v72
	v_ashrrev_i32_e32 v65, 31, v64
	v_lshl_add_u64 v[64:65], v[64:65], 2, s[4:5]
	global_load_dwordx2 v[68:69], v[64:65], off offset:16
	s_nop 0
	global_load_dwordx4 v[64:67], v[64:65], off
	s_and_saveexec_b64 s[0:1], s[40:41]
	s_cbranch_execz .LBB0_411
	v_or_b32_e32 v70, v142, v70
	v_lshlrev_b32_e32 v70, 7, v70
	v_mov_b32_e32 v71, v177
	v_lshl_add_u64 v[82:83], v[134:135], 0, v[70:71]
	v_lshl_add_u64 v[84:85], v[132:133], 0, v[70:71]
	global_load_dwordx4 v[74:77], v[82:83], off
	global_load_dwordx4 v[78:81], v[84:85], off
	s_waitcnt vmcnt(0)
	v_pk_mul_f32 v[86:87], v[60:61], v[78:79]
	v_pk_mul_f32 v[70:71], v[52:53], v[78:79]
	v_mul_f32_e32 v78, v62, v76
	v_mul_f32_e32 v88, v54, v80
	v_mul_f32_e32 v90, v62, v80
	v_mul_f32_e32 v76, v54, v76
	v_mov_b32_e32 v54, v63
	v_mov_b32_e32 v80, v77
	v_mov_b32_e32 v62, v55
	v_pk_mul_f32 v[92:93], v[54:55], v[80:81]
	v_pk_mul_f32 v[54:55], v[62:63], v[80:81]
	v_mov_b32_e32 v79, v92
	v_mov_b32_e32 v89, v93
	v_mov_b32_e32 v77, v54
	v_mov_b32_e32 v91, v55
	v_pk_fma_f32 v[60:61], v[60:61], v[74:75], v[70:71] neg_lo:[0,0,1] neg_hi:[0,0,1]
	v_pk_add_f32 v[70:71], v[78:79], v[88:89] neg_lo:[0,1] neg_hi:[0,1]
	v_pk_fma_f32 v[52:53], v[52:53], v[74:75], v[86:87]
	v_pk_add_f32 v[54:55], v[76:77], v[90:91]
	global_load_dwordx4 v[74:77], v[82:83], off offset:64
	global_load_dwordx4 v[78:81], v[84:85], off offset:64
	s_waitcnt vmcnt(1)
	v_mul_f32_e32 v82, v58, v76
	s_waitcnt vmcnt(0)
	v_mul_f32_e32 v84, v50, v80
	v_mul_f32_e32 v86, v58, v80
	v_mul_f32_e32 v76, v50, v76
	v_mov_b32_e32 v50, v59
	v_mov_b32_e32 v80, v77
	v_pk_mul_f32 v[88:89], v[50:51], v[80:81]
	v_mov_b32_e32 v58, v51
	v_pk_mul_f32 v[62:63], v[56:57], v[78:79]
	v_pk_mul_f32 v[78:79], v[48:49], v[78:79]
	v_mov_b32_e32 v83, v88
	v_mov_b32_e32 v85, v89
	v_pk_mul_f32 v[50:51], v[58:59], v[80:81]
	v_pk_fma_f32 v[56:57], v[56:57], v[74:75], v[78:79] neg_lo:[0,0,1] neg_hi:[0,0,1]
	v_pk_add_f32 v[78:79], v[82:83], v[84:85] neg_lo:[0,1] neg_hi:[0,1]
	v_mov_b32_e32 v77, v50
	v_mov_b32_e32 v87, v51
	v_pk_fma_f32 v[48:49], v[48:49], v[74:75], v[62:63]
	v_pk_add_f32 v[50:51], v[76:77], v[86:87]
	v_mov_b32_e32 v58, v78
	v_mov_b32_e32 v59, v79
	v_mov_b32_e32 v62, v70
	v_mov_b32_e32 v63, v71
.LBB0_411:
	s_or_b64 exec, exec, s[0:1]
	s_waitcnt vmcnt(0)
	v_add_f32_e32 v64, 0, v64
	v_add_f32_e32 v64, v64, v65
	v_add_f32_e32 v64, v64, v66
	v_add_f32_e32 v64, v64, v67
	v_add_f32_e32 v64, v64, v68
	v_add_f32_e32 v64, v64, v69
	v_fmamk_f32 v64, v64, 0x3b2aaaab, v252
	v_mul_f32_e32 v65, 0x4b800000, v64
	v_cmp_gt_f32_e64 s[0:1], s25, v64
	s_nop 1
	v_cndmask_b32_e64 v64, v64, v65, s[0:1]
	v_rsq_f32_e32 v66, v64
	v_mov_b64_e32 v[64:65], s[22:23]
	v_mul_f32_e32 v67, 0x45800000, v66
	v_cndmask_b32_e64 v66, v66, v67, s[0:1]
	v_mul_f32_e32 v66, 0x3dd53b94, v66
	v_pk_mul_f32 v[62:63], v[66:67], v[62:63] op_sel_hi:[0,1]
	v_pk_mul_f32 v[60:61], v[66:67], v[60:61] op_sel_hi:[0,1]
	v_pk_mul_f32 v[58:59], v[66:67], v[58:59] op_sel_hi:[0,1]
	v_pk_mul_f32 v[56:57], v[66:67], v[56:57] op_sel_hi:[0,1]
	s_nop 0
	s_nop 0
	s_nop 0
	s_nop 0
	s_nop 0
	s_nop 0
	s_nop 0
	s_nop 0
	v_mad_i64_i32 v[64:65], s[0:1], v72, s8, v[64:65]
	v_lshl_add_u64 v[64:65], v[64:65], 0, v[128:129]
	s_waitcnt lgkmcnt(0)
	s_nop 0
	v_mov_b32_e32 v67, v56
	s_nop 1
	v_permlane16_swap_b32_e32 v60, v67
	s_waitcnt lgkmcnt(0)
	s_nop 0
	v_mov_b32_e32 v56, v61
	v_mov_b32_e32 v61, v57
	s_nop 1
	v_permlane16_swap_b32_e32 v56, v61
	s_waitcnt lgkmcnt(0)
	s_nop 0
	v_mov_b32_e32 v57, v62
	v_mov_b32_e32 v62, v58
	s_nop 1
	v_permlane16_swap_b32_e32 v57, v62
	s_waitcnt lgkmcnt(0)
	s_nop 0
	v_mov_b32_e32 v58, v63
	s_nop 1
	v_permlane16_swap_b32_e32 v58, v59
	v_cvt_pk_bf16_f32 v56, v60, v56
	v_cvt_pk_bf16_f32 v57, v57, v58
	v_cvt_pk_bf16_f32 v58, v67, v61
	v_lshl_add_u64 v[60:61], v[64:65], 0, v[104:105]
	v_cvt_pk_bf16_f32 v59, v62, v59
	v_lshl_add_u64 v[60:61], v[60:61], 0, v[176:177]
	v_pk_mul_f32 v[54:55], v[66:67], v[54:55] op_sel_hi:[0,1]
	v_pk_mul_f32 v[52:53], v[66:67], v[52:53] op_sel_hi:[0,1]
	v_pk_mul_f32 v[50:51], v[66:67], v[50:51] op_sel_hi:[0,1]
	v_pk_mul_f32 v[48:49], v[66:67], v[48:49] op_sel_hi:[0,1]
	global_store_dwordx4 v[60:61], v[56:59], off
	s_nop 0
	v_cndmask_b32_e32 v61, v55, v51, vcc
	s_nop 0
	s_nop 0
	s_nop 0
	s_nop 0
	s_nop 0
	ds_bpermute_b32 v61, v130, v61
	v_mov_b64_e32 v[56:57], s[34:35]
	v_mad_i64_i32 v[56:57], s[0:1], v72, s8, v[56:57]
	v_lshl_add_u64 v[56:57], v[56:57], 0, v[128:129]
	s_waitcnt lgkmcnt(1)
	s_nop 0
	v_mov_b32_e32 v58, v48
	s_nop 1
	v_permlane16_swap_b32_e32 v52, v58
	s_waitcnt lgkmcnt(1)
	s_nop 0
	v_mov_b32_e32 v48, v53
	v_mov_b32_e32 v53, v49
	s_nop 1
	v_permlane16_swap_b32_e32 v48, v53
	s_waitcnt lgkmcnt(1)
	s_nop 0
	v_mov_b32_e32 v49, v54
	v_mov_b32_e32 v54, v50
	s_nop 1
	v_permlane16_swap_b32_e32 v49, v54
	s_waitcnt lgkmcnt(0)
	v_cndmask_b32_e32 v50, v61, v55, vcc
	v_cvt_pk_bf16_f32 v48, v52, v48
	v_cvt_pk_bf16_f32 v49, v49, v50
	v_cvt_pk_bf16_f32 v50, v58, v53
	v_lshl_add_u64 v[52:53], v[56:57], 0, v[104:105]
	v_cndmask_b32_e32 v51, v51, v61, vcc
	v_lshl_add_u64 v[52:53], v[52:53], 0, v[176:177]
	s_mov_b32 s0, 0x3900000
	v_cvt_pk_bf16_f32 v51, v54, v51
	v_add_co_u32_e64 v52, s[0:1], s0, v52
	v_or_b32_e32 v54, 0x50, v143
	s_nop 0
	v_addc_co_u32_e64 v53, s[0:1], 0, v53, s[0:1]
	v_or_b32_e32 v56, v144, v54
	global_store_dwordx4 v[52:53], v[48:51], off offset:64
	s_nop 1
	v_lshlrev_b32_e32 v48, 3, v56
	v_ashrrev_i32_e32 v49, 31, v48
	v_lshl_add_u64 v[48:49], v[48:49], 2, s[4:5]
	global_load_dwordx2 v[52:53], v[48:49], off offset:16
	s_nop 0
	global_load_dwordx4 v[48:51], v[48:49], off
	s_and_saveexec_b64 s[0:1], s[40:41]
	s_cbranch_execz .LBB0_413
	v_or_b32_e32 v54, v142, v54
	v_lshlrev_b32_e32 v54, 7, v54
	v_mov_b32_e32 v55, v177
	v_lshl_add_u64 v[66:67], v[134:135], 0, v[54:55]
	v_lshl_add_u64 v[68:69], v[132:133], 0, v[54:55]
	global_load_dwordx4 v[58:61], v[66:67], off
	global_load_dwordx4 v[62:65], v[68:69], off
	s_waitcnt vmcnt(0)
	v_pk_mul_f32 v[70:71], v[44:45], v[62:63]
	v_pk_mul_f32 v[54:55], v[32:33], v[62:63]
	v_mul_f32_e32 v62, v46, v60
	v_mul_f32_e32 v72, v34, v64
	v_mul_f32_e32 v74, v46, v64
	v_mul_f32_e32 v60, v34, v60
	v_mov_b32_e32 v34, v47
	v_mov_b32_e32 v64, v61
	v_mov_b32_e32 v46, v35
	v_pk_mul_f32 v[76:77], v[34:35], v[64:65]
	v_pk_mul_f32 v[34:35], v[46:47], v[64:65]
	v_mov_b32_e32 v63, v76
	v_mov_b32_e32 v73, v77
	v_mov_b32_e32 v61, v34
	v_mov_b32_e32 v75, v35
	v_pk_fma_f32 v[44:45], v[44:45], v[58:59], v[54:55] neg_lo:[0,0,1] neg_hi:[0,0,1]
	v_pk_add_f32 v[54:55], v[62:63], v[72:73] neg_lo:[0,1] neg_hi:[0,1]
	v_pk_fma_f32 v[32:33], v[32:33], v[58:59], v[70:71]
	v_pk_add_f32 v[34:35], v[60:61], v[74:75]
	global_load_dwordx4 v[58:61], v[66:67], off offset:64
	global_load_dwordx4 v[62:65], v[68:69], off offset:64
	s_waitcnt vmcnt(1)
	v_mul_f32_e32 v66, v42, v60
	s_waitcnt vmcnt(0)
	v_mul_f32_e32 v68, v38, v64
	v_mul_f32_e32 v70, v42, v64
	v_mul_f32_e32 v60, v38, v60
	v_mov_b32_e32 v38, v43
	v_mov_b32_e32 v64, v61
	v_pk_mul_f32 v[72:73], v[38:39], v[64:65]
	v_mov_b32_e32 v42, v39
	v_pk_mul_f32 v[46:47], v[40:41], v[62:63]
	v_pk_mul_f32 v[62:63], v[36:37], v[62:63]
	v_mov_b32_e32 v67, v72
	v_mov_b32_e32 v69, v73
	v_pk_mul_f32 v[38:39], v[42:43], v[64:65]
	v_pk_fma_f32 v[40:41], v[40:41], v[58:59], v[62:63] neg_lo:[0,0,1] neg_hi:[0,0,1]
	v_pk_add_f32 v[62:63], v[66:67], v[68:69] neg_lo:[0,1] neg_hi:[0,1]
	v_mov_b32_e32 v61, v38
	v_mov_b32_e32 v71, v39
	v_pk_fma_f32 v[36:37], v[36:37], v[58:59], v[46:47]
	v_pk_add_f32 v[38:39], v[60:61], v[70:71]
	v_mov_b32_e32 v42, v62
	v_mov_b32_e32 v43, v63
	v_mov_b32_e32 v46, v54
	v_mov_b32_e32 v47, v55
.LBB0_413:
	s_or_b64 exec, exec, s[0:1]
	s_waitcnt vmcnt(0)
	v_add_f32_e32 v48, 0, v48
	v_add_f32_e32 v48, v48, v49
	v_add_f32_e32 v48, v48, v50
	v_add_f32_e32 v48, v48, v51
	v_add_f32_e32 v48, v48, v52
	v_add_f32_e32 v48, v48, v53
	v_fmamk_f32 v48, v48, 0x3b2aaaab, v252
	v_mul_f32_e32 v49, 0x4b800000, v48
	v_cmp_gt_f32_e64 s[0:1], s25, v48
	v_mov_b32_e32 v105, v177
	s_nop 0
	v_cndmask_b32_e64 v48, v48, v49, s[0:1]
	v_rsq_f32_e32 v50, v48
	v_mov_b64_e32 v[48:49], s[22:23]
	v_mul_f32_e32 v51, 0x45800000, v50
	v_cndmask_b32_e64 v50, v50, v51, s[0:1]
	v_mul_f32_e32 v50, 0x3dd53b94, v50
	v_pk_mul_f32 v[46:47], v[50:51], v[46:47] op_sel_hi:[0,1]
	v_pk_mul_f32 v[44:45], v[50:51], v[44:45] op_sel_hi:[0,1]
	v_pk_mul_f32 v[42:43], v[50:51], v[42:43] op_sel_hi:[0,1]
	v_pk_mul_f32 v[40:41], v[50:51], v[40:41] op_sel_hi:[0,1]
	s_nop 0
	s_nop 0
	s_nop 0
	s_nop 0
	s_nop 0
	s_nop 0
	s_nop 0
	s_nop 0
	v_mad_i64_i32 v[48:49], s[0:1], v56, s8, v[48:49]
	v_lshl_add_u64 v[48:49], v[48:49], 0, v[128:129]
	s_waitcnt lgkmcnt(0)
	s_nop 0
	v_mov_b32_e32 v51, v40
	s_nop 1
	v_permlane16_swap_b32_e32 v44, v51
	s_waitcnt lgkmcnt(0)
	s_nop 0
	v_mov_b32_e32 v40, v45
	v_mov_b32_e32 v45, v41
	s_nop 1
	v_permlane16_swap_b32_e32 v40, v45
	s_waitcnt lgkmcnt(0)
	s_nop 0
	v_mov_b32_e32 v41, v46
	v_mov_b32_e32 v46, v42
	s_nop 1
	v_permlane16_swap_b32_e32 v41, v46
	s_waitcnt lgkmcnt(0)
	s_nop 0
	v_mov_b32_e32 v42, v47
	s_nop 1
	v_permlane16_swap_b32_e32 v42, v43
	v_cvt_pk_bf16_f32 v40, v44, v40
	v_cvt_pk_bf16_f32 v41, v41, v42
	v_cvt_pk_bf16_f32 v42, v51, v45
	v_lshl_add_u64 v[44:45], v[48:49], 0, v[104:105]
	v_cvt_pk_bf16_f32 v43, v46, v43
	v_lshl_add_u64 v[44:45], v[44:45], 0, v[176:177]
	v_pk_mul_f32 v[34:35], v[50:51], v[34:35] op_sel_hi:[0,1]
	v_pk_mul_f32 v[32:33], v[50:51], v[32:33] op_sel_hi:[0,1]
	v_pk_mul_f32 v[38:39], v[50:51], v[38:39] op_sel_hi:[0,1]
	v_pk_mul_f32 v[36:37], v[50:51], v[36:37] op_sel_hi:[0,1]
	global_store_dwordx4 v[44:45], v[40:43], off
	v_cndmask_b32_e32 v44, v34, v38, vcc
	v_cndmask_b32_e32 v45, v35, v39, vcc
	s_nop 0
	s_nop 0
	s_nop 0
	s_nop 0
	ds_bpermute_b32 v44, v130, v44
	ds_bpermute_b32 v45, v130, v45
	v_mov_b64_e32 v[40:41], s[34:35]
	v_mad_i64_i32 v[40:41], s[0:1], v56, s8, v[40:41]
	v_lshl_add_u64 v[40:41], v[40:41], 0, v[128:129]
	s_waitcnt lgkmcnt(2)
	s_nop 0
	s_nop 1
	v_permlane16_swap_b32_e32 v32, v36
	s_waitcnt lgkmcnt(2)
	s_nop 0
	s_nop 1
	v_permlane16_swap_b32_e32 v33, v37
	s_waitcnt lgkmcnt(1)
	v_cndmask_b32_e32 v34, v44, v34, vcc
	s_waitcnt lgkmcnt(0)
	v_cndmask_b32_e32 v35, v45, v35, vcc
	v_cvt_pk_bf16_f32 v32, v32, v33
	v_cvt_pk_bf16_f32 v33, v34, v35
	v_cvt_pk_bf16_f32 v34, v36, v37
	v_lshl_add_u64 v[36:37], v[40:41], 0, v[104:105]
	v_cndmask_b32_e32 v38, v38, v44, vcc
	v_cndmask_b32_e32 v39, v39, v45, vcc
	v_lshl_add_u64 v[36:37], v[36:37], 0, v[176:177]
	s_mov_b32 s0, 0x3900000
	v_cvt_pk_bf16_f32 v35, v38, v39
	v_add_co_u32_e64 v36, s[0:1], s0, v36
	v_or_b32_e32 v38, 0x60, v143
	s_nop 0
	v_addc_co_u32_e64 v37, s[0:1], 0, v37, s[0:1]
	v_or_b32_e32 v40, v144, v38
	global_store_dwordx4 v[36:37], v[32:35], off offset:64
	s_nop 1
	v_lshlrev_b32_e32 v32, 3, v40
	v_ashrrev_i32_e32 v33, 31, v32
	v_lshl_add_u64 v[32:33], v[32:33], 2, s[4:5]
	global_load_dwordx2 v[36:37], v[32:33], off offset:16
	s_nop 0
	global_load_dwordx4 v[32:35], v[32:33], off
	s_and_saveexec_b64 s[0:1], s[40:41]
	s_cbranch_execz .LBB0_415
	v_or_b32_e32 v38, v142, v38
	v_lshlrev_b32_e32 v38, 7, v38
	v_mov_b32_e32 v39, v177
	v_lshl_add_u64 v[50:51], v[134:135], 0, v[38:39]
	v_lshl_add_u64 v[52:53], v[132:133], 0, v[38:39]
	global_load_dwordx4 v[42:45], v[50:51], off
	global_load_dwordx4 v[46:49], v[52:53], off
	s_waitcnt vmcnt(0)
	v_pk_mul_f32 v[54:55], v[24:25], v[46:47]
	v_pk_mul_f32 v[38:39], v[20:21], v[46:47]
	v_mul_f32_e32 v46, v26, v44
	v_mul_f32_e32 v56, v22, v48
	v_mul_f32_e32 v58, v26, v48
	v_mul_f32_e32 v44, v22, v44
	v_mov_b32_e32 v22, v27
	v_mov_b32_e32 v48, v45
	v_mov_b32_e32 v26, v23
	v_pk_mul_f32 v[60:61], v[22:23], v[48:49]
	v_pk_mul_f32 v[22:23], v[26:27], v[48:49]
	v_mov_b32_e32 v47, v60
	v_mov_b32_e32 v57, v61
	v_mov_b32_e32 v45, v22
	v_mov_b32_e32 v59, v23
	v_pk_fma_f32 v[24:25], v[24:25], v[42:43], v[38:39] neg_lo:[0,0,1] neg_hi:[0,0,1]
	v_pk_add_f32 v[38:39], v[46:47], v[56:57] neg_lo:[0,1] neg_hi:[0,1]
	v_pk_fma_f32 v[20:21], v[20:21], v[42:43], v[54:55]
	v_pk_add_f32 v[22:23], v[44:45], v[58:59]
	global_load_dwordx4 v[42:45], v[50:51], off offset:64
	global_load_dwordx4 v[46:49], v[52:53], off offset:64
	s_waitcnt vmcnt(1)
	v_mul_f32_e32 v50, v30, v44
	s_waitcnt vmcnt(0)
	v_mul_f32_e32 v52, v18, v48
	v_mul_f32_e32 v54, v30, v48
	v_mul_f32_e32 v44, v18, v44
	v_mov_b32_e32 v18, v31
	v_mov_b32_e32 v48, v45
	v_pk_mul_f32 v[56:57], v[18:19], v[48:49]
	v_mov_b32_e32 v30, v19
	v_pk_mul_f32 v[26:27], v[28:29], v[46:47]
	v_pk_mul_f32 v[46:47], v[16:17], v[46:47]
	v_mov_b32_e32 v51, v56
	v_mov_b32_e32 v53, v57
	v_pk_mul_f32 v[18:19], v[30:31], v[48:49]
	v_pk_fma_f32 v[28:29], v[28:29], v[42:43], v[46:47] neg_lo:[0,0,1] neg_hi:[0,0,1]
	v_pk_add_f32 v[46:47], v[50:51], v[52:53] neg_lo:[0,1] neg_hi:[0,1]
	v_mov_b32_e32 v45, v18
	v_mov_b32_e32 v55, v19
	v_pk_fma_f32 v[16:17], v[16:17], v[42:43], v[26:27]
	v_pk_add_f32 v[18:19], v[44:45], v[54:55]
	v_mov_b32_e32 v30, v46
	v_mov_b32_e32 v31, v47
	v_mov_b32_e32 v26, v38
	v_mov_b32_e32 v27, v39
.LBB0_415:
	s_or_b64 exec, exec, s[0:1]
	s_waitcnt vmcnt(0)
	v_add_f32_e32 v32, 0, v32
	v_add_f32_e32 v32, v32, v33
	v_add_f32_e32 v32, v32, v34
	v_add_f32_e32 v32, v32, v35
	v_add_f32_e32 v32, v32, v36
	v_add_f32_e32 v32, v32, v37
	v_fmamk_f32 v32, v32, 0x3b2aaaab, v252
	v_mul_f32_e32 v33, 0x4b800000, v32
	v_cmp_gt_f32_e64 s[0:1], s25, v32
	s_nop 1
	v_cndmask_b32_e64 v32, v32, v33, s[0:1]
	v_rsq_f32_e32 v34, v32
	v_mov_b64_e32 v[32:33], s[22:23]
	v_mul_f32_e32 v35, 0x45800000, v34
	v_cndmask_b32_e64 v34, v34, v35, s[0:1]
	v_mul_f32_e32 v34, 0x3dd53b94, v34
	v_pk_mul_f32 v[26:27], v[34:35], v[26:27] op_sel_hi:[0,1]
	v_pk_mul_f32 v[24:25], v[34:35], v[24:25] op_sel_hi:[0,1]
	v_pk_mul_f32 v[30:31], v[34:35], v[30:31] op_sel_hi:[0,1]
	v_pk_mul_f32 v[28:29], v[34:35], v[28:29] op_sel_hi:[0,1]
	v_cndmask_b32_e32 v35, v24, v28, vcc
	s_nop 0
	s_nop 0
	s_nop 0
	ds_bpermute_b32 v35, v130, v35
	s_nop 0
	s_nop 0
	s_nop 0
	v_mad_i64_i32 v[32:33], s[0:1], v40, s8, v[32:33]
	v_lshl_add_u64 v[32:33], v[32:33], 0, v[128:129]
	s_waitcnt lgkmcnt(0)
	v_cndmask_b32_e32 v24, v35, v24, vcc
	v_cndmask_b32_e32 v28, v28, v35, vcc
	s_waitcnt lgkmcnt(0)
	s_nop 0
	s_nop 1
	v_permlane16_swap_b32_e32 v25, v29
	s_waitcnt lgkmcnt(0)
	s_nop 0
	s_waitcnt lgkmcnt(0)
	s_nop 0
	s_nop 1
	v_permlane16_swap_b32_e32 v26, v30
	s_nop 1
	v_permlane16_swap_b32_e32 v27, v31
	v_cvt_pk_bf16_f32 v24, v24, v25
	v_cvt_pk_bf16_f32 v25, v26, v27
	v_cvt_pk_bf16_f32 v26, v28, v29
	v_lshl_add_u64 v[28:29], v[32:33], 0, v[104:105]
	v_cvt_pk_bf16_f32 v27, v30, v31
	v_lshl_add_u64 v[28:29], v[28:29], 0, v[176:177]
	v_pk_mul_f32 v[22:23], v[34:35], v[22:23] op_sel_hi:[0,1]
	v_pk_mul_f32 v[20:21], v[34:35], v[20:21] op_sel_hi:[0,1]
	v_pk_mul_f32 v[18:19], v[34:35], v[18:19] op_sel_hi:[0,1]
	v_pk_mul_f32 v[16:17], v[34:35], v[16:17] op_sel_hi:[0,1]
	global_store_dwordx4 v[28:29], v[24:27], off
	s_nop 0
	v_cndmask_b32_e32 v29, v23, v19, vcc
	s_nop 0
	s_nop 0
	s_nop 0
	s_nop 0
	s_nop 0
	ds_bpermute_b32 v29, v130, v29
	v_mov_b64_e32 v[24:25], s[34:35]
	v_mad_i64_i32 v[24:25], s[0:1], v40, s8, v[24:25]
	v_lshl_add_u64 v[24:25], v[24:25], 0, v[128:129]
	s_waitcnt lgkmcnt(1)
	s_nop 0
	v_mov_b32_e32 v26, v16
	s_nop 1
	v_permlane16_swap_b32_e32 v20, v26
	s_waitcnt lgkmcnt(1)
	s_nop 0
	v_mov_b32_e32 v16, v21
	v_mov_b32_e32 v21, v17
	s_nop 1
	v_permlane16_swap_b32_e32 v16, v21
	s_waitcnt lgkmcnt(1)
	s_nop 0
	v_mov_b32_e32 v17, v22
	v_mov_b32_e32 v22, v18
	s_nop 1
	v_permlane16_swap_b32_e32 v17, v22
	s_waitcnt lgkmcnt(0)
	v_cndmask_b32_e32 v18, v29, v23, vcc
	v_cvt_pk_bf16_f32 v16, v20, v16
	v_cvt_pk_bf16_f32 v17, v17, v18
	v_cvt_pk_bf16_f32 v18, v26, v21
	v_lshl_add_u64 v[20:21], v[24:25], 0, v[104:105]
	v_cndmask_b32_e32 v19, v19, v29, vcc
	v_lshl_add_u64 v[20:21], v[20:21], 0, v[176:177]
	s_mov_b32 s0, 0x3900000
	v_cvt_pk_bf16_f32 v19, v22, v19
	v_add_co_u32_e64 v20, s[0:1], s0, v20
	v_or_b32_e32 v22, 0x70, v143
	s_nop 0
	v_addc_co_u32_e64 v21, s[0:1], 0, v21, s[0:1]
	v_or_b32_e32 v24, v144, v22
	global_store_dwordx4 v[20:21], v[16:19], off offset:64
	s_nop 1
	v_lshlrev_b32_e32 v16, 3, v24
	v_ashrrev_i32_e32 v17, 31, v16
	v_lshl_add_u64 v[16:17], v[16:17], 2, s[4:5]
	global_load_dwordx2 v[20:21], v[16:17], off offset:16
	s_nop 0
	global_load_dwordx4 v[16:19], v[16:17], off
	s_and_saveexec_b64 s[0:1], s[40:41]
	s_cbranch_execz .LBB0_417
	v_or_b32_e32 v22, v142, v22
	v_lshlrev_b32_e32 v22, 7, v22
	v_mov_b32_e32 v23, v177
	v_lshl_add_u64 v[34:35], v[134:135], 0, v[22:23]
	v_lshl_add_u64 v[36:37], v[132:133], 0, v[22:23]
	global_load_dwordx4 v[26:29], v[34:35], off
	global_load_dwordx4 v[30:33], v[36:37], off
	s_waitcnt vmcnt(0)
	v_pk_mul_f32 v[38:39], v[8:9], v[30:31]
	v_pk_mul_f32 v[22:23], v[0:1], v[30:31]
	v_mul_f32_e32 v30, v10, v28
	v_mul_f32_e32 v40, v2, v32
	v_mul_f32_e32 v42, v10, v32
	v_mul_f32_e32 v28, v2, v28
	v_mov_b32_e32 v2, v11
	v_mov_b32_e32 v32, v29
	v_mov_b32_e32 v10, v3
	v_pk_mul_f32 v[44:45], v[2:3], v[32:33]
	v_pk_mul_f32 v[2:3], v[10:11], v[32:33]
	v_mov_b32_e32 v31, v44
	v_mov_b32_e32 v41, v45
	v_mov_b32_e32 v29, v2
	v_mov_b32_e32 v43, v3
	v_pk_fma_f32 v[8:9], v[8:9], v[26:27], v[22:23] neg_lo:[0,0,1] neg_hi:[0,0,1]
	v_pk_add_f32 v[22:23], v[30:31], v[40:41] neg_lo:[0,1] neg_hi:[0,1]
	v_pk_fma_f32 v[0:1], v[0:1], v[26:27], v[38:39]
	v_pk_add_f32 v[2:3], v[28:29], v[42:43]
	global_load_dwordx4 v[26:29], v[34:35], off offset:64
	global_load_dwordx4 v[30:33], v[36:37], off offset:64
	s_waitcnt vmcnt(1)
	v_mul_f32_e32 v34, v14, v28
	s_waitcnt vmcnt(0)
	v_mul_f32_e32 v36, v6, v32
	v_mul_f32_e32 v38, v14, v32
	v_mul_f32_e32 v28, v6, v28
	v_mov_b32_e32 v6, v15
	v_mov_b32_e32 v32, v29
	v_pk_mul_f32 v[40:41], v[6:7], v[32:33]
	v_mov_b32_e32 v14, v7
	v_pk_mul_f32 v[10:11], v[12:13], v[30:31]
	v_pk_mul_f32 v[30:31], v[4:5], v[30:31]
	v_mov_b32_e32 v35, v40
	v_mov_b32_e32 v37, v41
	v_pk_mul_f32 v[6:7], v[14:15], v[32:33]
	v_pk_fma_f32 v[12:13], v[12:13], v[26:27], v[30:31] neg_lo:[0,0,1] neg_hi:[0,0,1]
	v_pk_add_f32 v[30:31], v[34:35], v[36:37] neg_lo:[0,1] neg_hi:[0,1]
	v_mov_b32_e32 v29, v6
	v_mov_b32_e32 v39, v7
	v_pk_fma_f32 v[4:5], v[4:5], v[26:27], v[10:11]
	v_pk_add_f32 v[6:7], v[28:29], v[38:39]
	v_mov_b32_e32 v14, v30
	v_mov_b32_e32 v15, v31
	v_mov_b32_e32 v10, v22
	v_mov_b32_e32 v11, v23
.LBB0_417:
	s_or_b64 exec, exec, s[0:1]
	s_waitcnt vmcnt(0)
	v_add_f32_e32 v16, 0, v16
	v_add_f32_e32 v16, v16, v17
	v_add_f32_e32 v16, v16, v18
	v_add_f32_e32 v16, v16, v19
	v_add_f32_e32 v16, v16, v20
	v_add_f32_e32 v16, v16, v21
	v_fmamk_f32 v16, v16, 0x3b2aaaab, v252
	v_mul_f32_e32 v17, 0x4b800000, v16
	v_cmp_gt_f32_e64 s[0:1], s25, v16
	v_mov_b32_e32 v105, v177
	s_nop 0
	v_cndmask_b32_e64 v16, v16, v17, s[0:1]
	v_rsq_f32_e32 v18, v16
	v_mov_b64_e32 v[16:17], s[22:23]
	v_mul_f32_e32 v19, 0x45800000, v18
	v_cndmask_b32_e64 v18, v18, v19, s[0:1]
	v_mul_f32_e32 v18, 0x3dd53b94, v18
	v_pk_mul_f32 v[10:11], v[18:19], v[10:11] op_sel_hi:[0,1]
	v_pk_mul_f32 v[8:9], v[18:19], v[8:9] op_sel_hi:[0,1]
	v_pk_mul_f32 v[14:15], v[18:19], v[14:15] op_sel_hi:[0,1]
	v_pk_mul_f32 v[12:13], v[18:19], v[12:13] op_sel_hi:[0,1]
	v_cndmask_b32_e32 v19, v8, v12, vcc
	s_nop 0
	s_nop 0
	s_nop 0
	ds_bpermute_b32 v19, v130, v19
	s_nop 0
	s_nop 0
	s_nop 0
	v_mad_i64_i32 v[16:17], s[0:1], v24, s8, v[16:17]
	v_lshl_add_u64 v[16:17], v[16:17], 0, v[128:129]
	s_waitcnt lgkmcnt(0)
	v_cndmask_b32_e32 v8, v19, v8, vcc
	v_cndmask_b32_e32 v12, v12, v19, vcc
	s_waitcnt lgkmcnt(0)
	s_nop 0
	s_nop 1
	v_permlane16_swap_b32_e32 v9, v13
	s_waitcnt lgkmcnt(0)
	s_nop 0
	s_waitcnt lgkmcnt(0)
	s_nop 0
	s_nop 1
	v_permlane16_swap_b32_e32 v10, v14
	s_nop 1
	v_permlane16_swap_b32_e32 v11, v15
	v_cvt_pk_bf16_f32 v8, v8, v9
	v_cvt_pk_bf16_f32 v9, v10, v11
	v_cvt_pk_bf16_f32 v10, v12, v13
	v_lshl_add_u64 v[12:13], v[16:17], 0, v[104:105]
	v_cvt_pk_bf16_f32 v11, v14, v15
	v_lshl_add_u64 v[12:13], v[12:13], 0, v[176:177]
	v_pk_mul_f32 v[2:3], v[18:19], v[2:3] op_sel_hi:[0,1]
	v_pk_mul_f32 v[0:1], v[18:19], v[0:1] op_sel_hi:[0,1]
	v_pk_mul_f32 v[6:7], v[18:19], v[6:7] op_sel_hi:[0,1]
	v_pk_mul_f32 v[4:5], v[18:19], v[4:5] op_sel_hi:[0,1]
	global_store_dwordx4 v[12:13], v[8:11], off
	v_cndmask_b32_e32 v12, v2, v6, vcc
	v_cndmask_b32_e32 v13, v3, v7, vcc
	s_nop 0
	s_nop 0
	s_nop 0
	s_nop 0
	ds_bpermute_b32 v12, v130, v12
	ds_bpermute_b32 v13, v130, v13
	v_mov_b64_e32 v[8:9], s[34:35]
	v_mad_i64_i32 v[8:9], s[0:1], v24, s8, v[8:9]
	v_lshl_add_u64 v[8:9], v[8:9], 0, v[128:129]
	s_waitcnt lgkmcnt(2)
	s_nop 0
	s_nop 1
	v_permlane16_swap_b32_e32 v0, v4
	s_waitcnt lgkmcnt(2)
	s_nop 0
	s_nop 1
	v_permlane16_swap_b32_e32 v1, v5
	s_waitcnt lgkmcnt(1)
	v_cndmask_b32_e32 v2, v12, v2, vcc
	s_waitcnt lgkmcnt(0)
	v_cndmask_b32_e32 v3, v13, v3, vcc
	v_cvt_pk_bf16_f32 v0, v0, v1
	v_cvt_pk_bf16_f32 v1, v2, v3
	v_cvt_pk_bf16_f32 v2, v4, v5
	v_lshl_add_u64 v[4:5], v[8:9], 0, v[104:105]
	v_lshl_add_u64 v[4:5], v[4:5], 0, v[176:177]
	v_cndmask_b32_e32 v6, v6, v12, vcc
	v_cndmask_b32_e32 v7, v7, v13, vcc
	v_add_co_u32_e32 v4, vcc, 0x3900000, v4
	v_cvt_pk_bf16_f32 v3, v6, v7
	s_nop 0
	v_addc_co_u32_e32 v5, vcc, 0, v5, vcc
	global_store_dwordx4 v[4:5], v[0:3], off offset:64

.LBB0_456:
	v_lshl_add_u32 v52, v147, 3, s9
	v_cmp_lt_i32_e32 vcc, v189, v202
	v_mad_u64_u32 v[128:129], s[0:1], v52, s8, v[128:129]
	v_lshlrev_b32_e32 v176, 7, v149
	v_bfe_u32 v133, v146, 4, 1
	v_cndmask_b32_e32 v54, v203, v189, vcc
	v_lshl_add_u64 v[52:53], s[94:95], 0, v[176:177]
	v_lshlrev_b32_e32 v129, 2, v54
	v_lshlrev_b32_e32 v176, 5, v133
	v_lshlrev_b32_e32 v54, 3, v148
	v_lshl_add_u64 v[52:53], v[52:53], 0, v[176:177]
	v_and_b32_e32 v176, 16, v54
	v_lshl_add_u64 v[130:131], v[52:53], 0, v[176:177]
	v_add_u32_e32 v52, v128, v145
	v_mad_i64_i32 v[56:57], s[0:1], v52, s18, v[130:131]
	v_pk_mul_f32 v[52:53], v[126:127], v[134:135] op_sel_hi:[1,0]
	v_pk_mul_f32 v[54:55], v[124:125], v[134:135] op_sel_hi:[1,0]
	v_pk_mul_f32 v[58:59], v[122:123], v[134:135] op_sel_hi:[1,0]
	v_pk_mul_f32 v[120:121], v[120:121], v[134:135] op_sel_hi:[1,0]
	v_cmp_eq_u32_e64 s[40:41], 0, v133
	v_pk_mul_f32 v[112:113], v[112:113], v[134:135] op_sel_hi:[1,0]
	s_and_b64 vcc, exec, s[42:43]
	s_nop 0
	s_nop 0
	s_nop 0
	s_nop 0
	s_nop 0
	s_nop 0
	s_nop 0
	s_nop 0
	s_waitcnt lgkmcnt(0)
	s_nop 0
	s_nop 1
	v_permlane16_swap_b32_e32 v54, v120
	s_waitcnt lgkmcnt(0)
	s_nop 0
	s_nop 1
	v_permlane16_swap_b32_e32 v55, v121
	s_waitcnt lgkmcnt(0)
	s_nop 0
	v_mov_b32_e32 v122, v52
	s_nop 1
	v_permlane16_swap_b32_e32 v122, v58
	s_waitcnt lgkmcnt(0)
	s_nop 0
	s_nop 1
	v_permlane16_swap_b32_e32 v53, v59
	v_cvt_pk_bf16_f32 v52, v54, v55
	v_cvt_pk_bf16_f32 v53, v122, v53
	v_cvt_pk_bf16_f32 v54, v120, v121
	v_cvt_pk_bf16_f32 v55, v58, v59
	global_store_dwordx4 v[56:57], v[52:55], off
	v_pk_mul_f32 v[58:59], v[114:115], v[134:135] op_sel_hi:[1,0]
	s_nop 0
	v_pk_mul_f32 v[52:53], v[118:119], v[134:135] op_sel_hi:[1,0]
	v_pk_mul_f32 v[54:55], v[116:117], v[134:135] op_sel_hi:[1,0]
	s_nop 0
	s_nop 0
	s_nop 0
	s_nop 0
	s_nop 0
	s_nop 0
	s_nop 0
	s_nop 0
	s_waitcnt lgkmcnt(0)
	s_nop 0
	s_nop 1
	v_permlane16_swap_b32_e32 v54, v112
	s_waitcnt lgkmcnt(0)
	s_nop 0
	s_nop 1
	v_permlane16_swap_b32_e32 v55, v113
	s_waitcnt lgkmcnt(0)
	s_nop 0
	v_mov_b32_e32 v114, v52
	s_nop 1
	v_permlane16_swap_b32_e32 v114, v58
	s_waitcnt lgkmcnt(0)
	s_nop 0
	s_nop 1
	v_permlane16_swap_b32_e32 v53, v59
	v_cvt_pk_bf16_f32 v52, v54, v55
	v_cvt_pk_bf16_f32 v53, v114, v53
	v_cvt_pk_bf16_f32 v54, v112, v113
	v_cvt_pk_bf16_f32 v55, v58, v59
	v_or_b32_e32 v112, 16, v145
	global_store_dwordx4 v[56:57], v[52:55], off offset:64
	s_cbranch_vccnz .LBB0_458
	s_nop 0
	v_add_u32_e32 v52, v144, v112
	v_ashrrev_i32_e32 v53, 31, v52
	v_lshl_add_u64 v[52:53], v[52:53], 4, s[2:3]
	global_load_dwordx4 v[52:55], v[52:53], off
	s_waitcnt vmcnt(0)
	v_add_f32_e32 v52, v52, v53
	v_add_f32_e32 v52, v52, v54
	v_add_f32_e32 v52, v52, v55
	v_fmamk_f32 v52, v52, 0x3b800000, v252
	v_mul_f32_e32 v53, 0x4b800000, v52
	v_cmp_gt_f32_e32 vcc, s25, v52
	s_nop 1
	v_cndmask_b32_e32 v52, v52, v53, vcc
	v_rsq_f32_e32 v52, v52
	s_nop 0
	v_mul_f32_e32 v53, 0x45800000, v52
	v_cndmask_b32_e32 v132, v52, v53, vcc
.LBB0_458:
	s_nop 0
	v_add_u32_e32 v52, v128, v112
	v_mad_i64_i32 v[56:57], s[0:1], v52, s18, v[130:131]
	v_pk_mul_f32 v[52:53], v[110:111], v[132:133] op_sel_hi:[1,0]
	v_pk_mul_f32 v[54:55], v[108:109], v[132:133] op_sel_hi:[1,0]
	v_pk_mul_f32 v[58:59], v[106:107], v[132:133] op_sel_hi:[1,0]
	v_pk_mul_f32 v[104:105], v[104:105], v[132:133] op_sel_hi:[1,0]
	s_nop 0
	s_nop 0
	s_nop 0
	s_nop 0
	s_nop 0
	s_nop 0
	s_nop 0
	s_nop 0
	v_pk_mul_f32 v[96:97], v[96:97], v[132:133] op_sel_hi:[1,0]
	s_waitcnt lgkmcnt(0)
	s_nop 0
	s_nop 1
	v_permlane16_swap_b32_e32 v54, v104
	s_waitcnt lgkmcnt(0)
	s_nop 0
	s_nop 1
	v_permlane16_swap_b32_e32 v55, v105
	s_waitcnt lgkmcnt(0)
	s_nop 0
	v_mov_b32_e32 v106, v52
	s_nop 1
	v_permlane16_swap_b32_e32 v106, v58
	s_waitcnt lgkmcnt(0)
	s_nop 0
	s_nop 1
	v_permlane16_swap_b32_e32 v53, v59
	v_cvt_pk_bf16_f32 v52, v54, v55
	v_cvt_pk_bf16_f32 v53, v106, v53
	v_cvt_pk_bf16_f32 v54, v104, v105
	v_cvt_pk_bf16_f32 v55, v58, v59
	global_store_dwordx4 v[56:57], v[52:55], off
	v_pk_mul_f32 v[58:59], v[98:99], v[132:133] op_sel_hi:[1,0]
	s_and_b64 vcc, exec, s[42:43]
	v_pk_mul_f32 v[52:53], v[102:103], v[132:133] op_sel_hi:[1,0]
	v_pk_mul_f32 v[54:55], v[100:101], v[132:133] op_sel_hi:[1,0]
	s_nop 0
	s_nop 0
	s_nop 0
	s_nop 0
	s_nop 0
	s_nop 0
	s_nop 0
	s_nop 0
	s_waitcnt lgkmcnt(0)
	s_nop 0
	s_nop 1
	v_permlane16_swap_b32_e32 v54, v96
	s_waitcnt lgkmcnt(0)
	s_nop 0
	s_nop 1
	v_permlane16_swap_b32_e32 v55, v97
	s_waitcnt lgkmcnt(0)
	s_nop 0
	v_mov_b32_e32 v98, v52
	s_nop 1
	v_permlane16_swap_b32_e32 v98, v58
	s_waitcnt lgkmcnt(0)
	s_nop 0
	s_nop 1
	v_permlane16_swap_b32_e32 v53, v59
	v_cvt_pk_bf16_f32 v52, v54, v55
	v_cvt_pk_bf16_f32 v53, v98, v53
	v_cvt_pk_bf16_f32 v54, v96, v97
	v_cvt_pk_bf16_f32 v55, v58, v59
	v_or_b32_e32 v97, 32, v145
	v_mov_b32_e32 v96, 1.0
	v_mov_b32_e32 v98, 1.0
	global_store_dwordx4 v[56:57], v[52:55], off offset:64
	s_cbranch_vccnz .LBB0_460
	s_nop 0
	v_add_u32_e32 v52, v144, v97
	v_ashrrev_i32_e32 v53, 31, v52
	v_lshl_add_u64 v[52:53], v[52:53], 4, s[2:3]
	global_load_dwordx4 v[52:55], v[52:53], off
	s_waitcnt vmcnt(0)
	v_add_f32_e32 v52, v52, v53
	v_add_f32_e32 v52, v52, v54
	v_add_f32_e32 v52, v52, v55
	v_fmamk_f32 v52, v52, 0x3b800000, v252
	v_mul_f32_e32 v53, 0x4b800000, v52
	v_cmp_gt_f32_e32 vcc, s25, v52
	s_nop 1
	v_cndmask_b32_e32 v52, v52, v53, vcc
	v_rsq_f32_e32 v52, v52
	s_nop 0
	v_mul_f32_e32 v53, 0x45800000, v52
	v_cndmask_b32_e32 v98, v52, v53, vcc
.LBB0_460:
	s_nop 0
	v_add_u32_e32 v52, v128, v97
	v_mad_i64_i32 v[56:57], s[0:1], v52, s18, v[130:131]
	v_pk_mul_f32 v[52:53], v[94:95], v[98:99] op_sel_hi:[1,0]
	v_pk_mul_f32 v[54:55], v[92:93], v[98:99] op_sel_hi:[1,0]
	v_pk_mul_f32 v[58:59], v[90:91], v[98:99] op_sel_hi:[1,0]
	v_pk_mul_f32 v[88:89], v[88:89], v[98:99] op_sel_hi:[1,0]
	s_nop 0
	s_nop 0
	s_nop 0
	s_nop 0
	s_nop 0
	s_nop 0
	s_nop 0
	s_nop 0
	v_pk_mul_f32 v[80:81], v[80:81], v[98:99] op_sel_hi:[1,0]
	s_waitcnt lgkmcnt(0)
	s_nop 0
	s_nop 1
	v_permlane16_swap_b32_e32 v54, v88
	s_waitcnt lgkmcnt(0)
	s_nop 0
	s_nop 1
	v_permlane16_swap_b32_e32 v55, v89
	s_waitcnt lgkmcnt(0)
	s_nop 0
	v_mov_b32_e32 v90, v52
	s_nop 1
	v_permlane16_swap_b32_e32 v90, v58
	s_waitcnt lgkmcnt(0)
	s_nop 0
	s_nop 1
	v_permlane16_swap_b32_e32 v53, v59
	v_cvt_pk_bf16_f32 v52, v54, v55
	v_cvt_pk_bf16_f32 v53, v90, v53
	v_cvt_pk_bf16_f32 v54, v88, v89
	v_cvt_pk_bf16_f32 v55, v58, v59
	global_store_dwordx4 v[56:57], v[52:55], off
	v_pk_mul_f32 v[58:59], v[82:83], v[98:99] op_sel_hi:[1,0]
	s_and_b64 vcc, exec, s[42:43]
	v_pk_mul_f32 v[52:53], v[86:87], v[98:99] op_sel_hi:[1,0]
	v_pk_mul_f32 v[54:55], v[84:85], v[98:99] op_sel_hi:[1,0]
	s_nop 0
	s_nop 0
	s_nop 0
	s_nop 0
	s_nop 0
	s_nop 0
	s_nop 0
	s_nop 0
	s_waitcnt lgkmcnt(0)
	s_nop 0
	s_nop 1
	v_permlane16_swap_b32_e32 v54, v80
	s_waitcnt lgkmcnt(0)
	s_nop 0
	s_nop 1
	v_permlane16_swap_b32_e32 v55, v81
	s_waitcnt lgkmcnt(0)
	s_nop 0
	v_mov_b32_e32 v82, v52
	s_nop 1
	v_permlane16_swap_b32_e32 v82, v58
	s_waitcnt lgkmcnt(0)
	s_nop 0
	s_nop 1
	v_permlane16_swap_b32_e32 v53, v59
	v_cvt_pk_bf16_f32 v52, v54, v55
	v_cvt_pk_bf16_f32 v53, v82, v53
	v_cvt_pk_bf16_f32 v54, v80, v81
	v_cvt_pk_bf16_f32 v55, v58, v59
	v_or_b32_e32 v80, 48, v145
	global_store_dwordx4 v[56:57], v[52:55], off offset:64
	s_cbranch_vccnz .LBB0_462
	s_nop 0
	v_add_u32_e32 v52, v144, v80
	v_ashrrev_i32_e32 v53, 31, v52
	v_lshl_add_u64 v[52:53], v[52:53], 4, s[2:3]
	global_load_dwordx4 v[52:55], v[52:53], off
	s_waitcnt vmcnt(0)
	v_add_f32_e32 v52, v52, v53
	v_add_f32_e32 v52, v52, v54
	v_add_f32_e32 v52, v52, v55
	v_fmamk_f32 v52, v52, 0x3b800000, v252
	v_mul_f32_e32 v53, 0x4b800000, v52
	v_cmp_gt_f32_e32 vcc, s25, v52
	s_nop 1
	v_cndmask_b32_e32 v52, v52, v53, vcc
	v_rsq_f32_e32 v52, v52
	s_nop 0
	v_mul_f32_e32 v53, 0x45800000, v52
	v_cndmask_b32_e32 v96, v52, v53, vcc
.LBB0_462:
	s_nop 0
	v_add_u32_e32 v52, v128, v80
	v_mad_i64_i32 v[56:57], s[0:1], v52, s18, v[130:131]
	v_pk_mul_f32 v[52:53], v[78:79], v[96:97] op_sel_hi:[1,0]
	v_pk_mul_f32 v[54:55], v[76:77], v[96:97] op_sel_hi:[1,0]
	v_pk_mul_f32 v[58:59], v[74:75], v[96:97] op_sel_hi:[1,0]
	v_pk_mul_f32 v[72:73], v[72:73], v[96:97] op_sel_hi:[1,0]
	s_nop 0
	s_nop 0
	s_nop 0
	s_nop 0
	s_nop 0
	s_nop 0
	s_nop 0
	s_nop 0
	v_pk_mul_f32 v[64:65], v[64:65], v[96:97] op_sel_hi:[1,0]
	s_waitcnt lgkmcnt(0)
	s_nop 0
	s_nop 1
	v_permlane16_swap_b32_e32 v54, v72
	s_waitcnt lgkmcnt(0)
	s_nop 0
	s_nop 1
	v_permlane16_swap_b32_e32 v55, v73
	s_waitcnt lgkmcnt(0)
	s_nop 0
	v_mov_b32_e32 v74, v52
	s_nop 1
	v_permlane16_swap_b32_e32 v74, v58
	s_waitcnt lgkmcnt(0)
	s_nop 0
	s_nop 1
	v_permlane16_swap_b32_e32 v53, v59
	v_cvt_pk_bf16_f32 v52, v54, v55
	v_cvt_pk_bf16_f32 v53, v74, v53
	v_cvt_pk_bf16_f32 v54, v72, v73
	v_cvt_pk_bf16_f32 v55, v58, v59
	global_store_dwordx4 v[56:57], v[52:55], off
	v_pk_mul_f32 v[58:59], v[66:67], v[96:97] op_sel_hi:[1,0]
	s_and_b64 vcc, exec, s[42:43]
	v_pk_mul_f32 v[52:53], v[70:71], v[96:97] op_sel_hi:[1,0]
	v_pk_mul_f32 v[54:55], v[68:69], v[96:97] op_sel_hi:[1,0]
	s_nop 0
	s_nop 0
	s_nop 0
	s_nop 0
	s_nop 0
	s_nop 0
	s_nop 0
	s_nop 0
	s_waitcnt lgkmcnt(0)
	s_nop 0
	s_nop 1
	v_permlane16_swap_b32_e32 v54, v64
	s_waitcnt lgkmcnt(0)
	s_nop 0
	s_nop 1
	v_permlane16_swap_b32_e32 v55, v65
	s_waitcnt lgkmcnt(0)
	s_nop 0
	v_mov_b32_e32 v66, v52
	s_nop 1
	v_permlane16_swap_b32_e32 v66, v58
	s_waitcnt lgkmcnt(0)
	s_nop 0
	s_nop 1
	v_permlane16_swap_b32_e32 v53, v59
	v_cvt_pk_bf16_f32 v52, v54, v55
	v_cvt_pk_bf16_f32 v53, v66, v53
	v_cvt_pk_bf16_f32 v54, v64, v65
	v_cvt_pk_bf16_f32 v55, v58, v59
	v_or_b32_e32 v65, 64, v145
	v_mov_b32_e32 v64, 1.0
	v_mov_b32_e32 v66, 1.0
	global_store_dwordx4 v[56:57], v[52:55], off offset:64
	s_cbranch_vccnz .LBB0_464
	s_nop 0
	v_add_u32_e32 v52, v144, v65
	v_ashrrev_i32_e32 v53, 31, v52
	v_lshl_add_u64 v[52:53], v[52:53], 4, s[2:3]
	global_load_dwordx4 v[52:55], v[52:53], off
	s_waitcnt vmcnt(0)
	v_add_f32_e32 v52, v52, v53
	v_add_f32_e32 v52, v52, v54
	v_add_f32_e32 v52, v52, v55
	v_fmamk_f32 v52, v52, 0x3b800000, v252
	v_mul_f32_e32 v53, 0x4b800000, v52
	v_cmp_gt_f32_e32 vcc, s25, v52
	s_nop 1
	v_cndmask_b32_e32 v52, v52, v53, vcc
	v_rsq_f32_e32 v52, v52
	s_nop 0
	v_mul_f32_e32 v53, 0x45800000, v52
	v_cndmask_b32_e32 v66, v52, v53, vcc
.LBB0_464:
	s_nop 0
	v_add_u32_e32 v52, v128, v65
	v_mad_i64_i32 v[56:57], s[0:1], v52, s18, v[130:131]
	v_pk_mul_f32 v[52:53], v[62:63], v[66:67] op_sel_hi:[1,0]
	v_pk_mul_f32 v[54:55], v[60:61], v[66:67] op_sel_hi:[1,0]
	v_pk_mul_f32 v[58:59], v[158:159], v[66:67] op_sel_hi:[1,0]
	v_pk_mul_f32 v[60:61], v[156:157], v[66:67] op_sel_hi:[1,0]
	s_nop 0
	s_nop 0
	s_nop 0
	v_cndmask_b32_e64 v67, v53, v59, s[40:41]
	s_nop 0
	s_nop 0
	s_nop 0
	ds_bpermute_b32 v67, v129, v67
	s_and_b64 vcc, exec, s[42:43]
	s_waitcnt lgkmcnt(1)
	s_nop 0
	s_nop 1
	v_permlane16_swap_b32_e32 v54, v60
	s_waitcnt lgkmcnt(1)
	s_nop 0
	s_nop 1
	v_permlane16_swap_b32_e32 v55, v61
	s_waitcnt lgkmcnt(1)
	s_nop 0
	v_mov_b32_e32 v62, v52
	s_nop 1
	v_permlane16_swap_b32_e32 v62, v58
	s_waitcnt lgkmcnt(0)
	v_cndmask_b32_e64 v53, v67, v53, s[40:41]
	v_cndmask_b32_e64 v59, v59, v67, s[40:41]
	v_cvt_pk_bf16_f32 v52, v54, v55
	v_cvt_pk_bf16_f32 v53, v62, v53
	v_cvt_pk_bf16_f32 v54, v60, v61
	v_cvt_pk_bf16_f32 v55, v58, v59
	global_store_dwordx4 v[56:57], v[52:55], off
	v_pk_mul_f32 v[50:51], v[50:51], v[66:67] op_sel_hi:[1,0]
	v_pk_mul_f32 v[48:49], v[48:49], v[66:67] op_sel_hi:[1,0]
	v_pk_mul_f32 v[52:53], v[154:155], v[66:67] op_sel_hi:[1,0]
	v_pk_mul_f32 v[54:55], v[152:153], v[66:67] op_sel_hi:[1,0]
	s_nop 0
	s_nop 0
	s_nop 0
	s_nop 0
	s_nop 0
	s_nop 0
	s_nop 0
	s_nop 0
	s_waitcnt lgkmcnt(0)
	s_nop 0
	v_mov_b32_e32 v58, v48
	s_nop 1
	v_permlane16_swap_b32_e32 v54, v58
	s_waitcnt lgkmcnt(0)
	s_nop 0
	v_mov_b32_e32 v48, v55
	v_mov_b32_e32 v55, v49
	s_nop 1
	v_permlane16_swap_b32_e32 v48, v55
	s_waitcnt lgkmcnt(0)
	s_nop 0
	v_mov_b32_e32 v49, v52
	v_mov_b32_e32 v52, v50
	s_nop 1
	v_permlane16_swap_b32_e32 v49, v52
	s_waitcnt lgkmcnt(0)
	s_nop 0
	v_mov_b32_e32 v50, v53
	s_nop 1
	v_permlane16_swap_b32_e32 v50, v51
	v_cvt_pk_bf16_f32 v48, v54, v48
	v_cvt_pk_bf16_f32 v49, v49, v50
	v_cvt_pk_bf16_f32 v50, v58, v55
	v_cvt_pk_bf16_f32 v51, v52, v51
	global_store_dwordx4 v[56:57], v[48:51], off offset:64
	s_nop 1
	v_or_b32_e32 v48, 0x50, v145
	s_cbranch_vccnz .LBB0_466
	v_add_u32_e32 v50, v144, v48
	v_ashrrev_i32_e32 v51, 31, v50
	v_lshl_add_u64 v[50:51], v[50:51], 4, s[2:3]
	global_load_dwordx4 v[50:53], v[50:51], off
	s_waitcnt vmcnt(0)
	v_add_f32_e32 v49, v50, v51
	v_add_f32_e32 v49, v49, v52
	v_add_f32_e32 v49, v49, v53
	v_fmamk_f32 v49, v49, 0x3b800000, v252
	v_mul_f32_e32 v50, 0x4b800000, v49
	v_cmp_gt_f32_e32 vcc, s25, v49
	s_nop 1
	v_cndmask_b32_e32 v49, v49, v50, vcc
	v_rsq_f32_e32 v49, v49
	s_nop 0
	v_mul_f32_e32 v50, 0x45800000, v49
	v_cndmask_b32_e32 v64, v49, v50, vcc
.LBB0_466:
	v_pk_mul_f32 v[46:47], v[46:47], v[64:65] op_sel_hi:[1,0]
	v_pk_mul_f32 v[44:45], v[44:45], v[64:65] op_sel_hi:[1,0]
	v_pk_mul_f32 v[42:43], v[42:43], v[64:65] op_sel_hi:[1,0]
	v_pk_mul_f32 v[40:41], v[40:41], v[64:65] op_sel_hi:[1,0]
	s_nop 0
	s_nop 0
	s_nop 0
	s_nop 0
	s_nop 0
	s_nop 0
	s_nop 0
	s_nop 0
	v_add_u32_e32 v48, v128, v48
	s_waitcnt lgkmcnt(0)
	s_nop 0
	v_mov_b32_e32 v50, v40
	s_nop 1
	v_permlane16_swap_b32_e32 v44, v50
	s_waitcnt lgkmcnt(0)
	s_nop 0
	v_mov_b32_e32 v40, v45
	v_mov_b32_e32 v45, v41
	s_nop 1
	v_permlane16_swap_b32_e32 v40, v45
	s_waitcnt lgkmcnt(0)
	s_nop 0
	v_mov_b32_e32 v41, v46
	v_mov_b32_e32 v46, v42
	s_nop 1
	v_permlane16_swap_b32_e32 v41, v46
	s_waitcnt lgkmcnt(0)
	s_nop 0
	v_mov_b32_e32 v42, v47
	s_nop 1
	v_permlane16_swap_b32_e32 v42, v43
	v_mad_i64_i32 v[48:49], s[0:1], v48, s18, v[130:131]
	v_cvt_pk_bf16_f32 v40, v44, v40
	v_cvt_pk_bf16_f32 v41, v41, v42
	v_cvt_pk_bf16_f32 v42, v50, v45
	v_cvt_pk_bf16_f32 v43, v46, v43
	v_pk_mul_f32 v[38:39], v[38:39], v[64:65] op_sel_hi:[1,0]
	v_pk_mul_f32 v[36:37], v[36:37], v[64:65] op_sel_hi:[1,0]
	v_pk_mul_f32 v[34:35], v[34:35], v[64:65] op_sel_hi:[1,0]
	v_pk_mul_f32 v[32:33], v[32:33], v[64:65] op_sel_hi:[1,0]
	global_store_dwordx4 v[48:49], v[40:43], off
	s_and_b64 vcc, exec, s[42:43]
	s_nop 0
	s_nop 0
	s_nop 0
	s_nop 0
	s_nop 0
	s_nop 0
	s_nop 0
	s_nop 0
	s_nop 0
	s_waitcnt lgkmcnt(0)
	s_nop 0
	v_mov_b32_e32 v40, v32
	s_nop 1
	v_permlane16_swap_b32_e32 v36, v40
	s_waitcnt lgkmcnt(0)
	s_nop 0
	v_mov_b32_e32 v32, v37
	v_mov_b32_e32 v37, v33
	s_nop 1
	v_permlane16_swap_b32_e32 v32, v37
	s_waitcnt lgkmcnt(0)
	s_nop 0
	v_mov_b32_e32 v33, v38
	v_mov_b32_e32 v38, v34
	s_nop 1
	v_permlane16_swap_b32_e32 v33, v38
	s_waitcnt lgkmcnt(0)
	s_nop 0
	v_mov_b32_e32 v34, v39
	s_nop 1
	v_permlane16_swap_b32_e32 v34, v35
	v_cvt_pk_bf16_f32 v32, v36, v32
	v_cvt_pk_bf16_f32 v33, v33, v34
	v_cvt_pk_bf16_f32 v34, v40, v37
	v_cvt_pk_bf16_f32 v35, v38, v35
	global_store_dwordx4 v[48:49], v[32:35], off offset:64
	s_nop 1
	v_or_b32_e32 v33, 0x60, v145
	v_mov_b32_e32 v32, 1.0
	v_mov_b32_e32 v34, 1.0
	s_cbranch_vccnz .LBB0_468
	v_add_u32_e32 v34, v144, v33
	v_ashrrev_i32_e32 v35, 31, v34
	v_lshl_add_u64 v[34:35], v[34:35], 4, s[2:3]
	global_load_dwordx4 v[34:37], v[34:35], off
	s_waitcnt vmcnt(0)
	v_add_f32_e32 v34, v34, v35
	v_add_f32_e32 v34, v34, v36
	v_add_f32_e32 v34, v34, v37
	v_fmamk_f32 v34, v34, 0x3b800000, v252
	v_mul_f32_e32 v35, 0x4b800000, v34
	v_cmp_gt_f32_e32 vcc, s25, v34
	s_nop 1
	v_cndmask_b32_e32 v34, v34, v35, vcc
	v_rsq_f32_e32 v34, v34
	s_nop 0
	v_mul_f32_e32 v35, 0x45800000, v34
	v_cndmask_b32_e32 v34, v34, v35, vcc
.LBB0_468:
	v_add_u32_e32 v33, v128, v33
	v_pk_mul_f32 v[30:31], v[30:31], v[34:35] op_sel_hi:[1,0]
	v_pk_mul_f32 v[28:29], v[28:29], v[34:35] op_sel_hi:[1,0]
	v_pk_mul_f32 v[26:27], v[26:27], v[34:35] op_sel_hi:[1,0]
	v_pk_mul_f32 v[24:25], v[24:25], v[34:35] op_sel_hi:[1,0]
	v_mad_i64_i32 v[36:37], s[0:1], v33, s18, v[130:131]
	s_nop 0
	v_cndmask_b32_e64 v35, v29, v25, s[40:41]
	s_nop 0
	s_nop 0
	s_nop 0
	ds_bpermute_b32 v35, v129, v35
	s_nop 0
	s_nop 0
	s_and_b64 vcc, exec, s[42:43]
	s_waitcnt lgkmcnt(1)
	s_nop 0
	v_mov_b32_e32 v33, v24
	s_nop 1
	v_permlane16_swap_b32_e32 v28, v33
	s_waitcnt lgkmcnt(0)
	v_cndmask_b32_e64 v24, v35, v29, s[40:41]
	v_cndmask_b32_e64 v29, v25, v35, s[40:41]
	s_waitcnt lgkmcnt(0)
	s_nop 0
	v_mov_b32_e32 v25, v30
	v_mov_b32_e32 v30, v26
	s_nop 1
	v_permlane16_swap_b32_e32 v25, v30
	s_waitcnt lgkmcnt(0)
	s_nop 0
	v_mov_b32_e32 v26, v31
	s_nop 1
	v_permlane16_swap_b32_e32 v26, v27
	v_cvt_pk_bf16_f32 v24, v28, v24
	v_cvt_pk_bf16_f32 v25, v25, v26
	v_cvt_pk_bf16_f32 v26, v33, v29
	v_cvt_pk_bf16_f32 v27, v30, v27
	v_pk_mul_f32 v[22:23], v[22:23], v[34:35] op_sel_hi:[1,0]
	v_pk_mul_f32 v[20:21], v[20:21], v[34:35] op_sel_hi:[1,0]
	v_pk_mul_f32 v[18:19], v[18:19], v[34:35] op_sel_hi:[1,0]
	v_pk_mul_f32 v[16:17], v[16:17], v[34:35] op_sel_hi:[1,0]
	global_store_dwordx4 v[36:37], v[24:27], off
	s_nop 1
	s_nop 0
	s_nop 0
	s_nop 0
	s_nop 0
	s_nop 0
	s_nop 0
	s_nop 0
	s_nop 0
	s_waitcnt lgkmcnt(0)
	s_nop 0
	v_mov_b32_e32 v24, v16
	s_nop 1
	v_permlane16_swap_b32_e32 v20, v24
	s_waitcnt lgkmcnt(0)
	s_nop 0
	v_mov_b32_e32 v16, v21
	v_mov_b32_e32 v21, v17
	s_nop 1
	v_permlane16_swap_b32_e32 v16, v21
	s_waitcnt lgkmcnt(0)
	s_nop 0
	v_mov_b32_e32 v17, v22
	v_mov_b32_e32 v22, v18
	s_nop 1
	v_permlane16_swap_b32_e32 v17, v22
	s_waitcnt lgkmcnt(0)
	s_nop 0
	v_mov_b32_e32 v18, v23
	s_nop 1
	v_permlane16_swap_b32_e32 v18, v19
	v_cvt_pk_bf16_f32 v16, v20, v16
	v_cvt_pk_bf16_f32 v17, v17, v18
	v_cvt_pk_bf16_f32 v18, v24, v21
	v_cvt_pk_bf16_f32 v19, v22, v19
	global_store_dwordx4 v[36:37], v[16:19], off offset:64
	s_nop 1
	v_or_b32_e32 v16, 0x70, v145
	s_cbranch_vccnz .LBB0_390
	v_add_u32_e32 v18, v144, v16
	v_ashrrev_i32_e32 v19, 31, v18
	v_lshl_add_u64 v[18:19], v[18:19], 4, s[2:3]
	global_load_dwordx4 v[18:21], v[18:19], off
	s_waitcnt vmcnt(0)
	v_add_f32_e32 v17, v18, v19
	v_add_f32_e32 v17, v17, v20
	v_add_f32_e32 v17, v17, v21
	v_fmamk_f32 v17, v17, 0x3b800000, v252
	v_mul_f32_e32 v18, 0x4b800000, v17
	v_cmp_gt_f32_e32 vcc, s25, v17
	s_nop 1
	v_cndmask_b32_e32 v17, v17, v18, vcc
	v_rsq_f32_e32 v17, v17
	s_nop 0
	v_mul_f32_e32 v18, 0x45800000, v17
	v_cndmask_b32_e32 v32, v17, v18, vcc
	s_branch .LBB0_390

.LBB0_484:
	s_or_b64 exec, exec, s[30:31]
	s_nop 0
	s_nop 0
	s_nop 0
	s_nop 0
	s_nop 0
	s_nop 0
	s_nop 0
	s_nop 0
	v_mov_b64_e32 v[20:21], s[4:5]
	s_movk_i32 s42, 0x300
	v_mad_i64_i32 v[20:21], s[30:31], v16, s42, v[20:21]
	v_lshlrev_b64 v[22:23], 1, v[134:135]
	v_lshl_add_u64 v[20:21], v[20:21], 0, v[22:23]
	s_waitcnt lgkmcnt(0)
	s_nop 0
	v_mov_b32_e32 v17, v8
	s_nop 1
	v_permlane16_swap_b32_e32 v12, v17
	s_waitcnt lgkmcnt(0)
	s_nop 0
	v_mov_b32_e32 v8, v13
	v_mov_b32_e32 v13, v9
	s_nop 1
	v_permlane16_swap_b32_e32 v8, v13
	s_waitcnt lgkmcnt(0)
	s_nop 0
	v_mov_b32_e32 v9, v14
	v_mov_b32_e32 v14, v10
	s_nop 1
	v_permlane16_swap_b32_e32 v9, v14
	s_waitcnt lgkmcnt(0)
	s_nop 0
	v_mov_b32_e32 v10, v15
	s_nop 1
	v_permlane16_swap_b32_e32 v10, v11
	v_lshlrev_b32_e32 v176, 1, v180
	v_cvt_pk_bf16_f32 v8, v12, v8
	v_cvt_pk_bf16_f32 v9, v9, v10
	v_cvt_pk_bf16_f32 v10, v17, v13
	v_cvt_pk_bf16_f32 v11, v14, v11
	v_lshl_add_u64 v[12:13], v[20:21], 0, v[176:177]
	v_lshlrev_b32_e32 v14, 1, v179
	v_mov_b32_e32 v15, v177
	v_lshl_add_u64 v[12:13], v[12:13], 0, v[14:15]
	global_store_dwordx4 v[12:13], v[8:11], off
	s_nop 0
	v_cndmask_b32_e64 v13, v7, v3, s[40:41]
	s_nop 0
	s_nop 0
	s_nop 0
	s_nop 0
	s_nop 0
	ds_bpermute_b32 v13, v18, v13
	v_mov_b64_e32 v[8:9], s[34:35]
	v_mad_i64_i32 v[8:9], s[30:31], v16, s42, v[8:9]
	v_lshl_add_u64 v[8:9], v[8:9], 0, v[22:23]
	s_waitcnt lgkmcnt(1)
	s_nop 0
	v_mov_b32_e32 v10, v0
	s_nop 1
	v_permlane16_swap_b32_e32 v4, v10
	s_waitcnt lgkmcnt(1)
	s_nop 0
	v_mov_b32_e32 v0, v5
	v_mov_b32_e32 v5, v1
	s_nop 1
	v_permlane16_swap_b32_e32 v0, v5
	s_waitcnt lgkmcnt(1)
	s_nop 0
	v_mov_b32_e32 v1, v6
	v_mov_b32_e32 v6, v2
	s_nop 1
	v_permlane16_swap_b32_e32 v1, v6
	s_waitcnt lgkmcnt(0)
	v_cndmask_b32_e64 v2, v13, v7, s[40:41]
	v_cvt_pk_bf16_f32 v0, v4, v0
	v_cvt_pk_bf16_f32 v1, v1, v2
	v_cvt_pk_bf16_f32 v2, v10, v5
	v_lshl_add_u64 v[4:5], v[8:9], 0, v[176:177]
	v_lshl_add_u64 v[4:5], v[4:5], 0, v[14:15]
	v_cndmask_b32_e64 v3, v3, v13, s[40:41]
	v_add_co_u32_e32 v4, vcc, 0xa700000, v4
	v_cvt_pk_bf16_f32 v3, v6, v3
	s_nop 0
	v_addc_co_u32_e32 v5, vcc, 0, v5, vcc
	global_store_dwordx4 v[4:5], v[0:3], off offset:64

.LBB0_487:
	s_waitcnt lgkmcnt(0)
	s_barrier
	ds_read_b128 v[224:227], v184
	ds_read_b128 v[228:231], v184 offset:1024
	ds_read_b128 v[232:235], v184 offset:2048
	ds_read_b128 v[236:239], v184 offset:3072
	ds_read_b128 v[190:193], v185
	ds_read_b128 v[194:197], v185 offset:1024
	ds_read_b128 v[198:201], v185 offset:2048
	ds_read_b128 v[204:207], v185 offset:3072
	ds_read_b128 v[208:211], v185 offset:4096
	ds_read_b128 v[212:215], v185 offset:5120
	ds_read_b128 v[216:219], v185 offset:6144
	ds_read_b128 v[220:223], v185 offset:7168
	s_movk_i32 vcc_lo, 0x6000
	s_cmp_eq_u32 m0, 2
	s_cselect_b32 vcc_lo, 0xffff4000, vcc_lo
	s_add_u32 m0, m0, 1
	s_cmp_eq_u32 m0, 3
	s_cselect_b32 m0, 0, m0
	v_add_u32_e32 v185, vcc_lo, v185
	v_add_u32_e32 v184, vcc_lo, v184
	v_xor_b32_e32 v185, 64, v185
	v_xor_b32_e32 v184, 64, v184
	s_waitcnt lgkmcnt(7)
	v_mfma_f32_16x16x32_bf16 v[172:175], v[224:227], v[190:193], v[172:175]
	v_mfma_f32_16x16x32_bf16 v[168:171], v[228:231], v[190:193], v[168:171]
	v_mfma_f32_16x16x32_bf16 v[164:167], v[232:235], v[190:193], v[164:167]
	v_mfma_f32_16x16x32_bf16 v[156:159], v[236:239], v[190:193], v[156:159]
	ds_read_b128 v[190:193], v185
	s_waitcnt lgkmcnt(7)
	v_mfma_f32_16x16x32_bf16 v[144:147], v[224:227], v[194:197], v[144:147]
	v_mfma_f32_16x16x32_bf16 v[136:139], v[228:231], v[194:197], v[136:139]
	v_mfma_f32_16x16x32_bf16 v[132:135], v[232:235], v[194:197], v[132:135]
	v_mfma_f32_16x16x32_bf16 v[120:123], v[236:239], v[194:197], v[120:123]
	ds_read_b128 v[194:197], v185 offset:1024
	s_waitcnt lgkmcnt(7)
	v_mfma_f32_16x16x32_bf16 v[112:115], v[224:227], v[198:201], v[112:115]
	v_mfma_f32_16x16x32_bf16 v[108:111], v[228:231], v[198:201], v[108:111]
	v_mfma_f32_16x16x32_bf16 v[96:99], v[232:235], v[198:201], v[96:99]
	v_mfma_f32_16x16x32_bf16 v[92:95], v[236:239], v[198:201], v[92:95]
	ds_read_b128 v[198:201], v185 offset:2048
	s_waitcnt lgkmcnt(7)
	v_mfma_f32_16x16x32_bf16 v[88:91], v[224:227], v[204:207], v[88:91]
	v_mfma_f32_16x16x32_bf16 v[80:83], v[228:231], v[204:207], v[80:83]
	v_mfma_f32_16x16x32_bf16 v[72:75], v[232:235], v[204:207], v[72:75]
	v_mfma_f32_16x16x32_bf16 v[68:71], v[236:239], v[204:207], v[68:71]
	ds_read_b128 v[204:207], v185 offset:3072
	s_waitcnt lgkmcnt(7)
	v_mfma_f32_16x16x32_bf16 v[60:63], v[224:227], v[208:211], v[60:63]
	v_mfma_f32_16x16x32_bf16 v[52:55], v[228:231], v[208:211], v[52:55]
	v_mfma_f32_16x16x32_bf16 v[48:51], v[232:235], v[208:211], v[48:51]
	v_mfma_f32_16x16x32_bf16 v[44:47], v[236:239], v[208:211], v[44:47]
	ds_read_b128 v[208:211], v185 offset:4096
	s_waitcnt lgkmcnt(7)
	v_mfma_f32_16x16x32_bf16 v[40:43], v[224:227], v[212:215], v[40:43]
	v_mfma_f32_16x16x32_bf16 v[36:39], v[228:231], v[212:215], v[36:39]
	v_mfma_f32_16x16x32_bf16 v[32:35], v[232:235], v[212:215], v[32:35]
	v_mfma_f32_16x16x32_bf16 v[28:31], v[236:239], v[212:215], v[28:31]
	ds_read_b128 v[212:215], v185 offset:5120
	s_waitcnt lgkmcnt(7)
	v_mfma_f32_16x16x32_bf16 v[24:27], v[224:227], v[216:219], v[24:27]
	v_mfma_f32_16x16x32_bf16 v[20:23], v[228:231], v[216:219], v[20:23]
	v_mfma_f32_16x16x32_bf16 v[16:19], v[232:235], v[216:219], v[16:19]
	v_mfma_f32_16x16x32_bf16 v[12:15], v[236:239], v[216:219], v[12:15]
	ds_read_b128 v[216:219], v185 offset:6144
	s_waitcnt lgkmcnt(7)
	v_mfma_f32_16x16x32_bf16 v[8:11], v[224:227], v[220:223], v[8:11]
	v_mfma_f32_16x16x32_bf16 v[4:7], v[228:231], v[220:223], v[4:7]
	v_mfma_f32_16x16x32_bf16 v[0:3], v[232:235], v[220:223], v[0:3]
	v_mfma_f32_16x16x32_bf16 v[116:119], v[236:239], v[220:223], v[116:119]
	ds_read_b128 v[220:223], v185 offset:7168
	ds_read_b128 v[224:227], v184
	ds_read_b128 v[228:231], v184 offset:1024
	ds_read_b128 v[232:235], v184 offset:2048
	ds_read_b128 v[236:239], v184 offset:3072
	s_movk_i32 vcc_lo, 0x6000
	s_cmp_eq_u32 m0, 2
	s_cselect_b32 vcc_lo, 0xffff4000, vcc_lo
	s_add_u32 m0, m0, 1
	s_cmp_eq_u32 m0, 3
	s_cselect_b32 m0, 0, m0
	v_add_u32_e32 v185, vcc_lo, v185
	v_add_u32_e32 v184, vcc_lo, v184
	v_xor_b32_e32 v185, 64, v185
	v_xor_b32_e32 v184, 64, v184
	s_sub_u32 vcc_lo, s30, s98
	v_add_u32_e32 v186, vcc_lo, v178
	v_add_u32_e32 v187, vcc_lo, v180
	s_barrier
	s_waitcnt lgkmcnt(0)
	v_mfma_f32_16x16x32_bf16 v[172:175], v[224:227], v[190:193], v[172:175]
	s_waitcnt vmcnt(11)
	v_mfma_f32_16x16x32_bf16 v[168:171], v[228:231], v[190:193], v[168:171]
	ds_write_b128 v183, v[160:163]
	v_add_u32_e32 v160, s26, v186
	v_mfma_f32_16x16x32_bf16 v[164:167], v[232:235], v[190:193], v[164:167]
	global_load_dwordx4 v[160:163], v160, s[98:99] offset:128
	v_mfma_f32_16x16x32_bf16 v[156:159], v[236:239], v[190:193], v[156:159]
	s_waitcnt vmcnt(11)
	ds_write_b128 v183, v[152:155] offset:2048
	v_mfma_f32_16x16x32_bf16 v[144:147], v[224:227], v[194:197], v[144:147]
	v_add_u32_e32 v152, s27, v186
	v_mfma_f32_16x16x32_bf16 v[136:139], v[228:231], v[194:197], v[136:139]
	global_load_dwordx4 v[152:155], v152, s[98:99] offset:128
	s_waitcnt vmcnt(11)
	v_mfma_f32_16x16x32_bf16 v[132:135], v[232:235], v[194:197], v[132:135]
	ds_write_b128 v183, v[148:151] offset:4096
	v_mfma_f32_16x16x32_bf16 v[120:123], v[236:239], v[194:197], v[120:123]
	v_add_u32_e32 v148, s20, v186
	global_load_dwordx4 v[148:151], v148, s[98:99] offset:128
	v_mfma_f32_16x16x32_bf16 v[112:115], v[224:227], v[198:201], v[112:115]
	s_waitcnt vmcnt(11)
	v_mfma_f32_16x16x32_bf16 v[108:111], v[228:231], v[198:201], v[108:111]
	ds_write_b128 v183, v[128:131] offset:6144
	v_add_u32_e32 v128, s21, v186
	v_mfma_f32_16x16x32_bf16 v[96:99], v[232:235], v[198:201], v[96:99]
	global_load_dwordx4 v[128:131], v128, s[98:99] offset:128
	v_mfma_f32_16x16x32_bf16 v[92:95], v[236:239], v[198:201], v[92:95]
	s_waitcnt vmcnt(11)
	ds_write_b128 v183, v[124:127] offset:8192
	v_mfma_f32_16x16x32_bf16 v[88:91], v[224:227], v[204:207], v[88:91]
	v_add_u32_e32 v124, s56, v186
	v_mfma_f32_16x16x32_bf16 v[80:83], v[228:231], v[204:207], v[80:83]
	global_load_dwordx4 v[124:127], v124, s[98:99] offset:128
	s_waitcnt vmcnt(11)
	v_mfma_f32_16x16x32_bf16 v[72:75], v[232:235], v[204:207], v[72:75]
	ds_write_b128 v183, v[104:107] offset:10240
	v_mfma_f32_16x16x32_bf16 v[68:71], v[236:239], v[204:207], v[68:71]
	v_add_u32_e32 v104, s57, v186
	global_load_dwordx4 v[104:107], v104, s[98:99] offset:128
	v_mfma_f32_16x16x32_bf16 v[60:63], v[224:227], v[208:211], v[60:63]
	s_waitcnt vmcnt(11)
	v_mfma_f32_16x16x32_bf16 v[52:55], v[228:231], v[208:211], v[52:55]
	ds_write_b128 v183, v[100:103] offset:12288
	v_add_u32_e32 v100, s24, v186
	v_mfma_f32_16x16x32_bf16 v[48:51], v[232:235], v[208:211], v[48:51]
	global_load_dwordx4 v[100:103], v100, s[98:99] offset:128
	v_mfma_f32_16x16x32_bf16 v[44:47], v[236:239], v[208:211], v[44:47]
	s_waitcnt vmcnt(11)
	ds_write_b128 v183, v[84:87] offset:14336
	v_mfma_f32_16x16x32_bf16 v[40:43], v[224:227], v[212:215], v[40:43]
	v_add_u32_e32 v84, s96, v186
	v_mfma_f32_16x16x32_bf16 v[36:39], v[228:231], v[212:215], v[36:39]
	global_load_dwordx4 v[84:87], v84, s[98:99] offset:128
	s_waitcnt vmcnt(11)
	v_mfma_f32_16x16x32_bf16 v[32:35], v[232:235], v[212:215], v[32:35]
	ds_write_b128 v183, v[140:143] offset:16384
	v_mfma_f32_16x16x32_bf16 v[28:31], v[236:239], v[212:215], v[28:31]
	v_add_u32_e32 v140, 0x1800000, v187
	global_load_dwordx4 v[140:143], v140, s[98:99] offset:128
	v_mfma_f32_16x16x32_bf16 v[24:27], v[224:227], v[216:219], v[24:27]
	s_waitcnt vmcnt(11)
	v_mfma_f32_16x16x32_bf16 v[20:23], v[228:231], v[216:219], v[20:23]
	ds_write_b128 v183, v[76:79] offset:18432
	v_add_u32_e32 v76, 0x1810000, v187
	v_mfma_f32_16x16x32_bf16 v[16:19], v[232:235], v[216:219], v[16:19]
	global_load_dwordx4 v[76:79], v76, s[98:99] offset:128
	v_mfma_f32_16x16x32_bf16 v[12:15], v[236:239], v[216:219], v[12:15]
	s_waitcnt vmcnt(11)
	ds_write_b128 v183, v[64:67] offset:20480
	v_mfma_f32_16x16x32_bf16 v[8:11], v[224:227], v[220:223], v[8:11]
	v_add_u32_e32 v64, 0x1820000, v187
	v_mfma_f32_16x16x32_bf16 v[4:7], v[228:231], v[220:223], v[4:7]
	global_load_dwordx4 v[64:67], v64, s[98:99] offset:128
	s_waitcnt vmcnt(11)
	v_mfma_f32_16x16x32_bf16 v[0:3], v[232:235], v[220:223], v[0:3]
	ds_write_b128 v183, v[56:59] offset:22528
	v_mfma_f32_16x16x32_bf16 v[116:119], v[236:239], v[220:223], v[116:119]
	v_add_u32_e32 v56, 0x1830000, v187
	global_load_dwordx4 v[56:59], v56, s[98:99] offset:128
	v_cmp_gt_u32_e32 vcc, 0x6000, v183
	v_add_u32_e32 v182, 0xc000, v183
	v_add_u32_e32 v183, 0xffffa000, v183
	s_nop 0
	v_cndmask_b32_e32 v183, v183, v182, vcc
	s_add_u32 s30, s30, 0x80
	s_addc_u32 s31, s31, 0
	s_cmpk_lg_i32 s30, 0x780
	s_cbranch_scc1 .LBB0_487
	s_waitcnt lgkmcnt(0)
	s_barrier
	ds_read_b128 v[224:227], v184
	ds_read_b128 v[228:231], v184 offset:1024
	ds_read_b128 v[232:235], v184 offset:2048
	ds_read_b128 v[236:239], v184 offset:3072
	ds_read_b128 v[190:193], v185
	ds_read_b128 v[194:197], v185 offset:1024
	ds_read_b128 v[198:201], v185 offset:2048
	ds_read_b128 v[204:207], v185 offset:3072
	ds_read_b128 v[208:211], v185 offset:4096
	ds_read_b128 v[212:215], v185 offset:5120
	ds_read_b128 v[216:219], v185 offset:6144
	ds_read_b128 v[220:223], v185 offset:7168
	s_movk_i32 vcc_lo, 0x6000
	s_cmp_eq_u32 m0, 2
	s_cselect_b32 vcc_lo, 0xffff4000, vcc_lo
	s_add_u32 m0, m0, 1
	s_cmp_eq_u32 m0, 3
	s_cselect_b32 m0, 0, m0
	v_add_u32_e32 v185, vcc_lo, v185
	v_add_u32_e32 v184, vcc_lo, v184
	v_xor_b32_e32 v185, 64, v185
	v_xor_b32_e32 v184, 64, v184
	s_waitcnt lgkmcnt(7)
	v_mfma_f32_16x16x32_bf16 v[172:175], v[224:227], v[190:193], v[172:175]
	v_mfma_f32_16x16x32_bf16 v[168:171], v[228:231], v[190:193], v[168:171]
	v_mfma_f32_16x16x32_bf16 v[164:167], v[232:235], v[190:193], v[164:167]
	v_mfma_f32_16x16x32_bf16 v[156:159], v[236:239], v[190:193], v[156:159]
	ds_read_b128 v[190:193], v185
	s_waitcnt lgkmcnt(7)
	v_mfma_f32_16x16x32_bf16 v[144:147], v[224:227], v[194:197], v[144:147]
	v_mfma_f32_16x16x32_bf16 v[136:139], v[228:231], v[194:197], v[136:139]
	v_mfma_f32_16x16x32_bf16 v[132:135], v[232:235], v[194:197], v[132:135]
	v_mfma_f32_16x16x32_bf16 v[120:123], v[236:239], v[194:197], v[120:123]
	ds_read_b128 v[194:197], v185 offset:1024
	s_waitcnt lgkmcnt(7)
	v_mfma_f32_16x16x32_bf16 v[112:115], v[224:227], v[198:201], v[112:115]
	v_mfma_f32_16x16x32_bf16 v[108:111], v[228:231], v[198:201], v[108:111]
	v_mfma_f32_16x16x32_bf16 v[96:99], v[232:235], v[198:201], v[96:99]
	v_mfma_f32_16x16x32_bf16 v[92:95], v[236:239], v[198:201], v[92:95]
	ds_read_b128 v[198:201], v185 offset:2048
	s_waitcnt lgkmcnt(7)
	v_mfma_f32_16x16x32_bf16 v[88:91], v[224:227], v[204:207], v[88:91]
	v_mfma_f32_16x16x32_bf16 v[80:83], v[228:231], v[204:207], v[80:83]
	v_mfma_f32_16x16x32_bf16 v[72:75], v[232:235], v[204:207], v[72:75]
	v_mfma_f32_16x16x32_bf16 v[68:71], v[236:239], v[204:207], v[68:71]
	ds_read_b128 v[204:207], v185 offset:3072
	s_waitcnt lgkmcnt(7)
	v_mfma_f32_16x16x32_bf16 v[60:63], v[224:227], v[208:211], v[60:63]
	v_mfma_f32_16x16x32_bf16 v[52:55], v[228:231], v[208:211], v[52:55]
	v_mfma_f32_16x16x32_bf16 v[48:51], v[232:235], v[208:211], v[48:51]
	v_mfma_f32_16x16x32_bf16 v[44:47], v[236:239], v[208:211], v[44:47]
	ds_read_b128 v[208:211], v185 offset:4096
	s_waitcnt lgkmcnt(7)
	v_mfma_f32_16x16x32_bf16 v[40:43], v[224:227], v[212:215], v[40:43]
	v_mfma_f32_16x16x32_bf16 v[36:39], v[228:231], v[212:215], v[36:39]
	v_mfma_f32_16x16x32_bf16 v[32:35], v[232:235], v[212:215], v[32:35]
	v_mfma_f32_16x16x32_bf16 v[28:31], v[236:239], v[212:215], v[28:31]
	ds_read_b128 v[212:215], v185 offset:5120
	s_waitcnt lgkmcnt(7)
	v_mfma_f32_16x16x32_bf16 v[24:27], v[224:227], v[216:219], v[24:27]
	v_mfma_f32_16x16x32_bf16 v[20:23], v[228:231], v[216:219], v[20:23]
	v_mfma_f32_16x16x32_bf16 v[16:19], v[232:235], v[216:219], v[16:19]
	v_mfma_f32_16x16x32_bf16 v[12:15], v[236:239], v[216:219], v[12:15]
	ds_read_b128 v[216:219], v185 offset:6144
	s_waitcnt lgkmcnt(7)
	v_mfma_f32_16x16x32_bf16 v[8:11], v[224:227], v[220:223], v[8:11]
	v_mfma_f32_16x16x32_bf16 v[4:7], v[228:231], v[220:223], v[4:7]
	v_mfma_f32_16x16x32_bf16 v[0:3], v[232:235], v[220:223], v[0:3]
	v_mfma_f32_16x16x32_bf16 v[116:119], v[236:239], v[220:223], v[116:119]
	ds_read_b128 v[220:223], v185 offset:7168
	ds_read_b128 v[224:227], v184
	ds_read_b128 v[228:231], v184 offset:1024
	ds_read_b128 v[232:235], v184 offset:2048
	ds_read_b128 v[236:239], v184 offset:3072
	s_movk_i32 vcc_lo, 0x6000
	s_cmp_eq_u32 m0, 2
	s_cselect_b32 vcc_lo, 0xffff4000, vcc_lo
	s_add_u32 m0, m0, 1
	s_cmp_eq_u32 m0, 3
	s_cselect_b32 m0, 0, m0
	v_add_u32_e32 v185, vcc_lo, v185
	v_add_u32_e32 v184, vcc_lo, v184
	v_xor_b32_e32 v185, 64, v185
	v_xor_b32_e32 v184, 64, v184
	s_waitcnt lgkmcnt(0)
	v_mfma_f32_16x16x32_bf16 v[172:175], v[224:227], v[190:193], v[172:175]
	v_mfma_f32_16x16x32_bf16 v[168:171], v[228:231], v[190:193], v[168:171]
	v_mfma_f32_16x16x32_bf16 v[164:167], v[232:235], v[190:193], v[164:167]
	v_mfma_f32_16x16x32_bf16 v[156:159], v[236:239], v[190:193], v[156:159]
	v_mfma_f32_16x16x32_bf16 v[144:147], v[224:227], v[194:197], v[144:147]
	v_mfma_f32_16x16x32_bf16 v[136:139], v[228:231], v[194:197], v[136:139]
	v_mfma_f32_16x16x32_bf16 v[132:135], v[232:235], v[194:197], v[132:135]
	v_mfma_f32_16x16x32_bf16 v[120:123], v[236:239], v[194:197], v[120:123]
	v_mfma_f32_16x16x32_bf16 v[112:115], v[224:227], v[198:201], v[112:115]
	v_mfma_f32_16x16x32_bf16 v[108:111], v[228:231], v[198:201], v[108:111]
	v_mfma_f32_16x16x32_bf16 v[96:99], v[232:235], v[198:201], v[96:99]
	v_mfma_f32_16x16x32_bf16 v[92:95], v[236:239], v[198:201], v[92:95]
	v_mfma_f32_16x16x32_bf16 v[88:91], v[224:227], v[204:207], v[88:91]
	v_mfma_f32_16x16x32_bf16 v[80:83], v[228:231], v[204:207], v[80:83]
	v_mfma_f32_16x16x32_bf16 v[72:75], v[232:235], v[204:207], v[72:75]
	v_mfma_f32_16x16x32_bf16 v[68:71], v[236:239], v[204:207], v[68:71]
	v_mfma_f32_16x16x32_bf16 v[60:63], v[224:227], v[208:211], v[60:63]
	v_mfma_f32_16x16x32_bf16 v[52:55], v[228:231], v[208:211], v[52:55]
	v_mfma_f32_16x16x32_bf16 v[48:51], v[232:235], v[208:211], v[48:51]
	v_mfma_f32_16x16x32_bf16 v[44:47], v[236:239], v[208:211], v[44:47]
	v_mfma_f32_16x16x32_bf16 v[40:43], v[224:227], v[212:215], v[40:43]
	v_mfma_f32_16x16x32_bf16 v[36:39], v[228:231], v[212:215], v[36:39]
	v_mfma_f32_16x16x32_bf16 v[32:35], v[232:235], v[212:215], v[32:35]
	v_mfma_f32_16x16x32_bf16 v[28:31], v[236:239], v[212:215], v[28:31]
	v_mfma_f32_16x16x32_bf16 v[24:27], v[224:227], v[216:219], v[24:27]
	v_mfma_f32_16x16x32_bf16 v[20:23], v[228:231], v[216:219], v[20:23]
	v_mfma_f32_16x16x32_bf16 v[16:19], v[232:235], v[216:219], v[16:19]
	v_mfma_f32_16x16x32_bf16 v[12:15], v[236:239], v[216:219], v[12:15]
	v_mfma_f32_16x16x32_bf16 v[8:11], v[224:227], v[220:223], v[8:11]
	v_mfma_f32_16x16x32_bf16 v[4:7], v[228:231], v[220:223], v[4:7]
	v_mfma_f32_16x16x32_bf16 v[0:3], v[232:235], v[220:223], v[0:3]
	v_mfma_f32_16x16x32_bf16 v[116:119], v[236:239], v[220:223], v[116:119]
	v_lshrrev_b32_e32 v224, 4, v188
	v_and_b32_e32 v225, 7, v188
	v_bitop3_b32 v226, v224, v225, 3 bitop3:0x6c
	v_lshlrev_b32_e32 v227, 7, v188
	v_bfe_u32 v228, v188, 4, 2
	v_and_b32_e32 v229, 0xffffc780, v227
	v_and_b32_e32 v227, 0x2780, v227
	v_bitop3_b32 v228, v228, v225, 4 bitop3:0x36
	v_lshlrev_b32_e32 v226, 4, v226
	v_lshlrev_b32_e32 v228, 4, v228
	v_or_b32_e32 v185, v229, v226
	v_or_b32_e32 v184, v227, v226
	v_or_b32_e32 v183, v229, v228
	v_or_b32_e32 v182, v227, v228
	s_waitcnt vmcnt(0)
	s_barrier
	s_waitcnt vmcnt(11)
	ds_write_b128 v176, v[160:163]
	s_waitcnt vmcnt(10)
	ds_write_b128 v176, v[152:155] offset:4096
	s_waitcnt vmcnt(9)
	ds_write_b128 v176, v[148:151] offset:8192
	s_waitcnt vmcnt(8)
	ds_write_b128 v176, v[128:131] offset:12288
	s_waitcnt vmcnt(7)
	ds_write_b128 v176, v[124:127] offset:16384
	s_waitcnt vmcnt(6)
	ds_write_b128 v176, v[104:107] offset:20480
	s_waitcnt vmcnt(5)
	ds_write_b128 v176, v[100:103] offset:24576
	s_waitcnt vmcnt(4)
	ds_write_b128 v176, v[84:87] offset:28672
	s_waitcnt vmcnt(3)
	ds_write_b128 v176, v[140:143] offset:32768
	s_waitcnt vmcnt(2)
	ds_write_b128 v176, v[76:79] offset:36864
	s_waitcnt vmcnt(1)
	ds_write_b128 v176, v[64:67] offset:40960
	s_waitcnt vmcnt(0)
	ds_write_b128 v176, v[56:59] offset:45056
	s_waitcnt lgkmcnt(0)
	s_barrier
	ds_read_b128 v[56:59], v185
	ds_read_b128 v[64:67], v185 offset:2048
	ds_read_b128 v[76:79], v185 offset:4096
	ds_read_b128 v[84:87], v185 offset:6144
	ds_read_b128 v[100:103], v185 offset:8192
	ds_read_b128 v[104:107], v185 offset:10240
	ds_read_b128 v[124:127], v185 offset:12288
	ds_read_b128 v[128:131], v185 offset:14336
	ds_read_b128 v[140:143], v184 offset:32768
	ds_read_b128 v[148:151], v184 offset:34816
	ds_read_b128 v[152:155], v184 offset:36864
	ds_read_b128 v[160:163], v184 offset:38912
	s_waitcnt lgkmcnt(3)
	v_mfma_f32_16x16x32_bf16 v[172:175], v[140:143], v[56:59], v[172:175]
	s_waitcnt lgkmcnt(2)
	v_mfma_f32_16x16x32_bf16 v[168:171], v[148:151], v[56:59], v[168:171]
	s_waitcnt lgkmcnt(1)
	v_mfma_f32_16x16x32_bf16 v[164:167], v[152:155], v[56:59], v[164:167]
	s_waitcnt lgkmcnt(0)
	v_mfma_f32_16x16x32_bf16 v[56:59], v[160:163], v[56:59], v[156:159]
	v_mfma_f32_16x16x32_bf16 v[144:147], v[140:143], v[64:67], v[144:147]
	v_mfma_f32_16x16x32_bf16 v[136:139], v[148:151], v[64:67], v[136:139]
	v_mfma_f32_16x16x32_bf16 v[132:135], v[152:155], v[64:67], v[132:135]
	v_mfma_f32_16x16x32_bf16 v[64:67], v[160:163], v[64:67], v[120:123]
	v_mfma_f32_16x16x32_bf16 v[156:159], v[140:143], v[76:79], v[112:115]
	v_mfma_f32_16x16x32_bf16 v[178:181], v[148:151], v[76:79], v[108:111]
	v_mfma_f32_16x16x32_bf16 v[184:187], v[152:155], v[76:79], v[96:99]
	v_mfma_f32_16x16x32_bf16 v[76:79], v[160:163], v[76:79], v[92:95]
	v_mfma_f32_16x16x32_bf16 v[60:63], v[140:143], v[100:103], v[60:63]
	v_mfma_f32_16x16x32_bf16 v[52:55], v[148:151], v[100:103], v[52:55]
	v_mfma_f32_16x16x32_bf16 v[48:51], v[152:155], v[100:103], v[48:51]
	v_mfma_f32_16x16x32_bf16 v[44:47], v[160:163], v[100:103], v[44:47]
	v_mfma_f32_16x16x32_bf16 v[40:43], v[140:143], v[104:107], v[40:43]
	v_mfma_f32_16x16x32_bf16 v[36:39], v[148:151], v[104:107], v[36:39]
	v_mfma_f32_16x16x32_bf16 v[32:35], v[152:155], v[104:107], v[32:35]
	v_mfma_f32_16x16x32_bf16 v[28:31], v[160:163], v[104:107], v[28:31]
	v_mfma_f32_16x16x32_bf16 v[24:27], v[140:143], v[124:127], v[24:27]
	v_mfma_f32_16x16x32_bf16 v[20:23], v[148:151], v[124:127], v[20:23]
	v_mfma_f32_16x16x32_bf16 v[16:19], v[152:155], v[124:127], v[16:19]
	v_mfma_f32_16x16x32_bf16 v[12:15], v[160:163], v[124:127], v[12:15]
	v_mfma_f32_16x16x32_bf16 v[8:11], v[140:143], v[128:131], v[8:11]
	v_mfma_f32_16x16x32_bf16 v[4:7], v[148:151], v[128:131], v[4:7]
	v_mfma_f32_16x16x32_bf16 v[0:3], v[152:155], v[128:131], v[0:3]
	v_mfma_f32_16x16x32_bf16 v[190:193], v[140:143], v[84:87], v[88:91]
	v_mfma_f32_16x16x32_bf16 v[194:197], v[148:151], v[84:87], v[80:83]
	v_mfma_f32_16x16x32_bf16 v[198:201], v[152:155], v[84:87], v[72:75]
	v_mfma_f32_16x16x32_bf16 v[204:207], v[160:163], v[84:87], v[68:71]
	v_mfma_f32_16x16x32_bf16 v[140:143], v[160:163], v[128:131], v[116:119]
	s_nop 1
	ds_read_b128 v[68:71], v183
	ds_read_b128 v[72:75], v183 offset:2048
	ds_read_b128 v[80:83], v183 offset:4096
	ds_read_b128 v[128:131], v183 offset:6144
	ds_read_b128 v[148:151], v183 offset:8192
	ds_read_b128 v[152:155], v183 offset:10240
	ds_read_b128 v[160:163], v183 offset:12288
	ds_read_b128 v[208:211], v183 offset:14336
	ds_read_b128 v[212:215], v182 offset:32768
	ds_read_b128 v[216:219], v182 offset:34816
	ds_read_b128 v[220:223], v182 offset:36864
	ds_read_b128 v[224:227], v182 offset:38912
	s_waitcnt lgkmcnt(3)
	v_mfma_f32_16x16x32_bf16 v[124:127], v[212:215], v[68:71], v[172:175]
	s_movk_i32 s30, 0x6c0
	s_waitcnt lgkmcnt(2)
	v_mfma_f32_16x16x32_bf16 v[120:123], v[216:219], v[68:71], v[168:171]
	s_waitcnt lgkmcnt(1)
	v_mfma_f32_16x16x32_bf16 v[116:119], v[220:223], v[68:71], v[164:167]
	s_waitcnt lgkmcnt(0)
	v_mfma_f32_16x16x32_bf16 v[112:115], v[224:227], v[68:71], v[56:59]
	v_mfma_f32_16x16x32_bf16 v[108:111], v[212:215], v[72:75], v[144:147]
	v_mfma_f32_16x16x32_bf16 v[104:107], v[216:219], v[72:75], v[136:139]
	v_mfma_f32_16x16x32_bf16 v[100:103], v[220:223], v[72:75], v[132:135]
	v_mfma_f32_16x16x32_bf16 v[96:99], v[224:227], v[72:75], v[64:67]
	v_mfma_f32_16x16x32_bf16 v[92:95], v[212:215], v[80:83], v[156:159]
	v_mfma_f32_16x16x32_bf16 v[88:91], v[216:219], v[80:83], v[178:181]
	v_mfma_f32_16x16x32_bf16 v[84:87], v[220:223], v[80:83], v[184:187]
	v_mfma_f32_16x16x32_bf16 v[80:83], v[224:227], v[80:83], v[76:79]
	v_mfma_f32_16x16x32_bf16 v[76:79], v[212:215], v[128:131], v[190:193]
	v_mfma_f32_16x16x32_bf16 v[72:75], v[216:219], v[128:131], v[194:197]
	v_mfma_f32_16x16x32_bf16 v[68:71], v[220:223], v[128:131], v[198:201]
	v_mfma_f32_16x16x32_bf16 v[64:67], v[224:227], v[128:131], v[204:207]
	v_mov_b32_e32 v128, v188
	v_mov_b32_e32 v129, v188
	v_mfma_f32_16x16x32_bf16 v[60:63], v[212:215], v[148:151], v[60:63]
	s_nop 0
	v_and_or_b32 v134, v129, 64, s41
	v_mfma_f32_16x16x32_bf16 v[56:59], v[216:219], v[148:151], v[52:55]
	v_cmp_gt_i32_e32 vcc, s30, v134
	v_mfma_f32_16x16x32_bf16 v[52:55], v[220:223], v[148:151], v[48:51]
	v_mfma_f32_16x16x32_bf16 v[48:51], v[224:227], v[148:151], v[44:47]
	v_mfma_f32_16x16x32_bf16 v[44:47], v[212:215], v[152:155], v[40:43]
	v_mfma_f32_16x16x32_bf16 v[40:43], v[216:219], v[152:155], v[36:39]
	v_mfma_f32_16x16x32_bf16 v[36:39], v[220:223], v[152:155], v[32:35]
	v_mfma_f32_16x16x32_bf16 v[32:35], v[224:227], v[152:155], v[28:31]
	v_mfma_f32_16x16x32_bf16 v[28:31], v[212:215], v[160:163], v[24:27]
	v_mfma_f32_16x16x32_bf16 v[24:27], v[216:219], v[160:163], v[20:23]
	v_mfma_f32_16x16x32_bf16 v[20:23], v[220:223], v[160:163], v[16:19]
	v_mfma_f32_16x16x32_bf16 v[16:19], v[224:227], v[160:163], v[12:15]
	v_mfma_f32_16x16x32_bf16 v[12:15], v[212:215], v[208:211], v[8:11]
	v_mfma_f32_16x16x32_bf16 v[8:11], v[216:219], v[208:211], v[4:7]
	v_mfma_f32_16x16x32_bf16 v[4:7], v[220:223], v[208:211], v[0:3]
	v_mfma_f32_16x16x32_bf16 v[0:3], v[224:227], v[208:211], v[140:143]
	s_and_saveexec_b64 s[92:93], vcc
	s_cbranch_execz .LBB0_485
	v_and_b32_e32 v130, 0xffffff80, v129
	v_add_u32_e32 v183, s40, v130
	s_movk_i32 s30, 0xfff
	v_cmp_lt_i32_e64 s[48:49], s30, v183
	s_movk_i32 s30, 0x1000
	v_cmp_gt_i32_e64 s[44:45], s30, v183
	v_add_u32_e32 v130, 0xfffff000, v183
	v_bfe_u32 v141, v128, 4, 2
	s_movk_i32 s30, 0x27f
	v_ashrrev_i32_e32 v135, 10, v130
	v_ashrrev_i32_e32 v132, 8, v183
	v_cmp_lt_i32_e64 s[52:53], s30, v134
	s_movk_i32 s30, 0x280
	v_lshlrev_b32_e32 v130, 4, v141
	v_mov_b32_e32 v131, v177
	v_and_b32_e32 v140, 0x80, v129
	v_cmp_ne_u32_e64 s[50:51], s30, v134
	v_lshl_add_u64 v[138:139], s[84:85], 0, v[130:131]
	v_lshl_add_u64 v[136:137], s[82:83], 0, v[130:131]
	v_lshlrev_b32_e32 v130, 9, v132
	v_readlane_b32 s30, v255, 49
	v_and_b32_e32 v182, 15, v128
	v_and_b32_e32 v181, 0x380, v183
	v_or3_b32 v178, v130, s30, v140
	v_lshlrev_b32_e32 v130, 3, v132
	v_ashrrev_i32_e32 v131, 31, v130
	v_lshlrev_b64 v[132:133], 8, v[130:131]
	v_lshlrev_b32_e32 v130, 3, v135
	s_movk_i32 s30, 0x500
	v_bfe_u32 v129, v128, 4, 1
	v_lshrrev_b32_e32 v128, 2, v128
	v_mad_i64_i32 v[130:131], s[30:31], v130, s30, 0
	v_mov_b32_e32 v176, v134
	v_cmp_eq_u32_e64 s[40:41], 0, v129
	v_lshlrev_b32_e32 v180, 4, v129
	v_and_b32_e32 v179, 8, v128
	v_lshlrev_b32_e32 v128, 2, v141
	v_mov_b32_e32 v129, v177
	v_or_b32_e32 v132, v132, v140
	v_or_b32_e32 v130, v130, v181
	v_cmp_lt_i32_e64 s[46:47], s97, v134
	v_cmp_eq_u32_e64 s[42:43], 0, v141
	v_or_b32_e32 v140, v183, v182
	s_and_saveexec_b64 s[30:31], s[52:53]
	s_xor_b64 s[94:95], exec, s[30:31]
	s_cbranch_execz .LBB0_513
	s_and_saveexec_b64 s[30:31], s[50:51]
	s_xor_b64 s[30:31], exec, s[30:31]
	s_cbranch_execz .LBB0_492
	v_mul_f32_e32 v142, 0xbfb8aa3b, v124
	v_mul_f32_e32 v144, 0xbfb8aa3b, v120
	v_mul_f32_e32 v145, 0xbfb8aa3b, v125
	v_exp_f32_e32 v142, v142
	v_exp_f32_e32 v144, v144
	v_exp_f32_e32 v145, v145
	v_mul_f32_e32 v146, 0xbfb8aa3b, v121
	v_add_f32_e32 v142, 1.0, v142
	v_add_f32_e32 v144, 1.0, v144
	v_add_f32_e32 v145, 1.0, v145
	v_rcp_f32_e32 v142, v142
	v_rcp_f32_e32 v144, v144
	v_rcp_f32_e32 v145, v145
	v_exp_f32_e32 v146, v146
	v_mul_f32_e32 v142, v124, v142
	v_mul_f32_e32 v144, v120, v144
	v_mul_f32_e32 v145, v125, v145
	v_add_f32_e32 v120, 1.0, v146
	v_mul_f32_e32 v124, 0xbfb8aa3b, v126
	v_mul_f32_e32 v125, 0xbfb8aa3b, v122
	v_rcp_f32_e32 v120, v120
	v_exp_f32_e32 v124, v124
	v_exp_f32_e32 v125, v125
	v_ashrrev_i32_e32 v141, 31, v140
	v_mul_f32_e32 v146, v121, v120
	v_add_f32_e32 v120, 1.0, v124
	v_add_f32_e32 v121, 1.0, v125
	v_mul_f32_e32 v124, 0xbfb8aa3b, v127
	v_mul_f32_e32 v125, 0xbfb8aa3b, v123
	v_exp_f32_e32 v124, v124
	v_exp_f32_e32 v125, v125
	v_rcp_f32_e32 v120, v120
	v_rcp_f32_e32 v121, v121
	v_add_f32_e32 v124, 1.0, v124
	v_add_f32_e32 v125, 1.0, v125
	v_rcp_f32_e32 v124, v124
	v_rcp_f32_e32 v125, v125
	v_lshlrev_b64 v[140:141], 11, v[140:141]
	v_cmp_lt_i32_e32 vcc, v189, v202
	v_mul_f32_e32 v126, v126, v120
	v_mul_f32_e32 v122, v122, v121
	v_cndmask_b32_e32 v143, v203, v189, vcc
	v_mul_f32_e32 v127, v127, v124
	v_mul_f32_e32 v123, v123, v125
	v_lshl_add_u64 v[120:121], s[34:35], 0, v[140:141]
	v_lshlrev_b32_e32 v143, 2, v143
	v_lshl_add_u64 v[124:125], v[176:177], 1, v[120:121]
	s_nop 0
	s_nop 0
	s_nop 0
	s_nop 0
	s_nop 0
	s_nop 0
	s_nop 0
	s_nop 0
	s_mov_b32 s58, 0x96ff000
	s_waitcnt lgkmcnt(0)
	s_nop 0
	s_nop 1
	v_permlane16_swap_b32_e32 v142, v144
	s_waitcnt lgkmcnt(0)
	s_nop 0
	v_mov_b32_e32 v120, v145
	v_mov_b32_e32 v145, v146
	s_nop 1
	v_permlane16_swap_b32_e32 v120, v145
	s_waitcnt lgkmcnt(0)
	s_nop 0
	v_mov_b32_e32 v121, v126
	v_mov_b32_e32 v126, v122
	s_nop 1
	v_permlane16_swap_b32_e32 v121, v126
	s_waitcnt lgkmcnt(0)
	s_nop 0
	v_mov_b32_e32 v122, v127
	s_nop 1
	v_permlane16_swap_b32_e32 v122, v123
	v_cvt_pk_bf16_f32 v123, v126, v123
	v_lshlrev_b32_e32 v126, 1, v180
	v_mov_b32_e32 v127, v177
	v_lshlrev_b32_e32 v140, 1, v179
	v_mov_b32_e32 v141, v177
	v_lshl_add_u64 v[124:125], v[124:125], 0, v[126:127]
	v_lshl_add_u64 v[124:125], v[124:125], 0, v[140:141]
	v_add_co_u32_e32 v124, vcc, s58, v124
	v_cvt_pk_bf16_f32 v120, v142, v120
	v_cvt_pk_bf16_f32 v121, v121, v122
	v_cvt_pk_bf16_f32 v122, v144, v145
	v_addc_co_u32_e32 v125, vcc, 0, v125, vcc
	v_mul_f32_e32 v126, 0xbfb8aa3b, v116
	global_store_dwordx4 v[124:125], v[120:123], off offset:2688
	v_exp_f32_e32 v126, v126
	s_nop 0
	v_mul_f32_e32 v121, 0xbfb8aa3b, v112
	v_mul_f32_e32 v122, 0xbfb8aa3b, v117
	v_exp_f32_e32 v121, v121
	v_exp_f32_e32 v122, v122
	v_add_f32_e32 v120, 1.0, v126
	v_mul_f32_e32 v123, 0xbfb8aa3b, v113
	v_add_f32_e32 v121, 1.0, v121
	v_add_f32_e32 v122, 1.0, v122
	v_rcp_f32_e32 v120, v120
	v_rcp_f32_e32 v121, v121
	v_rcp_f32_e32 v122, v122
	v_exp_f32_e32 v123, v123
	v_mul_f32_e32 v116, v116, v120
	v_mul_f32_e32 v112, v112, v121
	v_mul_f32_e32 v117, v117, v122
	v_add_f32_e32 v120, 1.0, v123
	v_mul_f32_e32 v121, 0xbfb8aa3b, v118
	v_mul_f32_e32 v122, 0xbfb8aa3b, v114
	v_rcp_f32_e32 v120, v120
	v_exp_f32_e32 v121, v121
	v_exp_f32_e32 v122, v122
	v_mul_f32_e32 v123, 0xbfb8aa3b, v115
	v_mul_f32_e32 v113, v113, v120
	v_add_f32_e32 v120, 1.0, v121
	v_add_f32_e32 v121, 1.0, v122
	v_mul_f32_e32 v122, 0xbfb8aa3b, v119
	v_exp_f32_e32 v122, v122
	v_exp_f32_e32 v123, v123
	v_rcp_f32_e32 v120, v120
	v_rcp_f32_e32 v121, v121
	v_add_f32_e32 v122, 1.0, v122
	v_add_f32_e32 v123, 1.0, v123
	v_rcp_f32_e32 v122, v122
	v_rcp_f32_e32 v123, v123
	v_mul_f32_e32 v118, v118, v120
	v_mul_f32_e32 v114, v114, v121
	v_mul_f32_e32 v119, v119, v122
	v_mul_f32_e32 v115, v115, v123
	s_nop 0
	s_nop 0
	s_nop 0
	s_nop 0
	s_nop 0
	s_nop 0
	s_nop 0
	s_nop 0
	s_waitcnt lgkmcnt(0)
	s_nop 0
	v_mov_b32_e32 v120, v112
	s_nop 1
	v_permlane16_swap_b32_e32 v116, v120
	s_waitcnt lgkmcnt(0)
	s_nop 0
	v_mov_b32_e32 v112, v117
	v_mov_b32_e32 v117, v113
	s_nop 1
	v_permlane16_swap_b32_e32 v112, v117
	s_waitcnt lgkmcnt(0)
	s_nop 0
	v_mov_b32_e32 v113, v118
	v_mov_b32_e32 v118, v114
	s_nop 1
	v_permlane16_swap_b32_e32 v113, v118
	s_waitcnt lgkmcnt(0)
	s_nop 0
	v_mov_b32_e32 v114, v119
	s_nop 1
	v_permlane16_swap_b32_e32 v114, v115
	v_cvt_pk_bf16_f32 v112, v116, v112
	v_cvt_pk_bf16_f32 v113, v113, v114
	v_cvt_pk_bf16_f32 v114, v120, v117
	v_cvt_pk_bf16_f32 v115, v118, v115
	global_store_dwordx4 v[124:125], v[112:115], off offset:2752

.LBB0_519:
	s_or_b64 exec, exec, s[58:59]
	s_nop 0
	s_nop 0
	s_nop 0
	s_nop 0
	s_nop 0
	s_nop 0
	s_nop 0
	s_nop 0
	v_lshlrev_b64 v[140:141], 9, v[140:141]
	v_lshl_add_u64 v[140:141], s[14:15], 0, v[140:141]
	s_waitcnt lgkmcnt(0)
	s_nop 0
	v_mov_b32_e32 v143, v120
	s_nop 1
	v_permlane16_swap_b32_e32 v124, v143
	s_waitcnt lgkmcnt(0)
	s_nop 0
	v_mov_b32_e32 v120, v125
	v_mov_b32_e32 v125, v121
	s_nop 1
	v_permlane16_swap_b32_e32 v120, v125
	s_waitcnt lgkmcnt(0)
	s_nop 0
	v_mov_b32_e32 v121, v126
	v_mov_b32_e32 v126, v122
	s_nop 1
	v_permlane16_swap_b32_e32 v121, v126
	s_waitcnt lgkmcnt(0)
	s_nop 0
	v_lshl_add_u64 v[140:141], v[176:177], 1, v[140:141]
	v_mov_b32_e32 v122, v127
	s_nop 1
	v_permlane16_swap_b32_e32 v122, v123
	v_cvt_pk_bf16_f32 v120, v124, v120
	v_cvt_pk_bf16_f32 v121, v121, v122
	v_cvt_pk_bf16_f32 v122, v143, v125
	v_lshlrev_b32_e32 v124, 1, v180
	v_mov_b32_e32 v125, v177
	v_cvt_pk_bf16_f32 v123, v126, v123
	v_lshlrev_b32_e32 v126, 1, v179
	v_mov_b32_e32 v127, v177
	v_lshl_add_u64 v[124:125], v[140:141], 0, v[124:125]
	v_lshl_add_u64 v[124:125], v[124:125], 0, v[126:127]
	s_mov_b32 s58, 0xacff000
	v_add_co_u32_e32 v124, vcc, s58, v124
	s_nop 1
	v_addc_co_u32_e32 v125, vcc, 0, v125, vcc
	global_store_dwordx4 v[124:125], v[120:123], off offset:3328
	s_nop 1
	s_nop 0
	s_nop 0
	s_nop 0
	s_nop 0
	s_nop 0
	s_nop 0
	s_nop 0
	s_nop 0
	s_waitcnt lgkmcnt(0)
	s_nop 0
	v_mov_b32_e32 v120, v112
	s_nop 1
	v_permlane16_swap_b32_e32 v116, v120
	s_waitcnt lgkmcnt(0)
	s_nop 0
	v_mov_b32_e32 v112, v117
	v_mov_b32_e32 v117, v113
	s_nop 1
	v_permlane16_swap_b32_e32 v112, v117
	s_waitcnt lgkmcnt(0)
	s_nop 0
	v_mov_b32_e32 v113, v118
	v_mov_b32_e32 v118, v114
	s_nop 1
	v_permlane16_swap_b32_e32 v113, v118
	s_waitcnt lgkmcnt(0)
	s_nop 0
	v_mov_b32_e32 v114, v119
	s_nop 1
	v_permlane16_swap_b32_e32 v114, v115
	v_cvt_pk_bf16_f32 v112, v116, v112
	v_cvt_pk_bf16_f32 v113, v113, v114
	v_cvt_pk_bf16_f32 v114, v120, v117
	v_cvt_pk_bf16_f32 v115, v118, v115
	global_store_dwordx4 v[124:125], v[112:115], off offset:3392

.LBB0_523:
	s_or_b64 exec, exec, s[58:59]
	s_nop 0
	s_nop 0
	s_nop 0
	s_nop 0
	s_nop 0
	s_nop 0
	s_nop 0
	s_nop 0
	v_mov_b64_e32 v[144:145], s[4:5]
	s_movk_i32 vcc_lo, 0x300
	v_mad_i64_i32 v[144:145], s[58:59], v140, vcc_lo, v[144:145]
	v_lshlrev_b64 v[146:147], 1, v[134:135]
	s_waitcnt lgkmcnt(0)
	s_nop 0
	v_mov_b32_e32 v141, v120
	s_nop 1
	v_permlane16_swap_b32_e32 v124, v141
	s_waitcnt lgkmcnt(0)
	s_nop 0
	v_mov_b32_e32 v120, v125
	v_mov_b32_e32 v125, v121
	s_nop 1
	v_permlane16_swap_b32_e32 v120, v125
	s_waitcnt lgkmcnt(0)
	s_nop 0
	v_mov_b32_e32 v121, v126
	v_mov_b32_e32 v126, v122
	s_nop 1
	v_permlane16_swap_b32_e32 v121, v126
	s_waitcnt lgkmcnt(0)
	s_nop 0
	v_lshl_add_u64 v[144:145], v[144:145], 0, v[146:147]
	v_mov_b32_e32 v122, v127
	s_nop 1
	v_permlane16_swap_b32_e32 v122, v123
	v_cvt_pk_bf16_f32 v120, v124, v120
	v_cvt_pk_bf16_f32 v121, v121, v122
	v_cvt_pk_bf16_f32 v122, v141, v125
	v_lshlrev_b32_e32 v124, 1, v180
	v_mov_b32_e32 v125, v177
	v_cvt_pk_bf16_f32 v123, v126, v123
	v_lshl_add_u64 v[126:127], v[144:145], 0, v[124:125]
	v_lshlrev_b32_e32 v144, 1, v179
	v_mov_b32_e32 v145, v177
	v_lshl_add_u64 v[126:127], v[126:127], 0, v[144:145]
	global_store_dwordx4 v[126:127], v[120:123], off
	s_nop 0
	v_cndmask_b32_e64 v127, v119, v115, s[40:41]
	s_nop 0
	s_nop 0
	s_nop 0
	s_nop 0
	s_nop 0
	ds_bpermute_b32 v127, v142, v127
	v_mov_b64_e32 v[120:121], s[34:35]
	v_mad_i64_i32 v[120:121], s[58:59], v140, vcc_lo, v[120:121]
	v_lshl_add_u64 v[120:121], v[120:121], 0, v[146:147]
	s_waitcnt lgkmcnt(1)
	s_nop 0
	v_mov_b32_e32 v122, v112
	s_nop 1
	v_permlane16_swap_b32_e32 v116, v122
	s_waitcnt lgkmcnt(1)
	s_nop 0
	v_mov_b32_e32 v112, v117
	v_mov_b32_e32 v117, v113
	s_nop 1
	v_permlane16_swap_b32_e32 v112, v117
	s_waitcnt lgkmcnt(1)
	s_nop 0
	v_mov_b32_e32 v113, v118
	v_mov_b32_e32 v118, v114
	s_nop 1
	v_permlane16_swap_b32_e32 v113, v118
	s_waitcnt lgkmcnt(0)
	v_cndmask_b32_e64 v114, v127, v119, s[40:41]
	v_cvt_pk_bf16_f32 v112, v116, v112
	v_cvt_pk_bf16_f32 v113, v113, v114
	v_cvt_pk_bf16_f32 v114, v122, v117
	v_lshl_add_u64 v[116:117], v[120:121], 0, v[124:125]
	v_lshl_add_u64 v[116:117], v[116:117], 0, v[144:145]
	v_cndmask_b32_e64 v115, v115, v127, s[40:41]
	v_add_co_u32_e32 v116, vcc, 0xa700000, v116
	v_cvt_pk_bf16_f32 v115, v118, v115
	s_nop 0
	v_addc_co_u32_e32 v117, vcc, 0, v117, vcc
	global_store_dwordx4 v[116:117], v[112:115], off offset:64

.LBB0_525:
	s_or_b64 exec, exec, s[30:31]
	v_or_b32_e32 v116, 16, v182
	v_or_b32_e32 v112, v183, v116
	s_and_saveexec_b64 s[30:31], s[52:53]
	s_xor_b64 s[94:95], exec, s[30:31]
	s_cbranch_execz .LBB0_549
	s_and_saveexec_b64 s[30:31], s[50:51]
	s_xor_b64 s[30:31], exec, s[30:31]
	s_cbranch_execz .LBB0_528
	v_mul_f32_e32 v114, 0xbfb8aa3b, v108
	v_mul_f32_e32 v116, 0xbfb8aa3b, v104
	v_mul_f32_e32 v117, 0xbfb8aa3b, v109
	v_exp_f32_e32 v114, v114
	v_exp_f32_e32 v116, v116
	v_exp_f32_e32 v117, v117
	v_mul_f32_e32 v118, 0xbfb8aa3b, v105
	v_add_f32_e32 v114, 1.0, v114
	v_add_f32_e32 v116, 1.0, v116
	v_add_f32_e32 v117, 1.0, v117
	v_rcp_f32_e32 v114, v114
	v_rcp_f32_e32 v116, v116
	v_rcp_f32_e32 v117, v117
	v_exp_f32_e32 v118, v118
	v_mul_f32_e32 v114, v108, v114
	v_mul_f32_e32 v116, v104, v116
	v_mul_f32_e32 v117, v109, v117
	v_add_f32_e32 v104, 1.0, v118
	v_mul_f32_e32 v108, 0xbfb8aa3b, v110
	v_mul_f32_e32 v109, 0xbfb8aa3b, v106
	v_rcp_f32_e32 v104, v104
	v_exp_f32_e32 v108, v108
	v_exp_f32_e32 v109, v109
	v_ashrrev_i32_e32 v113, 31, v112
	v_mul_f32_e32 v118, v105, v104
	v_add_f32_e32 v104, 1.0, v108
	v_add_f32_e32 v105, 1.0, v109
	v_mul_f32_e32 v108, 0xbfb8aa3b, v111
	v_mul_f32_e32 v109, 0xbfb8aa3b, v107
	v_exp_f32_e32 v108, v108
	v_exp_f32_e32 v109, v109
	v_rcp_f32_e32 v104, v104
	v_rcp_f32_e32 v105, v105
	v_add_f32_e32 v108, 1.0, v108
	v_add_f32_e32 v109, 1.0, v109
	v_rcp_f32_e32 v108, v108
	v_rcp_f32_e32 v109, v109
	v_lshlrev_b64 v[112:113], 11, v[112:113]
	v_cmp_lt_i32_e32 vcc, v189, v202
	v_mul_f32_e32 v110, v110, v104
	v_mul_f32_e32 v106, v106, v105
	v_cndmask_b32_e32 v115, v203, v189, vcc
	v_mul_f32_e32 v111, v111, v108
	v_mul_f32_e32 v107, v107, v109
	v_lshl_add_u64 v[104:105], s[34:35], 0, v[112:113]
	v_lshlrev_b32_e32 v115, 2, v115
	v_lshl_add_u64 v[108:109], v[176:177], 1, v[104:105]
	s_nop 0
	s_nop 0
	s_nop 0
	s_nop 0
	s_nop 0
	s_nop 0
	s_nop 0
	s_nop 0
	s_mov_b32 s58, 0x96ff000
	s_waitcnt lgkmcnt(0)
	s_nop 0
	s_nop 1
	v_permlane16_swap_b32_e32 v114, v116
	s_waitcnt lgkmcnt(0)
	s_nop 0
	v_mov_b32_e32 v104, v117
	v_mov_b32_e32 v117, v118
	s_nop 1
	v_permlane16_swap_b32_e32 v104, v117
	s_waitcnt lgkmcnt(0)
	s_nop 0
	v_mov_b32_e32 v105, v110
	v_mov_b32_e32 v110, v106
	s_nop 1
	v_permlane16_swap_b32_e32 v105, v110
	s_waitcnt lgkmcnt(0)
	s_nop 0
	v_mov_b32_e32 v106, v111
	s_nop 1
	v_permlane16_swap_b32_e32 v106, v107
	v_cvt_pk_bf16_f32 v107, v110, v107
	v_lshlrev_b32_e32 v110, 1, v180
	v_mov_b32_e32 v111, v177
	v_lshlrev_b32_e32 v112, 1, v179
	v_mov_b32_e32 v113, v177
	v_lshl_add_u64 v[108:109], v[108:109], 0, v[110:111]
	v_lshl_add_u64 v[108:109], v[108:109], 0, v[112:113]
	v_add_co_u32_e32 v108, vcc, s58, v108
	v_cvt_pk_bf16_f32 v104, v114, v104
	v_cvt_pk_bf16_f32 v105, v105, v106
	v_cvt_pk_bf16_f32 v106, v116, v117
	v_addc_co_u32_e32 v109, vcc, 0, v109, vcc
	v_mul_f32_e32 v110, 0xbfb8aa3b, v100
	global_store_dwordx4 v[108:109], v[104:107], off offset:2688
	v_exp_f32_e32 v110, v110
	s_nop 0
	v_mul_f32_e32 v105, 0xbfb8aa3b, v96
	v_mul_f32_e32 v106, 0xbfb8aa3b, v101
	v_exp_f32_e32 v105, v105
	v_exp_f32_e32 v106, v106
	v_add_f32_e32 v104, 1.0, v110
	v_mul_f32_e32 v107, 0xbfb8aa3b, v97
	v_add_f32_e32 v105, 1.0, v105
	v_add_f32_e32 v106, 1.0, v106
	v_rcp_f32_e32 v104, v104
	v_rcp_f32_e32 v105, v105
	v_rcp_f32_e32 v106, v106
	v_exp_f32_e32 v107, v107
	v_mul_f32_e32 v100, v100, v104
	v_mul_f32_e32 v96, v96, v105
	v_mul_f32_e32 v101, v101, v106
	v_add_f32_e32 v104, 1.0, v107
	v_mul_f32_e32 v105, 0xbfb8aa3b, v102
	v_mul_f32_e32 v106, 0xbfb8aa3b, v98
	v_rcp_f32_e32 v104, v104
	v_exp_f32_e32 v105, v105
	v_exp_f32_e32 v106, v106
	v_mul_f32_e32 v107, 0xbfb8aa3b, v99
	v_mul_f32_e32 v97, v97, v104
	v_add_f32_e32 v104, 1.0, v105
	v_add_f32_e32 v105, 1.0, v106
	v_mul_f32_e32 v106, 0xbfb8aa3b, v103
	v_exp_f32_e32 v106, v106
	v_exp_f32_e32 v107, v107
	v_rcp_f32_e32 v104, v104
	v_rcp_f32_e32 v105, v105
	v_add_f32_e32 v106, 1.0, v106
	v_add_f32_e32 v107, 1.0, v107
	v_rcp_f32_e32 v106, v106
	v_rcp_f32_e32 v107, v107
	v_mul_f32_e32 v102, v102, v104
	v_mul_f32_e32 v98, v98, v105
	v_mul_f32_e32 v103, v103, v106
	v_mul_f32_e32 v99, v99, v107
	s_nop 0
	s_nop 0
	s_nop 0
	s_nop 0
	s_nop 0
	s_nop 0
	s_nop 0
	s_nop 0
	s_waitcnt lgkmcnt(0)
	s_nop 0
	v_mov_b32_e32 v104, v96
	s_nop 1
	v_permlane16_swap_b32_e32 v100, v104
	s_waitcnt lgkmcnt(0)
	s_nop 0
	v_mov_b32_e32 v96, v101
	v_mov_b32_e32 v101, v97
	s_nop 1
	v_permlane16_swap_b32_e32 v96, v101
	s_waitcnt lgkmcnt(0)
	s_nop 0
	v_mov_b32_e32 v97, v102
	v_mov_b32_e32 v102, v98
	s_nop 1
	v_permlane16_swap_b32_e32 v97, v102
	s_waitcnt lgkmcnt(0)
	s_nop 0
	v_mov_b32_e32 v98, v103
	s_nop 1
	v_permlane16_swap_b32_e32 v98, v99
	v_cvt_pk_bf16_f32 v96, v100, v96
	v_cvt_pk_bf16_f32 v97, v97, v98
	v_cvt_pk_bf16_f32 v98, v104, v101
	v_cvt_pk_bf16_f32 v99, v102, v99
	global_store_dwordx4 v[108:109], v[96:99], off offset:2752

.LBB0_555:
	s_or_b64 exec, exec, s[58:59]
	s_nop 0
	s_nop 0
	s_nop 0
	s_nop 0
	s_nop 0
	s_nop 0
	s_nop 0
	s_nop 0
	v_lshlrev_b64 v[112:113], 9, v[112:113]
	v_lshl_add_u64 v[112:113], s[14:15], 0, v[112:113]
	s_waitcnt lgkmcnt(0)
	s_nop 0
	v_mov_b32_e32 v115, v104
	s_nop 1
	v_permlane16_swap_b32_e32 v108, v115
	s_waitcnt lgkmcnt(0)
	s_nop 0
	v_mov_b32_e32 v104, v109
	v_mov_b32_e32 v109, v105
	s_nop 1
	v_permlane16_swap_b32_e32 v104, v109
	s_waitcnt lgkmcnt(0)
	s_nop 0
	v_mov_b32_e32 v105, v110
	v_mov_b32_e32 v110, v106
	s_nop 1
	v_permlane16_swap_b32_e32 v105, v110
	s_waitcnt lgkmcnt(0)
	s_nop 0
	v_lshl_add_u64 v[112:113], v[176:177], 1, v[112:113]
	v_mov_b32_e32 v106, v111
	s_nop 1
	v_permlane16_swap_b32_e32 v106, v107
	v_cvt_pk_bf16_f32 v104, v108, v104
	v_cvt_pk_bf16_f32 v105, v105, v106
	v_cvt_pk_bf16_f32 v106, v115, v109
	v_lshlrev_b32_e32 v108, 1, v180
	v_mov_b32_e32 v109, v177
	v_cvt_pk_bf16_f32 v107, v110, v107
	v_lshlrev_b32_e32 v110, 1, v179
	v_mov_b32_e32 v111, v177
	v_lshl_add_u64 v[108:109], v[112:113], 0, v[108:109]
	v_lshl_add_u64 v[108:109], v[108:109], 0, v[110:111]
	s_mov_b32 s58, 0xacff000
	v_add_co_u32_e32 v108, vcc, s58, v108
	s_nop 1
	v_addc_co_u32_e32 v109, vcc, 0, v109, vcc
	global_store_dwordx4 v[108:109], v[104:107], off offset:3328
	s_nop 1
	s_nop 0
	s_nop 0
	s_nop 0
	s_nop 0
	s_nop 0
	s_nop 0
	s_nop 0
	s_nop 0
	s_waitcnt lgkmcnt(0)
	s_nop 0
	v_mov_b32_e32 v104, v96
	s_nop 1
	v_permlane16_swap_b32_e32 v100, v104
	s_waitcnt lgkmcnt(0)
	s_nop 0
	v_mov_b32_e32 v96, v101
	v_mov_b32_e32 v101, v97
	s_nop 1
	v_permlane16_swap_b32_e32 v96, v101
	s_waitcnt lgkmcnt(0)
	s_nop 0
	v_mov_b32_e32 v97, v102
	v_mov_b32_e32 v102, v98
	s_nop 1
	v_permlane16_swap_b32_e32 v97, v102
	s_waitcnt lgkmcnt(0)
	s_nop 0
	v_mov_b32_e32 v98, v103
	s_nop 1
	v_permlane16_swap_b32_e32 v98, v99
	v_cvt_pk_bf16_f32 v96, v100, v96
	v_cvt_pk_bf16_f32 v97, v97, v98
	v_cvt_pk_bf16_f32 v98, v104, v101
	v_cvt_pk_bf16_f32 v99, v102, v99
	global_store_dwordx4 v[108:109], v[96:99], off offset:3392

.LBB0_559:
	s_or_b64 exec, exec, s[58:59]
	s_nop 0
	s_nop 0
	s_nop 0
	s_nop 0
	s_nop 0
	s_nop 0
	s_nop 0
	s_nop 0
	v_mov_b64_e32 v[116:117], s[4:5]
	s_movk_i32 vcc_lo, 0x300
	v_mad_i64_i32 v[116:117], s[58:59], v112, vcc_lo, v[116:117]
	v_lshlrev_b64 v[118:119], 1, v[134:135]
	s_waitcnt lgkmcnt(0)
	s_nop 0
	v_mov_b32_e32 v113, v104
	s_nop 1
	v_permlane16_swap_b32_e32 v108, v113
	s_waitcnt lgkmcnt(0)
	s_nop 0
	v_mov_b32_e32 v104, v109
	v_mov_b32_e32 v109, v105
	s_nop 1
	v_permlane16_swap_b32_e32 v104, v109
	s_waitcnt lgkmcnt(0)
	s_nop 0
	v_mov_b32_e32 v105, v110
	v_mov_b32_e32 v110, v106
	s_nop 1
	v_permlane16_swap_b32_e32 v105, v110
	s_waitcnt lgkmcnt(0)
	s_nop 0
	v_lshl_add_u64 v[116:117], v[116:117], 0, v[118:119]
	v_mov_b32_e32 v106, v111
	s_nop 1
	v_permlane16_swap_b32_e32 v106, v107
	v_cvt_pk_bf16_f32 v104, v108, v104
	v_cvt_pk_bf16_f32 v105, v105, v106
	v_cvt_pk_bf16_f32 v106, v113, v109
	v_lshlrev_b32_e32 v108, 1, v180
	v_mov_b32_e32 v109, v177
	v_cvt_pk_bf16_f32 v107, v110, v107
	v_lshl_add_u64 v[110:111], v[116:117], 0, v[108:109]
	v_lshlrev_b32_e32 v116, 1, v179
	v_mov_b32_e32 v117, v177
	v_lshl_add_u64 v[110:111], v[110:111], 0, v[116:117]
	global_store_dwordx4 v[110:111], v[104:107], off
	s_nop 0
	v_cndmask_b32_e64 v111, v103, v99, s[40:41]
	s_nop 0
	s_nop 0
	s_nop 0
	s_nop 0
	s_nop 0
	ds_bpermute_b32 v111, v114, v111
	v_mov_b64_e32 v[104:105], s[34:35]
	v_mad_i64_i32 v[104:105], s[58:59], v112, vcc_lo, v[104:105]
	v_lshl_add_u64 v[104:105], v[104:105], 0, v[118:119]
	s_waitcnt lgkmcnt(1)
	s_nop 0
	v_mov_b32_e32 v106, v96
	s_nop 1
	v_permlane16_swap_b32_e32 v100, v106
	s_waitcnt lgkmcnt(1)
	s_nop 0
	v_mov_b32_e32 v96, v101
	v_mov_b32_e32 v101, v97
	s_nop 1
	v_permlane16_swap_b32_e32 v96, v101
	s_waitcnt lgkmcnt(1)
	s_nop 0
	v_mov_b32_e32 v97, v102
	v_mov_b32_e32 v102, v98
	s_nop 1
	v_permlane16_swap_b32_e32 v97, v102
	s_waitcnt lgkmcnt(0)
	v_cndmask_b32_e64 v98, v111, v103, s[40:41]
	v_cvt_pk_bf16_f32 v96, v100, v96
	v_cvt_pk_bf16_f32 v97, v97, v98
	v_cvt_pk_bf16_f32 v98, v106, v101
	v_lshl_add_u64 v[100:101], v[104:105], 0, v[108:109]
	v_lshl_add_u64 v[100:101], v[100:101], 0, v[116:117]
	v_cndmask_b32_e64 v99, v99, v111, s[40:41]
	v_add_co_u32_e32 v100, vcc, 0xa700000, v100
	v_cvt_pk_bf16_f32 v99, v102, v99
	s_nop 0
	v_addc_co_u32_e32 v101, vcc, 0, v101, vcc
	global_store_dwordx4 v[100:101], v[96:99], off offset:64

.LBB0_561:
	s_or_b64 exec, exec, s[30:31]
	v_or_b32_e32 v100, 32, v182
	v_or_b32_e32 v96, v183, v100
	s_and_saveexec_b64 s[30:31], s[52:53]
	s_xor_b64 s[94:95], exec, s[30:31]
	s_cbranch_execz .LBB0_585
	s_and_saveexec_b64 s[30:31], s[50:51]
	s_xor_b64 s[30:31], exec, s[30:31]
	s_cbranch_execz .LBB0_564
	v_mul_f32_e32 v98, 0xbfb8aa3b, v92
	v_mul_f32_e32 v100, 0xbfb8aa3b, v88
	v_mul_f32_e32 v101, 0xbfb8aa3b, v93
	v_exp_f32_e32 v98, v98
	v_exp_f32_e32 v100, v100
	v_exp_f32_e32 v101, v101
	v_mul_f32_e32 v102, 0xbfb8aa3b, v89
	v_add_f32_e32 v98, 1.0, v98
	v_add_f32_e32 v100, 1.0, v100
	v_add_f32_e32 v101, 1.0, v101
	v_rcp_f32_e32 v98, v98
	v_rcp_f32_e32 v100, v100
	v_rcp_f32_e32 v101, v101
	v_exp_f32_e32 v102, v102
	v_mul_f32_e32 v98, v92, v98
	v_mul_f32_e32 v100, v88, v100
	v_mul_f32_e32 v101, v93, v101
	v_add_f32_e32 v88, 1.0, v102
	v_mul_f32_e32 v92, 0xbfb8aa3b, v94
	v_mul_f32_e32 v93, 0xbfb8aa3b, v90
	v_rcp_f32_e32 v88, v88
	v_exp_f32_e32 v92, v92
	v_exp_f32_e32 v93, v93
	v_ashrrev_i32_e32 v97, 31, v96
	v_mul_f32_e32 v102, v89, v88
	v_add_f32_e32 v88, 1.0, v92
	v_add_f32_e32 v89, 1.0, v93
	v_mul_f32_e32 v92, 0xbfb8aa3b, v95
	v_mul_f32_e32 v93, 0xbfb8aa3b, v91
	v_exp_f32_e32 v92, v92
	v_exp_f32_e32 v93, v93
	v_rcp_f32_e32 v88, v88
	v_rcp_f32_e32 v89, v89
	v_add_f32_e32 v92, 1.0, v92
	v_add_f32_e32 v93, 1.0, v93
	v_rcp_f32_e32 v92, v92
	v_rcp_f32_e32 v93, v93
	v_lshlrev_b64 v[96:97], 11, v[96:97]
	v_cmp_lt_i32_e32 vcc, v189, v202
	v_mul_f32_e32 v94, v94, v88
	v_mul_f32_e32 v90, v90, v89
	v_cndmask_b32_e32 v99, v203, v189, vcc
	v_mul_f32_e32 v95, v95, v92
	v_mul_f32_e32 v91, v91, v93
	v_lshl_add_u64 v[88:89], s[34:35], 0, v[96:97]
	v_lshlrev_b32_e32 v99, 2, v99
	v_lshl_add_u64 v[92:93], v[176:177], 1, v[88:89]
	s_nop 0
	s_nop 0
	s_nop 0
	s_nop 0
	s_nop 0
	s_nop 0
	s_nop 0
	s_nop 0
	s_mov_b32 s58, 0x96ff000
	s_waitcnt lgkmcnt(0)
	s_nop 0
	s_nop 1
	v_permlane16_swap_b32_e32 v98, v100
	s_waitcnt lgkmcnt(0)
	s_nop 0
	v_mov_b32_e32 v88, v101
	v_mov_b32_e32 v101, v102
	s_nop 1
	v_permlane16_swap_b32_e32 v88, v101
	s_waitcnt lgkmcnt(0)
	s_nop 0
	v_mov_b32_e32 v89, v94
	v_mov_b32_e32 v94, v90
	s_nop 1
	v_permlane16_swap_b32_e32 v89, v94
	s_waitcnt lgkmcnt(0)
	s_nop 0
	v_mov_b32_e32 v90, v95
	s_nop 1
	v_permlane16_swap_b32_e32 v90, v91
	v_cvt_pk_bf16_f32 v91, v94, v91
	v_lshlrev_b32_e32 v94, 1, v180
	v_mov_b32_e32 v95, v177
	v_lshlrev_b32_e32 v96, 1, v179
	v_mov_b32_e32 v97, v177
	v_lshl_add_u64 v[92:93], v[92:93], 0, v[94:95]
	v_lshl_add_u64 v[92:93], v[92:93], 0, v[96:97]
	v_add_co_u32_e32 v92, vcc, s58, v92
	v_cvt_pk_bf16_f32 v88, v98, v88
	v_cvt_pk_bf16_f32 v89, v89, v90
	v_cvt_pk_bf16_f32 v90, v100, v101
	v_addc_co_u32_e32 v93, vcc, 0, v93, vcc
	v_mul_f32_e32 v94, 0xbfb8aa3b, v84
	global_store_dwordx4 v[92:93], v[88:91], off offset:2688
	v_exp_f32_e32 v94, v94
	s_nop 0
	v_mul_f32_e32 v89, 0xbfb8aa3b, v80
	v_mul_f32_e32 v90, 0xbfb8aa3b, v85
	v_exp_f32_e32 v89, v89
	v_exp_f32_e32 v90, v90
	v_add_f32_e32 v88, 1.0, v94
	v_mul_f32_e32 v91, 0xbfb8aa3b, v81
	v_add_f32_e32 v89, 1.0, v89
	v_add_f32_e32 v90, 1.0, v90
	v_rcp_f32_e32 v88, v88
	v_rcp_f32_e32 v89, v89
	v_rcp_f32_e32 v90, v90
	v_exp_f32_e32 v91, v91
	v_mul_f32_e32 v84, v84, v88
	v_mul_f32_e32 v80, v80, v89
	v_mul_f32_e32 v85, v85, v90
	v_add_f32_e32 v88, 1.0, v91
	v_mul_f32_e32 v89, 0xbfb8aa3b, v86
	v_mul_f32_e32 v90, 0xbfb8aa3b, v82
	v_rcp_f32_e32 v88, v88
	v_exp_f32_e32 v89, v89
	v_exp_f32_e32 v90, v90
	v_mul_f32_e32 v91, 0xbfb8aa3b, v83
	v_mul_f32_e32 v81, v81, v88
	v_add_f32_e32 v88, 1.0, v89
	v_add_f32_e32 v89, 1.0, v90
	v_mul_f32_e32 v90, 0xbfb8aa3b, v87
	v_exp_f32_e32 v90, v90
	v_exp_f32_e32 v91, v91
	v_rcp_f32_e32 v88, v88
	v_rcp_f32_e32 v89, v89
	v_add_f32_e32 v90, 1.0, v90
	v_add_f32_e32 v91, 1.0, v91
	v_rcp_f32_e32 v90, v90
	v_rcp_f32_e32 v91, v91
	v_mul_f32_e32 v86, v86, v88
	v_mul_f32_e32 v82, v82, v89
	v_mul_f32_e32 v87, v87, v90
	v_mul_f32_e32 v83, v83, v91
	s_nop 0
	s_nop 0
	s_nop 0
	s_nop 0
	s_nop 0
	s_nop 0
	s_nop 0
	s_nop 0
	s_waitcnt lgkmcnt(0)
	s_nop 0
	v_mov_b32_e32 v88, v80
	s_nop 1
	v_permlane16_swap_b32_e32 v84, v88
	s_waitcnt lgkmcnt(0)
	s_nop 0
	v_mov_b32_e32 v80, v85
	v_mov_b32_e32 v85, v81
	s_nop 1
	v_permlane16_swap_b32_e32 v80, v85
	s_waitcnt lgkmcnt(0)
	s_nop 0
	v_mov_b32_e32 v81, v86
	v_mov_b32_e32 v86, v82
	s_nop 1
	v_permlane16_swap_b32_e32 v81, v86
	s_waitcnt lgkmcnt(0)
	s_nop 0
	v_mov_b32_e32 v82, v87
	s_nop 1
	v_permlane16_swap_b32_e32 v82, v83
	v_cvt_pk_bf16_f32 v80, v84, v80
	v_cvt_pk_bf16_f32 v81, v81, v82
	v_cvt_pk_bf16_f32 v82, v88, v85
	v_cvt_pk_bf16_f32 v83, v86, v83
	global_store_dwordx4 v[92:93], v[80:83], off offset:2752

.LBB0_591:
	s_or_b64 exec, exec, s[58:59]
	s_nop 0
	s_nop 0
	s_nop 0
	s_nop 0
	s_nop 0
	s_nop 0
	s_nop 0
	s_nop 0
	v_lshlrev_b64 v[96:97], 9, v[96:97]
	v_lshl_add_u64 v[96:97], s[14:15], 0, v[96:97]
	s_waitcnt lgkmcnt(0)
	s_nop 0
	v_mov_b32_e32 v99, v88
	s_nop 1
	v_permlane16_swap_b32_e32 v92, v99
	s_waitcnt lgkmcnt(0)
	s_nop 0
	v_mov_b32_e32 v88, v93
	v_mov_b32_e32 v93, v89
	s_nop 1
	v_permlane16_swap_b32_e32 v88, v93
	s_waitcnt lgkmcnt(0)
	s_nop 0
	v_mov_b32_e32 v89, v94
	v_mov_b32_e32 v94, v90
	s_nop 1
	v_permlane16_swap_b32_e32 v89, v94
	s_waitcnt lgkmcnt(0)
	s_nop 0
	v_lshl_add_u64 v[96:97], v[176:177], 1, v[96:97]
	v_mov_b32_e32 v90, v95
	s_nop 1
	v_permlane16_swap_b32_e32 v90, v91
	v_cvt_pk_bf16_f32 v88, v92, v88
	v_cvt_pk_bf16_f32 v89, v89, v90
	v_cvt_pk_bf16_f32 v90, v99, v93
	v_lshlrev_b32_e32 v92, 1, v180
	v_mov_b32_e32 v93, v177
	v_cvt_pk_bf16_f32 v91, v94, v91
	v_lshlrev_b32_e32 v94, 1, v179
	v_mov_b32_e32 v95, v177
	v_lshl_add_u64 v[92:93], v[96:97], 0, v[92:93]
	v_lshl_add_u64 v[92:93], v[92:93], 0, v[94:95]
	s_mov_b32 s58, 0xacff000
	v_add_co_u32_e32 v92, vcc, s58, v92
	s_nop 1
	v_addc_co_u32_e32 v93, vcc, 0, v93, vcc
	global_store_dwordx4 v[92:93], v[88:91], off offset:3328
	s_nop 1
	s_nop 0
	s_nop 0
	s_nop 0
	s_nop 0
	s_nop 0
	s_nop 0
	s_nop 0
	s_nop 0
	s_waitcnt lgkmcnt(0)
	s_nop 0
	v_mov_b32_e32 v88, v80
	s_nop 1
	v_permlane16_swap_b32_e32 v84, v88
	s_waitcnt lgkmcnt(0)
	s_nop 0
	v_mov_b32_e32 v80, v85
	v_mov_b32_e32 v85, v81
	s_nop 1
	v_permlane16_swap_b32_e32 v80, v85
	s_waitcnt lgkmcnt(0)
	s_nop 0
	v_mov_b32_e32 v81, v86
	v_mov_b32_e32 v86, v82
	s_nop 1
	v_permlane16_swap_b32_e32 v81, v86
	s_waitcnt lgkmcnt(0)
	s_nop 0
	v_mov_b32_e32 v82, v87
	s_nop 1
	v_permlane16_swap_b32_e32 v82, v83
	v_cvt_pk_bf16_f32 v80, v84, v80
	v_cvt_pk_bf16_f32 v81, v81, v82
	v_cvt_pk_bf16_f32 v82, v88, v85
	v_cvt_pk_bf16_f32 v83, v86, v83
	global_store_dwordx4 v[92:93], v[80:83], off offset:3392

.LBB0_595:
	s_or_b64 exec, exec, s[58:59]
	s_nop 0
	s_nop 0
	s_nop 0
	s_nop 0
	s_nop 0
	s_nop 0
	s_nop 0
	s_nop 0
	v_mov_b64_e32 v[100:101], s[4:5]
	s_movk_i32 vcc_lo, 0x300
	v_mad_i64_i32 v[100:101], s[58:59], v96, vcc_lo, v[100:101]
	v_lshlrev_b64 v[102:103], 1, v[134:135]
	s_waitcnt lgkmcnt(0)
	s_nop 0
	v_mov_b32_e32 v97, v88
	s_nop 1
	v_permlane16_swap_b32_e32 v92, v97
	s_waitcnt lgkmcnt(0)
	s_nop 0
	v_mov_b32_e32 v88, v93
	v_mov_b32_e32 v93, v89
	s_nop 1
	v_permlane16_swap_b32_e32 v88, v93
	s_waitcnt lgkmcnt(0)
	s_nop 0
	v_mov_b32_e32 v89, v94
	v_mov_b32_e32 v94, v90
	s_nop 1
	v_permlane16_swap_b32_e32 v89, v94
	s_waitcnt lgkmcnt(0)
	s_nop 0
	v_lshl_add_u64 v[100:101], v[100:101], 0, v[102:103]
	v_mov_b32_e32 v90, v95
	s_nop 1
	v_permlane16_swap_b32_e32 v90, v91
	v_cvt_pk_bf16_f32 v88, v92, v88
	v_cvt_pk_bf16_f32 v89, v89, v90
	v_cvt_pk_bf16_f32 v90, v97, v93
	v_lshlrev_b32_e32 v92, 1, v180
	v_mov_b32_e32 v93, v177
	v_cvt_pk_bf16_f32 v91, v94, v91
	v_lshl_add_u64 v[94:95], v[100:101], 0, v[92:93]
	v_lshlrev_b32_e32 v100, 1, v179
	v_mov_b32_e32 v101, v177
	v_lshl_add_u64 v[94:95], v[94:95], 0, v[100:101]
	global_store_dwordx4 v[94:95], v[88:91], off
	s_nop 0
	v_cndmask_b32_e64 v95, v87, v83, s[40:41]
	s_nop 0
	s_nop 0
	s_nop 0
	s_nop 0
	s_nop 0
	ds_bpermute_b32 v95, v98, v95
	v_mov_b64_e32 v[88:89], s[34:35]
	v_mad_i64_i32 v[88:89], s[58:59], v96, vcc_lo, v[88:89]
	v_lshl_add_u64 v[88:89], v[88:89], 0, v[102:103]
	s_waitcnt lgkmcnt(1)
	s_nop 0
	v_mov_b32_e32 v90, v80
	s_nop 1
	v_permlane16_swap_b32_e32 v84, v90
	s_waitcnt lgkmcnt(1)
	s_nop 0
	v_mov_b32_e32 v80, v85
	v_mov_b32_e32 v85, v81
	s_nop 1
	v_permlane16_swap_b32_e32 v80, v85
	s_waitcnt lgkmcnt(1)
	s_nop 0
	v_mov_b32_e32 v81, v86
	v_mov_b32_e32 v86, v82
	s_nop 1
	v_permlane16_swap_b32_e32 v81, v86
	s_waitcnt lgkmcnt(0)
	v_cndmask_b32_e64 v82, v95, v87, s[40:41]
	v_cvt_pk_bf16_f32 v80, v84, v80
	v_cvt_pk_bf16_f32 v81, v81, v82
	v_cvt_pk_bf16_f32 v82, v90, v85
	v_lshl_add_u64 v[84:85], v[88:89], 0, v[92:93]
	v_lshl_add_u64 v[84:85], v[84:85], 0, v[100:101]
	v_cndmask_b32_e64 v83, v83, v95, s[40:41]
	v_add_co_u32_e32 v84, vcc, 0xa700000, v84
	v_cvt_pk_bf16_f32 v83, v86, v83
	s_nop 0
	v_addc_co_u32_e32 v85, vcc, 0, v85, vcc
	global_store_dwordx4 v[84:85], v[80:83], off offset:64

.LBB0_597:
	s_or_b64 exec, exec, s[30:31]
	v_or_b32_e32 v84, 48, v182
	v_or_b32_e32 v80, v183, v84
	s_and_saveexec_b64 s[30:31], s[52:53]
	s_xor_b64 s[94:95], exec, s[30:31]
	s_cbranch_execz .LBB0_621
	s_and_saveexec_b64 s[30:31], s[50:51]
	s_xor_b64 s[30:31], exec, s[30:31]
	s_cbranch_execz .LBB0_600
	v_mul_f32_e32 v82, 0xbfb8aa3b, v76
	v_mul_f32_e32 v84, 0xbfb8aa3b, v72
	v_mul_f32_e32 v85, 0xbfb8aa3b, v77
	v_exp_f32_e32 v82, v82
	v_exp_f32_e32 v84, v84
	v_exp_f32_e32 v85, v85
	v_mul_f32_e32 v86, 0xbfb8aa3b, v73
	v_add_f32_e32 v82, 1.0, v82
	v_add_f32_e32 v84, 1.0, v84
	v_add_f32_e32 v85, 1.0, v85
	v_rcp_f32_e32 v82, v82
	v_rcp_f32_e32 v84, v84
	v_rcp_f32_e32 v85, v85
	v_exp_f32_e32 v86, v86
	v_mul_f32_e32 v82, v76, v82
	v_mul_f32_e32 v84, v72, v84
	v_mul_f32_e32 v85, v77, v85
	v_add_f32_e32 v72, 1.0, v86
	v_mul_f32_e32 v76, 0xbfb8aa3b, v78
	v_mul_f32_e32 v77, 0xbfb8aa3b, v74
	v_rcp_f32_e32 v72, v72
	v_exp_f32_e32 v76, v76
	v_exp_f32_e32 v77, v77
	v_ashrrev_i32_e32 v81, 31, v80
	v_mul_f32_e32 v86, v73, v72
	v_add_f32_e32 v72, 1.0, v76
	v_add_f32_e32 v73, 1.0, v77
	v_mul_f32_e32 v76, 0xbfb8aa3b, v79
	v_mul_f32_e32 v77, 0xbfb8aa3b, v75
	v_exp_f32_e32 v76, v76
	v_exp_f32_e32 v77, v77
	v_rcp_f32_e32 v72, v72
	v_rcp_f32_e32 v73, v73
	v_add_f32_e32 v76, 1.0, v76
	v_add_f32_e32 v77, 1.0, v77
	v_rcp_f32_e32 v76, v76
	v_rcp_f32_e32 v77, v77
	v_lshlrev_b64 v[80:81], 11, v[80:81]
	v_cmp_lt_i32_e32 vcc, v189, v202
	v_mul_f32_e32 v78, v78, v72
	v_mul_f32_e32 v74, v74, v73
	v_cndmask_b32_e32 v83, v203, v189, vcc
	v_mul_f32_e32 v79, v79, v76
	v_mul_f32_e32 v75, v75, v77
	v_lshl_add_u64 v[72:73], s[34:35], 0, v[80:81]
	v_lshlrev_b32_e32 v83, 2, v83
	v_lshl_add_u64 v[76:77], v[176:177], 1, v[72:73]
	s_nop 0
	s_nop 0
	s_nop 0
	s_nop 0
	s_nop 0
	s_nop 0
	s_nop 0
	s_nop 0
	s_mov_b32 s58, 0x96ff000
	s_waitcnt lgkmcnt(0)
	s_nop 0
	s_nop 1
	v_permlane16_swap_b32_e32 v82, v84
	s_waitcnt lgkmcnt(0)
	s_nop 0
	v_mov_b32_e32 v72, v85
	v_mov_b32_e32 v85, v86
	s_nop 1
	v_permlane16_swap_b32_e32 v72, v85
	s_waitcnt lgkmcnt(0)
	s_nop 0
	v_mov_b32_e32 v73, v78
	v_mov_b32_e32 v78, v74
	s_nop 1
	v_permlane16_swap_b32_e32 v73, v78
	s_waitcnt lgkmcnt(0)
	s_nop 0
	v_mov_b32_e32 v74, v79
	s_nop 1
	v_permlane16_swap_b32_e32 v74, v75
	v_cvt_pk_bf16_f32 v75, v78, v75
	v_lshlrev_b32_e32 v78, 1, v180
	v_mov_b32_e32 v79, v177
	v_lshlrev_b32_e32 v80, 1, v179
	v_mov_b32_e32 v81, v177
	v_lshl_add_u64 v[76:77], v[76:77], 0, v[78:79]
	v_lshl_add_u64 v[76:77], v[76:77], 0, v[80:81]
	v_add_co_u32_e32 v76, vcc, s58, v76
	v_cvt_pk_bf16_f32 v72, v82, v72
	v_cvt_pk_bf16_f32 v73, v73, v74
	v_cvt_pk_bf16_f32 v74, v84, v85
	v_addc_co_u32_e32 v77, vcc, 0, v77, vcc
	v_mul_f32_e32 v78, 0xbfb8aa3b, v68
	global_store_dwordx4 v[76:77], v[72:75], off offset:2688
	v_exp_f32_e32 v78, v78
	s_nop 0
	v_mul_f32_e32 v73, 0xbfb8aa3b, v64
	v_mul_f32_e32 v74, 0xbfb8aa3b, v69
	v_exp_f32_e32 v73, v73
	v_exp_f32_e32 v74, v74
	v_add_f32_e32 v72, 1.0, v78
	v_mul_f32_e32 v75, 0xbfb8aa3b, v65
	v_add_f32_e32 v73, 1.0, v73
	v_add_f32_e32 v74, 1.0, v74
	v_rcp_f32_e32 v72, v72
	v_rcp_f32_e32 v73, v73
	v_rcp_f32_e32 v74, v74
	v_exp_f32_e32 v75, v75
	v_mul_f32_e32 v68, v68, v72
	v_mul_f32_e32 v64, v64, v73
	v_mul_f32_e32 v69, v69, v74
	v_add_f32_e32 v72, 1.0, v75
	v_mul_f32_e32 v73, 0xbfb8aa3b, v70
	v_mul_f32_e32 v74, 0xbfb8aa3b, v66
	v_rcp_f32_e32 v72, v72
	v_exp_f32_e32 v73, v73
	v_exp_f32_e32 v74, v74
	v_mul_f32_e32 v75, 0xbfb8aa3b, v67
	v_mul_f32_e32 v65, v65, v72
	v_add_f32_e32 v72, 1.0, v73
	v_add_f32_e32 v73, 1.0, v74
	v_mul_f32_e32 v74, 0xbfb8aa3b, v71
	v_exp_f32_e32 v74, v74
	v_exp_f32_e32 v75, v75
	v_rcp_f32_e32 v72, v72
	v_rcp_f32_e32 v73, v73
	v_add_f32_e32 v74, 1.0, v74
	v_add_f32_e32 v75, 1.0, v75
	v_rcp_f32_e32 v74, v74
	v_rcp_f32_e32 v75, v75
	v_mul_f32_e32 v70, v70, v72
	v_mul_f32_e32 v66, v66, v73
	v_mul_f32_e32 v71, v71, v74
	v_mul_f32_e32 v67, v67, v75
	s_nop 0
	s_nop 0
	s_nop 0
	s_nop 0
	s_nop 0
	s_nop 0
	s_nop 0
	s_nop 0
	s_waitcnt lgkmcnt(0)
	s_nop 0
	v_mov_b32_e32 v72, v64
	s_nop 1
	v_permlane16_swap_b32_e32 v68, v72
	s_waitcnt lgkmcnt(0)
	s_nop 0
	v_mov_b32_e32 v64, v69
	v_mov_b32_e32 v69, v65
	s_nop 1
	v_permlane16_swap_b32_e32 v64, v69
	s_waitcnt lgkmcnt(0)
	s_nop 0
	v_mov_b32_e32 v65, v70
	v_mov_b32_e32 v70, v66
	s_nop 1
	v_permlane16_swap_b32_e32 v65, v70
	s_waitcnt lgkmcnt(0)
	s_nop 0
	v_mov_b32_e32 v66, v71
	s_nop 1
	v_permlane16_swap_b32_e32 v66, v67
	v_cvt_pk_bf16_f32 v64, v68, v64
	v_cvt_pk_bf16_f32 v65, v65, v66
	v_cvt_pk_bf16_f32 v66, v72, v69
	v_cvt_pk_bf16_f32 v67, v70, v67
	global_store_dwordx4 v[76:77], v[64:67], off offset:2752

.LBB0_627:
	s_or_b64 exec, exec, s[58:59]
	s_nop 0
	s_nop 0
	s_nop 0
	s_nop 0
	s_nop 0
	s_nop 0
	s_nop 0
	s_nop 0
	v_lshlrev_b64 v[80:81], 9, v[80:81]
	v_lshl_add_u64 v[80:81], s[14:15], 0, v[80:81]
	s_waitcnt lgkmcnt(0)
	s_nop 0
	v_mov_b32_e32 v83, v72
	s_nop 1
	v_permlane16_swap_b32_e32 v76, v83
	s_waitcnt lgkmcnt(0)
	s_nop 0
	v_mov_b32_e32 v72, v77
	v_mov_b32_e32 v77, v73
	s_nop 1
	v_permlane16_swap_b32_e32 v72, v77
	s_waitcnt lgkmcnt(0)
	s_nop 0
	v_mov_b32_e32 v73, v78
	v_mov_b32_e32 v78, v74
	s_nop 1
	v_permlane16_swap_b32_e32 v73, v78
	s_waitcnt lgkmcnt(0)
	s_nop 0
	v_lshl_add_u64 v[80:81], v[176:177], 1, v[80:81]
	v_mov_b32_e32 v74, v79
	s_nop 1
	v_permlane16_swap_b32_e32 v74, v75
	v_cvt_pk_bf16_f32 v72, v76, v72
	v_cvt_pk_bf16_f32 v73, v73, v74
	v_cvt_pk_bf16_f32 v74, v83, v77
	v_lshlrev_b32_e32 v76, 1, v180
	v_mov_b32_e32 v77, v177
	v_cvt_pk_bf16_f32 v75, v78, v75
	v_lshlrev_b32_e32 v78, 1, v179
	v_mov_b32_e32 v79, v177
	v_lshl_add_u64 v[76:77], v[80:81], 0, v[76:77]
	v_lshl_add_u64 v[76:77], v[76:77], 0, v[78:79]
	s_mov_b32 s58, 0xacff000
	v_add_co_u32_e32 v76, vcc, s58, v76
	s_nop 1
	v_addc_co_u32_e32 v77, vcc, 0, v77, vcc
	global_store_dwordx4 v[76:77], v[72:75], off offset:3328
	s_nop 1
	s_nop 0
	s_nop 0
	s_nop 0
	s_nop 0
	s_nop 0
	s_nop 0
	s_nop 0
	s_nop 0
	s_waitcnt lgkmcnt(0)
	s_nop 0
	v_mov_b32_e32 v72, v64
	s_nop 1
	v_permlane16_swap_b32_e32 v68, v72
	s_waitcnt lgkmcnt(0)
	s_nop 0
	v_mov_b32_e32 v64, v69
	v_mov_b32_e32 v69, v65
	s_nop 1
	v_permlane16_swap_b32_e32 v64, v69
	s_waitcnt lgkmcnt(0)
	s_nop 0
	v_mov_b32_e32 v65, v70
	v_mov_b32_e32 v70, v66
	s_nop 1
	v_permlane16_swap_b32_e32 v65, v70
	s_waitcnt lgkmcnt(0)
	s_nop 0
	v_mov_b32_e32 v66, v71
	s_nop 1
	v_permlane16_swap_b32_e32 v66, v67
	v_cvt_pk_bf16_f32 v64, v68, v64
	v_cvt_pk_bf16_f32 v65, v65, v66
	v_cvt_pk_bf16_f32 v66, v72, v69
	v_cvt_pk_bf16_f32 v67, v70, v67
	global_store_dwordx4 v[76:77], v[64:67], off offset:3392

.LBB0_631:
	s_or_b64 exec, exec, s[58:59]
	s_nop 0
	s_nop 0
	s_nop 0
	s_nop 0
	s_nop 0
	s_nop 0
	s_nop 0
	s_nop 0
	v_mov_b64_e32 v[84:85], s[4:5]
	s_movk_i32 vcc_lo, 0x300
	v_mad_i64_i32 v[84:85], s[58:59], v80, vcc_lo, v[84:85]
	v_lshlrev_b64 v[86:87], 1, v[134:135]
	s_waitcnt lgkmcnt(0)
	s_nop 0
	v_mov_b32_e32 v81, v72
	s_nop 1
	v_permlane16_swap_b32_e32 v76, v81
	s_waitcnt lgkmcnt(0)
	s_nop 0
	v_mov_b32_e32 v72, v77
	v_mov_b32_e32 v77, v73
	s_nop 1
	v_permlane16_swap_b32_e32 v72, v77
	s_waitcnt lgkmcnt(0)
	s_nop 0
	v_mov_b32_e32 v73, v78
	v_mov_b32_e32 v78, v74
	s_nop 1
	v_permlane16_swap_b32_e32 v73, v78
	s_waitcnt lgkmcnt(0)
	s_nop 0
	v_lshl_add_u64 v[84:85], v[84:85], 0, v[86:87]
	v_mov_b32_e32 v74, v79
	s_nop 1
	v_permlane16_swap_b32_e32 v74, v75
	v_cvt_pk_bf16_f32 v72, v76, v72
	v_cvt_pk_bf16_f32 v73, v73, v74
	v_cvt_pk_bf16_f32 v74, v81, v77
	v_lshlrev_b32_e32 v76, 1, v180
	v_mov_b32_e32 v77, v177
	v_cvt_pk_bf16_f32 v75, v78, v75
	v_lshl_add_u64 v[78:79], v[84:85], 0, v[76:77]
	v_lshlrev_b32_e32 v84, 1, v179
	v_mov_b32_e32 v85, v177
	v_lshl_add_u64 v[78:79], v[78:79], 0, v[84:85]
	global_store_dwordx4 v[78:79], v[72:75], off
	s_nop 0
	v_cndmask_b32_e64 v79, v71, v67, s[40:41]
	s_nop 0
	s_nop 0
	s_nop 0
	s_nop 0
	s_nop 0
	ds_bpermute_b32 v79, v82, v79
	v_mov_b64_e32 v[72:73], s[34:35]
	v_mad_i64_i32 v[72:73], s[58:59], v80, vcc_lo, v[72:73]
	v_lshl_add_u64 v[72:73], v[72:73], 0, v[86:87]
	s_waitcnt lgkmcnt(1)
	s_nop 0
	v_mov_b32_e32 v74, v64
	s_nop 1
	v_permlane16_swap_b32_e32 v68, v74
	s_waitcnt lgkmcnt(1)
	s_nop 0
	v_mov_b32_e32 v64, v69
	v_mov_b32_e32 v69, v65
	s_nop 1
	v_permlane16_swap_b32_e32 v64, v69
	s_waitcnt lgkmcnt(1)
	s_nop 0
	v_mov_b32_e32 v65, v70
	v_mov_b32_e32 v70, v66
	s_nop 1
	v_permlane16_swap_b32_e32 v65, v70
	s_waitcnt lgkmcnt(0)
	v_cndmask_b32_e64 v66, v79, v71, s[40:41]
	v_cvt_pk_bf16_f32 v64, v68, v64
	v_cvt_pk_bf16_f32 v65, v65, v66
	v_cvt_pk_bf16_f32 v66, v74, v69
	v_lshl_add_u64 v[68:69], v[72:73], 0, v[76:77]
	v_lshl_add_u64 v[68:69], v[68:69], 0, v[84:85]
	v_cndmask_b32_e64 v67, v67, v79, s[40:41]
	v_add_co_u32_e32 v68, vcc, 0xa700000, v68
	v_cvt_pk_bf16_f32 v67, v70, v67
	s_nop 0
	v_addc_co_u32_e32 v69, vcc, 0, v69, vcc
	global_store_dwordx4 v[68:69], v[64:67], off offset:64

.LBB0_633:
	s_or_b64 exec, exec, s[30:31]
	v_or_b32_e32 v68, 64, v182
	v_or_b32_e32 v64, v183, v68
	s_and_saveexec_b64 s[30:31], s[52:53]
	s_xor_b64 s[94:95], exec, s[30:31]
	s_cbranch_execz .LBB0_657
	s_and_saveexec_b64 s[30:31], s[50:51]
	s_xor_b64 s[30:31], exec, s[30:31]
	s_cbranch_execz .LBB0_636
	v_mul_f32_e32 v66, 0xbfb8aa3b, v60
	v_mul_f32_e32 v68, 0xbfb8aa3b, v56
	v_mul_f32_e32 v69, 0xbfb8aa3b, v61
	v_exp_f32_e32 v66, v66
	v_exp_f32_e32 v68, v68
	v_exp_f32_e32 v69, v69
	v_mul_f32_e32 v70, 0xbfb8aa3b, v57
	v_add_f32_e32 v66, 1.0, v66
	v_add_f32_e32 v68, 1.0, v68
	v_add_f32_e32 v69, 1.0, v69
	v_rcp_f32_e32 v66, v66
	v_rcp_f32_e32 v68, v68
	v_rcp_f32_e32 v69, v69
	v_exp_f32_e32 v70, v70
	v_mul_f32_e32 v66, v60, v66
	v_mul_f32_e32 v68, v56, v68
	v_mul_f32_e32 v69, v61, v69
	v_add_f32_e32 v56, 1.0, v70
	v_mul_f32_e32 v60, 0xbfb8aa3b, v62
	v_mul_f32_e32 v61, 0xbfb8aa3b, v58
	v_rcp_f32_e32 v56, v56
	v_exp_f32_e32 v60, v60
	v_exp_f32_e32 v61, v61
	v_ashrrev_i32_e32 v65, 31, v64
	v_mul_f32_e32 v70, v57, v56
	v_add_f32_e32 v56, 1.0, v60
	v_add_f32_e32 v57, 1.0, v61
	v_mul_f32_e32 v60, 0xbfb8aa3b, v63
	v_mul_f32_e32 v61, 0xbfb8aa3b, v59
	v_exp_f32_e32 v60, v60
	v_exp_f32_e32 v61, v61
	v_rcp_f32_e32 v56, v56
	v_rcp_f32_e32 v57, v57
	v_add_f32_e32 v60, 1.0, v60
	v_add_f32_e32 v61, 1.0, v61
	v_rcp_f32_e32 v60, v60
	v_rcp_f32_e32 v61, v61
	v_lshlrev_b64 v[64:65], 11, v[64:65]
	v_cmp_lt_i32_e32 vcc, v189, v202
	v_mul_f32_e32 v62, v62, v56
	v_mul_f32_e32 v58, v58, v57
	v_cndmask_b32_e32 v67, v203, v189, vcc
	v_mul_f32_e32 v63, v63, v60
	v_mul_f32_e32 v59, v59, v61
	v_lshl_add_u64 v[56:57], s[34:35], 0, v[64:65]
	v_lshlrev_b32_e32 v67, 2, v67
	v_lshl_add_u64 v[60:61], v[176:177], 1, v[56:57]
	s_nop 0
	s_nop 0
	s_nop 0
	s_nop 0
	s_nop 0
	s_nop 0
	s_nop 0
	s_nop 0
	s_mov_b32 s58, 0x96ff000
	s_waitcnt lgkmcnt(0)
	s_nop 0
	s_nop 1
	v_permlane16_swap_b32_e32 v66, v68
	s_waitcnt lgkmcnt(0)
	s_nop 0
	v_mov_b32_e32 v56, v69
	v_mov_b32_e32 v69, v70
	s_nop 1
	v_permlane16_swap_b32_e32 v56, v69
	s_waitcnt lgkmcnt(0)
	s_nop 0
	v_mov_b32_e32 v57, v62
	v_mov_b32_e32 v62, v58
	s_nop 1
	v_permlane16_swap_b32_e32 v57, v62
	s_waitcnt lgkmcnt(0)
	s_nop 0
	v_mov_b32_e32 v58, v63
	s_nop 1
	v_permlane16_swap_b32_e32 v58, v59
	v_cvt_pk_bf16_f32 v59, v62, v59
	v_lshlrev_b32_e32 v62, 1, v180
	v_mov_b32_e32 v63, v177
	v_lshlrev_b32_e32 v64, 1, v179
	v_mov_b32_e32 v65, v177
	v_lshl_add_u64 v[60:61], v[60:61], 0, v[62:63]
	v_lshl_add_u64 v[60:61], v[60:61], 0, v[64:65]
	v_add_co_u32_e32 v60, vcc, s58, v60
	v_cvt_pk_bf16_f32 v56, v66, v56
	v_cvt_pk_bf16_f32 v57, v57, v58
	v_cvt_pk_bf16_f32 v58, v68, v69
	v_addc_co_u32_e32 v61, vcc, 0, v61, vcc
	v_mul_f32_e32 v62, 0xbfb8aa3b, v52
	global_store_dwordx4 v[60:61], v[56:59], off offset:2688
	v_exp_f32_e32 v62, v62
	s_nop 0
	v_mul_f32_e32 v57, 0xbfb8aa3b, v48
	v_mul_f32_e32 v58, 0xbfb8aa3b, v53
	v_exp_f32_e32 v57, v57
	v_exp_f32_e32 v58, v58
	v_add_f32_e32 v56, 1.0, v62
	v_mul_f32_e32 v59, 0xbfb8aa3b, v49
	v_add_f32_e32 v57, 1.0, v57
	v_add_f32_e32 v58, 1.0, v58
	v_rcp_f32_e32 v56, v56
	v_rcp_f32_e32 v57, v57
	v_rcp_f32_e32 v58, v58
	v_exp_f32_e32 v59, v59
	v_mul_f32_e32 v52, v52, v56
	v_mul_f32_e32 v48, v48, v57
	v_mul_f32_e32 v53, v53, v58
	v_add_f32_e32 v56, 1.0, v59
	v_mul_f32_e32 v57, 0xbfb8aa3b, v54
	v_mul_f32_e32 v58, 0xbfb8aa3b, v50
	v_rcp_f32_e32 v56, v56
	v_exp_f32_e32 v57, v57
	v_exp_f32_e32 v58, v58
	v_mul_f32_e32 v59, 0xbfb8aa3b, v51
	v_mul_f32_e32 v49, v49, v56
	v_add_f32_e32 v56, 1.0, v57
	v_add_f32_e32 v57, 1.0, v58
	v_mul_f32_e32 v58, 0xbfb8aa3b, v55
	v_exp_f32_e32 v58, v58
	v_exp_f32_e32 v59, v59
	v_rcp_f32_e32 v56, v56
	v_rcp_f32_e32 v57, v57
	v_add_f32_e32 v58, 1.0, v58
	v_add_f32_e32 v59, 1.0, v59
	v_rcp_f32_e32 v58, v58
	v_rcp_f32_e32 v59, v59
	v_mul_f32_e32 v54, v54, v56
	v_mul_f32_e32 v50, v50, v57
	v_mul_f32_e32 v55, v55, v58
	v_mul_f32_e32 v51, v51, v59
	s_nop 0
	s_nop 0
	s_nop 0
	s_nop 0
	s_nop 0
	s_nop 0
	s_nop 0
	s_nop 0
	s_waitcnt lgkmcnt(0)
	s_nop 0
	v_mov_b32_e32 v56, v48
	s_nop 1
	v_permlane16_swap_b32_e32 v52, v56
	s_waitcnt lgkmcnt(0)
	s_nop 0
	v_mov_b32_e32 v48, v53
	v_mov_b32_e32 v53, v49
	s_nop 1
	v_permlane16_swap_b32_e32 v48, v53
	s_waitcnt lgkmcnt(0)
	s_nop 0
	v_mov_b32_e32 v49, v54
	v_mov_b32_e32 v54, v50
	s_nop 1
	v_permlane16_swap_b32_e32 v49, v54
	s_waitcnt lgkmcnt(0)
	s_nop 0
	v_mov_b32_e32 v50, v55
	s_nop 1
	v_permlane16_swap_b32_e32 v50, v51
	v_cvt_pk_bf16_f32 v48, v52, v48
	v_cvt_pk_bf16_f32 v49, v49, v50
	v_cvt_pk_bf16_f32 v50, v56, v53
	v_cvt_pk_bf16_f32 v51, v54, v51
	global_store_dwordx4 v[60:61], v[48:51], off offset:2752

.LBB0_663:
	s_or_b64 exec, exec, s[58:59]
	s_nop 0
	s_nop 0
	s_nop 0
	s_nop 0
	s_nop 0
	s_nop 0
	s_nop 0
	s_nop 0
	v_lshlrev_b64 v[64:65], 9, v[64:65]
	v_lshl_add_u64 v[64:65], s[14:15], 0, v[64:65]
	s_waitcnt lgkmcnt(0)
	s_nop 0
	v_mov_b32_e32 v67, v56
	s_nop 1
	v_permlane16_swap_b32_e32 v60, v67
	s_waitcnt lgkmcnt(0)
	s_nop 0
	v_mov_b32_e32 v56, v61
	v_mov_b32_e32 v61, v57
	s_nop 1
	v_permlane16_swap_b32_e32 v56, v61
	s_waitcnt lgkmcnt(0)
	s_nop 0
	v_mov_b32_e32 v57, v62
	v_mov_b32_e32 v62, v58
	s_nop 1
	v_permlane16_swap_b32_e32 v57, v62
	s_waitcnt lgkmcnt(0)
	s_nop 0
	v_lshl_add_u64 v[64:65], v[176:177], 1, v[64:65]
	v_mov_b32_e32 v58, v63
	s_nop 1
	v_permlane16_swap_b32_e32 v58, v59
	v_cvt_pk_bf16_f32 v56, v60, v56
	v_cvt_pk_bf16_f32 v57, v57, v58
	v_cvt_pk_bf16_f32 v58, v67, v61
	v_lshlrev_b32_e32 v60, 1, v180
	v_mov_b32_e32 v61, v177
	v_cvt_pk_bf16_f32 v59, v62, v59
	v_lshlrev_b32_e32 v62, 1, v179
	v_mov_b32_e32 v63, v177
	v_lshl_add_u64 v[60:61], v[64:65], 0, v[60:61]
	v_lshl_add_u64 v[60:61], v[60:61], 0, v[62:63]
	s_mov_b32 s58, 0xacff000
	v_add_co_u32_e32 v60, vcc, s58, v60
	s_nop 1
	v_addc_co_u32_e32 v61, vcc, 0, v61, vcc
	global_store_dwordx4 v[60:61], v[56:59], off offset:3328
	s_nop 1
	s_nop 0
	s_nop 0
	s_nop 0
	s_nop 0
	s_nop 0
	s_nop 0
	s_nop 0
	s_nop 0
	s_waitcnt lgkmcnt(0)
	s_nop 0
	v_mov_b32_e32 v56, v48
	s_nop 1
	v_permlane16_swap_b32_e32 v52, v56
	s_waitcnt lgkmcnt(0)
	s_nop 0
	v_mov_b32_e32 v48, v53
	v_mov_b32_e32 v53, v49
	s_nop 1
	v_permlane16_swap_b32_e32 v48, v53
	s_waitcnt lgkmcnt(0)
	s_nop 0
	v_mov_b32_e32 v49, v54
	v_mov_b32_e32 v54, v50
	s_nop 1
	v_permlane16_swap_b32_e32 v49, v54
	s_waitcnt lgkmcnt(0)
	s_nop 0
	v_mov_b32_e32 v50, v55
	s_nop 1
	v_permlane16_swap_b32_e32 v50, v51
	v_cvt_pk_bf16_f32 v48, v52, v48
	v_cvt_pk_bf16_f32 v49, v49, v50
	v_cvt_pk_bf16_f32 v50, v56, v53
	v_cvt_pk_bf16_f32 v51, v54, v51
	global_store_dwordx4 v[60:61], v[48:51], off offset:3392

.LBB0_667:
	s_or_b64 exec, exec, s[58:59]
	s_nop 0
	s_nop 0
	s_nop 0
	s_nop 0
	s_nop 0
	s_nop 0
	s_nop 0
	s_nop 0
	v_mov_b64_e32 v[68:69], s[4:5]
	s_movk_i32 vcc_lo, 0x300
	v_mad_i64_i32 v[68:69], s[58:59], v64, vcc_lo, v[68:69]
	v_lshlrev_b64 v[70:71], 1, v[134:135]
	s_waitcnt lgkmcnt(0)
	s_nop 0
	v_mov_b32_e32 v65, v56
	s_nop 1
	v_permlane16_swap_b32_e32 v60, v65
	s_waitcnt lgkmcnt(0)
	s_nop 0
	v_mov_b32_e32 v56, v61
	v_mov_b32_e32 v61, v57
	s_nop 1
	v_permlane16_swap_b32_e32 v56, v61
	s_waitcnt lgkmcnt(0)
	s_nop 0
	v_mov_b32_e32 v57, v62
	v_mov_b32_e32 v62, v58
	s_nop 1
	v_permlane16_swap_b32_e32 v57, v62
	s_waitcnt lgkmcnt(0)
	s_nop 0
	v_lshl_add_u64 v[68:69], v[68:69], 0, v[70:71]
	v_mov_b32_e32 v58, v63
	s_nop 1
	v_permlane16_swap_b32_e32 v58, v59
	v_cvt_pk_bf16_f32 v56, v60, v56
	v_cvt_pk_bf16_f32 v57, v57, v58
	v_cvt_pk_bf16_f32 v58, v65, v61
	v_lshlrev_b32_e32 v60, 1, v180
	v_mov_b32_e32 v61, v177
	v_cvt_pk_bf16_f32 v59, v62, v59
	v_lshl_add_u64 v[62:63], v[68:69], 0, v[60:61]
	v_lshlrev_b32_e32 v68, 1, v179
	v_mov_b32_e32 v69, v177
	v_lshl_add_u64 v[62:63], v[62:63], 0, v[68:69]
	global_store_dwordx4 v[62:63], v[56:59], off
	s_nop 0
	v_cndmask_b32_e64 v63, v55, v51, s[40:41]
	s_nop 0
	s_nop 0
	s_nop 0
	s_nop 0
	s_nop 0
	ds_bpermute_b32 v63, v66, v63
	v_mov_b64_e32 v[56:57], s[34:35]
	v_mad_i64_i32 v[56:57], s[58:59], v64, vcc_lo, v[56:57]
	v_lshl_add_u64 v[56:57], v[56:57], 0, v[70:71]
	s_waitcnt lgkmcnt(1)
	s_nop 0
	v_mov_b32_e32 v58, v48
	s_nop 1
	v_permlane16_swap_b32_e32 v52, v58
	s_waitcnt lgkmcnt(1)
	s_nop 0
	v_mov_b32_e32 v48, v53
	v_mov_b32_e32 v53, v49
	s_nop 1
	v_permlane16_swap_b32_e32 v48, v53
	s_waitcnt lgkmcnt(1)
	s_nop 0
	v_mov_b32_e32 v49, v54
	v_mov_b32_e32 v54, v50
	s_nop 1
	v_permlane16_swap_b32_e32 v49, v54
	s_waitcnt lgkmcnt(0)
	v_cndmask_b32_e64 v50, v63, v55, s[40:41]
	v_cvt_pk_bf16_f32 v48, v52, v48
	v_cvt_pk_bf16_f32 v49, v49, v50
	v_cvt_pk_bf16_f32 v50, v58, v53
	v_lshl_add_u64 v[52:53], v[56:57], 0, v[60:61]
	v_lshl_add_u64 v[52:53], v[52:53], 0, v[68:69]
	v_cndmask_b32_e64 v51, v51, v63, s[40:41]
	v_add_co_u32_e32 v52, vcc, 0xa700000, v52
	v_cvt_pk_bf16_f32 v51, v54, v51
	s_nop 0
	v_addc_co_u32_e32 v53, vcc, 0, v53, vcc
	global_store_dwordx4 v[52:53], v[48:51], off offset:64

.LBB0_669:
	s_or_b64 exec, exec, s[30:31]
	v_or_b32_e32 v52, 0x50, v182
	v_or_b32_e32 v48, v183, v52
	s_and_saveexec_b64 s[30:31], s[52:53]
	s_xor_b64 s[94:95], exec, s[30:31]
	s_cbranch_execz .LBB0_693
	s_and_saveexec_b64 s[30:31], s[50:51]
	s_xor_b64 s[30:31], exec, s[30:31]
	s_cbranch_execz .LBB0_672
	v_mul_f32_e32 v50, 0xbfb8aa3b, v44
	v_mul_f32_e32 v52, 0xbfb8aa3b, v40
	v_mul_f32_e32 v53, 0xbfb8aa3b, v45
	v_exp_f32_e32 v50, v50
	v_exp_f32_e32 v52, v52
	v_exp_f32_e32 v53, v53
	v_mul_f32_e32 v54, 0xbfb8aa3b, v41
	v_add_f32_e32 v50, 1.0, v50
	v_add_f32_e32 v52, 1.0, v52
	v_add_f32_e32 v53, 1.0, v53
	v_rcp_f32_e32 v50, v50
	v_rcp_f32_e32 v52, v52
	v_rcp_f32_e32 v53, v53
	v_exp_f32_e32 v54, v54
	v_mul_f32_e32 v50, v44, v50
	v_mul_f32_e32 v52, v40, v52
	v_mul_f32_e32 v53, v45, v53
	v_add_f32_e32 v40, 1.0, v54
	v_mul_f32_e32 v44, 0xbfb8aa3b, v46
	v_mul_f32_e32 v45, 0xbfb8aa3b, v42
	v_rcp_f32_e32 v40, v40
	v_exp_f32_e32 v44, v44
	v_exp_f32_e32 v45, v45
	v_ashrrev_i32_e32 v49, 31, v48
	v_mul_f32_e32 v54, v41, v40
	v_add_f32_e32 v40, 1.0, v44
	v_add_f32_e32 v41, 1.0, v45
	v_mul_f32_e32 v44, 0xbfb8aa3b, v47
	v_mul_f32_e32 v45, 0xbfb8aa3b, v43
	v_exp_f32_e32 v44, v44
	v_exp_f32_e32 v45, v45
	v_rcp_f32_e32 v40, v40
	v_rcp_f32_e32 v41, v41
	v_add_f32_e32 v44, 1.0, v44
	v_add_f32_e32 v45, 1.0, v45
	v_rcp_f32_e32 v44, v44
	v_rcp_f32_e32 v45, v45
	v_lshlrev_b64 v[48:49], 11, v[48:49]
	v_cmp_lt_i32_e32 vcc, v189, v202
	v_mul_f32_e32 v46, v46, v40
	v_mul_f32_e32 v42, v42, v41
	v_cndmask_b32_e32 v51, v203, v189, vcc
	v_mul_f32_e32 v47, v47, v44
	v_mul_f32_e32 v43, v43, v45
	v_lshl_add_u64 v[40:41], s[34:35], 0, v[48:49]
	v_lshlrev_b32_e32 v51, 2, v51
	v_lshl_add_u64 v[44:45], v[176:177], 1, v[40:41]
	s_nop 0
	s_nop 0
	s_nop 0
	s_nop 0
	s_nop 0
	s_nop 0
	s_nop 0
	s_nop 0
	s_mov_b32 s58, 0x96ff000
	s_waitcnt lgkmcnt(0)
	s_nop 0
	s_nop 1
	v_permlane16_swap_b32_e32 v50, v52
	s_waitcnt lgkmcnt(0)
	s_nop 0
	v_mov_b32_e32 v40, v53
	v_mov_b32_e32 v53, v54
	s_nop 1
	v_permlane16_swap_b32_e32 v40, v53
	s_waitcnt lgkmcnt(0)
	s_nop 0
	v_mov_b32_e32 v41, v46
	v_mov_b32_e32 v46, v42
	s_nop 1
	v_permlane16_swap_b32_e32 v41, v46
	s_waitcnt lgkmcnt(0)
	s_nop 0
	v_mov_b32_e32 v42, v47
	s_nop 1
	v_permlane16_swap_b32_e32 v42, v43
	v_cvt_pk_bf16_f32 v43, v46, v43
	v_lshlrev_b32_e32 v46, 1, v180
	v_mov_b32_e32 v47, v177
	v_lshlrev_b32_e32 v48, 1, v179
	v_mov_b32_e32 v49, v177
	v_lshl_add_u64 v[44:45], v[44:45], 0, v[46:47]
	v_lshl_add_u64 v[44:45], v[44:45], 0, v[48:49]
	v_add_co_u32_e32 v44, vcc, s58, v44
	v_cvt_pk_bf16_f32 v40, v50, v40
	v_cvt_pk_bf16_f32 v41, v41, v42
	v_cvt_pk_bf16_f32 v42, v52, v53
	v_addc_co_u32_e32 v45, vcc, 0, v45, vcc
	v_mul_f32_e32 v46, 0xbfb8aa3b, v36
	global_store_dwordx4 v[44:45], v[40:43], off offset:2688
	v_exp_f32_e32 v46, v46
	s_nop 0
	v_mul_f32_e32 v41, 0xbfb8aa3b, v32
	v_mul_f32_e32 v42, 0xbfb8aa3b, v37
	v_exp_f32_e32 v41, v41
	v_exp_f32_e32 v42, v42
	v_add_f32_e32 v40, 1.0, v46
	v_mul_f32_e32 v43, 0xbfb8aa3b, v33
	v_add_f32_e32 v41, 1.0, v41
	v_add_f32_e32 v42, 1.0, v42
	v_rcp_f32_e32 v40, v40
	v_rcp_f32_e32 v41, v41
	v_rcp_f32_e32 v42, v42
	v_exp_f32_e32 v43, v43
	v_mul_f32_e32 v36, v36, v40
	v_mul_f32_e32 v32, v32, v41
	v_mul_f32_e32 v37, v37, v42
	v_add_f32_e32 v40, 1.0, v43
	v_mul_f32_e32 v41, 0xbfb8aa3b, v38
	v_mul_f32_e32 v42, 0xbfb8aa3b, v34
	v_rcp_f32_e32 v40, v40
	v_exp_f32_e32 v41, v41
	v_exp_f32_e32 v42, v42
	v_mul_f32_e32 v43, 0xbfb8aa3b, v35
	v_mul_f32_e32 v33, v33, v40
	v_add_f32_e32 v40, 1.0, v41
	v_add_f32_e32 v41, 1.0, v42
	v_mul_f32_e32 v42, 0xbfb8aa3b, v39
	v_exp_f32_e32 v42, v42
	v_exp_f32_e32 v43, v43
	v_rcp_f32_e32 v40, v40
	v_rcp_f32_e32 v41, v41
	v_add_f32_e32 v42, 1.0, v42
	v_add_f32_e32 v43, 1.0, v43
	v_rcp_f32_e32 v42, v42
	v_rcp_f32_e32 v43, v43
	v_mul_f32_e32 v38, v38, v40
	v_mul_f32_e32 v34, v34, v41
	v_mul_f32_e32 v39, v39, v42
	v_mul_f32_e32 v35, v35, v43
	s_nop 0
	s_nop 0
	s_nop 0
	s_nop 0
	s_nop 0
	s_nop 0
	s_nop 0
	s_nop 0
	s_waitcnt lgkmcnt(0)
	s_nop 0
	v_mov_b32_e32 v40, v32
	s_nop 1
	v_permlane16_swap_b32_e32 v36, v40
	s_waitcnt lgkmcnt(0)
	s_nop 0
	v_mov_b32_e32 v32, v37
	v_mov_b32_e32 v37, v33
	s_nop 1
	v_permlane16_swap_b32_e32 v32, v37
	s_waitcnt lgkmcnt(0)
	s_nop 0
	v_mov_b32_e32 v33, v38
	v_mov_b32_e32 v38, v34
	s_nop 1
	v_permlane16_swap_b32_e32 v33, v38
	s_waitcnt lgkmcnt(0)
	s_nop 0
	v_mov_b32_e32 v34, v39
	s_nop 1
	v_permlane16_swap_b32_e32 v34, v35
	v_cvt_pk_bf16_f32 v32, v36, v32
	v_cvt_pk_bf16_f32 v33, v33, v34
	v_cvt_pk_bf16_f32 v34, v40, v37
	v_cvt_pk_bf16_f32 v35, v38, v35
	global_store_dwordx4 v[44:45], v[32:35], off offset:2752

.LBB0_699:
	s_or_b64 exec, exec, s[58:59]
	s_nop 0
	s_nop 0
	s_nop 0
	s_nop 0
	s_nop 0
	s_nop 0
	s_nop 0
	s_nop 0
	v_lshlrev_b64 v[48:49], 9, v[48:49]
	v_lshl_add_u64 v[48:49], s[14:15], 0, v[48:49]
	s_waitcnt lgkmcnt(0)
	s_nop 0
	v_mov_b32_e32 v51, v40
	s_nop 1
	v_permlane16_swap_b32_e32 v44, v51
	s_waitcnt lgkmcnt(0)
	s_nop 0
	v_mov_b32_e32 v40, v45
	v_mov_b32_e32 v45, v41
	s_nop 1
	v_permlane16_swap_b32_e32 v40, v45
	s_waitcnt lgkmcnt(0)
	s_nop 0
	v_mov_b32_e32 v41, v46
	v_mov_b32_e32 v46, v42
	s_nop 1
	v_permlane16_swap_b32_e32 v41, v46
	s_waitcnt lgkmcnt(0)
	s_nop 0
	v_lshl_add_u64 v[48:49], v[176:177], 1, v[48:49]
	v_mov_b32_e32 v42, v47
	s_nop 1
	v_permlane16_swap_b32_e32 v42, v43
	v_cvt_pk_bf16_f32 v40, v44, v40
	v_cvt_pk_bf16_f32 v41, v41, v42
	v_cvt_pk_bf16_f32 v42, v51, v45
	v_lshlrev_b32_e32 v44, 1, v180
	v_mov_b32_e32 v45, v177
	v_cvt_pk_bf16_f32 v43, v46, v43
	v_lshlrev_b32_e32 v46, 1, v179
	v_mov_b32_e32 v47, v177
	v_lshl_add_u64 v[44:45], v[48:49], 0, v[44:45]
	v_lshl_add_u64 v[44:45], v[44:45], 0, v[46:47]
	s_mov_b32 s58, 0xacff000
	v_add_co_u32_e32 v44, vcc, s58, v44
	s_nop 1
	v_addc_co_u32_e32 v45, vcc, 0, v45, vcc
	global_store_dwordx4 v[44:45], v[40:43], off offset:3328
	s_nop 1
	s_nop 0
	s_nop 0
	s_nop 0
	s_nop 0
	s_nop 0
	s_nop 0
	s_nop 0
	s_nop 0
	s_waitcnt lgkmcnt(0)
	s_nop 0
	v_mov_b32_e32 v40, v32
	s_nop 1
	v_permlane16_swap_b32_e32 v36, v40
	s_waitcnt lgkmcnt(0)
	s_nop 0
	v_mov_b32_e32 v32, v37
	v_mov_b32_e32 v37, v33
	s_nop 1
	v_permlane16_swap_b32_e32 v32, v37
	s_waitcnt lgkmcnt(0)
	s_nop 0
	v_mov_b32_e32 v33, v38
	v_mov_b32_e32 v38, v34
	s_nop 1
	v_permlane16_swap_b32_e32 v33, v38
	s_waitcnt lgkmcnt(0)
	s_nop 0
	v_mov_b32_e32 v34, v39
	s_nop 1
	v_permlane16_swap_b32_e32 v34, v35
	v_cvt_pk_bf16_f32 v32, v36, v32
	v_cvt_pk_bf16_f32 v33, v33, v34
	v_cvt_pk_bf16_f32 v34, v40, v37
	v_cvt_pk_bf16_f32 v35, v38, v35
	global_store_dwordx4 v[44:45], v[32:35], off offset:3392

.LBB0_703:
	s_or_b64 exec, exec, s[58:59]
	s_nop 0
	s_nop 0
	s_nop 0
	s_nop 0
	s_nop 0
	s_nop 0
	s_nop 0
	s_nop 0
	v_mov_b64_e32 v[52:53], s[4:5]
	s_movk_i32 vcc_lo, 0x300
	v_mad_i64_i32 v[52:53], s[58:59], v48, vcc_lo, v[52:53]
	v_lshlrev_b64 v[54:55], 1, v[134:135]
	s_waitcnt lgkmcnt(0)
	s_nop 0
	v_mov_b32_e32 v49, v40
	s_nop 1
	v_permlane16_swap_b32_e32 v44, v49
	s_waitcnt lgkmcnt(0)
	s_nop 0
	v_mov_b32_e32 v40, v45
	v_mov_b32_e32 v45, v41
	s_nop 1
	v_permlane16_swap_b32_e32 v40, v45
	s_waitcnt lgkmcnt(0)
	s_nop 0
	v_mov_b32_e32 v41, v46
	v_mov_b32_e32 v46, v42
	s_nop 1
	v_permlane16_swap_b32_e32 v41, v46
	s_waitcnt lgkmcnt(0)
	s_nop 0
	v_lshl_add_u64 v[52:53], v[52:53], 0, v[54:55]
	v_mov_b32_e32 v42, v47
	s_nop 1
	v_permlane16_swap_b32_e32 v42, v43
	v_cvt_pk_bf16_f32 v40, v44, v40
	v_cvt_pk_bf16_f32 v41, v41, v42
	v_cvt_pk_bf16_f32 v42, v49, v45
	v_lshlrev_b32_e32 v44, 1, v180
	v_mov_b32_e32 v45, v177
	v_cvt_pk_bf16_f32 v43, v46, v43
	v_lshl_add_u64 v[46:47], v[52:53], 0, v[44:45]
	v_lshlrev_b32_e32 v52, 1, v179
	v_mov_b32_e32 v53, v177
	v_lshl_add_u64 v[46:47], v[46:47], 0, v[52:53]
	global_store_dwordx4 v[46:47], v[40:43], off
	s_nop 0
	v_cndmask_b32_e64 v47, v39, v35, s[40:41]
	s_nop 0
	s_nop 0
	s_nop 0
	s_nop 0
	s_nop 0
	ds_bpermute_b32 v47, v50, v47
	v_mov_b64_e32 v[40:41], s[34:35]
	v_mad_i64_i32 v[40:41], s[58:59], v48, vcc_lo, v[40:41]
	v_lshl_add_u64 v[40:41], v[40:41], 0, v[54:55]
	s_waitcnt lgkmcnt(1)
	s_nop 0
	v_mov_b32_e32 v42, v32
	s_nop 1
	v_permlane16_swap_b32_e32 v36, v42
	s_waitcnt lgkmcnt(1)
	s_nop 0
	v_mov_b32_e32 v32, v37
	v_mov_b32_e32 v37, v33
	s_nop 1
	v_permlane16_swap_b32_e32 v32, v37
	s_waitcnt lgkmcnt(1)
	s_nop 0
	v_mov_b32_e32 v33, v38
	v_mov_b32_e32 v38, v34
	s_nop 1
	v_permlane16_swap_b32_e32 v33, v38
	s_waitcnt lgkmcnt(0)
	v_cndmask_b32_e64 v34, v47, v39, s[40:41]
	v_cvt_pk_bf16_f32 v32, v36, v32
	v_cvt_pk_bf16_f32 v33, v33, v34
	v_cvt_pk_bf16_f32 v34, v42, v37
	v_lshl_add_u64 v[36:37], v[40:41], 0, v[44:45]
	v_lshl_add_u64 v[36:37], v[36:37], 0, v[52:53]
	v_cndmask_b32_e64 v35, v35, v47, s[40:41]
	v_add_co_u32_e32 v36, vcc, 0xa700000, v36
	v_cvt_pk_bf16_f32 v35, v38, v35
	s_nop 0
	v_addc_co_u32_e32 v37, vcc, 0, v37, vcc
	global_store_dwordx4 v[36:37], v[32:35], off offset:64

.LBB0_705:
	s_or_b64 exec, exec, s[30:31]
	v_or_b32_e32 v36, 0x60, v182
	v_or_b32_e32 v32, v183, v36
	s_and_saveexec_b64 s[30:31], s[52:53]
	s_xor_b64 s[94:95], exec, s[30:31]
	s_cbranch_execz .LBB0_729
	s_and_saveexec_b64 s[30:31], s[50:51]
	s_xor_b64 s[30:31], exec, s[30:31]
	s_cbranch_execz .LBB0_708
	v_mul_f32_e32 v34, 0xbfb8aa3b, v28
	v_mul_f32_e32 v36, 0xbfb8aa3b, v24
	v_mul_f32_e32 v37, 0xbfb8aa3b, v29
	v_exp_f32_e32 v34, v34
	v_exp_f32_e32 v36, v36
	v_exp_f32_e32 v37, v37
	v_mul_f32_e32 v38, 0xbfb8aa3b, v25
	v_add_f32_e32 v34, 1.0, v34
	v_add_f32_e32 v36, 1.0, v36
	v_add_f32_e32 v37, 1.0, v37
	v_rcp_f32_e32 v34, v34
	v_rcp_f32_e32 v36, v36
	v_rcp_f32_e32 v37, v37
	v_exp_f32_e32 v38, v38
	v_mul_f32_e32 v34, v28, v34
	v_mul_f32_e32 v36, v24, v36
	v_mul_f32_e32 v37, v29, v37
	v_add_f32_e32 v24, 1.0, v38
	v_mul_f32_e32 v28, 0xbfb8aa3b, v30
	v_mul_f32_e32 v29, 0xbfb8aa3b, v26
	v_rcp_f32_e32 v24, v24
	v_exp_f32_e32 v28, v28
	v_exp_f32_e32 v29, v29
	v_ashrrev_i32_e32 v33, 31, v32
	v_mul_f32_e32 v38, v25, v24
	v_add_f32_e32 v24, 1.0, v28
	v_add_f32_e32 v25, 1.0, v29
	v_mul_f32_e32 v28, 0xbfb8aa3b, v31
	v_mul_f32_e32 v29, 0xbfb8aa3b, v27
	v_exp_f32_e32 v28, v28
	v_exp_f32_e32 v29, v29
	v_rcp_f32_e32 v24, v24
	v_rcp_f32_e32 v25, v25
	v_add_f32_e32 v28, 1.0, v28
	v_add_f32_e32 v29, 1.0, v29
	v_rcp_f32_e32 v28, v28
	v_rcp_f32_e32 v29, v29
	v_lshlrev_b64 v[32:33], 11, v[32:33]
	v_cmp_lt_i32_e32 vcc, v189, v202
	v_mul_f32_e32 v30, v30, v24
	v_mul_f32_e32 v26, v26, v25
	v_cndmask_b32_e32 v35, v203, v189, vcc
	v_mul_f32_e32 v31, v31, v28
	v_mul_f32_e32 v27, v27, v29
	v_lshl_add_u64 v[24:25], s[34:35], 0, v[32:33]
	v_lshlrev_b32_e32 v35, 2, v35
	v_lshl_add_u64 v[28:29], v[176:177], 1, v[24:25]
	s_nop 0
	s_nop 0
	s_nop 0
	s_nop 0
	s_nop 0
	s_nop 0
	s_nop 0
	s_nop 0
	s_mov_b32 s58, 0x96ff000
	s_waitcnt lgkmcnt(0)
	s_nop 0
	s_nop 1
	v_permlane16_swap_b32_e32 v34, v36
	s_waitcnt lgkmcnt(0)
	s_nop 0
	v_mov_b32_e32 v24, v37
	v_mov_b32_e32 v37, v38
	s_nop 1
	v_permlane16_swap_b32_e32 v24, v37
	s_waitcnt lgkmcnt(0)
	s_nop 0
	v_mov_b32_e32 v25, v30
	v_mov_b32_e32 v30, v26
	s_nop 1
	v_permlane16_swap_b32_e32 v25, v30
	s_waitcnt lgkmcnt(0)
	s_nop 0
	v_mov_b32_e32 v26, v31
	s_nop 1
	v_permlane16_swap_b32_e32 v26, v27
	v_cvt_pk_bf16_f32 v27, v30, v27
	v_lshlrev_b32_e32 v30, 1, v180
	v_mov_b32_e32 v31, v177
	v_lshlrev_b32_e32 v32, 1, v179
	v_mov_b32_e32 v33, v177
	v_lshl_add_u64 v[28:29], v[28:29], 0, v[30:31]
	v_lshl_add_u64 v[28:29], v[28:29], 0, v[32:33]
	v_add_co_u32_e32 v28, vcc, s58, v28
	v_cvt_pk_bf16_f32 v24, v34, v24
	v_cvt_pk_bf16_f32 v25, v25, v26
	v_cvt_pk_bf16_f32 v26, v36, v37
	v_addc_co_u32_e32 v29, vcc, 0, v29, vcc
	v_mul_f32_e32 v30, 0xbfb8aa3b, v20
	global_store_dwordx4 v[28:29], v[24:27], off offset:2688
	v_exp_f32_e32 v30, v30
	s_nop 0
	v_mul_f32_e32 v25, 0xbfb8aa3b, v16
	v_mul_f32_e32 v26, 0xbfb8aa3b, v21
	v_exp_f32_e32 v25, v25
	v_exp_f32_e32 v26, v26
	v_add_f32_e32 v24, 1.0, v30
	v_mul_f32_e32 v27, 0xbfb8aa3b, v17
	v_add_f32_e32 v25, 1.0, v25
	v_add_f32_e32 v26, 1.0, v26
	v_rcp_f32_e32 v24, v24
	v_rcp_f32_e32 v25, v25
	v_rcp_f32_e32 v26, v26
	v_exp_f32_e32 v27, v27
	v_mul_f32_e32 v20, v20, v24
	v_mul_f32_e32 v16, v16, v25
	v_mul_f32_e32 v21, v21, v26
	v_add_f32_e32 v24, 1.0, v27
	v_mul_f32_e32 v25, 0xbfb8aa3b, v22
	v_mul_f32_e32 v26, 0xbfb8aa3b, v18
	v_rcp_f32_e32 v24, v24
	v_exp_f32_e32 v25, v25
	v_exp_f32_e32 v26, v26
	v_mul_f32_e32 v27, 0xbfb8aa3b, v19
	v_mul_f32_e32 v17, v17, v24
	v_add_f32_e32 v24, 1.0, v25
	v_add_f32_e32 v25, 1.0, v26
	v_mul_f32_e32 v26, 0xbfb8aa3b, v23
	v_exp_f32_e32 v26, v26
	v_exp_f32_e32 v27, v27
	v_rcp_f32_e32 v24, v24
	v_rcp_f32_e32 v25, v25
	v_add_f32_e32 v26, 1.0, v26
	v_add_f32_e32 v27, 1.0, v27
	v_rcp_f32_e32 v26, v26
	v_rcp_f32_e32 v27, v27
	v_mul_f32_e32 v22, v22, v24
	v_mul_f32_e32 v18, v18, v25
	v_mul_f32_e32 v23, v23, v26
	v_mul_f32_e32 v19, v19, v27
	s_nop 0
	s_nop 0
	s_nop 0
	s_nop 0
	s_nop 0
	s_nop 0
	s_nop 0
	s_nop 0
	s_waitcnt lgkmcnt(0)
	s_nop 0
	v_mov_b32_e32 v24, v16
	s_nop 1
	v_permlane16_swap_b32_e32 v20, v24
	s_waitcnt lgkmcnt(0)
	s_nop 0
	v_mov_b32_e32 v16, v21
	v_mov_b32_e32 v21, v17
	s_nop 1
	v_permlane16_swap_b32_e32 v16, v21
	s_waitcnt lgkmcnt(0)
	s_nop 0
	v_mov_b32_e32 v17, v22
	v_mov_b32_e32 v22, v18
	s_nop 1
	v_permlane16_swap_b32_e32 v17, v22
	s_waitcnt lgkmcnt(0)
	s_nop 0
	v_mov_b32_e32 v18, v23
	s_nop 1
	v_permlane16_swap_b32_e32 v18, v19
	v_cvt_pk_bf16_f32 v16, v20, v16
	v_cvt_pk_bf16_f32 v17, v17, v18
	v_cvt_pk_bf16_f32 v18, v24, v21
	v_cvt_pk_bf16_f32 v19, v22, v19
	global_store_dwordx4 v[28:29], v[16:19], off offset:2752

.LBB0_735:
	s_or_b64 exec, exec, s[58:59]
	s_nop 0
	s_nop 0
	s_nop 0
	s_nop 0
	s_nop 0
	s_nop 0
	s_nop 0
	s_nop 0
	v_lshlrev_b64 v[32:33], 9, v[32:33]
	v_lshl_add_u64 v[32:33], s[14:15], 0, v[32:33]
	s_waitcnt lgkmcnt(0)
	s_nop 0
	v_mov_b32_e32 v35, v24
	s_nop 1
	v_permlane16_swap_b32_e32 v28, v35
	s_waitcnt lgkmcnt(0)
	s_nop 0
	v_mov_b32_e32 v24, v29
	v_mov_b32_e32 v29, v25
	s_nop 1
	v_permlane16_swap_b32_e32 v24, v29
	s_waitcnt lgkmcnt(0)
	s_nop 0
	v_mov_b32_e32 v25, v30
	v_mov_b32_e32 v30, v26
	s_nop 1
	v_permlane16_swap_b32_e32 v25, v30
	s_waitcnt lgkmcnt(0)
	s_nop 0
	v_lshl_add_u64 v[32:33], v[176:177], 1, v[32:33]
	v_mov_b32_e32 v26, v31
	s_nop 1
	v_permlane16_swap_b32_e32 v26, v27
	v_cvt_pk_bf16_f32 v24, v28, v24
	v_cvt_pk_bf16_f32 v25, v25, v26
	v_cvt_pk_bf16_f32 v26, v35, v29
	v_lshlrev_b32_e32 v28, 1, v180
	v_mov_b32_e32 v29, v177
	v_cvt_pk_bf16_f32 v27, v30, v27
	v_lshlrev_b32_e32 v30, 1, v179
	v_mov_b32_e32 v31, v177
	v_lshl_add_u64 v[28:29], v[32:33], 0, v[28:29]
	v_lshl_add_u64 v[28:29], v[28:29], 0, v[30:31]
	s_mov_b32 s58, 0xacff000
	v_add_co_u32_e32 v28, vcc, s58, v28
	s_nop 1
	v_addc_co_u32_e32 v29, vcc, 0, v29, vcc
	global_store_dwordx4 v[28:29], v[24:27], off offset:3328
	s_nop 1
	s_nop 0
	s_nop 0
	s_nop 0
	s_nop 0
	s_nop 0
	s_nop 0
	s_nop 0
	s_nop 0
	s_waitcnt lgkmcnt(0)
	s_nop 0
	v_mov_b32_e32 v24, v16
	s_nop 1
	v_permlane16_swap_b32_e32 v20, v24
	s_waitcnt lgkmcnt(0)
	s_nop 0
	v_mov_b32_e32 v16, v21
	v_mov_b32_e32 v21, v17
	s_nop 1
	v_permlane16_swap_b32_e32 v16, v21
	s_waitcnt lgkmcnt(0)
	s_nop 0
	v_mov_b32_e32 v17, v22
	v_mov_b32_e32 v22, v18
	s_nop 1
	v_permlane16_swap_b32_e32 v17, v22
	s_waitcnt lgkmcnt(0)
	s_nop 0
	v_mov_b32_e32 v18, v23
	s_nop 1
	v_permlane16_swap_b32_e32 v18, v19
	v_cvt_pk_bf16_f32 v16, v20, v16
	v_cvt_pk_bf16_f32 v17, v17, v18
	v_cvt_pk_bf16_f32 v18, v24, v21
	v_cvt_pk_bf16_f32 v19, v22, v19
	global_store_dwordx4 v[28:29], v[16:19], off offset:3392

.LBB0_739:
	s_or_b64 exec, exec, s[58:59]
	s_nop 0
	s_nop 0
	s_nop 0
	s_nop 0
	s_nop 0
	s_nop 0
	s_nop 0
	s_nop 0
	v_mov_b64_e32 v[36:37], s[4:5]
	s_movk_i32 vcc_lo, 0x300
	v_mad_i64_i32 v[36:37], s[58:59], v32, vcc_lo, v[36:37]
	v_lshlrev_b64 v[38:39], 1, v[134:135]
	s_waitcnt lgkmcnt(0)
	s_nop 0
	v_mov_b32_e32 v33, v24
	s_nop 1
	v_permlane16_swap_b32_e32 v28, v33
	s_waitcnt lgkmcnt(0)
	s_nop 0
	v_mov_b32_e32 v24, v29
	v_mov_b32_e32 v29, v25
	s_nop 1
	v_permlane16_swap_b32_e32 v24, v29
	s_waitcnt lgkmcnt(0)
	s_nop 0
	v_mov_b32_e32 v25, v30
	v_mov_b32_e32 v30, v26
	s_nop 1
	v_permlane16_swap_b32_e32 v25, v30
	s_waitcnt lgkmcnt(0)
	s_nop 0
	v_lshl_add_u64 v[36:37], v[36:37], 0, v[38:39]
	v_mov_b32_e32 v26, v31
	s_nop 1
	v_permlane16_swap_b32_e32 v26, v27
	v_cvt_pk_bf16_f32 v24, v28, v24
	v_cvt_pk_bf16_f32 v25, v25, v26
	v_cvt_pk_bf16_f32 v26, v33, v29
	v_lshlrev_b32_e32 v28, 1, v180
	v_mov_b32_e32 v29, v177
	v_cvt_pk_bf16_f32 v27, v30, v27
	v_lshl_add_u64 v[30:31], v[36:37], 0, v[28:29]
	v_lshlrev_b32_e32 v36, 1, v179
	v_mov_b32_e32 v37, v177
	v_lshl_add_u64 v[30:31], v[30:31], 0, v[36:37]
	global_store_dwordx4 v[30:31], v[24:27], off
	s_nop 0
	v_cndmask_b32_e64 v31, v23, v19, s[40:41]
	s_nop 0
	s_nop 0
	s_nop 0
	s_nop 0
	s_nop 0
	ds_bpermute_b32 v31, v34, v31
	v_mov_b64_e32 v[24:25], s[34:35]
	v_mad_i64_i32 v[24:25], s[58:59], v32, vcc_lo, v[24:25]
	v_lshl_add_u64 v[24:25], v[24:25], 0, v[38:39]
	s_waitcnt lgkmcnt(1)
	s_nop 0
	v_mov_b32_e32 v26, v16
	s_nop 1
	v_permlane16_swap_b32_e32 v20, v26
	s_waitcnt lgkmcnt(1)
	s_nop 0
	v_mov_b32_e32 v16, v21
	v_mov_b32_e32 v21, v17
	s_nop 1
	v_permlane16_swap_b32_e32 v16, v21
	s_waitcnt lgkmcnt(1)
	s_nop 0
	v_mov_b32_e32 v17, v22
	v_mov_b32_e32 v22, v18
	s_nop 1
	v_permlane16_swap_b32_e32 v17, v22
	s_waitcnt lgkmcnt(0)
	v_cndmask_b32_e64 v18, v31, v23, s[40:41]
	v_cvt_pk_bf16_f32 v16, v20, v16
	v_cvt_pk_bf16_f32 v17, v17, v18
	v_cvt_pk_bf16_f32 v18, v26, v21
	v_lshl_add_u64 v[20:21], v[24:25], 0, v[28:29]
	v_lshl_add_u64 v[20:21], v[20:21], 0, v[36:37]
	v_cndmask_b32_e64 v19, v19, v31, s[40:41]
	v_add_co_u32_e32 v20, vcc, 0xa700000, v20
	v_cvt_pk_bf16_f32 v19, v22, v19
	s_nop 0
	v_addc_co_u32_e32 v21, vcc, 0, v21, vcc
	global_store_dwordx4 v[20:21], v[16:19], off offset:64

.LBB0_741:
	s_or_b64 exec, exec, s[30:31]
	v_or_b32_e32 v22, 0x70, v182
	v_or_b32_e32 v16, v183, v22
	s_and_saveexec_b64 s[30:31], s[52:53]
	s_xor_b64 s[52:53], exec, s[30:31]
	s_cbranch_execz .LBB0_765
	s_and_saveexec_b64 s[30:31], s[50:51]
	s_xor_b64 s[30:31], exec, s[30:31]
	s_cbranch_execz .LBB0_744
	v_mul_f32_e32 v18, 0xbfb8aa3b, v12
	v_mul_f32_e32 v20, 0xbfb8aa3b, v8
	v_mul_f32_e32 v21, 0xbfb8aa3b, v13
	v_exp_f32_e32 v18, v18
	v_exp_f32_e32 v20, v20
	v_exp_f32_e32 v21, v21
	v_mul_f32_e32 v22, 0xbfb8aa3b, v9
	v_add_f32_e32 v18, 1.0, v18
	v_add_f32_e32 v20, 1.0, v20
	v_add_f32_e32 v21, 1.0, v21
	v_rcp_f32_e32 v18, v18
	v_rcp_f32_e32 v20, v20
	v_rcp_f32_e32 v21, v21
	v_exp_f32_e32 v22, v22
	v_mul_f32_e32 v18, v12, v18
	v_mul_f32_e32 v20, v8, v20
	v_mul_f32_e32 v21, v13, v21
	v_add_f32_e32 v8, 1.0, v22
	v_mul_f32_e32 v12, 0xbfb8aa3b, v14
	v_mul_f32_e32 v13, 0xbfb8aa3b, v10
	v_rcp_f32_e32 v8, v8
	v_exp_f32_e32 v12, v12
	v_exp_f32_e32 v13, v13
	v_ashrrev_i32_e32 v17, 31, v16
	v_mul_f32_e32 v22, v9, v8
	v_add_f32_e32 v8, 1.0, v12
	v_add_f32_e32 v9, 1.0, v13
	v_mul_f32_e32 v12, 0xbfb8aa3b, v15
	v_mul_f32_e32 v13, 0xbfb8aa3b, v11
	v_exp_f32_e32 v12, v12
	v_exp_f32_e32 v13, v13
	v_rcp_f32_e32 v8, v8
	v_rcp_f32_e32 v9, v9
	v_add_f32_e32 v12, 1.0, v12
	v_add_f32_e32 v13, 1.0, v13
	v_rcp_f32_e32 v12, v12
	v_rcp_f32_e32 v13, v13
	v_lshlrev_b64 v[16:17], 11, v[16:17]
	v_cmp_lt_i32_e32 vcc, v189, v202
	v_mul_f32_e32 v14, v14, v8
	v_mul_f32_e32 v10, v10, v9
	v_cndmask_b32_e32 v19, v203, v189, vcc
	v_mul_f32_e32 v15, v15, v12
	v_mul_f32_e32 v11, v11, v13
	v_lshl_add_u64 v[8:9], s[34:35], 0, v[16:17]
	v_lshlrev_b32_e32 v19, 2, v19
	v_lshl_add_u64 v[12:13], v[176:177], 1, v[8:9]
	s_nop 0
	s_nop 0
	s_nop 0
	s_nop 0
	s_nop 0
	s_nop 0
	s_nop 0
	s_nop 0
	v_lshlrev_b32_e32 v176, 1, v180
	s_waitcnt lgkmcnt(0)
	s_nop 0
	s_nop 1
	v_permlane16_swap_b32_e32 v18, v20
	s_waitcnt lgkmcnt(0)
	s_nop 0
	v_mov_b32_e32 v8, v21
	v_mov_b32_e32 v21, v22
	s_nop 1
	v_permlane16_swap_b32_e32 v8, v21
	s_waitcnt lgkmcnt(0)
	s_nop 0
	v_mov_b32_e32 v9, v14
	v_mov_b32_e32 v14, v10
	s_nop 1
	v_permlane16_swap_b32_e32 v9, v14
	s_waitcnt lgkmcnt(0)
	s_nop 0
	v_mov_b32_e32 v10, v15
	s_nop 1
	v_permlane16_swap_b32_e32 v10, v11
	v_cvt_pk_bf16_f32 v11, v14, v11
	v_lshlrev_b32_e32 v14, 1, v179
	v_mov_b32_e32 v15, v177
	v_lshl_add_u64 v[12:13], v[12:13], 0, v[176:177]
	v_lshl_add_u64 v[12:13], v[12:13], 0, v[14:15]
	s_mov_b32 s50, 0x96ff000
	v_add_co_u32_e32 v12, vcc, s50, v12
	v_cvt_pk_bf16_f32 v8, v18, v8
	v_cvt_pk_bf16_f32 v9, v9, v10
	v_cvt_pk_bf16_f32 v10, v20, v21
	v_addc_co_u32_e32 v13, vcc, 0, v13, vcc
	v_mul_f32_e32 v14, 0xbfb8aa3b, v4
	global_store_dwordx4 v[12:13], v[8:11], off offset:2688
	v_exp_f32_e32 v14, v14
	s_nop 0
	v_mul_f32_e32 v9, 0xbfb8aa3b, v0
	v_mul_f32_e32 v10, 0xbfb8aa3b, v5
	v_exp_f32_e32 v9, v9
	v_exp_f32_e32 v10, v10
	v_add_f32_e32 v8, 1.0, v14
	v_mul_f32_e32 v11, 0xbfb8aa3b, v1
	v_add_f32_e32 v9, 1.0, v9
	v_add_f32_e32 v10, 1.0, v10
	v_rcp_f32_e32 v8, v8
	v_rcp_f32_e32 v9, v9
	v_rcp_f32_e32 v10, v10
	v_exp_f32_e32 v11, v11
	v_mul_f32_e32 v4, v4, v8
	v_mul_f32_e32 v0, v0, v9
	v_mul_f32_e32 v5, v5, v10
	v_add_f32_e32 v8, 1.0, v11
	v_mul_f32_e32 v9, 0xbfb8aa3b, v6
	v_mul_f32_e32 v10, 0xbfb8aa3b, v2
	v_rcp_f32_e32 v8, v8
	v_exp_f32_e32 v9, v9
	v_exp_f32_e32 v10, v10
	v_mul_f32_e32 v11, 0xbfb8aa3b, v3
	v_mul_f32_e32 v1, v1, v8
	v_add_f32_e32 v8, 1.0, v9
	v_add_f32_e32 v9, 1.0, v10
	v_mul_f32_e32 v10, 0xbfb8aa3b, v7
	v_exp_f32_e32 v10, v10
	v_exp_f32_e32 v11, v11
	v_rcp_f32_e32 v8, v8
	v_rcp_f32_e32 v9, v9
	v_add_f32_e32 v10, 1.0, v10
	v_add_f32_e32 v11, 1.0, v11
	v_rcp_f32_e32 v10, v10
	v_rcp_f32_e32 v11, v11
	v_mul_f32_e32 v6, v6, v8
	v_mul_f32_e32 v2, v2, v9
	v_mul_f32_e32 v7, v7, v10
	v_mul_f32_e32 v3, v3, v11
	s_nop 0
	s_nop 0
	s_nop 0
	s_nop 0
	s_nop 0
	s_nop 0
	s_nop 0
	s_nop 0
	s_waitcnt lgkmcnt(0)
	s_nop 0
	v_mov_b32_e32 v8, v0
	s_nop 1
	v_permlane16_swap_b32_e32 v4, v8
	s_waitcnt lgkmcnt(0)
	s_nop 0
	v_mov_b32_e32 v0, v5
	v_mov_b32_e32 v5, v1
	s_nop 1
	v_permlane16_swap_b32_e32 v0, v5
	s_waitcnt lgkmcnt(0)
	s_nop 0
	v_mov_b32_e32 v1, v6
	v_mov_b32_e32 v6, v2
	s_nop 1
	v_permlane16_swap_b32_e32 v1, v6
	s_waitcnt lgkmcnt(0)
	s_nop 0
	v_mov_b32_e32 v2, v7
	s_nop 1
	v_permlane16_swap_b32_e32 v2, v3
	v_cvt_pk_bf16_f32 v0, v4, v0
	v_cvt_pk_bf16_f32 v1, v1, v2
	v_cvt_pk_bf16_f32 v2, v8, v5
	v_cvt_pk_bf16_f32 v3, v6, v3
	global_store_dwordx4 v[12:13], v[0:3], off offset:2752

.LBB0_771:
	s_or_b64 exec, exec, s[44:45]
	s_nop 0
	s_nop 0
	s_nop 0
	s_nop 0
	s_nop 0
	s_nop 0
	s_nop 0
	s_nop 0
	v_lshlrev_b64 v[16:17], 9, v[16:17]
	v_lshl_add_u64 v[16:17], s[14:15], 0, v[16:17]
	v_lshl_add_u64 v[16:17], v[176:177], 1, v[16:17]
	s_waitcnt lgkmcnt(0)
	s_nop 0
	v_mov_b32_e32 v19, v8
	s_nop 1
	v_permlane16_swap_b32_e32 v12, v19
	s_waitcnt lgkmcnt(0)
	s_nop 0
	v_mov_b32_e32 v8, v13
	v_mov_b32_e32 v13, v9
	s_nop 1
	v_permlane16_swap_b32_e32 v8, v13
	s_waitcnt lgkmcnt(0)
	s_nop 0
	v_mov_b32_e32 v9, v14
	v_mov_b32_e32 v14, v10
	s_nop 1
	v_permlane16_swap_b32_e32 v9, v14
	s_waitcnt lgkmcnt(0)
	s_nop 0
	v_mov_b32_e32 v10, v15
	s_nop 1
	v_permlane16_swap_b32_e32 v10, v11
	v_lshlrev_b32_e32 v176, 1, v180
	v_cvt_pk_bf16_f32 v8, v12, v8
	v_cvt_pk_bf16_f32 v9, v9, v10
	v_cvt_pk_bf16_f32 v10, v19, v13
	v_cvt_pk_bf16_f32 v11, v14, v11
	v_lshlrev_b32_e32 v12, 1, v179
	v_mov_b32_e32 v13, v177
	v_lshl_add_u64 v[14:15], v[16:17], 0, v[176:177]
	v_lshl_add_u64 v[12:13], v[14:15], 0, v[12:13]
	s_mov_b32 s44, 0xacff000
	v_add_co_u32_e32 v12, vcc, s44, v12
	s_nop 1
	v_addc_co_u32_e32 v13, vcc, 0, v13, vcc
	global_store_dwordx4 v[12:13], v[8:11], off offset:3328
	s_nop 1
	s_nop 0
	s_nop 0
	s_nop 0
	s_nop 0
	s_nop 0
	s_nop 0
	s_nop 0
	s_nop 0
	s_waitcnt lgkmcnt(0)
	s_nop 0
	v_mov_b32_e32 v8, v0
	s_nop 1
	v_permlane16_swap_b32_e32 v4, v8
	s_waitcnt lgkmcnt(0)
	s_nop 0
	v_mov_b32_e32 v0, v5
	v_mov_b32_e32 v5, v1
	s_nop 1
	v_permlane16_swap_b32_e32 v0, v5
	s_waitcnt lgkmcnt(0)
	s_nop 0
	v_mov_b32_e32 v1, v6
	v_mov_b32_e32 v6, v2
	s_nop 1
	v_permlane16_swap_b32_e32 v1, v6
	s_waitcnt lgkmcnt(0)
	s_nop 0
	v_mov_b32_e32 v2, v7
	s_nop 1
	v_permlane16_swap_b32_e32 v2, v3
	v_cvt_pk_bf16_f32 v0, v4, v0
	v_cvt_pk_bf16_f32 v1, v1, v2
	v_cvt_pk_bf16_f32 v2, v8, v5
	v_cvt_pk_bf16_f32 v3, v6, v3
	global_store_dwordx4 v[12:13], v[0:3], off offset:3392

.LBB0_802:
	s_waitcnt lgkmcnt(0)
	s_barrier
	ds_read_b128 v[224:227], v184
	ds_read_b128 v[228:231], v184 offset:1024
	ds_read_b128 v[232:235], v184 offset:2048
	ds_read_b128 v[236:239], v184 offset:3072
	ds_read_b128 v[190:193], v185
	ds_read_b128 v[194:197], v185 offset:1024
	ds_read_b128 v[198:201], v185 offset:2048
	ds_read_b128 v[204:207], v185 offset:3072
	ds_read_b128 v[208:211], v185 offset:4096
	ds_read_b128 v[212:215], v185 offset:5120
	ds_read_b128 v[216:219], v185 offset:6144
	ds_read_b128 v[220:223], v185 offset:7168
	s_movk_i32 vcc_lo, 0x6000
	s_cmp_eq_u32 m0, 2
	s_cselect_b32 vcc_lo, 0xffff4000, vcc_lo
	s_add_u32 m0, m0, 1
	s_cmp_eq_u32 m0, 3
	s_cselect_b32 m0, 0, m0
	v_add_u32_e32 v185, vcc_lo, v185
	v_add_u32_e32 v184, vcc_lo, v184
	v_xor_b32_e32 v185, 64, v185
	v_xor_b32_e32 v184, 64, v184
	s_waitcnt lgkmcnt(7)
	v_mfma_f32_16x16x32_bf16 v[172:175], v[224:227], v[190:193], v[172:175]
	v_mfma_f32_16x16x32_bf16 v[168:171], v[228:231], v[190:193], v[168:171]
	v_mfma_f32_16x16x32_bf16 v[164:167], v[232:235], v[190:193], v[164:167]
	v_mfma_f32_16x16x32_bf16 v[160:163], v[236:239], v[190:193], v[160:163]
	ds_read_b128 v[190:193], v185
	s_waitcnt lgkmcnt(7)
	v_mfma_f32_16x16x32_bf16 v[156:159], v[224:227], v[194:197], v[156:159]
	v_mfma_f32_16x16x32_bf16 v[152:155], v[228:231], v[194:197], v[152:155]
	v_mfma_f32_16x16x32_bf16 v[148:151], v[232:235], v[194:197], v[148:151]
	v_mfma_f32_16x16x32_bf16 v[144:147], v[236:239], v[194:197], v[144:147]
	ds_read_b128 v[194:197], v185 offset:1024
	s_waitcnt lgkmcnt(7)
	v_mfma_f32_16x16x32_bf16 v[136:139], v[224:227], v[198:201], v[136:139]
	v_mfma_f32_16x16x32_bf16 v[132:135], v[228:231], v[198:201], v[132:135]
	v_mfma_f32_16x16x32_bf16 v[128:131], v[232:235], v[198:201], v[128:131]
	v_mfma_f32_16x16x32_bf16 v[124:127], v[236:239], v[198:201], v[124:127]
	ds_read_b128 v[198:201], v185 offset:2048
	s_waitcnt lgkmcnt(7)
	v_mfma_f32_16x16x32_bf16 v[120:123], v[224:227], v[204:207], v[120:123]
	v_mfma_f32_16x16x32_bf16 v[108:111], v[228:231], v[204:207], v[108:111]
	v_mfma_f32_16x16x32_bf16 v[100:103], v[232:235], v[204:207], v[100:103]
	v_mfma_f32_16x16x32_bf16 v[96:99], v[236:239], v[204:207], v[96:99]
	ds_read_b128 v[204:207], v185 offset:3072
	s_waitcnt lgkmcnt(7)
	v_mfma_f32_16x16x32_bf16 v[92:95], v[224:227], v[208:211], v[92:95]
	v_mfma_f32_16x16x32_bf16 v[84:87], v[228:231], v[208:211], v[84:87]
	v_mfma_f32_16x16x32_bf16 v[76:79], v[232:235], v[208:211], v[76:79]
	v_mfma_f32_16x16x32_bf16 v[72:75], v[236:239], v[208:211], v[72:75]
	ds_read_b128 v[208:211], v185 offset:4096
	s_waitcnt lgkmcnt(7)
	v_mfma_f32_16x16x32_bf16 v[64:67], v[224:227], v[212:215], v[64:67]
	v_mfma_f32_16x16x32_bf16 v[52:55], v[228:231], v[212:215], v[52:55]
	v_mfma_f32_16x16x32_bf16 v[48:51], v[232:235], v[212:215], v[48:51]
	v_mfma_f32_16x16x32_bf16 v[44:47], v[236:239], v[212:215], v[44:47]
	ds_read_b128 v[212:215], v185 offset:5120
	s_waitcnt lgkmcnt(7)
	v_mfma_f32_16x16x32_bf16 v[36:39], v[224:227], v[216:219], v[36:39]
	v_mfma_f32_16x16x32_bf16 v[28:31], v[228:231], v[216:219], v[28:31]
	v_mfma_f32_16x16x32_bf16 v[24:27], v[232:235], v[216:219], v[24:27]
	v_mfma_f32_16x16x32_bf16 v[20:23], v[236:239], v[216:219], v[20:23]
	ds_read_b128 v[216:219], v185 offset:6144
	s_waitcnt lgkmcnt(7)
	v_mfma_f32_16x16x32_bf16 v[12:15], v[224:227], v[220:223], v[12:15]
	v_mfma_f32_16x16x32_bf16 v[4:7], v[228:231], v[220:223], v[4:7]
	v_mfma_f32_16x16x32_bf16 v[0:3], v[232:235], v[220:223], v[0:3]
	v_mfma_f32_16x16x32_bf16 v[140:143], v[236:239], v[220:223], v[140:143]
	ds_read_b128 v[220:223], v185 offset:7168
	ds_read_b128 v[224:227], v184
	ds_read_b128 v[228:231], v184 offset:1024
	ds_read_b128 v[232:235], v184 offset:2048
	ds_read_b128 v[236:239], v184 offset:3072
	s_movk_i32 vcc_lo, 0x6000
	s_cmp_eq_u32 m0, 2
	s_cselect_b32 vcc_lo, 0xffff4000, vcc_lo
	s_add_u32 m0, m0, 1
	s_cmp_eq_u32 m0, 3
	s_cselect_b32 m0, 0, m0
	v_add_u32_e32 v185, vcc_lo, v185
	v_add_u32_e32 v184, vcc_lo, v184
	v_xor_b32_e32 v185, 64, v185
	v_xor_b32_e32 v184, 64, v184
	s_sub_u32 vcc_lo, s6, s98
	v_add_u32_e32 v186, vcc_lo, v178
	v_add_u32_e32 v187, vcc_lo, v180
	s_barrier
	s_waitcnt lgkmcnt(0)
	v_mfma_f32_16x16x32_bf16 v[172:175], v[224:227], v[190:193], v[172:175]
	s_waitcnt vmcnt(11)
	v_mfma_f32_16x16x32_bf16 v[168:171], v[228:231], v[190:193], v[168:171]
	ds_write_b128 v183, v[116:119]
	v_add_u32_e32 v116, s26, v187
	v_mfma_f32_16x16x32_bf16 v[164:167], v[232:235], v[190:193], v[164:167]
	global_load_dwordx4 v[116:119], v116, s[98:99] offset:128
	v_mfma_f32_16x16x32_bf16 v[160:163], v[236:239], v[190:193], v[160:163]
	s_waitcnt vmcnt(11)
	ds_write_b128 v183, v[112:115] offset:2048
	v_mfma_f32_16x16x32_bf16 v[156:159], v[224:227], v[194:197], v[156:159]
	v_add_u32_e32 v112, s27, v187
	v_mfma_f32_16x16x32_bf16 v[152:155], v[228:231], v[194:197], v[152:155]
	global_load_dwordx4 v[112:115], v112, s[98:99] offset:128
	s_waitcnt vmcnt(11)
	v_mfma_f32_16x16x32_bf16 v[148:151], v[232:235], v[194:197], v[148:151]
	ds_write_b128 v183, v[104:107] offset:4096
	v_mfma_f32_16x16x32_bf16 v[144:147], v[236:239], v[194:197], v[144:147]
	v_add_u32_e32 v104, s20, v187
	global_load_dwordx4 v[104:107], v104, s[98:99] offset:128
	v_mfma_f32_16x16x32_bf16 v[136:139], v[224:227], v[198:201], v[136:139]
	s_waitcnt vmcnt(11)
	v_mfma_f32_16x16x32_bf16 v[132:135], v[228:231], v[198:201], v[132:135]
	ds_write_b128 v183, v[88:91] offset:6144
	v_add_u32_e32 v88, s21, v187
	v_mfma_f32_16x16x32_bf16 v[128:131], v[232:235], v[198:201], v[128:131]
	global_load_dwordx4 v[88:91], v88, s[98:99] offset:128
	v_mfma_f32_16x16x32_bf16 v[124:127], v[236:239], v[198:201], v[124:127]
	s_waitcnt vmcnt(11)
	ds_write_b128 v183, v[80:83] offset:8192
	v_mfma_f32_16x16x32_bf16 v[120:123], v[224:227], v[204:207], v[120:123]
	v_add_u32_e32 v80, s56, v187
	v_mfma_f32_16x16x32_bf16 v[108:111], v[228:231], v[204:207], v[108:111]
	global_load_dwordx4 v[80:83], v80, s[98:99] offset:128
	s_waitcnt vmcnt(11)
	v_mfma_f32_16x16x32_bf16 v[100:103], v[232:235], v[204:207], v[100:103]
	ds_write_b128 v183, v[68:71] offset:10240
	v_mfma_f32_16x16x32_bf16 v[96:99], v[236:239], v[204:207], v[96:99]
	v_add_u32_e32 v68, s57, v187
	global_load_dwordx4 v[68:71], v68, s[98:99] offset:128
	v_mfma_f32_16x16x32_bf16 v[92:95], v[224:227], v[208:211], v[92:95]
	s_waitcnt vmcnt(11)
	v_mfma_f32_16x16x32_bf16 v[84:87], v[228:231], v[208:211], v[84:87]
	ds_write_b128 v183, v[60:63] offset:12288
	v_add_u32_e32 v60, s24, v187
	v_mfma_f32_16x16x32_bf16 v[76:79], v[232:235], v[208:211], v[76:79]
	global_load_dwordx4 v[60:63], v60, s[98:99] offset:128
	v_mfma_f32_16x16x32_bf16 v[72:75], v[236:239], v[208:211], v[72:75]
	s_waitcnt vmcnt(11)
	ds_write_b128 v183, v[40:43] offset:14336
	v_mfma_f32_16x16x32_bf16 v[64:67], v[224:227], v[212:215], v[64:67]
	v_add_u32_e32 v40, s96, v187
	v_mfma_f32_16x16x32_bf16 v[52:55], v[228:231], v[212:215], v[52:55]
	global_load_dwordx4 v[40:43], v40, s[98:99] offset:128
	s_waitcnt vmcnt(11)
	v_mfma_f32_16x16x32_bf16 v[48:51], v[232:235], v[212:215], v[48:51]
	ds_write_b128 v183, v[56:59] offset:16384
	v_mfma_f32_16x16x32_bf16 v[44:47], v[236:239], v[212:215], v[44:47]
	v_mov_b32_e32 v56, v186
	global_load_dwordx4 v[56:59], v56, s[98:99] offset:128
	v_mfma_f32_16x16x32_bf16 v[36:39], v[224:227], v[216:219], v[36:39]
	s_waitcnt vmcnt(11)
	v_mfma_f32_16x16x32_bf16 v[28:31], v[228:231], v[216:219], v[28:31]
	ds_write_b128 v183, v[32:35] offset:18432
	v_add_u32_e32 v32, s13, v186
	v_mfma_f32_16x16x32_bf16 v[24:27], v[232:235], v[216:219], v[24:27]
	global_load_dwordx4 v[32:35], v32, s[98:99] offset:128
	v_mfma_f32_16x16x32_bf16 v[20:23], v[236:239], v[216:219], v[20:23]
	s_waitcnt vmcnt(11)
	ds_write_b128 v183, v[16:19] offset:20480
	v_mfma_f32_16x16x32_bf16 v[12:15], v[224:227], v[220:223], v[12:15]
	v_add_u32_e32 v16, s12, v186
	v_mfma_f32_16x16x32_bf16 v[4:7], v[228:231], v[220:223], v[4:7]
	global_load_dwordx4 v[16:19], v16, s[98:99] offset:128
	s_waitcnt vmcnt(11)
	v_mfma_f32_16x16x32_bf16 v[0:3], v[232:235], v[220:223], v[0:3]
	ds_write_b128 v183, v[8:11] offset:22528
	v_mfma_f32_16x16x32_bf16 v[140:143], v[236:239], v[220:223], v[140:143]
	v_add_u32_e32 v8, s11, v186
	global_load_dwordx4 v[8:11], v8, s[98:99] offset:128
	v_cmp_gt_u32_e32 vcc, 0x6000, v183
	v_add_u32_e32 v182, 0xc000, v183
	v_add_u32_e32 v183, 0xffffa000, v183
	s_nop 0
	v_cndmask_b32_e32 v183, v183, v182, vcc
	s_add_u32 s6, s6, 0x80
	s_addc_u32 s7, s7, 0
	s_cmpk_lg_i32 s6, 0x780
	s_cbranch_scc1 .LBB0_802
	s_waitcnt lgkmcnt(0)
	s_barrier
	ds_read_b128 v[224:227], v184
	ds_read_b128 v[228:231], v184 offset:1024
	ds_read_b128 v[232:235], v184 offset:2048
	ds_read_b128 v[236:239], v184 offset:3072
	ds_read_b128 v[190:193], v185
	ds_read_b128 v[194:197], v185 offset:1024
	ds_read_b128 v[198:201], v185 offset:2048
	ds_read_b128 v[204:207], v185 offset:3072
	ds_read_b128 v[208:211], v185 offset:4096
	ds_read_b128 v[212:215], v185 offset:5120
	ds_read_b128 v[216:219], v185 offset:6144
	ds_read_b128 v[220:223], v185 offset:7168
	s_movk_i32 vcc_lo, 0x6000
	s_cmp_eq_u32 m0, 2
	s_cselect_b32 vcc_lo, 0xffff4000, vcc_lo
	s_add_u32 m0, m0, 1
	s_cmp_eq_u32 m0, 3
	s_cselect_b32 m0, 0, m0
	v_add_u32_e32 v185, vcc_lo, v185
	v_add_u32_e32 v184, vcc_lo, v184
	v_xor_b32_e32 v185, 64, v185
	v_xor_b32_e32 v184, 64, v184
	s_waitcnt lgkmcnt(7)
	v_mfma_f32_16x16x32_bf16 v[172:175], v[224:227], v[190:193], v[172:175]
	v_mfma_f32_16x16x32_bf16 v[168:171], v[228:231], v[190:193], v[168:171]
	v_mfma_f32_16x16x32_bf16 v[164:167], v[232:235], v[190:193], v[164:167]
	v_mfma_f32_16x16x32_bf16 v[160:163], v[236:239], v[190:193], v[160:163]
	ds_read_b128 v[190:193], v185
	s_waitcnt lgkmcnt(7)
	v_mfma_f32_16x16x32_bf16 v[156:159], v[224:227], v[194:197], v[156:159]
	v_mfma_f32_16x16x32_bf16 v[152:155], v[228:231], v[194:197], v[152:155]
	v_mfma_f32_16x16x32_bf16 v[148:151], v[232:235], v[194:197], v[148:151]
	v_mfma_f32_16x16x32_bf16 v[144:147], v[236:239], v[194:197], v[144:147]
	ds_read_b128 v[194:197], v185 offset:1024
	s_waitcnt lgkmcnt(7)
	v_mfma_f32_16x16x32_bf16 v[136:139], v[224:227], v[198:201], v[136:139]
	v_mfma_f32_16x16x32_bf16 v[132:135], v[228:231], v[198:201], v[132:135]
	v_mfma_f32_16x16x32_bf16 v[128:131], v[232:235], v[198:201], v[128:131]
	v_mfma_f32_16x16x32_bf16 v[124:127], v[236:239], v[198:201], v[124:127]
	ds_read_b128 v[198:201], v185 offset:2048
	s_waitcnt lgkmcnt(7)
	v_mfma_f32_16x16x32_bf16 v[120:123], v[224:227], v[204:207], v[120:123]
	v_mfma_f32_16x16x32_bf16 v[108:111], v[228:231], v[204:207], v[108:111]
	v_mfma_f32_16x16x32_bf16 v[100:103], v[232:235], v[204:207], v[100:103]
	v_mfma_f32_16x16x32_bf16 v[96:99], v[236:239], v[204:207], v[96:99]
	ds_read_b128 v[204:207], v185 offset:3072
	s_waitcnt lgkmcnt(7)
	v_mfma_f32_16x16x32_bf16 v[92:95], v[224:227], v[208:211], v[92:95]
	v_mfma_f32_16x16x32_bf16 v[84:87], v[228:231], v[208:211], v[84:87]
	v_mfma_f32_16x16x32_bf16 v[76:79], v[232:235], v[208:211], v[76:79]
	v_mfma_f32_16x16x32_bf16 v[72:75], v[236:239], v[208:211], v[72:75]
	ds_read_b128 v[208:211], v185 offset:4096
	s_waitcnt lgkmcnt(7)
	v_mfma_f32_16x16x32_bf16 v[64:67], v[224:227], v[212:215], v[64:67]
	v_mfma_f32_16x16x32_bf16 v[52:55], v[228:231], v[212:215], v[52:55]
	v_mfma_f32_16x16x32_bf16 v[48:51], v[232:235], v[212:215], v[48:51]
	v_mfma_f32_16x16x32_bf16 v[44:47], v[236:239], v[212:215], v[44:47]
	ds_read_b128 v[212:215], v185 offset:5120
	s_waitcnt lgkmcnt(7)
	v_mfma_f32_16x16x32_bf16 v[36:39], v[224:227], v[216:219], v[36:39]
	v_mfma_f32_16x16x32_bf16 v[28:31], v[228:231], v[216:219], v[28:31]
	v_mfma_f32_16x16x32_bf16 v[24:27], v[232:235], v[216:219], v[24:27]
	v_mfma_f32_16x16x32_bf16 v[20:23], v[236:239], v[216:219], v[20:23]
	ds_read_b128 v[216:219], v185 offset:6144
	s_waitcnt lgkmcnt(7)
	v_mfma_f32_16x16x32_bf16 v[12:15], v[224:227], v[220:223], v[12:15]
	v_mfma_f32_16x16x32_bf16 v[4:7], v[228:231], v[220:223], v[4:7]
	v_mfma_f32_16x16x32_bf16 v[0:3], v[232:235], v[220:223], v[0:3]
	v_mfma_f32_16x16x32_bf16 v[140:143], v[236:239], v[220:223], v[140:143]
	ds_read_b128 v[220:223], v185 offset:7168
	ds_read_b128 v[224:227], v184
	ds_read_b128 v[228:231], v184 offset:1024
	ds_read_b128 v[232:235], v184 offset:2048
	ds_read_b128 v[236:239], v184 offset:3072
	s_movk_i32 vcc_lo, 0x6000
	s_cmp_eq_u32 m0, 2
	s_cselect_b32 vcc_lo, 0xffff4000, vcc_lo
	s_add_u32 m0, m0, 1
	s_cmp_eq_u32 m0, 3
	s_cselect_b32 m0, 0, m0
	v_add_u32_e32 v185, vcc_lo, v185
	v_add_u32_e32 v184, vcc_lo, v184
	v_xor_b32_e32 v185, 64, v185
	v_xor_b32_e32 v184, 64, v184
	s_waitcnt lgkmcnt(0)
	v_mfma_f32_16x16x32_bf16 v[172:175], v[224:227], v[190:193], v[172:175]
	v_mfma_f32_16x16x32_bf16 v[168:171], v[228:231], v[190:193], v[168:171]
	v_mfma_f32_16x16x32_bf16 v[164:167], v[232:235], v[190:193], v[164:167]
	v_mfma_f32_16x16x32_bf16 v[160:163], v[236:239], v[190:193], v[160:163]
	v_mfma_f32_16x16x32_bf16 v[156:159], v[224:227], v[194:197], v[156:159]
	v_mfma_f32_16x16x32_bf16 v[152:155], v[228:231], v[194:197], v[152:155]
	v_mfma_f32_16x16x32_bf16 v[148:151], v[232:235], v[194:197], v[148:151]
	v_mfma_f32_16x16x32_bf16 v[144:147], v[236:239], v[194:197], v[144:147]
	v_mfma_f32_16x16x32_bf16 v[136:139], v[224:227], v[198:201], v[136:139]
	v_mfma_f32_16x16x32_bf16 v[132:135], v[228:231], v[198:201], v[132:135]
	v_mfma_f32_16x16x32_bf16 v[128:131], v[232:235], v[198:201], v[128:131]
	v_mfma_f32_16x16x32_bf16 v[124:127], v[236:239], v[198:201], v[124:127]
	v_mfma_f32_16x16x32_bf16 v[120:123], v[224:227], v[204:207], v[120:123]
	v_mfma_f32_16x16x32_bf16 v[108:111], v[228:231], v[204:207], v[108:111]
	v_mfma_f32_16x16x32_bf16 v[100:103], v[232:235], v[204:207], v[100:103]
	v_mfma_f32_16x16x32_bf16 v[96:99], v[236:239], v[204:207], v[96:99]
	v_mfma_f32_16x16x32_bf16 v[92:95], v[224:227], v[208:211], v[92:95]
	v_mfma_f32_16x16x32_bf16 v[84:87], v[228:231], v[208:211], v[84:87]
	v_mfma_f32_16x16x32_bf16 v[76:79], v[232:235], v[208:211], v[76:79]
	v_mfma_f32_16x16x32_bf16 v[72:75], v[236:239], v[208:211], v[72:75]
	v_mfma_f32_16x16x32_bf16 v[64:67], v[224:227], v[212:215], v[64:67]
	v_mfma_f32_16x16x32_bf16 v[52:55], v[228:231], v[212:215], v[52:55]
	v_mfma_f32_16x16x32_bf16 v[48:51], v[232:235], v[212:215], v[48:51]
	v_mfma_f32_16x16x32_bf16 v[44:47], v[236:239], v[212:215], v[44:47]
	v_mfma_f32_16x16x32_bf16 v[36:39], v[224:227], v[216:219], v[36:39]
	v_mfma_f32_16x16x32_bf16 v[28:31], v[228:231], v[216:219], v[28:31]
	v_mfma_f32_16x16x32_bf16 v[24:27], v[232:235], v[216:219], v[24:27]
	v_mfma_f32_16x16x32_bf16 v[20:23], v[236:239], v[216:219], v[20:23]
	v_mfma_f32_16x16x32_bf16 v[12:15], v[224:227], v[220:223], v[12:15]
	v_mfma_f32_16x16x32_bf16 v[4:7], v[228:231], v[220:223], v[4:7]
	v_mfma_f32_16x16x32_bf16 v[0:3], v[232:235], v[220:223], v[0:3]
	v_mfma_f32_16x16x32_bf16 v[140:143], v[236:239], v[220:223], v[140:143]
	v_lshrrev_b32_e32 v224, 4, v188
	v_and_b32_e32 v225, 7, v188
	v_bitop3_b32 v226, v224, v225, 3 bitop3:0x6c
	v_lshlrev_b32_e32 v227, 7, v188
	v_bfe_u32 v228, v188, 4, 2
	v_and_b32_e32 v229, 0xffffc780, v227
	v_and_b32_e32 v227, 0x2780, v227
	v_bitop3_b32 v228, v228, v225, 4 bitop3:0x36
	v_lshlrev_b32_e32 v226, 4, v226
	v_lshlrev_b32_e32 v228, 4, v228
	v_or_b32_e32 v185, v229, v226
	v_or_b32_e32 v184, v227, v226
	v_or_b32_e32 v183, v229, v228
	v_or_b32_e32 v182, v227, v228
	s_waitcnt vmcnt(0)
	s_barrier
	s_waitcnt vmcnt(10)
	ds_write_b128 v176, v[116:119]
	s_waitcnt vmcnt(9)
	ds_write_b128 v176, v[112:115] offset:4096
	s_waitcnt vmcnt(8)
	ds_write_b128 v176, v[104:107] offset:8192
	s_waitcnt vmcnt(7)
	ds_write_b128 v176, v[88:91] offset:12288
	s_waitcnt vmcnt(6)
	ds_write_b128 v176, v[80:83] offset:16384
	s_waitcnt vmcnt(5)
	ds_write_b128 v176, v[68:71] offset:20480
	s_waitcnt vmcnt(4)
	ds_write_b128 v176, v[60:63] offset:24576
	s_waitcnt vmcnt(3)
	ds_write_b128 v176, v[40:43] offset:28672
	ds_write_b128 v176, v[56:59] offset:32768
	s_waitcnt vmcnt(2)
	ds_write_b128 v176, v[32:35] offset:36864
	s_waitcnt vmcnt(1)
	ds_write_b128 v176, v[16:19] offset:40960
	s_waitcnt vmcnt(0)
	ds_write_b128 v176, v[8:11] offset:45056
	s_waitcnt lgkmcnt(0)
	s_barrier
	ds_read_b128 v[8:11], v185
	ds_read_b128 v[16:19], v185 offset:2048
	ds_read_b128 v[32:35], v185 offset:4096
	ds_read_b128 v[40:43], v185 offset:6144
	ds_read_b128 v[56:59], v185 offset:8192
	ds_read_b128 v[60:63], v185 offset:10240
	ds_read_b128 v[68:71], v185 offset:12288
	ds_read_b128 v[80:83], v185 offset:14336
	ds_read_b128 v[88:91], v184 offset:32768
	ds_read_b128 v[104:107], v184 offset:34816
	ds_read_b128 v[112:115], v184 offset:36864
	ds_read_b128 v[116:119], v184 offset:38912
	s_waitcnt lgkmcnt(3)
	v_mfma_f32_16x16x32_bf16 v[172:175], v[88:91], v[8:11], v[172:175]
	s_waitcnt lgkmcnt(2)
	v_mfma_f32_16x16x32_bf16 v[168:171], v[104:107], v[8:11], v[168:171]
	s_waitcnt lgkmcnt(1)
	v_mfma_f32_16x16x32_bf16 v[164:167], v[112:115], v[8:11], v[164:167]
	s_waitcnt lgkmcnt(0)
	v_mfma_f32_16x16x32_bf16 v[8:11], v[116:119], v[8:11], v[160:163]
	v_mfma_f32_16x16x32_bf16 v[156:159], v[88:91], v[16:19], v[156:159]
	v_mfma_f32_16x16x32_bf16 v[152:155], v[104:107], v[16:19], v[152:155]
	v_mfma_f32_16x16x32_bf16 v[148:151], v[112:115], v[16:19], v[148:151]
	v_mfma_f32_16x16x32_bf16 v[16:19], v[116:119], v[16:19], v[144:147]
	v_mfma_f32_16x16x32_bf16 v[136:139], v[88:91], v[32:35], v[136:139]
	v_mfma_f32_16x16x32_bf16 v[132:135], v[104:107], v[32:35], v[132:135]
	v_mfma_f32_16x16x32_bf16 v[128:131], v[112:115], v[32:35], v[128:131]
	v_mfma_f32_16x16x32_bf16 v[32:35], v[116:119], v[32:35], v[124:127]
	v_mfma_f32_16x16x32_bf16 v[120:123], v[88:91], v[40:43], v[120:123]
	v_mfma_f32_16x16x32_bf16 v[108:111], v[104:107], v[40:43], v[108:111]
	v_mfma_f32_16x16x32_bf16 v[100:103], v[112:115], v[40:43], v[100:103]
	v_mfma_f32_16x16x32_bf16 v[40:43], v[116:119], v[40:43], v[96:99]
	v_mfma_f32_16x16x32_bf16 v[92:95], v[88:91], v[56:59], v[92:95]
	v_mfma_f32_16x16x32_bf16 v[84:87], v[104:107], v[56:59], v[84:87]
	v_mfma_f32_16x16x32_bf16 v[76:79], v[112:115], v[56:59], v[76:79]
	v_mfma_f32_16x16x32_bf16 v[56:59], v[116:119], v[56:59], v[72:75]
	v_mfma_f32_16x16x32_bf16 v[64:67], v[88:91], v[60:63], v[64:67]
	v_mfma_f32_16x16x32_bf16 v[52:55], v[104:107], v[60:63], v[52:55]
	v_mfma_f32_16x16x32_bf16 v[72:75], v[112:115], v[60:63], v[48:51]
	v_mfma_f32_16x16x32_bf16 v[60:63], v[116:119], v[60:63], v[44:47]
	v_mfma_f32_16x16x32_bf16 v[96:99], v[88:91], v[68:71], v[36:39]
	v_mfma_f32_16x16x32_bf16 v[28:31], v[104:107], v[68:71], v[28:31]
	v_mfma_f32_16x16x32_bf16 v[124:127], v[112:115], v[68:71], v[24:27]
	v_mfma_f32_16x16x32_bf16 v[20:23], v[116:119], v[68:71], v[20:23]
	v_mfma_f32_16x16x32_bf16 v[12:15], v[88:91], v[80:83], v[12:15]
	v_mfma_f32_16x16x32_bf16 v[4:7], v[104:107], v[80:83], v[4:7]
	v_mfma_f32_16x16x32_bf16 v[0:3], v[112:115], v[80:83], v[0:3]
	v_mfma_f32_16x16x32_bf16 v[68:71], v[116:119], v[80:83], v[140:143]
	ds_read_b128 v[24:27], v183
	ds_read_b128 v[36:39], v183 offset:2048
	ds_read_b128 v[44:47], v183 offset:4096
	ds_read_b128 v[80:83], v183 offset:6144
	ds_read_b128 v[88:91], v183 offset:8192
	ds_read_b128 v[104:107], v183 offset:10240
	ds_read_b128 v[112:115], v183 offset:12288
	ds_read_b128 v[116:119], v183 offset:14336
	ds_read_b128 v[140:143], v182 offset:32768
	ds_read_b128 v[144:147], v182 offset:34816
	ds_read_b128 v[160:163], v182 offset:36864
	ds_read_b128 v[178:181], v182 offset:38912
	s_waitcnt lgkmcnt(3)
	v_mfma_f32_16x16x32_bf16 v[172:175], v[140:143], v[24:27], v[172:175]
	v_mov_b32_e32 v49, v188
	v_cmp_lt_i32_e32 vcc, v189, v202
	s_waitcnt lgkmcnt(2)
	v_mfma_f32_16x16x32_bf16 v[168:171], v[144:147], v[24:27], v[168:171]
	v_mov_b32_e32 v48, v188
	v_readlane_b32 s6, v253, 24
	s_waitcnt lgkmcnt(1)
	v_mfma_f32_16x16x32_bf16 v[164:167], v[160:163], v[24:27], v[164:167]
	v_and_b32_e32 v50, 0xffffff80, v48
	v_add_u32_e32 v51, s9, v50
	v_and_or_b32 v50, v48, 64, s10
	s_waitcnt lgkmcnt(0)
	v_mfma_f32_16x16x32_bf16 v[8:11], v[178:181], v[24:27], v[8:11]
	v_bfe_u32 v26, v49, 4, 1
	v_cndmask_b32_e32 v24, v203, v189, vcc
	v_cmp_eq_u32_e32 vcc, 0, v26
	v_lshlrev_b32_e32 v186, 2, v24
	v_mfma_f32_16x16x32_bf16 v[182:185], v[178:181], v[36:39], v[16:19]
	v_and_or_b32 v48, v49, 15, v51
	v_ashrrev_i32_e32 v51, 31, v50
	v_lshl_add_u64 v[50:51], v[50:51], 1, s[4:5]
	s_nop 0
	s_nop 0
	s_nop 0
	s_nop 0
	s_nop 0
	s_nop 0
	s_nop 0
	s_nop 0
	v_lshlrev_b32_e32 v176, 5, v26
	v_lshrrev_b32_e32 v27, 1, v49
	v_lshl_add_u64 v[24:25], v[50:51], 0, v[176:177]
	v_and_b32_e32 v176, 16, v27
	v_ashrrev_i32_e32 v49, 31, v48
	v_mfma_f32_16x16x32_bf16 v[156:159], v[140:143], v[36:39], v[156:159]
	v_lshl_add_u64 v[50:51], v[24:25], 0, v[176:177]
	v_lshlrev_b64 v[24:25], 11, v[48:49]
	s_waitcnt lgkmcnt(0)
	s_nop 0
	v_mfma_f32_16x16x32_bf16 v[152:155], v[144:147], v[36:39], v[152:155]
	v_mov_b32_e32 v26, v172
	v_mov_b32_e32 v27, v168
	s_nop 1
	v_permlane16_swap_b32_e32 v26, v27
	s_waitcnt lgkmcnt(0)
	s_nop 0
	v_lshl_add_u64 v[24:25], v[50:51], 0, v[24:25]
	v_mfma_f32_16x16x32_bf16 v[148:151], v[160:163], v[36:39], v[148:151]
	v_mov_b32_e32 v16, v173
	v_mov_b32_e32 v36, v169
	s_nop 1
	v_permlane16_swap_b32_e32 v16, v36
	s_waitcnt lgkmcnt(0)
	s_nop 0
	v_cvt_pk_bf16_f32 v16, v26, v16
	v_mfma_f32_16x16x32_bf16 v[190:193], v[178:181], v[44:47], v[32:35]
	v_readlane_b32 s7, v253, 25
	s_nop 1
	v_mov_b32_e32 v17, v174
	v_mov_b32_e32 v32, v170
	s_nop 1
	v_permlane16_swap_b32_e32 v17, v32
	s_waitcnt lgkmcnt(0)
	s_nop 0
	v_mov_b32_e32 v18, v175
	v_mov_b32_e32 v19, v171
	s_nop 1
	v_permlane16_swap_b32_e32 v18, v19
	v_cvt_pk_bf16_f32 v17, v17, v18
	v_cvt_pk_bf16_f32 v18, v27, v36
	v_cvt_pk_bf16_f32 v19, v32, v19
	global_store_dwordx4 v[24:25], v[16:19], off
	v_mfma_f32_16x16x32_bf16 v[120:123], v[140:143], v[80:83], v[120:123]
	s_nop 0
	s_nop 0
	s_nop 0
	s_nop 0
	s_nop 0
	s_nop 0
	s_nop 0
	s_nop 0
	s_nop 0
	v_mfma_f32_16x16x32_bf16 v[108:111], v[144:147], v[80:83], v[108:111]
	s_waitcnt lgkmcnt(0)
	s_nop 0
	v_mov_b32_e32 v26, v164
	v_mov_b32_e32 v16, v8
	s_nop 1
	v_permlane16_swap_b32_e32 v26, v16
	s_waitcnt lgkmcnt(0)
	s_nop 0
	v_mov_b32_e32 v8, v165
	v_mov_b32_e32 v17, v9
	s_nop 1
	v_permlane16_swap_b32_e32 v8, v17
	s_waitcnt lgkmcnt(0)
	s_nop 0
	v_mov_b32_e32 v9, v166
	v_mov_b32_e32 v18, v10
	s_nop 1
	v_permlane16_swap_b32_e32 v9, v18
	s_waitcnt lgkmcnt(0)
	s_nop 0
	v_mov_b32_e32 v10, v167
	s_nop 1
	v_permlane16_swap_b32_e32 v10, v11
	v_cvt_pk_bf16_f32 v8, v26, v8
	v_cvt_pk_bf16_f32 v9, v9, v10
	v_cvt_pk_bf16_f32 v10, v16, v17
	v_cvt_pk_bf16_f32 v11, v18, v11
	global_store_dwordx4 v[24:25], v[8:11], off offset:64
	v_mfma_f32_16x16x32_bf16 v[100:103], v[160:163], v[80:83], v[100:103]
	s_nop 0
	v_or_b32_e32 v8, 16, v48
	v_ashrrev_i32_e32 v9, 31, v8
	v_lshlrev_b64 v[8:9], 11, v[8:9]
	v_mfma_f32_16x16x32_bf16 v[80:83], v[178:181], v[80:83], v[40:43]
	s_nop 0
	s_nop 0
	s_nop 0
	v_mfma_f32_16x16x32_bf16 v[40:43], v[140:143], v[104:107], v[64:67]
	s_nop 0
	s_nop 1
	v_lshl_add_u64 v[64:65], v[50:51], 0, v[8:9]
	s_nop 0
	s_nop 0
	s_nop 0
	s_nop 0
	v_mfma_f32_16x16x32_bf16 v[136:139], v[140:143], v[44:47], v[136:139]
	s_waitcnt lgkmcnt(0)
	s_nop 0
	v_mfma_f32_16x16x32_bf16 v[132:135], v[144:147], v[44:47], v[132:135]
	v_mfma_f32_16x16x32_bf16 v[128:131], v[160:163], v[44:47], v[128:131]
	v_mfma_f32_16x16x32_bf16 v[44:47], v[144:147], v[104:107], v[52:55]
	v_mfma_f32_16x16x32_bf16 v[36:39], v[178:181], v[104:107], v[60:63]
	s_nop 1
	v_mov_b32_e32 v49, v156
	v_mov_b32_e32 v54, v152
	s_nop 1
	v_permlane16_swap_b32_e32 v49, v54
	s_waitcnt lgkmcnt(0)
	s_nop 0
	v_mov_b32_e32 v8, v157
	v_mov_b32_e32 v55, v153
	s_nop 1
	v_permlane16_swap_b32_e32 v8, v55
	s_nop 0
	v_mov_b32_e32 v53, v158
	v_mov_b32_e32 v60, v154
	s_nop 1
	v_permlane16_swap_b32_e32 v53, v60
	s_nop 0
	v_mov_b32_e32 v61, v159
	v_mov_b32_e32 v62, v155
	s_nop 1
	v_permlane16_swap_b32_e32 v61, v62
	v_cvt_pk_bf16_f32 v52, v49, v8
	v_cvt_pk_bf16_f32 v53, v53, v61
	v_cvt_pk_bf16_f32 v54, v54, v55
	v_cvt_pk_bf16_f32 v55, v60, v62
	v_mfma_f32_16x16x32_bf16 v[8:11], v[140:143], v[116:119], v[12:15]
	global_store_dwordx4 v[64:65], v[52:55], off
	s_nop 0
	s_nop 0
	v_mfma_f32_16x16x32_bf16 v[12:15], v[144:147], v[116:119], v[4:7]
	s_nop 0
	s_nop 0
	s_nop 0
	v_cndmask_b32_e32 v4, v148, v182, vcc
	ds_bpermute_b32 v54, v186, v4
	s_nop 0
	s_waitcnt lgkmcnt(1)
	s_nop 0
	v_mov_b32_e32 v60, v149
	v_mov_b32_e32 v49, v183
	s_nop 1
	v_permlane16_swap_b32_e32 v60, v49
	s_waitcnt lgkmcnt(1)
	s_nop 0
	s_waitcnt lgkmcnt(0)
	v_cndmask_b32_e32 v55, v54, v148, vcc
	v_cndmask_b32_e32 v54, v182, v54, vcc
	v_mov_b32_e32 v61, v150
	v_mov_b32_e32 v62, v184
	s_nop 1
	v_permlane16_swap_b32_e32 v61, v62
	s_waitcnt lgkmcnt(0)
	s_nop 0
	v_mov_b32_e32 v63, v151
	v_mov_b32_e32 v66, v185
	s_nop 1
	v_permlane16_swap_b32_e32 v63, v66
	v_cvt_pk_bf16_f32 v52, v55, v60
	v_cvt_pk_bf16_f32 v53, v61, v63
	v_cvt_pk_bf16_f32 v54, v54, v49
	v_cvt_pk_bf16_f32 v55, v62, v66
	global_store_dwordx4 v[64:65], v[52:55], off offset:64
	s_nop 0
	s_nop 0
	v_or_b32_e32 v52, 32, v48
	v_ashrrev_i32_e32 v53, 31, v52
	v_lshlrev_b64 v[52:53], 11, v[52:53]
	v_lshl_add_u64 v[60:61], v[50:51], 0, v[52:53]
	s_nop 0
	s_nop 0
	s_nop 0
	s_nop 0
	s_nop 0
	s_nop 0
	s_waitcnt lgkmcnt(0)
	s_nop 0
	v_mov_b32_e32 v55, v136
	v_mov_b32_e32 v49, v132
	s_nop 1
	v_permlane16_swap_b32_e32 v55, v49
	s_waitcnt lgkmcnt(0)
	s_nop 0
	v_mov_b32_e32 v62, v137
	v_mov_b32_e32 v63, v133
	s_nop 1
	v_permlane16_swap_b32_e32 v62, v63
	s_waitcnt lgkmcnt(0)
	s_nop 0
	v_mov_b32_e32 v64, v138
	v_mov_b32_e32 v65, v134
	s_nop 1
	v_permlane16_swap_b32_e32 v64, v65
	s_waitcnt lgkmcnt(0)
	s_nop 0
	v_mov_b32_e32 v53, v139
	v_mov_b32_e32 v66, v135
	s_nop 1
	v_permlane16_swap_b32_e32 v53, v66
	v_cvt_pk_bf16_f32 v52, v55, v62
	v_cvt_pk_bf16_f32 v53, v64, v53
	v_cvt_pk_bf16_f32 v54, v49, v63
	v_cvt_pk_bf16_f32 v55, v65, v66
	global_store_dwordx4 v[60:61], v[52:55], off
	s_nop 0
	s_nop 0
	s_nop 0
	s_nop 0
	s_nop 0
	s_nop 0
	s_nop 0
	s_nop 0
	s_waitcnt lgkmcnt(0)
	s_nop 0
	v_mov_b32_e32 v55, v128
	v_mov_b32_e32 v49, v190
	s_nop 1
	v_permlane16_swap_b32_e32 v55, v49
	s_waitcnt lgkmcnt(0)
	s_nop 0
	v_mov_b32_e32 v62, v129
	v_mov_b32_e32 v63, v191
	s_nop 1
	v_permlane16_swap_b32_e32 v62, v63
	s_waitcnt lgkmcnt(0)
	s_nop 0
	v_mov_b32_e32 v64, v130
	v_mov_b32_e32 v65, v192
	s_nop 1
	v_permlane16_swap_b32_e32 v64, v65
	s_waitcnt lgkmcnt(0)
	s_nop 0
	v_mov_b32_e32 v53, v131
	v_mov_b32_e32 v66, v193
	s_nop 1
	v_permlane16_swap_b32_e32 v53, v66
	v_cvt_pk_bf16_f32 v52, v55, v62
	v_cvt_pk_bf16_f32 v53, v64, v53
	v_cvt_pk_bf16_f32 v54, v49, v63
	v_cvt_pk_bf16_f32 v55, v65, v66
	global_store_dwordx4 v[60:61], v[52:55], off offset:64
	s_nop 0
	s_nop 0
	v_or_b32_e32 v52, 48, v48
	v_ashrrev_i32_e32 v53, 31, v52
	v_lshlrev_b64 v[52:53], 11, v[52:53]
	v_lshl_add_u64 v[60:61], v[50:51], 0, v[52:53]
	s_nop 0
	s_nop 0
	s_nop 0
	s_nop 0
	s_nop 0
	s_nop 0
	s_waitcnt lgkmcnt(0)
	s_nop 0
	v_mov_b32_e32 v55, v120
	v_mov_b32_e32 v49, v108
	s_nop 1
	v_permlane16_swap_b32_e32 v55, v49
	s_waitcnt lgkmcnt(0)
	s_nop 0
	v_mov_b32_e32 v62, v121
	v_mov_b32_e32 v63, v109
	s_nop 1
	v_permlane16_swap_b32_e32 v62, v63
	s_waitcnt lgkmcnt(0)
	s_nop 0
	v_mov_b32_e32 v64, v122
	v_mov_b32_e32 v65, v110
	s_nop 1
	v_permlane16_swap_b32_e32 v64, v65
	s_waitcnt lgkmcnt(0)
	s_nop 0
	v_mov_b32_e32 v53, v123
	v_mov_b32_e32 v66, v111
	s_nop 1
	v_permlane16_swap_b32_e32 v53, v66
	v_cvt_pk_bf16_f32 v52, v55, v62
	v_cvt_pk_bf16_f32 v53, v64, v53
	v_cvt_pk_bf16_f32 v54, v49, v63
	v_cvt_pk_bf16_f32 v55, v65, v66
	global_store_dwordx4 v[60:61], v[52:55], off
	s_nop 0
	s_nop 0
	s_nop 0
	s_nop 0
	s_nop 0
	s_nop 0
	s_nop 0
	s_nop 0
	s_waitcnt lgkmcnt(0)
	s_nop 0
	v_mov_b32_e32 v55, v100
	v_mov_b32_e32 v49, v80
	s_nop 1
	v_permlane16_swap_b32_e32 v55, v49
	s_waitcnt lgkmcnt(0)
	s_nop 0
	v_mov_b32_e32 v62, v101
	v_mov_b32_e32 v63, v81
	s_nop 1
	v_permlane16_swap_b32_e32 v62, v63
	s_waitcnt lgkmcnt(0)
	s_nop 0
	v_mov_b32_e32 v64, v102
	v_mov_b32_e32 v65, v82
	s_nop 1
	v_permlane16_swap_b32_e32 v64, v65
	s_waitcnt lgkmcnt(0)
	s_nop 0
	v_mov_b32_e32 v53, v103
	v_mov_b32_e32 v66, v83
	s_nop 1
	v_permlane16_swap_b32_e32 v53, v66
	v_mfma_f32_16x16x32_bf16 v[92:95], v[140:143], v[88:91], v[92:95]
	v_cvt_pk_bf16_f32 v52, v55, v62
	v_cvt_pk_bf16_f32 v53, v64, v53
	v_cvt_pk_bf16_f32 v54, v49, v63
	v_mfma_f32_16x16x32_bf16 v[84:87], v[144:147], v[88:91], v[84:87]
	v_cvt_pk_bf16_f32 v55, v65, v66
	global_store_dwordx4 v[60:61], v[52:55], off offset:64
	v_mfma_f32_16x16x32_bf16 v[76:79], v[160:163], v[88:91], v[76:79]
	s_nop 0
	v_or_b32_e32 v52, 64, v48
	v_ashrrev_i32_e32 v53, 31, v52
	v_lshlrev_b64 v[52:53], 11, v[52:53]
	v_lshl_add_u64 v[60:61], v[50:51], 0, v[52:53]
	s_nop 0
	s_nop 0
	s_nop 0
	s_nop 0
	s_nop 0
	s_nop 0
	s_nop 0
	s_nop 0
	v_mfma_f32_16x16x32_bf16 v[56:59], v[178:181], v[88:91], v[56:59]
	s_waitcnt lgkmcnt(0)
	s_nop 0
	v_mov_b32_e32 v55, v92
	v_mov_b32_e32 v49, v84
	s_nop 1
	v_permlane16_swap_b32_e32 v55, v49
	s_waitcnt lgkmcnt(0)
	s_nop 0
	v_mov_b32_e32 v62, v93
	v_mov_b32_e32 v63, v85
	s_nop 1
	v_permlane16_swap_b32_e32 v62, v63
	s_waitcnt lgkmcnt(0)
	s_nop 0
	v_mov_b32_e32 v64, v94
	v_mov_b32_e32 v65, v86
	s_nop 1
	v_permlane16_swap_b32_e32 v64, v65
	s_waitcnt lgkmcnt(0)
	s_nop 0
	v_mov_b32_e32 v53, v95
	v_mov_b32_e32 v66, v87
	s_nop 1
	v_permlane16_swap_b32_e32 v53, v66
	v_cvt_pk_bf16_f32 v52, v55, v62
	v_cvt_pk_bf16_f32 v53, v64, v53
	v_cvt_pk_bf16_f32 v54, v49, v63
	v_cvt_pk_bf16_f32 v55, v65, v66
	global_store_dwordx4 v[60:61], v[52:55], off
	s_nop 0
	s_nop 0
	s_nop 0
	s_nop 0
	s_nop 0
	s_nop 0
	s_nop 0
	s_nop 0
	s_waitcnt lgkmcnt(0)
	s_nop 0
	v_mov_b32_e32 v55, v76
	v_mov_b32_e32 v49, v56
	s_nop 1
	v_permlane16_swap_b32_e32 v55, v49
	s_waitcnt lgkmcnt(0)
	s_nop 0
	v_mov_b32_e32 v56, v77
	s_nop 1
	v_permlane16_swap_b32_e32 v56, v57
	s_waitcnt lgkmcnt(0)
	s_nop 0
	v_mov_b32_e32 v62, v78
	s_nop 1
	v_permlane16_swap_b32_e32 v62, v58
	s_waitcnt lgkmcnt(0)
	s_nop 0
	v_mov_b32_e32 v53, v79
	s_nop 1
	v_permlane16_swap_b32_e32 v53, v59
	v_cvt_pk_bf16_f32 v52, v55, v56
	v_cvt_pk_bf16_f32 v53, v62, v53
	v_cvt_pk_bf16_f32 v54, v49, v57
	v_cvt_pk_bf16_f32 v55, v58, v59
	global_store_dwordx4 v[60:61], v[52:55], off offset:64
	s_nop 0
	s_nop 0
	s_nop 0
	s_nop 0
	s_nop 0
	s_nop 0
	s_nop 0
	s_nop 0
	v_mfma_f32_16x16x32_bf16 v[32:35], v[160:163], v[104:107], v[72:75]
	v_or_b32_e32 v52, 0x50, v48
	v_ashrrev_i32_e32 v53, 31, v52
	v_lshlrev_b64 v[52:53], 11, v[52:53]
	s_waitcnt lgkmcnt(0)
	s_nop 0
	s_nop 1
	v_permlane16_swap_b32_e32 v40, v44
	s_waitcnt lgkmcnt(0)
	s_nop 0
	s_nop 1
	v_permlane16_swap_b32_e32 v41, v45
	s_waitcnt lgkmcnt(0)
	s_nop 0
	s_nop 1
	v_permlane16_swap_b32_e32 v42, v46
	s_waitcnt lgkmcnt(0)
	s_nop 0
	s_nop 1
	v_permlane16_swap_b32_e32 v43, v47
	v_lshl_add_u64 v[52:53], v[50:51], 0, v[52:53]
	v_cvt_pk_bf16_f32 v40, v40, v41
	v_cvt_pk_bf16_f32 v41, v42, v43
	v_cvt_pk_bf16_f32 v42, v44, v45
	v_cvt_pk_bf16_f32 v43, v46, v47
	global_store_dwordx4 v[52:53], v[40:43], off
	v_mfma_f32_16x16x32_bf16 v[24:27], v[140:143], v[112:115], v[96:99]
	s_nop 0
	s_nop 0
	s_nop 0
	s_nop 0
	s_nop 0
	s_nop 0
	s_nop 0
	s_nop 0
	s_nop 0
	v_mfma_f32_16x16x32_bf16 v[28:31], v[144:147], v[112:115], v[28:31]
	s_waitcnt lgkmcnt(0)
	s_nop 0
	s_nop 1
	v_permlane16_swap_b32_e32 v32, v36
	s_waitcnt lgkmcnt(0)
	s_nop 0
	s_nop 1
	v_permlane16_swap_b32_e32 v33, v37
	s_waitcnt lgkmcnt(0)
	s_nop 0
	s_nop 1
	v_permlane16_swap_b32_e32 v34, v38
	s_waitcnt lgkmcnt(0)
	s_nop 0
	s_nop 1
	v_permlane16_swap_b32_e32 v35, v39
	v_cvt_pk_bf16_f32 v32, v32, v33
	v_cvt_pk_bf16_f32 v33, v34, v35
	v_cvt_pk_bf16_f32 v34, v36, v37
	v_cvt_pk_bf16_f32 v35, v38, v39
	global_store_dwordx4 v[52:53], v[32:35], off offset:64
	s_nop 0
	s_nop 0
	s_nop 0
	s_nop 0
	s_nop 0
	s_nop 0
	s_nop 0
	s_nop 0
	v_mfma_f32_16x16x32_bf16 v[16:19], v[160:163], v[112:115], v[124:127]
	v_or_b32_e32 v32, 0x60, v48
	v_ashrrev_i32_e32 v33, 31, v32
	v_lshlrev_b64 v[32:33], 11, v[32:33]
	v_mfma_f32_16x16x32_bf16 v[20:23], v[178:181], v[112:115], v[20:23]
	s_waitcnt lgkmcnt(0)
	s_nop 0
	s_nop 1
	v_permlane16_swap_b32_e32 v24, v28
	s_waitcnt lgkmcnt(0)
	s_nop 0
	s_nop 1
	v_permlane16_swap_b32_e32 v25, v29
	s_waitcnt lgkmcnt(0)
	s_nop 0
	s_nop 1
	v_permlane16_swap_b32_e32 v26, v30
	s_waitcnt lgkmcnt(0)
	s_nop 0
	s_nop 1
	v_permlane16_swap_b32_e32 v27, v31
	v_lshl_add_u64 v[32:33], v[50:51], 0, v[32:33]
	v_cvt_pk_bf16_f32 v24, v24, v25
	v_cvt_pk_bf16_f32 v25, v26, v27
	v_cvt_pk_bf16_f32 v26, v28, v29
	v_cvt_pk_bf16_f32 v27, v30, v31
	global_store_dwordx4 v[32:33], v[24:27], off
	v_mfma_f32_16x16x32_bf16 v[0:3], v[160:163], v[116:119], v[0:3]
	s_nop 0
	s_nop 0
	s_nop 0
	s_nop 0
	s_nop 0
	s_nop 0
	s_nop 0
	s_nop 0
	s_nop 0
	v_mfma_f32_16x16x32_bf16 v[4:7], v[178:181], v[116:119], v[68:71]
	s_waitcnt lgkmcnt(0)
	s_nop 0
	s_nop 1
	v_permlane16_swap_b32_e32 v16, v20
	s_waitcnt lgkmcnt(0)
	s_nop 0
	s_nop 1
	v_permlane16_swap_b32_e32 v17, v21
	s_waitcnt lgkmcnt(0)
	s_nop 0
	s_nop 1
	v_permlane16_swap_b32_e32 v18, v22
	s_waitcnt lgkmcnt(0)
	s_nop 0
	s_nop 1
	v_permlane16_swap_b32_e32 v19, v23
	v_cvt_pk_bf16_f32 v16, v16, v17
	v_cvt_pk_bf16_f32 v17, v18, v19
	v_cvt_pk_bf16_f32 v18, v20, v21
	v_cvt_pk_bf16_f32 v19, v22, v23
	global_store_dwordx4 v[32:33], v[16:19], off offset:64
	s_nop 0
	s_nop 0
	s_nop 0
	s_nop 0
	s_nop 0
	s_nop 0
	s_nop 0
	s_nop 0
	v_or_b32_e32 v16, 0x70, v48
	v_ashrrev_i32_e32 v17, 31, v16
	v_lshlrev_b64 v[16:17], 11, v[16:17]
	s_waitcnt lgkmcnt(0)
	s_nop 0
	s_nop 1
	v_permlane16_swap_b32_e32 v8, v12
	s_waitcnt lgkmcnt(0)
	s_nop 0
	s_nop 1
	v_permlane16_swap_b32_e32 v9, v13
	s_waitcnt lgkmcnt(0)
	s_nop 0
	s_nop 1
	v_permlane16_swap_b32_e32 v10, v14
	s_waitcnt lgkmcnt(0)
	s_nop 0
	s_nop 1
	v_permlane16_swap_b32_e32 v11, v15
	v_lshl_add_u64 v[16:17], v[50:51], 0, v[16:17]
	v_cvt_pk_bf16_f32 v8, v8, v9
	v_cvt_pk_bf16_f32 v9, v10, v11
	v_cvt_pk_bf16_f32 v10, v12, v13
	v_cvt_pk_bf16_f32 v11, v14, v15
	global_store_dwordx4 v[16:17], v[8:11], off
	s_nop 1
	s_nop 0
	s_nop 0
	s_nop 0
	s_nop 0
	s_nop 0
	s_nop 0
	s_nop 0
	s_nop 0
	s_waitcnt lgkmcnt(0)
	s_nop 0
	s_nop 1
	v_permlane16_swap_b32_e32 v0, v4
	s_waitcnt lgkmcnt(0)
	s_nop 0
	s_nop 1
	v_permlane16_swap_b32_e32 v1, v5
	s_waitcnt lgkmcnt(0)
	s_nop 0
	s_nop 1
	v_permlane16_swap_b32_e32 v2, v6
	s_waitcnt lgkmcnt(0)
	s_nop 0
	s_nop 1
	v_permlane16_swap_b32_e32 v3, v7
	v_cvt_pk_bf16_f32 v0, v0, v1
	v_cvt_pk_bf16_f32 v1, v2, v3
	v_cvt_pk_bf16_f32 v2, v4, v5
	v_cvt_pk_bf16_f32 v3, v6, v7
	global_store_dwordx4 v[16:17], v[0:3], off offset:64
	s_load_dword s6, s[6:7], 0x0
	s_waitcnt lgkmcnt(0)
	s_add_i32 s8, s6, s8
	s_cmpk_gt_i32 s8, 0xff
	s_cbranch_scc0 .LBB0_801

.LBB0_1095:
	v_lshrrev_b32_e32 v52, 4, v162
	v_bfe_u32 v178, v162, 4, 1
	v_lshlrev_b32_e32 v52, 2, v52
	v_and_b32_e32 v54, 8, v52
	v_lshlrev_b32_e32 v52, 5, v178
	v_mov_b32_e32 v53, v177
	v_lshl_add_u64 v[52:53], v[160:161], 0, v[52:53]
	v_lshlrev_b32_e32 v160, 1, v54
	v_mov_b32_e32 v161, v177
	v_cmp_lt_i32_e32 vcc, v189, v202
	v_lshl_add_u64 v[162:163], v[52:53], 0, v[160:161]
	v_cmp_eq_u32_e64 s[42:43], 0, v178
	v_cndmask_b32_e32 v52, v203, v189, vcc
	v_lshlrev_b32_e32 v173, 2, v52
	s_nop 0
	s_nop 0
	s_nop 0
	s_nop 0
	s_nop 0
	s_nop 0
	s_nop 0
	s_nop 0
	s_andn2_b64 vcc, exec, s[48:49]
	s_waitcnt lgkmcnt(0)
	s_nop 0
	v_mov_b32_e32 v56, v144
	v_mov_b32_e32 v57, v148
	s_nop 1
	v_permlane16_swap_b32_e32 v56, v57
	s_waitcnt lgkmcnt(0)
	s_nop 0
	v_mov_b32_e32 v52, v145
	v_mov_b32_e32 v58, v149
	s_nop 1
	v_permlane16_swap_b32_e32 v52, v58
	s_waitcnt lgkmcnt(0)
	s_nop 0
	v_mov_b32_e32 v53, v146
	v_mov_b32_e32 v59, v150
	s_nop 1
	v_permlane16_swap_b32_e32 v53, v59
	s_waitcnt lgkmcnt(0)
	s_nop 0
	v_mov_b32_e32 v54, v147
	v_mov_b32_e32 v55, v151
	s_nop 1
	v_permlane16_swap_b32_e32 v54, v55
	v_cvt_pk_bf16_f32 v52, v56, v52
	v_cvt_pk_bf16_f32 v53, v53, v54
	v_cvt_pk_bf16_f32 v54, v57, v58
	v_cvt_pk_bf16_f32 v55, v59, v55
	global_store_dwordx4 v[162:163], v[52:55], off
	s_nop 1
	v_cndmask_b32_e64 v52, 0, 1, s[48:49]
	v_cmp_ne_u32_e64 s[44:45], 1, v52
	s_mov_b64 s[48:49], -1
	s_cbranch_vccnz .LBB0_1099
	v_mov_b64_e32 v[142:143], v[138:139]
	v_mov_b64_e32 v[134:135], v[130:131]
	s_and_b64 vcc, exec, s[40:41]
	v_mov_b64_e32 v[140:141], v[136:137]
	v_mov_b64_e32 v[132:133], v[128:129]
	s_cbranch_vccnz .LBB0_1098
	v_mul_f32_e32 v53, 0xbfb8aa3b, v136
	v_mul_f32_e32 v54, 0xbfb8aa3b, v129
	v_exp_f32_e32 v53, v53
	v_exp_f32_e32 v55, v54
	v_mul_f32_e32 v57, 0xbfb8aa3b, v138
	v_mul_f32_e32 v58, 0xbfb8aa3b, v131
	v_add_f32_e32 v53, 1.0, v53
	v_mul_f32_e32 v52, 0xbfb8aa3b, v128
	v_rcp_f32_e32 v54, v53
	v_add_f32_e32 v53, 1.0, v55
	v_mul_f32_e32 v55, 0xbfb8aa3b, v137
	v_mul_f32_e32 v56, 0xbfb8aa3b, v130
	v_exp_f32_e32 v57, v57
	v_exp_f32_e32 v59, v58
	v_mul_f32_e32 v58, 0xbfb8aa3b, v139
	v_exp_f32_e32 v52, v52
	v_exp_f32_e32 v55, v55
	v_exp_f32_e32 v56, v56
	v_exp_f32_e32 v132, v58
	v_add_f32_e32 v57, 1.0, v57
	v_add_f32_e32 v52, 1.0, v52
	v_add_f32_e32 v55, 1.0, v55
	v_add_f32_e32 v56, 1.0, v56
	v_rcp_f32_e32 v58, v57
	v_add_f32_e32 v57, 1.0, v59
	v_add_f32_e32 v59, 1.0, v132
	v_rcp_f32_e32 v52, v52
	v_rcp_f32_e32 v53, v53
	v_rcp_f32_e32 v56, v56
	v_rcp_f32_e32 v57, v57
	v_rcp_f32_e32 v59, v59
	v_rcp_f32_e32 v55, v55
	v_pk_mul_f32 v[132:133], v[128:129], v[52:53]
	v_pk_mul_f32 v[134:135], v[130:131], v[56:57]
	v_pk_mul_f32 v[142:143], v[138:139], v[58:59]
	v_pk_mul_f32 v[140:141], v[136:137], v[54:55]

.LBB0_1101:
	s_nop 0
	s_nop 0
	s_nop 0
	s_nop 0
	s_nop 0
	s_nop 0
	s_nop 0
	s_nop 0
	s_nop 0
	v_mov_b64_e32 v[138:139], v[98:99]
	s_waitcnt lgkmcnt(0)
	s_nop 0
	v_mov_b32_e32 v56, v132
	v_mov_b32_e32 v57, v140
	s_nop 1
	v_permlane16_swap_b32_e32 v56, v57
	s_waitcnt lgkmcnt(0)
	s_nop 0
	v_mov_b32_e32 v52, v133
	v_mov_b32_e32 v58, v141
	s_nop 1
	v_permlane16_swap_b32_e32 v52, v58
	s_waitcnt lgkmcnt(0)
	s_nop 0
	v_mov_b32_e32 v53, v134
	v_mov_b32_e32 v59, v142
	s_nop 1
	v_permlane16_swap_b32_e32 v53, v59
	s_waitcnt lgkmcnt(0)
	s_nop 0
	v_mov_b32_e32 v54, v135
	v_mov_b32_e32 v55, v143
	s_nop 1
	v_permlane16_swap_b32_e32 v54, v55
	v_mov_b64_e32 v[130:131], v[102:103]
	v_mov_b64_e32 v[142:143], v[106:107]
	v_mov_b64_e32 v[134:135], v[110:111]
	v_cvt_pk_bf16_f32 v52, v56, v52
	v_cvt_pk_bf16_f32 v53, v53, v54
	v_cvt_pk_bf16_f32 v54, v57, v58
	v_cvt_pk_bf16_f32 v55, v59, v55
	v_or_b32_e32 v146, 16, v170
	v_mov_b64_e32 v[136:137], v[96:97]
	v_mov_b64_e32 v[128:129], v[100:101]
	v_mov_b64_e32 v[140:141], v[104:105]
	v_mov_b64_e32 v[132:133], v[108:109]
	global_store_dwordx4 v[162:163], v[52:55], off offset:64
	s_and_saveexec_b64 s[48:49], s[22:23]
	s_cbranch_execz .LBB0_1103
	v_or_b32_e32 v52, v168, v146
	v_lshlrev_b32_e32 v52, 7, v52
	v_mov_b32_e32 v53, v177
	v_lshl_add_u64 v[136:137], v[154:155], 0, v[52:53]
	v_lshl_add_u64 v[140:141], v[152:153], 0, v[52:53]
	global_load_dwordx4 v[52:55], v[136:137], off
	global_load_dwordx4 v[56:59], v[140:141], off
	v_mov_b32_e32 v132, v111
	v_mov_b32_e32 v133, v103
	s_waitcnt vmcnt(1)
	v_mul_f32_e32 v130, v110, v54
	s_waitcnt vmcnt(0)
	v_mul_f32_e32 v134, v102, v58
	v_mul_f32_e32 v138, v110, v58
	v_mov_b32_e32 v58, v55
	v_pk_mul_f32 v[128:129], v[108:109], v[56:57]
	v_pk_mul_f32 v[56:57], v[100:101], v[56:57]
	v_pk_mul_f32 v[132:133], v[132:133], v[58:59]
	v_mul_f32_e32 v54, v102, v54
	v_mov_b32_e32 v131, v132
	v_mov_b32_e32 v135, v133
	v_pk_fma_f32 v[132:133], v[108:109], v[52:53], v[56:57] neg_lo:[0,0,1] neg_hi:[0,0,1]
	v_mov_b32_e32 v56, v103
	v_mov_b32_e32 v57, v111
	v_pk_mul_f32 v[56:57], v[56:57], v[58:59]
	v_pk_add_f32 v[134:135], v[130:131], v[134:135] neg_lo:[0,1] neg_hi:[0,1]
	v_mov_b32_e32 v55, v56
	v_mov_b32_e32 v139, v57
	v_pk_fma_f32 v[128:129], v[100:101], v[52:53], v[128:129]
	v_pk_add_f32 v[130:131], v[54:55], v[138:139]
	global_load_dwordx4 v[136:139], v[136:137], off offset:64
	s_nop 0
	global_load_dwordx4 v[52:55], v[140:141], off offset:64
	v_mov_b32_e32 v140, v107
	v_mov_b32_e32 v141, v99
	s_waitcnt vmcnt(1)
	v_mul_f32_e32 v58, v106, v138
	s_waitcnt vmcnt(0)
	v_mul_f32_e32 v142, v98, v54
	v_mul_f32_e32 v144, v106, v54
	v_mov_b32_e32 v54, v139
	v_pk_mul_f32 v[56:57], v[104:105], v[52:53]
	v_pk_mul_f32 v[52:53], v[96:97], v[52:53]
	v_pk_mul_f32 v[140:141], v[140:141], v[54:55]
	v_mul_f32_e32 v138, v98, v138
	v_mov_b32_e32 v59, v140
	v_mov_b32_e32 v143, v141
	v_pk_fma_f32 v[140:141], v[104:105], v[136:137], v[52:53] neg_lo:[0,0,1] neg_hi:[0,0,1]
	v_mov_b32_e32 v52, v99
	v_mov_b32_e32 v53, v107
	v_pk_mul_f32 v[52:53], v[52:53], v[54:55]
	v_pk_add_f32 v[142:143], v[58:59], v[142:143] neg_lo:[0,1] neg_hi:[0,1]
	v_mov_b32_e32 v139, v52
	v_mov_b32_e32 v145, v53
	v_pk_fma_f32 v[136:137], v[96:97], v[136:137], v[56:57]
	v_pk_add_f32 v[138:139], v[138:139], v[144:145]

.LBB0_1123:
	v_lshlrev_b32_e32 v52, 4, v178
	v_lshlrev_b32_e32 v162, 1, v52
	v_mov_b32_e32 v163, v177
	v_lshl_add_u64 v[52:53], v[164:165], 0, v[162:163]
	v_mov_b32_e32 v161, v177
	v_lshl_add_u64 v[164:165], v[52:53], 0, v[160:161]
	s_nop 0
	s_nop 0
	s_nop 0
	s_nop 0
	s_nop 0
	s_nop 0
	s_nop 0
	s_nop 0
	s_and_b64 vcc, exec, s[44:45]
	s_waitcnt lgkmcnt(0)
	s_nop 0
	v_mov_b32_e32 v56, v144
	v_mov_b32_e32 v57, v148
	s_nop 1
	v_permlane16_swap_b32_e32 v56, v57
	s_waitcnt lgkmcnt(0)
	s_nop 0
	v_mov_b32_e32 v52, v145
	v_mov_b32_e32 v58, v149
	s_nop 1
	v_permlane16_swap_b32_e32 v52, v58
	s_waitcnt lgkmcnt(0)
	s_nop 0
	v_mov_b32_e32 v53, v146
	v_mov_b32_e32 v59, v150
	s_nop 1
	v_permlane16_swap_b32_e32 v53, v59
	s_waitcnt lgkmcnt(0)
	s_nop 0
	v_mov_b32_e32 v54, v147
	v_mov_b32_e32 v55, v151
	s_nop 1
	v_permlane16_swap_b32_e32 v54, v55
	v_cvt_pk_bf16_f32 v52, v56, v52
	v_cvt_pk_bf16_f32 v53, v53, v54
	v_cvt_pk_bf16_f32 v54, v57, v58
	v_cvt_pk_bf16_f32 v55, v59, v55
	s_mov_b64 s[48:49], -1
	global_store_dwordx4 v[164:165], v[52:55], off
	s_cbranch_vccnz .LBB0_1127
	v_mov_b64_e32 v[142:143], v[138:139]
	v_mov_b64_e32 v[134:135], v[130:131]
	s_and_b64 vcc, exec, s[40:41]
	v_mov_b64_e32 v[140:141], v[136:137]
	v_mov_b64_e32 v[132:133], v[128:129]
	s_cbranch_vccnz .LBB0_1126
	v_mul_f32_e32 v53, 0xbfb8aa3b, v136
	v_mul_f32_e32 v54, 0xbfb8aa3b, v129
	v_exp_f32_e32 v53, v53
	v_exp_f32_e32 v55, v54
	v_mul_f32_e32 v57, 0xbfb8aa3b, v138
	v_mul_f32_e32 v58, 0xbfb8aa3b, v131
	v_add_f32_e32 v53, 1.0, v53
	v_mul_f32_e32 v52, 0xbfb8aa3b, v128
	v_rcp_f32_e32 v54, v53
	v_add_f32_e32 v53, 1.0, v55
	v_mul_f32_e32 v55, 0xbfb8aa3b, v137
	v_mul_f32_e32 v56, 0xbfb8aa3b, v130
	v_exp_f32_e32 v57, v57
	v_exp_f32_e32 v59, v58
	v_mul_f32_e32 v58, 0xbfb8aa3b, v139
	v_exp_f32_e32 v52, v52
	v_exp_f32_e32 v55, v55
	v_exp_f32_e32 v56, v56
	v_exp_f32_e32 v132, v58
	v_add_f32_e32 v57, 1.0, v57
	v_add_f32_e32 v52, 1.0, v52
	v_add_f32_e32 v55, 1.0, v55
	v_add_f32_e32 v56, 1.0, v56
	v_rcp_f32_e32 v58, v57
	v_add_f32_e32 v57, 1.0, v59
	v_add_f32_e32 v59, 1.0, v132
	v_rcp_f32_e32 v52, v52
	v_rcp_f32_e32 v53, v53
	v_rcp_f32_e32 v56, v56
	v_rcp_f32_e32 v57, v57
	v_rcp_f32_e32 v59, v59
	v_rcp_f32_e32 v55, v55
	v_pk_mul_f32 v[132:133], v[128:129], v[52:53]
	v_pk_mul_f32 v[134:135], v[130:131], v[56:57]
	v_pk_mul_f32 v[142:143], v[138:139], v[58:59]
	v_pk_mul_f32 v[140:141], v[136:137], v[54:55]

.LBB0_1129:
	s_nop 0
	s_nop 0
	s_nop 0
	s_nop 0
	s_nop 0
	s_nop 0
	s_nop 0
	s_nop 0
	s_nop 0
	v_mov_b64_e32 v[138:139], v[82:83]
	s_waitcnt lgkmcnt(0)
	s_nop 0
	v_mov_b32_e32 v56, v132
	v_mov_b32_e32 v57, v140
	s_nop 1
	v_permlane16_swap_b32_e32 v56, v57
	s_waitcnt lgkmcnt(0)
	s_nop 0
	v_mov_b32_e32 v52, v133
	v_mov_b32_e32 v58, v141
	s_nop 1
	v_permlane16_swap_b32_e32 v52, v58
	s_waitcnt lgkmcnt(0)
	s_nop 0
	v_mov_b32_e32 v53, v134
	v_mov_b32_e32 v59, v142
	s_nop 1
	v_permlane16_swap_b32_e32 v53, v59
	s_waitcnt lgkmcnt(0)
	s_nop 0
	v_mov_b32_e32 v54, v135
	v_mov_b32_e32 v55, v143
	s_nop 1
	v_permlane16_swap_b32_e32 v54, v55
	v_mov_b64_e32 v[130:131], v[86:87]
	v_mov_b64_e32 v[142:143], v[90:91]
	v_mov_b64_e32 v[134:135], v[94:95]
	v_cvt_pk_bf16_f32 v52, v56, v52
	v_cvt_pk_bf16_f32 v53, v53, v54
	v_cvt_pk_bf16_f32 v54, v57, v58
	v_cvt_pk_bf16_f32 v55, v59, v55
	v_or_b32_e32 v146, 32, v170
	v_mov_b64_e32 v[136:137], v[80:81]
	v_mov_b64_e32 v[128:129], v[84:85]
	v_mov_b64_e32 v[140:141], v[88:89]
	v_mov_b64_e32 v[132:133], v[92:93]
	global_store_dwordx4 v[164:165], v[52:55], off offset:64
	s_and_saveexec_b64 s[48:49], s[22:23]
	s_cbranch_execz .LBB0_1131
	v_or_b32_e32 v52, v168, v146
	v_lshlrev_b32_e32 v52, 7, v52
	v_mov_b32_e32 v53, v177
	v_lshl_add_u64 v[136:137], v[154:155], 0, v[52:53]
	v_lshl_add_u64 v[140:141], v[152:153], 0, v[52:53]
	global_load_dwordx4 v[52:55], v[136:137], off
	global_load_dwordx4 v[56:59], v[140:141], off
	v_mov_b32_e32 v132, v95
	v_mov_b32_e32 v133, v87
	s_waitcnt vmcnt(1)
	v_mul_f32_e32 v130, v94, v54
	s_waitcnt vmcnt(0)
	v_mul_f32_e32 v134, v86, v58
	v_mul_f32_e32 v138, v94, v58
	v_mov_b32_e32 v58, v55
	v_pk_mul_f32 v[128:129], v[92:93], v[56:57]
	v_pk_mul_f32 v[56:57], v[84:85], v[56:57]
	v_pk_mul_f32 v[132:133], v[132:133], v[58:59]
	v_mul_f32_e32 v54, v86, v54
	v_mov_b32_e32 v131, v132
	v_mov_b32_e32 v135, v133
	v_pk_fma_f32 v[132:133], v[92:93], v[52:53], v[56:57] neg_lo:[0,0,1] neg_hi:[0,0,1]
	v_mov_b32_e32 v56, v87
	v_mov_b32_e32 v57, v95
	v_pk_mul_f32 v[56:57], v[56:57], v[58:59]
	v_pk_add_f32 v[134:135], v[130:131], v[134:135] neg_lo:[0,1] neg_hi:[0,1]
	v_mov_b32_e32 v55, v56
	v_mov_b32_e32 v139, v57
	v_pk_fma_f32 v[128:129], v[84:85], v[52:53], v[128:129]
	v_pk_add_f32 v[130:131], v[54:55], v[138:139]
	global_load_dwordx4 v[136:139], v[136:137], off offset:64
	s_nop 0
	global_load_dwordx4 v[52:55], v[140:141], off offset:64
	v_mov_b32_e32 v140, v91
	v_mov_b32_e32 v141, v83
	s_waitcnt vmcnt(1)
	v_mul_f32_e32 v58, v90, v138
	s_waitcnt vmcnt(0)
	v_mul_f32_e32 v142, v82, v54
	v_mul_f32_e32 v144, v90, v54
	v_mov_b32_e32 v54, v139
	v_pk_mul_f32 v[56:57], v[88:89], v[52:53]
	v_pk_mul_f32 v[52:53], v[80:81], v[52:53]
	v_pk_mul_f32 v[140:141], v[140:141], v[54:55]
	v_mul_f32_e32 v138, v82, v138
	v_mov_b32_e32 v59, v140
	v_mov_b32_e32 v143, v141
	v_pk_fma_f32 v[140:141], v[88:89], v[136:137], v[52:53] neg_lo:[0,0,1] neg_hi:[0,0,1]
	v_mov_b32_e32 v52, v83
	v_mov_b32_e32 v53, v91
	v_pk_mul_f32 v[52:53], v[52:53], v[54:55]
	v_pk_add_f32 v[142:143], v[58:59], v[142:143] neg_lo:[0,1] neg_hi:[0,1]
	v_mov_b32_e32 v139, v52
	v_mov_b32_e32 v145, v53
	v_pk_fma_f32 v[136:137], v[80:81], v[136:137], v[56:57]
	v_pk_add_f32 v[138:139], v[138:139], v[144:145]

.LBB0_1151:
	v_mov_b32_e32 v163, v177
	v_lshl_add_u64 v[52:53], v[164:165], 0, v[162:163]
	v_mov_b32_e32 v161, v177
	v_lshl_add_u64 v[164:165], v[52:53], 0, v[160:161]
	s_nop 0
	s_nop 0
	s_nop 0
	s_nop 0
	s_nop 0
	s_nop 0
	s_nop 0
	s_nop 0
	s_and_b64 vcc, exec, s[44:45]
	s_waitcnt lgkmcnt(0)
	s_nop 0
	v_mov_b32_e32 v56, v144
	v_mov_b32_e32 v57, v148
	s_nop 1
	v_permlane16_swap_b32_e32 v56, v57
	s_waitcnt lgkmcnt(0)
	s_nop 0
	v_mov_b32_e32 v52, v145
	v_mov_b32_e32 v58, v149
	s_nop 1
	v_permlane16_swap_b32_e32 v52, v58
	s_waitcnt lgkmcnt(0)
	s_nop 0
	v_mov_b32_e32 v53, v146
	v_mov_b32_e32 v59, v150
	s_nop 1
	v_permlane16_swap_b32_e32 v53, v59
	s_waitcnt lgkmcnt(0)
	s_nop 0
	v_mov_b32_e32 v54, v147
	v_mov_b32_e32 v55, v151
	s_nop 1
	v_permlane16_swap_b32_e32 v54, v55
	v_cvt_pk_bf16_f32 v52, v56, v52
	v_cvt_pk_bf16_f32 v53, v53, v54
	v_cvt_pk_bf16_f32 v54, v57, v58
	v_cvt_pk_bf16_f32 v55, v59, v55
	s_mov_b64 s[48:49], -1
	global_store_dwordx4 v[164:165], v[52:55], off
	s_cbranch_vccnz .LBB0_1155
	v_mov_b64_e32 v[142:143], v[138:139]
	v_mov_b64_e32 v[134:135], v[130:131]
	s_and_b64 vcc, exec, s[40:41]
	v_mov_b64_e32 v[140:141], v[136:137]
	v_mov_b64_e32 v[132:133], v[128:129]
	s_cbranch_vccnz .LBB0_1154
	v_mul_f32_e32 v53, 0xbfb8aa3b, v136
	v_mul_f32_e32 v54, 0xbfb8aa3b, v129
	v_exp_f32_e32 v53, v53
	v_exp_f32_e32 v55, v54
	v_mul_f32_e32 v57, 0xbfb8aa3b, v138
	v_mul_f32_e32 v58, 0xbfb8aa3b, v131
	v_add_f32_e32 v53, 1.0, v53
	v_mul_f32_e32 v52, 0xbfb8aa3b, v128
	v_rcp_f32_e32 v54, v53
	v_add_f32_e32 v53, 1.0, v55
	v_mul_f32_e32 v55, 0xbfb8aa3b, v137
	v_mul_f32_e32 v56, 0xbfb8aa3b, v130
	v_exp_f32_e32 v57, v57
	v_exp_f32_e32 v59, v58
	v_mul_f32_e32 v58, 0xbfb8aa3b, v139
	v_exp_f32_e32 v52, v52
	v_exp_f32_e32 v55, v55
	v_exp_f32_e32 v56, v56
	v_exp_f32_e32 v132, v58
	v_add_f32_e32 v57, 1.0, v57
	v_add_f32_e32 v52, 1.0, v52
	v_add_f32_e32 v55, 1.0, v55
	v_add_f32_e32 v56, 1.0, v56
	v_rcp_f32_e32 v58, v57
	v_add_f32_e32 v57, 1.0, v59
	v_add_f32_e32 v59, 1.0, v132
	v_rcp_f32_e32 v52, v52
	v_rcp_f32_e32 v53, v53
	v_rcp_f32_e32 v56, v56
	v_rcp_f32_e32 v57, v57
	v_rcp_f32_e32 v59, v59
	v_rcp_f32_e32 v55, v55
	v_pk_mul_f32 v[132:133], v[128:129], v[52:53]
	v_pk_mul_f32 v[134:135], v[130:131], v[56:57]
	v_pk_mul_f32 v[142:143], v[138:139], v[58:59]
	v_pk_mul_f32 v[140:141], v[136:137], v[54:55]

.LBB0_1157:
	s_nop 0
	s_nop 0
	s_nop 0
	s_nop 0
	s_nop 0
	s_nop 0
	s_nop 0
	s_nop 0
	s_nop 0
	v_mov_b64_e32 v[138:139], v[66:67]
	s_waitcnt lgkmcnt(0)
	s_nop 0
	v_mov_b32_e32 v56, v132
	v_mov_b32_e32 v57, v140
	s_nop 1
	v_permlane16_swap_b32_e32 v56, v57
	s_waitcnt lgkmcnt(0)
	s_nop 0
	v_mov_b32_e32 v52, v133
	v_mov_b32_e32 v58, v141
	s_nop 1
	v_permlane16_swap_b32_e32 v52, v58
	s_waitcnt lgkmcnt(0)
	s_nop 0
	v_mov_b32_e32 v53, v134
	v_mov_b32_e32 v59, v142
	s_nop 1
	v_permlane16_swap_b32_e32 v53, v59
	s_waitcnt lgkmcnt(0)
	s_nop 0
	v_mov_b32_e32 v54, v135
	v_mov_b32_e32 v55, v143
	s_nop 1
	v_permlane16_swap_b32_e32 v54, v55
	v_mov_b64_e32 v[130:131], v[70:71]
	v_mov_b64_e32 v[142:143], v[74:75]
	v_mov_b64_e32 v[134:135], v[78:79]
	v_cvt_pk_bf16_f32 v52, v56, v52
	v_cvt_pk_bf16_f32 v53, v53, v54
	v_cvt_pk_bf16_f32 v54, v57, v58
	v_cvt_pk_bf16_f32 v55, v59, v55
	v_or_b32_e32 v146, 48, v170
	v_mov_b64_e32 v[136:137], v[64:65]
	v_mov_b64_e32 v[128:129], v[68:69]
	v_mov_b64_e32 v[140:141], v[72:73]
	v_mov_b64_e32 v[132:133], v[76:77]
	global_store_dwordx4 v[164:165], v[52:55], off offset:64
	s_and_saveexec_b64 s[48:49], s[22:23]
	s_cbranch_execz .LBB0_1159
	v_or_b32_e32 v52, v168, v146
	v_lshlrev_b32_e32 v52, 7, v52
	v_mov_b32_e32 v53, v177
	v_lshl_add_u64 v[136:137], v[154:155], 0, v[52:53]
	v_lshl_add_u64 v[140:141], v[152:153], 0, v[52:53]
	global_load_dwordx4 v[52:55], v[136:137], off
	global_load_dwordx4 v[56:59], v[140:141], off
	v_mov_b32_e32 v132, v79
	v_mov_b32_e32 v133, v71
	s_waitcnt vmcnt(1)
	v_mul_f32_e32 v130, v78, v54
	s_waitcnt vmcnt(0)
	v_mul_f32_e32 v134, v70, v58
	v_mul_f32_e32 v138, v78, v58
	v_mov_b32_e32 v58, v55
	v_pk_mul_f32 v[128:129], v[76:77], v[56:57]
	v_pk_mul_f32 v[56:57], v[68:69], v[56:57]
	v_pk_mul_f32 v[132:133], v[132:133], v[58:59]
	v_mul_f32_e32 v54, v70, v54
	v_mov_b32_e32 v131, v132
	v_mov_b32_e32 v135, v133
	v_pk_fma_f32 v[132:133], v[76:77], v[52:53], v[56:57] neg_lo:[0,0,1] neg_hi:[0,0,1]
	v_mov_b32_e32 v56, v71
	v_mov_b32_e32 v57, v79
	v_pk_mul_f32 v[56:57], v[56:57], v[58:59]
	v_pk_add_f32 v[134:135], v[130:131], v[134:135] neg_lo:[0,1] neg_hi:[0,1]
	v_mov_b32_e32 v55, v56
	v_mov_b32_e32 v139, v57
	v_pk_fma_f32 v[128:129], v[68:69], v[52:53], v[128:129]
	v_pk_add_f32 v[130:131], v[54:55], v[138:139]
	global_load_dwordx4 v[136:139], v[136:137], off offset:64
	s_nop 0
	global_load_dwordx4 v[52:55], v[140:141], off offset:64
	v_mov_b32_e32 v140, v75
	v_mov_b32_e32 v141, v67
	s_waitcnt vmcnt(1)
	v_mul_f32_e32 v58, v74, v138
	s_waitcnt vmcnt(0)
	v_mul_f32_e32 v142, v66, v54
	v_mul_f32_e32 v144, v74, v54
	v_mov_b32_e32 v54, v139
	v_pk_mul_f32 v[56:57], v[72:73], v[52:53]
	v_pk_mul_f32 v[52:53], v[64:65], v[52:53]
	v_pk_mul_f32 v[140:141], v[140:141], v[54:55]
	v_mul_f32_e32 v138, v66, v138
	v_mov_b32_e32 v59, v140
	v_mov_b32_e32 v143, v141
	v_pk_fma_f32 v[140:141], v[72:73], v[136:137], v[52:53] neg_lo:[0,0,1] neg_hi:[0,0,1]
	v_mov_b32_e32 v52, v67
	v_mov_b32_e32 v53, v75
	v_pk_mul_f32 v[52:53], v[52:53], v[54:55]
	v_pk_add_f32 v[142:143], v[58:59], v[142:143] neg_lo:[0,1] neg_hi:[0,1]
	v_mov_b32_e32 v139, v52
	v_mov_b32_e32 v145, v53
	v_pk_fma_f32 v[136:137], v[64:65], v[136:137], v[56:57]
	v_pk_add_f32 v[138:139], v[138:139], v[144:145]

.LBB0_1185:
	s_nop 0
	s_nop 0
	s_nop 0
	s_nop 0
	s_nop 0
	s_nop 0
	s_nop 0
	s_nop 0
	s_nop 0
	v_mov_b64_e32 v[138:139], v[50:51]
	s_waitcnt lgkmcnt(0)
	s_nop 0
	v_mov_b32_e32 v56, v132
	v_mov_b32_e32 v57, v140
	s_nop 1
	v_permlane16_swap_b32_e32 v56, v57
	s_waitcnt lgkmcnt(0)
	s_nop 0
	v_mov_b32_e32 v52, v133
	v_mov_b32_e32 v58, v141
	s_nop 1
	v_permlane16_swap_b32_e32 v52, v58
	s_waitcnt lgkmcnt(0)
	s_nop 0
	v_mov_b32_e32 v53, v134
	v_mov_b32_e32 v59, v142
	s_nop 1
	v_permlane16_swap_b32_e32 v53, v59
	s_waitcnt lgkmcnt(0)
	s_nop 0
	v_mov_b32_e32 v54, v135
	v_mov_b32_e32 v55, v143
	s_nop 1
	v_permlane16_swap_b32_e32 v54, v55
	v_mov_b64_e32 v[128:129], v[180:181]
	v_mov_b64_e32 v[140:141], v[184:185]
	v_mov_b64_e32 v[134:135], v[62:63]
	v_cvt_pk_bf16_f32 v52, v56, v52
	v_cvt_pk_bf16_f32 v53, v53, v54
	v_cvt_pk_bf16_f32 v54, v57, v58
	v_cvt_pk_bf16_f32 v55, v59, v55
	v_or_b32_e32 v146, 64, v170
	v_mov_b64_e32 v[136:137], v[48:49]
	v_mov_b64_e32 v[130:131], v[182:183]
	v_mov_b64_e32 v[142:143], v[186:187]
	v_mov_b64_e32 v[132:133], v[60:61]
	global_store_dwordx4 v[164:165], v[52:55], off offset:64
	s_and_saveexec_b64 s[48:49], s[22:23]
	s_cbranch_execz .LBB0_1187
	v_or_b32_e32 v52, v168, v146
	v_lshlrev_b32_e32 v52, 7, v52
	v_mov_b32_e32 v53, v177
	v_lshl_add_u64 v[136:137], v[154:155], 0, v[52:53]
	v_lshl_add_u64 v[140:141], v[152:153], 0, v[52:53]
	global_load_dwordx4 v[52:55], v[136:137], off
	global_load_dwordx4 v[56:59], v[140:141], off
	v_mov_b32_e32 v132, v63
	v_mov_b32_e32 v133, v183
	s_waitcnt vmcnt(1)
	v_mul_f32_e32 v130, v62, v54
	s_waitcnt vmcnt(0)
	v_mul_f32_e32 v134, v182, v58
	v_mul_f32_e32 v138, v62, v58
	v_mov_b32_e32 v58, v55
	v_pk_mul_f32 v[128:129], v[60:61], v[56:57]
	v_pk_mul_f32 v[56:57], v[180:181], v[56:57]
	v_pk_mul_f32 v[132:133], v[132:133], v[58:59]
	v_mul_f32_e32 v54, v182, v54
	v_mov_b32_e32 v131, v132
	v_mov_b32_e32 v135, v133
	v_pk_fma_f32 v[132:133], v[60:61], v[52:53], v[56:57] neg_lo:[0,0,1] neg_hi:[0,0,1]
	v_mov_b32_e32 v56, v183
	v_mov_b32_e32 v57, v63
	v_pk_mul_f32 v[56:57], v[56:57], v[58:59]
	v_pk_add_f32 v[134:135], v[130:131], v[134:135] neg_lo:[0,1] neg_hi:[0,1]
	v_mov_b32_e32 v55, v56
	v_mov_b32_e32 v139, v57
	v_pk_fma_f32 v[128:129], v[180:181], v[52:53], v[128:129]
	v_pk_add_f32 v[130:131], v[54:55], v[138:139]
	global_load_dwordx4 v[136:139], v[136:137], off offset:64
	s_nop 0
	global_load_dwordx4 v[52:55], v[140:141], off offset:64
	v_mov_b32_e32 v140, v187
	v_mov_b32_e32 v141, v51
	s_waitcnt vmcnt(1)
	v_mul_f32_e32 v58, v186, v138
	s_waitcnt vmcnt(0)
	v_mul_f32_e32 v142, v50, v54
	v_mul_f32_e32 v144, v186, v54
	v_mov_b32_e32 v54, v139
	v_pk_mul_f32 v[56:57], v[184:185], v[52:53]
	v_pk_mul_f32 v[52:53], v[48:49], v[52:53]
	v_pk_mul_f32 v[140:141], v[140:141], v[54:55]
	v_mul_f32_e32 v138, v50, v138
	v_mov_b32_e32 v59, v140
	v_mov_b32_e32 v143, v141
	v_pk_fma_f32 v[140:141], v[184:185], v[136:137], v[52:53] neg_lo:[0,0,1] neg_hi:[0,0,1]
	v_mov_b32_e32 v52, v51
	v_mov_b32_e32 v53, v187
	v_pk_mul_f32 v[52:53], v[52:53], v[54:55]
	v_pk_add_f32 v[142:143], v[58:59], v[142:143] neg_lo:[0,1] neg_hi:[0,1]
	v_mov_b32_e32 v139, v52
	v_mov_b32_e32 v145, v53
	v_pk_fma_f32 v[136:137], v[48:49], v[136:137], v[56:57]
	v_pk_add_f32 v[138:139], v[138:139], v[144:145]

.LBB0_1213:
	s_nop 0
	s_nop 0
	s_nop 0
	s_nop 0
	s_nop 0
	s_nop 0
	s_nop 0
	s_nop 0
	s_nop 0
	v_mov_b64_e32 v[138:139], v[34:35]
	s_waitcnt lgkmcnt(0)
	s_nop 0
	v_mov_b32_e32 v56, v132
	v_mov_b32_e32 v57, v140
	s_nop 1
	v_permlane16_swap_b32_e32 v56, v57
	s_waitcnt lgkmcnt(0)
	s_nop 0
	v_mov_b32_e32 v52, v133
	v_mov_b32_e32 v58, v141
	s_nop 1
	v_permlane16_swap_b32_e32 v52, v58
	s_waitcnt lgkmcnt(0)
	s_nop 0
	v_mov_b32_e32 v53, v134
	v_mov_b32_e32 v59, v142
	s_nop 1
	v_permlane16_swap_b32_e32 v53, v59
	s_waitcnt lgkmcnt(0)
	s_nop 0
	v_mov_b32_e32 v54, v135
	v_mov_b32_e32 v55, v143
	s_nop 1
	v_permlane16_swap_b32_e32 v54, v55
	v_mov_b64_e32 v[130:131], v[38:39]
	v_mov_b64_e32 v[142:143], v[42:43]
	v_mov_b64_e32 v[134:135], v[46:47]
	v_cvt_pk_bf16_f32 v52, v56, v52
	v_cvt_pk_bf16_f32 v53, v53, v54
	v_cvt_pk_bf16_f32 v54, v57, v58
	v_cvt_pk_bf16_f32 v55, v59, v55
	v_or_b32_e32 v146, 0x50, v170
	v_mov_b64_e32 v[136:137], v[32:33]
	v_mov_b64_e32 v[128:129], v[36:37]
	v_mov_b64_e32 v[140:141], v[40:41]
	v_mov_b64_e32 v[132:133], v[44:45]
	global_store_dwordx4 v[164:165], v[52:55], off offset:64
	s_and_saveexec_b64 s[48:49], s[22:23]
	s_cbranch_execz .LBB0_1215
	v_or_b32_e32 v52, v168, v146
	v_lshlrev_b32_e32 v52, 7, v52
	v_mov_b32_e32 v53, v177
	v_lshl_add_u64 v[136:137], v[154:155], 0, v[52:53]
	v_lshl_add_u64 v[140:141], v[152:153], 0, v[52:53]
	global_load_dwordx4 v[52:55], v[136:137], off
	global_load_dwordx4 v[56:59], v[140:141], off
	v_mov_b32_e32 v132, v47
	v_mov_b32_e32 v133, v39
	s_waitcnt vmcnt(1)
	v_mul_f32_e32 v130, v46, v54
	s_waitcnt vmcnt(0)
	v_mul_f32_e32 v134, v38, v58
	v_mul_f32_e32 v138, v46, v58
	v_mov_b32_e32 v58, v55
	v_pk_mul_f32 v[128:129], v[44:45], v[56:57]
	v_pk_mul_f32 v[56:57], v[36:37], v[56:57]
	v_pk_mul_f32 v[132:133], v[132:133], v[58:59]
	v_mul_f32_e32 v54, v38, v54
	v_mov_b32_e32 v131, v132
	v_mov_b32_e32 v135, v133
	v_pk_fma_f32 v[132:133], v[44:45], v[52:53], v[56:57] neg_lo:[0,0,1] neg_hi:[0,0,1]
	v_mov_b32_e32 v56, v39
	v_mov_b32_e32 v57, v47
	v_pk_mul_f32 v[56:57], v[56:57], v[58:59]
	v_pk_add_f32 v[134:135], v[130:131], v[134:135] neg_lo:[0,1] neg_hi:[0,1]
	v_mov_b32_e32 v55, v56
	v_mov_b32_e32 v139, v57
	v_pk_fma_f32 v[128:129], v[36:37], v[52:53], v[128:129]
	v_pk_add_f32 v[130:131], v[54:55], v[138:139]
	global_load_dwordx4 v[136:139], v[136:137], off offset:64
	s_nop 0
	global_load_dwordx4 v[52:55], v[140:141], off offset:64
	v_mov_b32_e32 v140, v43
	v_mov_b32_e32 v141, v35
	s_waitcnt vmcnt(1)
	v_mul_f32_e32 v58, v42, v138
	s_waitcnt vmcnt(0)
	v_mul_f32_e32 v142, v34, v54
	v_mul_f32_e32 v144, v42, v54
	v_mov_b32_e32 v54, v139
	v_pk_mul_f32 v[56:57], v[40:41], v[52:53]
	v_pk_mul_f32 v[52:53], v[32:33], v[52:53]
	v_pk_mul_f32 v[140:141], v[140:141], v[54:55]
	v_mul_f32_e32 v138, v34, v138
	v_mov_b32_e32 v59, v140
	v_mov_b32_e32 v143, v141
	v_pk_fma_f32 v[140:141], v[40:41], v[136:137], v[52:53] neg_lo:[0,0,1] neg_hi:[0,0,1]
	v_mov_b32_e32 v52, v35
	v_mov_b32_e32 v53, v43
	v_pk_mul_f32 v[52:53], v[52:53], v[54:55]
	v_pk_add_f32 v[142:143], v[58:59], v[142:143] neg_lo:[0,1] neg_hi:[0,1]
	v_mov_b32_e32 v139, v52
	v_mov_b32_e32 v145, v53
	v_pk_fma_f32 v[136:137], v[32:33], v[136:137], v[56:57]
	v_pk_add_f32 v[138:139], v[138:139], v[144:145]

.LBB0_1241:
	s_nop 0
	s_nop 0
	s_nop 0
	s_nop 0
	s_nop 0
	s_nop 0
	s_nop 0
	s_nop 0
	s_nop 0
	v_mov_b64_e32 v[138:139], v[18:19]
	s_waitcnt lgkmcnt(0)
	s_nop 0
	v_mov_b32_e32 v56, v132
	v_mov_b32_e32 v57, v140
	s_nop 1
	v_permlane16_swap_b32_e32 v56, v57
	s_waitcnt lgkmcnt(0)
	s_nop 0
	v_mov_b32_e32 v52, v133
	v_mov_b32_e32 v58, v141
	s_nop 1
	v_permlane16_swap_b32_e32 v52, v58
	s_waitcnt lgkmcnt(0)
	s_nop 0
	v_mov_b32_e32 v53, v134
	v_mov_b32_e32 v59, v142
	s_nop 1
	v_permlane16_swap_b32_e32 v53, v59
	s_waitcnt lgkmcnt(0)
	s_nop 0
	v_mov_b32_e32 v54, v135
	v_mov_b32_e32 v55, v143
	s_nop 1
	v_permlane16_swap_b32_e32 v54, v55
	v_mov_b64_e32 v[130:131], v[22:23]
	v_mov_b64_e32 v[142:143], v[26:27]
	v_mov_b64_e32 v[134:135], v[30:31]
	v_cvt_pk_bf16_f32 v52, v56, v52
	v_cvt_pk_bf16_f32 v53, v53, v54
	v_cvt_pk_bf16_f32 v54, v57, v58
	v_cvt_pk_bf16_f32 v55, v59, v55
	v_or_b32_e32 v146, 0x60, v170
	v_mov_b64_e32 v[136:137], v[16:17]
	v_mov_b64_e32 v[128:129], v[20:21]
	v_mov_b64_e32 v[140:141], v[24:25]
	v_mov_b64_e32 v[132:133], v[28:29]
	global_store_dwordx4 v[164:165], v[52:55], off offset:64
	s_and_saveexec_b64 s[48:49], s[22:23]
	s_cbranch_execz .LBB0_1243
	v_or_b32_e32 v52, v168, v146
	v_lshlrev_b32_e32 v52, 7, v52
	v_mov_b32_e32 v53, v177
	v_lshl_add_u64 v[136:137], v[154:155], 0, v[52:53]
	v_lshl_add_u64 v[140:141], v[152:153], 0, v[52:53]
	global_load_dwordx4 v[52:55], v[136:137], off
	global_load_dwordx4 v[56:59], v[140:141], off
	v_mov_b32_e32 v132, v31
	v_mov_b32_e32 v133, v23
	s_waitcnt vmcnt(1)
	v_mul_f32_e32 v130, v30, v54
	s_waitcnt vmcnt(0)
	v_mul_f32_e32 v134, v22, v58
	v_mul_f32_e32 v138, v30, v58
	v_mov_b32_e32 v58, v55
	v_pk_mul_f32 v[128:129], v[28:29], v[56:57]
	v_pk_mul_f32 v[56:57], v[20:21], v[56:57]
	v_pk_mul_f32 v[132:133], v[132:133], v[58:59]
	v_mul_f32_e32 v54, v22, v54
	v_mov_b32_e32 v131, v132
	v_mov_b32_e32 v135, v133
	v_pk_fma_f32 v[132:133], v[28:29], v[52:53], v[56:57] neg_lo:[0,0,1] neg_hi:[0,0,1]
	v_mov_b32_e32 v56, v23
	v_mov_b32_e32 v57, v31
	v_pk_mul_f32 v[56:57], v[56:57], v[58:59]
	v_pk_add_f32 v[134:135], v[130:131], v[134:135] neg_lo:[0,1] neg_hi:[0,1]
	v_mov_b32_e32 v55, v56
	v_mov_b32_e32 v139, v57
	v_pk_fma_f32 v[128:129], v[20:21], v[52:53], v[128:129]
	v_pk_add_f32 v[130:131], v[54:55], v[138:139]
	global_load_dwordx4 v[136:139], v[136:137], off offset:64
	s_nop 0
	global_load_dwordx4 v[52:55], v[140:141], off offset:64
	v_mov_b32_e32 v140, v27
	v_mov_b32_e32 v141, v19
	s_waitcnt vmcnt(1)
	v_mul_f32_e32 v58, v26, v138
	s_waitcnt vmcnt(0)
	v_mul_f32_e32 v142, v18, v54
	v_mul_f32_e32 v144, v26, v54
	v_mov_b32_e32 v54, v139
	v_pk_mul_f32 v[56:57], v[24:25], v[52:53]
	v_pk_mul_f32 v[52:53], v[16:17], v[52:53]
	v_pk_mul_f32 v[140:141], v[140:141], v[54:55]
	v_mul_f32_e32 v138, v18, v138
	v_mov_b32_e32 v59, v140
	v_mov_b32_e32 v143, v141
	v_pk_fma_f32 v[140:141], v[24:25], v[136:137], v[52:53] neg_lo:[0,0,1] neg_hi:[0,0,1]
	v_mov_b32_e32 v52, v19
	v_mov_b32_e32 v53, v27
	v_pk_mul_f32 v[52:53], v[52:53], v[54:55]
	v_pk_add_f32 v[142:143], v[58:59], v[142:143] neg_lo:[0,1] neg_hi:[0,1]
	v_mov_b32_e32 v139, v52
	v_mov_b32_e32 v145, v53
	v_pk_fma_f32 v[136:137], v[16:17], v[136:137], v[56:57]
	v_pk_add_f32 v[138:139], v[138:139], v[144:145]

.LBB0_1269:
	s_nop 0
	s_nop 0
	s_nop 0
	s_nop 0
	s_nop 0
	s_nop 0
	s_nop 0
	s_nop 0
	s_nop 0
	v_mov_b64_e32 v[138:139], v[2:3]
	s_waitcnt lgkmcnt(0)
	s_nop 0
	v_mov_b32_e32 v56, v132
	v_mov_b32_e32 v57, v140
	s_nop 1
	v_permlane16_swap_b32_e32 v56, v57
	s_waitcnt lgkmcnt(0)
	s_nop 0
	v_mov_b32_e32 v52, v133
	v_mov_b32_e32 v58, v141
	s_nop 1
	v_permlane16_swap_b32_e32 v52, v58
	s_waitcnt lgkmcnt(0)
	s_nop 0
	v_mov_b32_e32 v53, v134
	v_mov_b32_e32 v59, v142
	s_nop 1
	v_permlane16_swap_b32_e32 v53, v59
	s_waitcnt lgkmcnt(0)
	s_nop 0
	v_mov_b32_e32 v54, v135
	v_mov_b32_e32 v55, v143
	s_nop 1
	v_permlane16_swap_b32_e32 v54, v55
	v_mov_b64_e32 v[130:131], v[6:7]
	v_mov_b64_e32 v[142:143], v[10:11]
	v_mov_b64_e32 v[134:135], v[14:15]
	v_cvt_pk_bf16_f32 v52, v56, v52
	v_cvt_pk_bf16_f32 v53, v53, v54
	v_cvt_pk_bf16_f32 v54, v57, v58
	v_cvt_pk_bf16_f32 v55, v59, v55
	v_or_b32_e32 v146, 0x70, v170
	v_mov_b64_e32 v[136:137], v[0:1]
	v_mov_b64_e32 v[128:129], v[4:5]
	v_mov_b64_e32 v[140:141], v[8:9]
	v_mov_b64_e32 v[132:133], v[12:13]
	global_store_dwordx4 v[164:165], v[52:55], off offset:64
	s_and_saveexec_b64 s[48:49], s[22:23]
	s_cbranch_execz .LBB0_1271
	v_or_b32_e32 v52, v168, v146
	v_lshlrev_b32_e32 v52, 7, v52
	v_mov_b32_e32 v53, v177
	v_lshl_add_u64 v[136:137], v[154:155], 0, v[52:53]
	v_lshl_add_u64 v[140:141], v[152:153], 0, v[52:53]
	global_load_dwordx4 v[52:55], v[136:137], off
	global_load_dwordx4 v[56:59], v[140:141], off
	v_mov_b32_e32 v132, v15
	v_mov_b32_e32 v133, v7
	s_waitcnt vmcnt(1)
	v_mul_f32_e32 v130, v14, v54
	s_waitcnt vmcnt(0)
	v_mul_f32_e32 v134, v6, v58
	v_mul_f32_e32 v138, v14, v58
	v_mov_b32_e32 v58, v55
	v_pk_mul_f32 v[128:129], v[12:13], v[56:57]
	v_pk_mul_f32 v[56:57], v[4:5], v[56:57]
	v_pk_mul_f32 v[132:133], v[132:133], v[58:59]
	v_mul_f32_e32 v54, v6, v54
	v_mov_b32_e32 v131, v132
	v_mov_b32_e32 v135, v133
	v_pk_fma_f32 v[132:133], v[12:13], v[52:53], v[56:57] neg_lo:[0,0,1] neg_hi:[0,0,1]
	v_mov_b32_e32 v56, v7
	v_mov_b32_e32 v57, v15
	v_pk_mul_f32 v[56:57], v[56:57], v[58:59]
	v_pk_add_f32 v[134:135], v[130:131], v[134:135] neg_lo:[0,1] neg_hi:[0,1]
	v_mov_b32_e32 v55, v56
	v_mov_b32_e32 v139, v57
	v_pk_fma_f32 v[128:129], v[4:5], v[52:53], v[128:129]
	v_pk_add_f32 v[130:131], v[54:55], v[138:139]
	global_load_dwordx4 v[136:139], v[136:137], off offset:64
	s_nop 0
	global_load_dwordx4 v[52:55], v[140:141], off offset:64
	v_mov_b32_e32 v140, v11
	v_mov_b32_e32 v141, v3
	s_waitcnt vmcnt(1)
	v_mul_f32_e32 v58, v10, v138
	s_waitcnt vmcnt(0)
	v_mul_f32_e32 v142, v2, v54
	v_mul_f32_e32 v144, v10, v54
	v_mov_b32_e32 v54, v139
	v_pk_mul_f32 v[56:57], v[8:9], v[52:53]
	v_pk_mul_f32 v[52:53], v[0:1], v[52:53]
	v_pk_mul_f32 v[140:141], v[140:141], v[54:55]
	v_mul_f32_e32 v138, v2, v138
	v_mov_b32_e32 v59, v140
	v_mov_b32_e32 v143, v141
	v_pk_fma_f32 v[140:141], v[8:9], v[136:137], v[52:53] neg_lo:[0,0,1] neg_hi:[0,0,1]
	v_mov_b32_e32 v52, v3
	v_mov_b32_e32 v53, v11
	v_pk_mul_f32 v[52:53], v[52:53], v[54:55]
	v_pk_add_f32 v[142:143], v[58:59], v[142:143] neg_lo:[0,1] neg_hi:[0,1]
	v_mov_b32_e32 v139, v52
	v_mov_b32_e32 v145, v53
	v_pk_fma_f32 v[136:137], v[0:1], v[136:137], v[56:57]
	v_pk_add_f32 v[138:139], v[138:139], v[144:145]

.LBB0_1291:
	v_mov_b32_e32 v163, v177
	v_lshl_add_u64 v[52:53], v[152:153], 0, v[162:163]
	v_mov_b32_e32 v161, v177
	v_lshl_add_u64 v[152:153], v[52:53], 0, v[160:161]
	s_nop 0
	s_nop 0
	s_nop 0
	s_nop 0
	s_nop 0
	s_nop 0
	s_nop 0
	s_nop 0
	s_and_b64 vcc, exec, s[44:45]
	s_waitcnt lgkmcnt(0)
	s_nop 0
	v_mov_b32_e32 v56, v144
	v_mov_b32_e32 v57, v148
	s_nop 1
	v_permlane16_swap_b32_e32 v56, v57
	s_waitcnt lgkmcnt(0)
	s_nop 0
	v_mov_b32_e32 v52, v145
	v_mov_b32_e32 v58, v149
	s_nop 1
	v_permlane16_swap_b32_e32 v52, v58
	s_waitcnt lgkmcnt(0)
	s_nop 0
	v_mov_b32_e32 v53, v146
	v_mov_b32_e32 v59, v150
	s_nop 1
	v_permlane16_swap_b32_e32 v53, v59
	s_waitcnt lgkmcnt(0)
	s_nop 0
	v_mov_b32_e32 v54, v147
	v_mov_b32_e32 v55, v151
	s_nop 1
	v_permlane16_swap_b32_e32 v54, v55
	v_cvt_pk_bf16_f32 v52, v56, v52
	v_cvt_pk_bf16_f32 v53, v53, v54
	v_cvt_pk_bf16_f32 v54, v57, v58
	v_cvt_pk_bf16_f32 v55, v59, v55
	s_mov_b64 s[22:23], -1
	global_store_dwordx4 v[152:153], v[52:55], off
	s_cbranch_vccnz .LBB0_1295
	v_mov_b64_e32 v[142:143], v[138:139]
	v_mov_b64_e32 v[134:135], v[130:131]
	s_and_b64 vcc, exec, s[40:41]
	v_mov_b64_e32 v[140:141], v[136:137]
	v_mov_b64_e32 v[132:133], v[128:129]
	s_cbranch_vccnz .LBB0_1294
	v_mul_f32_e32 v53, 0xbfb8aa3b, v136
	v_mul_f32_e32 v54, 0xbfb8aa3b, v129
	v_exp_f32_e32 v53, v53
	v_exp_f32_e32 v55, v54
	v_mul_f32_e32 v57, 0xbfb8aa3b, v138
	v_mul_f32_e32 v58, 0xbfb8aa3b, v131
	v_add_f32_e32 v53, 1.0, v53
	v_mul_f32_e32 v52, 0xbfb8aa3b, v128
	v_rcp_f32_e32 v54, v53
	v_add_f32_e32 v53, 1.0, v55
	v_mul_f32_e32 v55, 0xbfb8aa3b, v137
	v_mul_f32_e32 v56, 0xbfb8aa3b, v130
	v_exp_f32_e32 v57, v57
	v_exp_f32_e32 v59, v58
	v_mul_f32_e32 v58, 0xbfb8aa3b, v139
	v_exp_f32_e32 v52, v52
	v_exp_f32_e32 v55, v55
	v_exp_f32_e32 v56, v56
	v_exp_f32_e32 v132, v58
	v_add_f32_e32 v57, 1.0, v57
	v_add_f32_e32 v52, 1.0, v52
	v_add_f32_e32 v55, 1.0, v55
	v_add_f32_e32 v56, 1.0, v56
	v_rcp_f32_e32 v58, v57
	v_add_f32_e32 v57, 1.0, v59
	v_add_f32_e32 v59, 1.0, v132
	v_rcp_f32_e32 v52, v52
	v_rcp_f32_e32 v53, v53
	v_rcp_f32_e32 v56, v56
	v_rcp_f32_e32 v57, v57
	v_rcp_f32_e32 v59, v59
	v_rcp_f32_e32 v55, v55
	v_pk_mul_f32 v[132:133], v[128:129], v[52:53]
	v_pk_mul_f32 v[134:135], v[130:131], v[56:57]
	v_pk_mul_f32 v[142:143], v[138:139], v[58:59]
	v_pk_mul_f32 v[140:141], v[136:137], v[54:55]

.LBB0_1297:
	s_nop 0
	s_nop 0
	s_nop 0
	s_nop 0
	s_nop 0
	s_nop 0
	s_nop 0
	s_nop 0
	s_nop 0
	s_mov_b64 s[30:31], 0
	s_waitcnt lgkmcnt(0)
	s_nop 0
	v_mov_b32_e32 v56, v132
	v_mov_b32_e32 v57, v140
	s_nop 1
	v_permlane16_swap_b32_e32 v56, v57
	s_waitcnt lgkmcnt(0)
	s_nop 0
	v_mov_b32_e32 v52, v133
	v_mov_b32_e32 v58, v141
	s_nop 1
	v_permlane16_swap_b32_e32 v52, v58
	s_waitcnt lgkmcnt(0)
	s_nop 0
	v_mov_b32_e32 v53, v134
	v_mov_b32_e32 v59, v142
	s_nop 1
	v_permlane16_swap_b32_e32 v53, v59
	s_waitcnt lgkmcnt(0)
	s_nop 0
	v_mov_b32_e32 v54, v135
	v_mov_b32_e32 v55, v143
	s_nop 1
	v_permlane16_swap_b32_e32 v54, v55
	v_cvt_pk_bf16_f32 v52, v56, v52
	v_cvt_pk_bf16_f32 v53, v53, v54
	v_cvt_pk_bf16_f32 v54, v57, v58
	v_cvt_pk_bf16_f32 v55, v59, v55
	global_store_dwordx4 v[152:153], v[52:55], off offset:64
